# peel + trailing half runs the next unit's header before its post-epilogue offset barrier (overlaps the leading half's header and first load segment)
# baseline (speedup 1.0000x reference)
; #define PG8_STAGE(bufoff, gbase, voff) do { _Pragma("unroll") for (int _i = 0; _i < 2; ++_i) \
;         __builtin_amdgcn_global_load_lds((const unsigned*)((const char*)(gbase) + (voff)[_i]), (PG8_LAS unsigned*)(lds + (bufoff) + ldsw + _i * 8192), 16, 0, 0); } while (0)
; #define PG8_WAIT_V(n) asm volatile("s_waitcnt vmcnt(" #n ")" ::: "memory")
; #define PG8_BAR __builtin_amdgcn_s_barrier()
; template <class Epi, class Sched, bool ALIGN_EPI = false, bool SP2 = false>
; __device__ __forceinline__ void gemm_phase(PG8_LAS unsigned char* lds, const Gemm g, const Sched& S, const Epi& E) {
;     ...
;     for (int i = 0; i < 2; ++i) { int R, C; stage_rc(tid * 16 + i * 8192, R, C); const int Rb = Epi::PERM ? ((R & ~31) + perm32(R & 31)) : R;
;         voffA[i] = (unsigned)(R * g.lda + C) * 2u; voffB[i] = (unsigned)(Rb * g.ldb + C) * 2u; }
;     const size_t kstep = (size_t)(BK * 2);
;     const size_t hstepA = (size_t)HALF * g.lda * 2, hstepB = (size_t)HALF * g.ldb * 2;
;     const size_t tstepA = 2 * hstepA, tstepB = 2 * hstepB;
;     const unsigned ldsw = (unsigned)wid * 1024u;
;     const int aoff = lds_byte(wr * 64 + fr, fq * 8), boff = lds_byte(wc * 32 + fr, fq * 8);
;     ...
;     if constexpr (SP2) {
;         PG8_STAGE(PG8_SB(0, 0), cB, voffB); PG8_STAGE(PG8_SB(0, 1), cB + hstepB, voffB); PG8_STAGE(PG8_SA(0, 0), cA, voffA); PG8_STAGE(PG8_SA(0, 1), cA + hstepA, voffA);
;         if (wr == 1) PG8_BAR;
;         PG8_WAIT_V(2); PG8_BAR;
;         PG8_STAGE(PG8_SB(1, 0), cB + kstep, voffB); PG8_STAGE(PG8_SA(1, 0), cA + kstep, voffA); PG8_STAGE(PG8_SB(1, 1), cB + hstepB + kstep, voffB);
;         PG8_WAIT_V(6); PG8_BAR;
;     } else {
;         PG8_STAGE(PG8_SB(0, 0), cB, voffB); PG8_STAGE(PG8_SA(0, 0), cA, voffA); PG8_STAGE(PG8_SB(0, 1), cB + hstepB, voffB); PG8_STAGE(PG8_SA(0, 1), cA + hstepA, voffA);
;         if (wr == 1) PG8_BAR;
;         PG8_WAIT_V(4); PG8_BAR;
;         PG8_STAGE(PG8_SB(1, 0), cB + kstep, voffB); PG8_STAGE(PG8_SA(1, 0), cA + kstep, voffA); PG8_STAGE(PG8_SB(1, 1), cB + hstepB + kstep, voffB);
;         PG8_WAIT_V(6); PG8_BAR;
;     }
.LBB0_191:
	s_add_u32 s46, s78, 0x13c00000
	s_addc_u32 s47, s79, 0
	s_add_u32 s10, s78, 0x100000
	s_addc_u32 s11, s79, 0
	s_add_u32 s12, s78, 0x1bc00000
	s_mov_b64 s[14:15], 0x80
	s_addc_u32 s13, s79, 0
	s_and_b32 s5, s1, 3
	s_add_i32 m0, s40, 0x18000
	v_lshl_add_u64 v[8:9], v[8:9], 0, s[14:15]
	s_lshl_b32 s48, s0, 6
	s_lshl_b32 s7, s0, 13
	s_lshl_b32 s18, s5, 5
	s_lshl_b32 s5, s5, 12
	s_waitcnt vmcnt(2)
	s_barrier
	global_load_lds_dwordx4 v[8:9], off
	v_lshl_add_u64 v[6:7], v[6:7], 0, s[14:15]
	s_add_i32 m0, s40, 0x1a000
	s_add_i32 s49, s40, 0x8000
	s_add_i32 s50, s40, 0xa000
	global_load_lds_dwordx4 v[6:7], off
	v_lshl_add_u64 v[2:3], v[2:3], 0, s[14:15]
	s_mov_b32 m0, s49
	s_add_u32 s16, s28, 0x40080
	global_load_lds_dwordx4 v[2:3], off
	v_lshl_add_u64 v[2:3], v[4:5], 0, s[14:15]
	s_mov_b32 m0, s50
	s_addc_u32 s17, s29, 0
	global_load_lds_dwordx4 v[2:3], off
	s_add_i32 m0, s40, 0x1c000
	v_lshl_add_u64 v[2:3], s[16:17], 0, v[134:135]
	global_load_lds_dwordx4 v[2:3], off
	v_lshl_add_u64 v[2:3], s[16:17], 0, v[130:131]
	s_add_i32 m0, s40, 0x1e000
	v_and_b32_e32 v1, 15, v13
	global_load_lds_dwordx4 v[2:3], off
	v_bfe_u32 v3, v13, 4, 2
	v_lshlrev_b32_e32 v4, 4, v3
	v_lshlrev_b32_e32 v6, 2, v13
	v_lshlrev_b32_e32 v2, 3, v3
	v_lshl_or_b32 v5, v1, 6, v4
	v_and_b32_e32 v6, 32, v6
	s_cmpk_lt_u32 s2, 0x100
	v_bitop3_b32 v7, v5, s7, v6 bitop3:0xde
	v_bitop3_b32 v141, v5, s5, v6 bitop3:0xde
	v_or_b32_e32 v5, s18, v2
	s_cselect_b64 s[16:17], -1, 0
	v_lshlrev_b32_e32 v3, 2, v3
	s_lshl_b32 s1, s1, 4
	v_or_b32_e32 v161, 0xfffff800, v5
	v_and_or_b32 v140, s1, 16, v3
	v_mov_b32_e32 v5, v139
	v_lshlrev_b32_e32 v3, 14, v15
	s_sext_i32_i8 s0, s6
	v_lshl_add_u64 v[4:5], s[78:79], 0, v[4:5]
	s_mov_b64 s[6:7], 0x5800000
	v_and_b32_e32 v3, 0xffff8000, v3
	v_lshl_add_u64 v[144:145], v[4:5], 0, s[6:7]
	v_lshl_add_u32 v3, v14, 11, v3
	v_and_b32_e32 v4, 1, v15
	v_lshl_or_b32 v3, v4, 6, v3
	v_lshl_add_u32 v146, v16, 1, v3
	v_lshlrev_b32_e32 v3, 14, v10
	v_and_b32_e32 v3, 0xffff8000, v3
	v_lshl_add_u32 v3, v11, 11, v3
	v_and_b32_e32 v4, 1, v10
	s_waitcnt vmcnt(6)
	v_and_b32_e32 v6, 8, v2
	v_lshlrev_b32_e32 v138, 5, v1
	v_lshl_or_b32 v3, v4, 6, v3
	s_and_b32 s1, s18, 64
	v_lshl_add_u64 v[8:9], s[12:13], 0, v[138:139]
	v_lshlrev_b32_e32 v138, 1, v6
	v_lshl_add_u32 v148, v12, 1, v3
	s_add_i32 s53, 0, 0x10000
	s_add_i32 s54, 0, 0x14000
	v_mbcnt_lo_u32_b32 v3, -1, 0
	s_ashr_i32 s51, s82, 31
	s_mov_b32 s52, s82
	v_lshl_add_u64 v[142:143], v[8:9], 0, v[138:139]
	v_mov_b32_e32 v147, v139
	v_mov_b32_e32 v149, v139
	v_mov_b64_e32 v[150:151], 0x500
	v_mov_b64_e32 v[152:153], 0x4ff
	v_add_u32_e32 v163, s53, v141
	v_add_u32_e32 v165, s54, v141
	v_add_u32_e32 v167, 0, v7
	v_mbcnt_hi_u32_b32 v173, -1, v3
	v_mov_b32_e32 v175, 0x358637bd
	s_movk_i32 s55, 0x500
	v_lshlrev_b32_e32 v154, 1, v6
	s_lshl_b32 s56, s18, 1
	v_lshlrev_b32_e32 v156, 1, v2
	s_lshl_b32 s57, s1, 1
	s_movk_i32 s58, 0x1000
	s_movk_i32 s59, 0x3000
	v_mov_b32_e32 v183, 0x3e000000
	s_barrier
	s_mov_b32 s98, 0
	s_branch .LBB0_194

; #define PG8_STAGE(bufoff, gbase, voff) do { _Pragma("unroll") for (int _i = 0; _i < 2; ++_i) \
;         __builtin_amdgcn_global_load_lds((const unsigned*)((const char*)(gbase) + (voff)[_i]), (PG8_LAS unsigned*)(lds + (bufoff) + ldsw + _i * 8192), 16, 0, 0); } while (0)
; #define PG8_LDA(dst, b, h) do { _Pragma("unroll") for (int m = 0; m < 4; ++m) _Pragma("unroll") for (int k = 0; k < 2; ++k) dst[m][k] = *(const PG8_LAS bf16x8*)(lds + PG8_SA(b, h) + aoff + m * 2048 + k * 1024); } while (0)
; #define PG8_LDB(dst, b, h) do { _Pragma("unroll") for (int n = 0; n < 2; ++n) _Pragma("unroll") for (int k = 0; k < 2; ++k) dst[n][k] = *(const PG8_LAS bf16x8*)(lds + PG8_SB(b, h) + boff + n * 2048 + k * 1024); } while (0)
; #define PG8_WAIT_V(n) asm volatile("s_waitcnt vmcnt(" #n ")" ::: "memory")
; #define PG8_WAIT_L(n) asm volatile("s_waitcnt lgkmcnt(" #n ")" ::: "memory")
; template <class Epi, class Sched, bool ALIGN_EPI = false, bool SP2 = false>
; __device__ __forceinline__ void gemm_phase(PG8_LAS unsigned char* lds, const Gemm g, const Sched& S, const Epi& E) {
;     ...
;         const bool has_next = S.next(ui + 1, nxt);
;         const char* nA = has_next ? (const char*)g.A + (size_t)nxt.g * g.gsA * 2 + (size_t)nxt.pm * tstepA : cA; const char* nB = has_next ? (const char*)g.Bt + (size_t)nxt.g * g.gsB * 2 + (size_t)nxt.pn * tstepB : cB;
;         for (int t = 0; t < nt; t += 2) {
;             const bool last = (t == nt - 2);
;             const char* a1 = cA + (size_t)(t + 1) * kstep;
;             const char* a2 = last ? nA : cA + (size_t)(t + 2) * kstep; const char* b2 = last ? nB : cB + (size_t)(t + 2) * kstep;
;             const char* a3 = a2 + kstep; const char* b3 = b2 + kstep;
;             if (last && has_next) S.a_ready(nxt);
;             if constexpr (SP2) {
;             PG8_LDB(B0, 0, 0); PG8_LDB(B1, 0, 1); PG8_SCHED; PG8_LDA(At, 0, 0); PG8_STAGE(PG8_SA(1, 1), a1 + hstepA, voffA);
;             PG8_WAIT_V(8); PG8_WAIT_L(0); PG8_BAR; PG8_MMA(0, 0, At, B0); PG8_MMA(0, 1, At, B1); PG8_BAR; PG8_SCHED;
;             PG8_LDA(At, 0, 1); PG8_STAGE(PG8_SB(0, 0), b2, voffB); PG8_STAGE(PG8_SB(0, 1), b2 + hstepB, voffB); PG8_STAGE(PG8_SA(0, 0), a2, voffA);
;             PG8_WAIT_V(8); PG8_WAIT_L(0); PG8_BAR; PG8_MMA(1, 0, At, B0); PG8_MMA(1, 1, At, B1); PG8_BAR; PG8_SCHED;
;     ...
;         if constexpr (ALIGN_EPI) { if (wr == 1) PG8_BAR; }
.LBB0_196:
	s_ashr_i32 s21, s20, 31
	s_lshl_b64 s[22:23], s[20:21], 19
	s_add_u32 s22, s3, s22
	s_addc_u32 s23, s34, s23
	s_and_b64 s[24:25], s[6:7], exec
	s_cselect_b32 s1, s23, s27
	s_cselect_b32 s2, s22, s26
	s_ashr_i32 s19, s18, 31
	s_lshl_b64 s[24:25], s[18:19], 19
	s_add_u32 s24, s35, s24
	s_addc_u32 s25, s36, s25
	s_and_b64 s[30:31], s[6:7], exec
	s_cselect_b32 s5, s25, s29
	s_cselect_b32 s19, s24, s28
	s_add_u32 s26, s26, 0x40080
	s_addc_u32 s27, s27, 0
	s_add_u32 s21, s28, 0x100
	s_addc_u32 s33, s29, 0
	s_mov_b32 s60, -2
	s_waitcnt lgkmcnt(0)
	s_cmp_eq_u32 s98, 1
	s_cbranch_scc0 .Lhb_7344
	s_mov_b32 s98, 0
	s_barrier
.Lhb_7344:
	ds_read_b128 v[168:171], v163
	ds_read_b128 v[176:179], v163 offset:1024
	ds_read_b128 v[184:187], v163 offset:2048
	ds_read_b128 v[188:191], v163 offset:3072
	ds_read_b128 v[192:195], v165
	ds_read_b128 v[196:199], v165 offset:1024
	ds_read_b128 v[200:203], v165 offset:2048
	ds_read_b128 v[204:207], v165 offset:3072
	s_add_u32 s28, s26, 0xfffc0080
	s_addc_u32 s29, s27, -1
	s_cmp_eq_u32 s60, 12
	s_cselect_b32 s31, s1, s29
	s_cselect_b32 s30, s2, s28
	s_cselect_b32 s29, s5, s33
	s_cselect_b32 s28, s19, s21
	v_lshl_add_u64 v[158:159], s[26:27], 0, v[146:147]
	s_add_i32 m0, s40, 0xc000
	ds_read_b128 v[208:211], v167
	ds_read_b128 v[212:215], v167 offset:1024
	ds_read_b128 v[216:219], v167 offset:2048
	ds_read_b128 v[220:223], v167 offset:3072
	ds_read_b128 v[224:227], v167 offset:4096
	ds_read_b128 v[228:231], v167 offset:5120
	ds_read_b128 v[232:235], v167 offset:6144
	ds_read_b128 v[236:239], v167 offset:7168
	global_load_lds_dwordx4 v[158:159], off
	v_lshl_add_u64 v[158:159], s[26:27], 0, v[148:149]
	s_add_i32 m0, s40, 0xe000
	s_nop 0
	global_load_lds_dwordx4 v[158:159], off
	s_waitcnt vmcnt(8)
	s_waitcnt lgkmcnt(0)
	s_barrier
	s_setprio 1
	s_waitcnt lgkmcnt(0)
	v_mfma_f32_16x16x32_bf16 v[126:129], v[168:171], v[208:211], 0
	v_mfma_f32_16x16x32_bf16 v[122:125], v[184:187], v[208:211], 0
	v_mfma_f32_16x16x32_bf16 v[110:113], v[168:171], v[216:219], 0
	v_mfma_f32_16x16x32_bf16 v[106:109], v[184:187], v[216:219], 0
	v_mfma_f32_16x16x32_bf16 v[94:97], v[168:171], v[224:227], 0
	v_mfma_f32_16x16x32_bf16 v[90:93], v[184:187], v[224:227], 0
	v_mfma_f32_16x16x32_bf16 v[78:81], v[168:171], v[232:235], 0
	v_mfma_f32_16x16x32_bf16 v[74:77], v[184:187], v[232:235], 0
	v_mfma_f32_16x16x32_bf16 v[126:129], v[176:179], v[212:215], v[126:129]
	v_mfma_f32_16x16x32_bf16 v[122:125], v[188:191], v[212:215], v[122:125]
	v_mfma_f32_16x16x32_bf16 v[110:113], v[176:179], v[220:223], v[110:113]
	v_mfma_f32_16x16x32_bf16 v[106:109], v[188:191], v[220:223], v[106:109]
	v_mfma_f32_16x16x32_bf16 v[94:97], v[176:179], v[228:231], v[94:97]
	v_mfma_f32_16x16x32_bf16 v[90:93], v[188:191], v[228:231], v[90:93]
	v_mfma_f32_16x16x32_bf16 v[78:81], v[176:179], v[236:239], v[78:81]
	v_mfma_f32_16x16x32_bf16 v[74:77], v[188:191], v[236:239], v[74:77]
	s_setprio 0
	s_setprio 1
	v_mfma_f32_16x16x32_bf16 v[118:121], v[192:195], v[208:211], 0
	v_mfma_f32_16x16x32_bf16 v[114:117], v[200:203], v[208:211], 0
	v_mfma_f32_16x16x32_bf16 v[102:105], v[192:195], v[216:219], 0
	v_mfma_f32_16x16x32_bf16 v[98:101], v[200:203], v[216:219], 0
	v_mfma_f32_16x16x32_bf16 v[86:89], v[192:195], v[224:227], 0
	v_mfma_f32_16x16x32_bf16 v[82:85], v[200:203], v[224:227], 0
	v_mfma_f32_16x16x32_bf16 v[70:73], v[192:195], v[232:235], 0
	v_mfma_f32_16x16x32_bf16 v[66:69], v[200:203], v[232:235], 0
	v_mfma_f32_16x16x32_bf16 v[118:121], v[196:199], v[212:215], v[118:121]
	v_mfma_f32_16x16x32_bf16 v[114:117], v[204:207], v[212:215], v[114:117]
	v_mfma_f32_16x16x32_bf16 v[102:105], v[196:199], v[220:223], v[102:105]
	v_mfma_f32_16x16x32_bf16 v[98:101], v[204:207], v[220:223], v[98:101]
	v_mfma_f32_16x16x32_bf16 v[86:89], v[196:199], v[228:231], v[86:89]
	v_mfma_f32_16x16x32_bf16 v[82:85], v[204:207], v[228:231], v[82:85]
	v_mfma_f32_16x16x32_bf16 v[70:73], v[196:199], v[236:239], v[70:73]
	v_mfma_f32_16x16x32_bf16 v[66:69], v[204:207], v[236:239], v[66:69]
	s_setprio 0
	s_barrier
	s_add_i32 s61, s53, s37
	v_lshl_add_u64 v[158:159], s[28:29], 0, v[134:135]
	s_mov_b32 m0, s61
	ds_read_b128 v[208:211], v167 offset:16384
	ds_read_b128 v[212:215], v167 offset:17408
	ds_read_b128 v[216:219], v167 offset:18432
	ds_read_b128 v[220:223], v167 offset:19456
	ds_read_b128 v[224:227], v167 offset:20480
	ds_read_b128 v[228:231], v167 offset:21504
	ds_read_b128 v[232:235], v167 offset:22528
	ds_read_b128 v[236:239], v167 offset:23552
	global_load_lds_dwordx4 v[158:159], off
	s_add_i32 m0, s61, 0x2000
	s_add_u32 s62, s28, 0x40000
	v_lshl_add_u64 v[180:181], s[28:29], 0, v[130:131]
	s_addc_u32 s63, s29, 0
	s_add_i32 s61, s54, s37
	global_load_lds_dwordx4 v[180:181], off
	v_lshl_add_u64 v[240:241], s[62:63], 0, v[134:135]
	s_mov_b32 m0, s61
	v_lshl_add_u64 v[242:243], s[30:31], 0, v[132:133]
	global_load_lds_dwordx4 v[240:241], off
	v_lshl_add_u64 v[240:241], s[62:63], 0, v[130:131]
	s_add_i32 m0, s61, 0x2000
	s_nop 0
	global_load_lds_dwordx4 v[240:241], off
	v_lshl_add_u64 v[240:241], s[30:31], 0, v[136:137]
	s_mov_b32 m0, s40
	s_nop 0
	global_load_lds_dwordx4 v[240:241], off
	s_mov_b32 m0, s41
	s_nop 0
	global_load_lds_dwordx4 v[242:243], off
	s_waitcnt vmcnt(8)
	s_waitcnt lgkmcnt(0)
	s_barrier
; #define PG8_STAGE(bufoff, gbase, voff) do { _Pragma("unroll") for (int _i = 0; _i < 2; ++_i) \
;         __builtin_amdgcn_global_load_lds((const unsigned*)((const char*)(gbase) + (voff)[_i]), (PG8_LAS unsigned*)(lds + (bufoff) + ldsw + _i * 8192), 16, 0, 0); } while (0)
; #define PG8_LDA(dst, b, h) do { _Pragma("unroll") for (int m = 0; m < 4; ++m) _Pragma("unroll") for (int k = 0; k < 2; ++k) dst[m][k] = *(const PG8_LAS bf16x8*)(lds + PG8_SA(b, h) + aoff + m * 2048 + k * 1024); } while (0)
; #define PG8_LDB(dst, b, h) do { _Pragma("unroll") for (int n = 0; n < 2; ++n) _Pragma("unroll") for (int k = 0; k < 2; ++k) dst[n][k] = *(const PG8_LAS bf16x8*)(lds + PG8_SB(b, h) + boff + n * 2048 + k * 1024); } while (0)
; #define PG8_MMA(ai, bj, At, Bt) do { __builtin_amdgcn_s_setprio(1); _Pragma("unroll") for (int m = 0; m < 4; ++m) _Pragma("unroll") for (int n = 0; n < 2; ++n) _Pragma("unroll") for (int k = 0; k < 2; ++k) \
;         acc[ai][bj][m][n] = __builtin_amdgcn_mfma_f32_16x16x32_bf16(Bt[n][k], At[m][k], acc[ai][bj][m][n], 0, 0, 0); __builtin_amdgcn_s_setprio(0); } while (0)
; #define PG8_WAIT_V(n) asm volatile("s_waitcnt vmcnt(" #n ")" ::: "memory")
; #define PG8_WAIT_L(n) asm volatile("s_waitcnt lgkmcnt(" #n ")" ::: "memory")
; #define PG8_BAR __builtin_amdgcn_s_barrier()
; #define PG8_SCHED __builtin_amdgcn_sched_barrier(0)
; template <class Epi, class Sched, bool ALIGN_EPI = false, bool SP2 = false>
; __device__ __forceinline__ void gemm_phase(PG8_LAS unsigned char* lds, const Gemm g, const Sched& S, const Epi& E) {
;     ...
;             PG8_WAIT_V(8); PG8_WAIT_L(0); PG8_BAR; PG8_MMA(1, 0, At, B0); PG8_MMA(1, 1, At, B1); PG8_BAR; PG8_SCHED;
;             PG8_LDB(B0, 1, 0); PG8_LDB(B1, 1, 1); PG8_SCHED; PG8_LDA(At, 1, 0); PG8_STAGE(PG8_SA(0, 1), a2 + hstepA, voffA);
;             PG8_WAIT_V(8); PG8_WAIT_L(0); PG8_BAR; PG8_MMA(0, 0, At, B0); PG8_MMA(0, 1, At, B1); PG8_BAR; PG8_SCHED;
	s_setprio 1
	s_waitcnt lgkmcnt(0)
	v_mfma_f32_16x16x32_bf16 v[62:65], v[168:171], v[208:211], 0
	v_mfma_f32_16x16x32_bf16 v[58:61], v[184:187], v[208:211], 0
	v_mfma_f32_16x16x32_bf16 v[46:49], v[168:171], v[216:219], 0
	v_mfma_f32_16x16x32_bf16 v[42:45], v[184:187], v[216:219], 0
	v_mfma_f32_16x16x32_bf16 v[30:33], v[168:171], v[224:227], 0
	v_mfma_f32_16x16x32_bf16 v[26:29], v[184:187], v[224:227], 0
	v_mfma_f32_16x16x32_bf16 v[14:17], v[168:171], v[232:235], 0
	v_mfma_f32_16x16x32_bf16 v[10:13], v[184:187], v[232:235], 0
	v_mfma_f32_16x16x32_bf16 v[62:65], v[176:179], v[212:215], v[62:65]
	v_mfma_f32_16x16x32_bf16 v[58:61], v[188:191], v[212:215], v[58:61]
	v_mfma_f32_16x16x32_bf16 v[46:49], v[176:179], v[220:223], v[46:49]
	v_mfma_f32_16x16x32_bf16 v[42:45], v[188:191], v[220:223], v[42:45]
	v_mfma_f32_16x16x32_bf16 v[30:33], v[176:179], v[228:231], v[30:33]
	v_mfma_f32_16x16x32_bf16 v[26:29], v[188:191], v[228:231], v[26:29]
	v_mfma_f32_16x16x32_bf16 v[14:17], v[176:179], v[236:239], v[14:17]
	v_mfma_f32_16x16x32_bf16 v[10:13], v[188:191], v[236:239], v[10:13]
	s_setprio 0
	s_setprio 1
	v_mfma_f32_16x16x32_bf16 v[54:57], v[192:195], v[208:211], 0
	v_mfma_f32_16x16x32_bf16 v[50:53], v[200:203], v[208:211], 0
	v_mfma_f32_16x16x32_bf16 v[38:41], v[192:195], v[216:219], 0
	v_mfma_f32_16x16x32_bf16 v[34:37], v[200:203], v[216:219], 0
	v_mfma_f32_16x16x32_bf16 v[22:25], v[192:195], v[224:227], 0
	v_mfma_f32_16x16x32_bf16 v[18:21], v[200:203], v[224:227], 0
	v_mfma_f32_16x16x32_bf16 v[6:9], v[192:195], v[232:235], 0
	v_mfma_f32_16x16x32_bf16 v[2:5], v[200:203], v[232:235], 0
	v_mfma_f32_16x16x32_bf16 v[54:57], v[196:199], v[212:215], v[54:57]
	v_mfma_f32_16x16x32_bf16 v[50:53], v[204:207], v[212:215], v[50:53]
	v_mfma_f32_16x16x32_bf16 v[38:41], v[196:199], v[220:223], v[38:41]
	v_mfma_f32_16x16x32_bf16 v[34:37], v[204:207], v[220:223], v[34:37]
	v_mfma_f32_16x16x32_bf16 v[22:25], v[196:199], v[228:231], v[22:25]
	v_mfma_f32_16x16x32_bf16 v[18:21], v[204:207], v[228:231], v[18:21]
	v_mfma_f32_16x16x32_bf16 v[6:9], v[196:199], v[236:239], v[6:9]
	v_mfma_f32_16x16x32_bf16 v[2:5], v[204:207], v[236:239], v[2:5]
	s_setprio 0
	s_barrier
	s_add_i32 s61, 0, 0x18000
	v_add_u32_e32 v138, s61, v141
	s_add_i32 s62, 0, 0x1c000
	ds_read_b128 v[168:171], v138
	ds_read_b128 v[176:179], v138 offset:1024
	ds_read_b128 v[184:187], v138 offset:2048
	ds_read_b128 v[188:191], v138 offset:3072
	v_add_u32_e32 v138, s62, v141
	ds_read_b128 v[192:195], v138
	ds_read_b128 v[196:199], v138 offset:1024
	ds_read_b128 v[200:203], v138 offset:2048
	ds_read_b128 v[204:207], v138 offset:3072
	s_add_u32 s30, s30, 0x40000
	s_addc_u32 s31, s31, 0
	s_mov_b32 m0, s42
	v_lshl_add_u64 v[244:245], s[30:31], 0, v[136:137]
	ds_read_b128 v[208:211], v167 offset:32768
	ds_read_b128 v[212:215], v167 offset:33792
	ds_read_b128 v[216:219], v167 offset:34816
	ds_read_b128 v[220:223], v167 offset:35840
	ds_read_b128 v[224:227], v167 offset:36864
	ds_read_b128 v[228:231], v167 offset:37888
	ds_read_b128 v[232:235], v167 offset:38912
	ds_read_b128 v[236:239], v167 offset:39936
	global_load_lds_dwordx4 v[244:245], off
	v_lshl_add_u64 v[244:245], s[30:31], 0, v[132:133]
	s_mov_b32 m0, s43
	s_nop 0
	global_load_lds_dwordx4 v[244:245], off
	s_waitcnt vmcnt(8)
	s_waitcnt lgkmcnt(0)
	s_barrier
	s_setprio 1
	s_waitcnt lgkmcnt(0)
	v_mfma_f32_16x16x32_bf16 v[126:129], v[168:171], v[208:211], v[126:129]
	v_mfma_f32_16x16x32_bf16 v[122:125], v[184:187], v[208:211], v[122:125]
	v_mfma_f32_16x16x32_bf16 v[110:113], v[168:171], v[216:219], v[110:113]
	v_mfma_f32_16x16x32_bf16 v[106:109], v[184:187], v[216:219], v[106:109]
	v_mfma_f32_16x16x32_bf16 v[94:97], v[168:171], v[224:227], v[94:97]
	v_mfma_f32_16x16x32_bf16 v[90:93], v[184:187], v[224:227], v[90:93]
	v_mfma_f32_16x16x32_bf16 v[78:81], v[168:171], v[232:235], v[78:81]
	v_mfma_f32_16x16x32_bf16 v[74:77], v[184:187], v[232:235], v[74:77]
	v_mfma_f32_16x16x32_bf16 v[126:129], v[176:179], v[212:215], v[126:129]
	v_mfma_f32_16x16x32_bf16 v[122:125], v[188:191], v[212:215], v[122:125]
	v_mfma_f32_16x16x32_bf16 v[110:113], v[176:179], v[220:223], v[110:113]
	v_mfma_f32_16x16x32_bf16 v[106:109], v[188:191], v[220:223], v[106:109]
	v_mfma_f32_16x16x32_bf16 v[94:97], v[176:179], v[228:231], v[94:97]
	v_mfma_f32_16x16x32_bf16 v[90:93], v[188:191], v[228:231], v[90:93]
	v_mfma_f32_16x16x32_bf16 v[78:81], v[176:179], v[236:239], v[78:81]
	v_mfma_f32_16x16x32_bf16 v[74:77], v[188:191], v[236:239], v[74:77]
	s_setprio 0
	s_setprio 1
	v_mfma_f32_16x16x32_bf16 v[118:121], v[192:195], v[208:211], v[118:121]
	v_mfma_f32_16x16x32_bf16 v[114:117], v[200:203], v[208:211], v[114:117]
	v_mfma_f32_16x16x32_bf16 v[102:105], v[192:195], v[216:219], v[102:105]
	v_mfma_f32_16x16x32_bf16 v[98:101], v[200:203], v[216:219], v[98:101]
	v_mfma_f32_16x16x32_bf16 v[86:89], v[192:195], v[224:227], v[86:89]
	v_mfma_f32_16x16x32_bf16 v[82:85], v[200:203], v[224:227], v[82:85]
	v_mfma_f32_16x16x32_bf16 v[70:73], v[192:195], v[232:235], v[70:73]
	v_mfma_f32_16x16x32_bf16 v[66:69], v[200:203], v[232:235], v[66:69]
	v_mfma_f32_16x16x32_bf16 v[118:121], v[196:199], v[212:215], v[118:121]
	v_mfma_f32_16x16x32_bf16 v[114:117], v[204:207], v[212:215], v[114:117]
	v_mfma_f32_16x16x32_bf16 v[102:105], v[196:199], v[220:223], v[102:105]
	v_mfma_f32_16x16x32_bf16 v[98:101], v[204:207], v[220:223], v[98:101]
	v_mfma_f32_16x16x32_bf16 v[86:89], v[196:199], v[228:231], v[86:89]
	v_mfma_f32_16x16x32_bf16 v[82:85], v[204:207], v[228:231], v[82:85]
	v_mfma_f32_16x16x32_bf16 v[70:73], v[196:199], v[236:239], v[70:73]
	v_mfma_f32_16x16x32_bf16 v[66:69], v[204:207], v[236:239], v[66:69]
	s_setprio 0
	s_barrier
; #define PG8_STAGE(bufoff, gbase, voff) do { _Pragma("unroll") for (int _i = 0; _i < 2; ++_i) \
;         __builtin_amdgcn_global_load_lds((const unsigned*)((const char*)(gbase) + (voff)[_i]), (PG8_LAS unsigned*)(lds + (bufoff) + ldsw + _i * 8192), 16, 0, 0); } while (0)
; #define PG8_LDA(dst, b, h) do { _Pragma("unroll") for (int m = 0; m < 4; ++m) _Pragma("unroll") for (int k = 0; k < 2; ++k) dst[m][k] = *(const PG8_LAS bf16x8*)(lds + PG8_SA(b, h) + aoff + m * 2048 + k * 1024); } while (0)
; #define PG8_MMA(ai, bj, At, Bt) do { __builtin_amdgcn_s_setprio(1); _Pragma("unroll") for (int m = 0; m < 4; ++m) _Pragma("unroll") for (int n = 0; n < 2; ++n) _Pragma("unroll") for (int k = 0; k < 2; ++k) \
;         acc[ai][bj][m][n] = __builtin_amdgcn_mfma_f32_16x16x32_bf16(Bt[n][k], At[m][k], acc[ai][bj][m][n], 0, 0, 0); __builtin_amdgcn_s_setprio(0); } while (0)
; #define PG8_WAIT_V(n) asm volatile("s_waitcnt vmcnt(" #n ")" ::: "memory")
; #define PG8_WAIT_L(n) asm volatile("s_waitcnt lgkmcnt(" #n ")" ::: "memory")
; #define PG8_BAR __builtin_amdgcn_s_barrier()
; #define PG8_SCHED __builtin_amdgcn_sched_barrier(0)
; template <class Epi, class Sched, bool ALIGN_EPI = false, bool SP2 = false>
; __device__ __forceinline__ void gemm_phase(PG8_LAS unsigned char* lds, const Gemm g, const Sched& S, const Epi& E) {
;     ...
;         for (int t = 0; t < nt; t += 2) {
;     ...
;             PG8_LDA(At, 1, 1); PG8_STAGE(PG8_SB(1, 0), b3, voffB); PG8_STAGE(PG8_SB(1, 1), b3 + hstepB, voffB); PG8_STAGE(PG8_SA(1, 0), a3, voffA);
;             PG8_WAIT_V(8); PG8_WAIT_L(0); PG8_BAR; PG8_MMA(1, 0, At, B0); PG8_MMA(1, 1, At, B1); PG8_BAR; PG8_SCHED;
	s_add_i32 s30, s61, s37
	v_lshl_add_u64 v[158:159], v[158:159], 0, s[14:15]
	s_mov_b32 m0, s30
	ds_read_b128 v[208:211], v167 offset:49152
	ds_read_b128 v[212:215], v167 offset:50176
	ds_read_b128 v[216:219], v167 offset:51200
	ds_read_b128 v[220:223], v167 offset:52224
	ds_read_b128 v[224:227], v167 offset:53248
	ds_read_b128 v[228:231], v167 offset:54272
	ds_read_b128 v[232:235], v167 offset:55296
	ds_read_b128 v[236:239], v167 offset:56320
	global_load_lds_dwordx4 v[158:159], off
	s_add_i32 m0, s30, 0x2000
	s_add_u32 s28, s28, 0x40080
	v_lshl_add_u64 v[158:159], v[180:181], 0, s[14:15]
	s_addc_u32 s29, s29, 0
	s_add_i32 s30, s62, s37
	global_load_lds_dwordx4 v[158:159], off
	v_lshl_add_u64 v[158:159], s[28:29], 0, v[134:135]
	s_mov_b32 m0, s30
	s_nop 0
	global_load_lds_dwordx4 v[158:159], off
	v_lshl_add_u64 v[158:159], s[28:29], 0, v[130:131]
	s_add_i32 m0, s30, 0x2000
	s_nop 0
	global_load_lds_dwordx4 v[158:159], off
	v_lshl_add_u64 v[158:159], v[240:241], 0, s[14:15]
	s_mov_b32 m0, s49
	s_nop 0
	global_load_lds_dwordx4 v[158:159], off
	v_lshl_add_u64 v[158:159], v[242:243], 0, s[14:15]
	s_mov_b32 m0, s50
	s_nop 0
	global_load_lds_dwordx4 v[158:159], off
	s_waitcnt vmcnt(8)
	s_waitcnt lgkmcnt(0)
	s_barrier
	s_setprio 1
	s_waitcnt lgkmcnt(0)
	v_mfma_f32_16x16x32_bf16 v[62:65], v[168:171], v[208:211], v[62:65]
	v_mfma_f32_16x16x32_bf16 v[58:61], v[184:187], v[208:211], v[58:61]
	v_mfma_f32_16x16x32_bf16 v[46:49], v[168:171], v[216:219], v[46:49]
	v_mfma_f32_16x16x32_bf16 v[42:45], v[184:187], v[216:219], v[42:45]
	v_mfma_f32_16x16x32_bf16 v[30:33], v[168:171], v[224:227], v[30:33]
	v_mfma_f32_16x16x32_bf16 v[26:29], v[184:187], v[224:227], v[26:29]
	v_mfma_f32_16x16x32_bf16 v[14:17], v[168:171], v[232:235], v[14:17]
	v_mfma_f32_16x16x32_bf16 v[10:13], v[184:187], v[232:235], v[10:13]
	v_mfma_f32_16x16x32_bf16 v[62:65], v[176:179], v[212:215], v[62:65]
	v_mfma_f32_16x16x32_bf16 v[58:61], v[188:191], v[212:215], v[58:61]
	v_mfma_f32_16x16x32_bf16 v[46:49], v[176:179], v[220:223], v[46:49]
	v_mfma_f32_16x16x32_bf16 v[42:45], v[188:191], v[220:223], v[42:45]
	v_mfma_f32_16x16x32_bf16 v[30:33], v[176:179], v[228:231], v[30:33]
	v_mfma_f32_16x16x32_bf16 v[26:29], v[188:191], v[228:231], v[26:29]
	v_mfma_f32_16x16x32_bf16 v[14:17], v[176:179], v[236:239], v[14:17]
	v_mfma_f32_16x16x32_bf16 v[10:13], v[188:191], v[236:239], v[10:13]
	s_setprio 0
	s_setprio 1
	v_mfma_f32_16x16x32_bf16 v[54:57], v[192:195], v[208:211], v[54:57]
	v_mfma_f32_16x16x32_bf16 v[50:53], v[200:203], v[208:211], v[50:53]
	v_mfma_f32_16x16x32_bf16 v[38:41], v[192:195], v[216:219], v[38:41]
	v_mfma_f32_16x16x32_bf16 v[34:37], v[200:203], v[216:219], v[34:37]
	v_mfma_f32_16x16x32_bf16 v[22:25], v[192:195], v[224:227], v[22:25]
	v_mfma_f32_16x16x32_bf16 v[18:21], v[200:203], v[224:227], v[18:21]
	v_mfma_f32_16x16x32_bf16 v[6:9], v[192:195], v[232:235], v[6:9]
	v_mfma_f32_16x16x32_bf16 v[2:5], v[200:203], v[232:235], v[2:5]
	v_mfma_f32_16x16x32_bf16 v[54:57], v[196:199], v[212:215], v[54:57]
	v_mfma_f32_16x16x32_bf16 v[50:53], v[204:207], v[212:215], v[50:53]
	v_mfma_f32_16x16x32_bf16 v[38:41], v[196:199], v[220:223], v[38:41]
	v_mfma_f32_16x16x32_bf16 v[34:37], v[204:207], v[220:223], v[34:37]
	v_mfma_f32_16x16x32_bf16 v[22:25], v[196:199], v[228:231], v[22:25]
	v_mfma_f32_16x16x32_bf16 v[18:21], v[204:207], v[228:231], v[18:21]
	v_mfma_f32_16x16x32_bf16 v[6:9], v[196:199], v[236:239], v[6:9]
	v_mfma_f32_16x16x32_bf16 v[2:5], v[204:207], v[236:239], v[2:5]
	s_setprio 0
	s_barrier
	s_add_i32 s60, s60, 2
	s_add_u32 s26, s26, 0x100
	s_addc_u32 s27, s27, 0
	s_add_u32 s21, s21, 0x100
	s_addc_u32 s33, s33, 0
	s_cmp_gt_u32 s60, 13

; #define PG8_BAR __builtin_amdgcn_s_barrier()
; template <class Epi, class Sched, bool ALIGN_EPI = false, bool SP2 = false>
; __device__ __forceinline__ void gemm_phase(PG8_LAS unsigned char* lds, const Gemm g, const Sched& S, const Epi& E) {
;     ...
;         if constexpr (ALIGN_EPI) { if (wr == 0) PG8_BAR; }
;         if constexpr (!Epi::AFTER_DRAIN) { E(acc, cur, wr, wc, fr, fq); S.done(cur); }
;         if (!has_next) break;
; #pragma unroll
;         for (int a = 0; a < 2; ++a)
; #pragma unroll
;             for (int b = 0; b < 2; ++b)
; #pragma unroll
;                 for (int m = 0; m < 4; ++m)
; #pragma unroll
;                     for (int n = 0; n < 2; ++n) acc[a][b][m][n] = (f32x4){0.f, 0.f, 0.f, 0.f};
;         cur = nxt; cA = nA; cB = nB; ++ui;
;         if constexpr (ALIGN_EPI) { if (wr == 1) PG8_BAR; }
.LBB0_209:
	s_andn2_b64 vcc, exec, s[8:9]
	s_cbranch_vccnz .LBB0_192
	s_mov_b32 s98, 1
	s_branch .LBB0_192

; #define PG8_STAGE(bufoff, gbase, voff) do { _Pragma("unroll") for (int _i = 0; _i < 2; ++_i) \
;         __builtin_amdgcn_global_load_lds((const unsigned*)((const char*)(gbase) + (voff)[_i]), (PG8_LAS unsigned*)(lds + (bufoff) + ldsw + _i * 8192), 16, 0, 0); } while (0)
; #define PG8_WAIT_V(n) asm volatile("s_waitcnt vmcnt(" #n ")" ::: "memory")
; #define PG8_BAR __builtin_amdgcn_s_barrier()
; template <class Epi, class Sched, bool ALIGN_EPI = false, bool SP2 = false>
; __device__ __forceinline__ void gemm_phase(PG8_LAS unsigned char* lds, const Gemm g, const Sched& S, const Epi& E) {
;     ...
;     for (int i = 0; i < 2; ++i) { int R, C; stage_rc(tid * 16 + i * 8192, R, C); const int Rb = Epi::PERM ? ((R & ~31) + perm32(R & 31)) : R;
;         voffA[i] = (unsigned)(R * g.lda + C) * 2u; voffB[i] = (unsigned)(Rb * g.ldb + C) * 2u; }
;     const size_t kstep = (size_t)(BK * 2);
;     const size_t hstepA = (size_t)HALF * g.lda * 2, hstepB = (size_t)HALF * g.ldb * 2;
;     const size_t tstepA = 2 * hstepA, tstepB = 2 * hstepB;
;     const unsigned ldsw = (unsigned)wid * 1024u;
;     const int aoff = lds_byte(wr * 64 + fr, fq * 8), boff = lds_byte(wc * 32 + fr, fq * 8);
;     ...
;     if constexpr (SP2) {
;         PG8_STAGE(PG8_SB(0, 0), cB, voffB); PG8_STAGE(PG8_SB(0, 1), cB + hstepB, voffB); PG8_STAGE(PG8_SA(0, 0), cA, voffA); PG8_STAGE(PG8_SA(0, 1), cA + hstepA, voffA);
;         if (wr == 1) PG8_BAR;
;         PG8_WAIT_V(2); PG8_BAR;
;         PG8_STAGE(PG8_SB(1, 0), cB + kstep, voffB); PG8_STAGE(PG8_SA(1, 0), cA + kstep, voffA); PG8_STAGE(PG8_SB(1, 1), cB + hstepB + kstep, voffB);
;         PG8_WAIT_V(6); PG8_BAR;
;     } else {
;         PG8_STAGE(PG8_SB(0, 0), cB, voffB); PG8_STAGE(PG8_SA(0, 0), cA, voffA); PG8_STAGE(PG8_SB(0, 1), cB + hstepB, voffB); PG8_STAGE(PG8_SA(0, 1), cA + hstepA, voffA);
;         if (wr == 1) PG8_BAR;
;         PG8_WAIT_V(4); PG8_BAR;
;         PG8_STAGE(PG8_SB(1, 0), cB + kstep, voffB); PG8_STAGE(PG8_SA(1, 0), cA + kstep, voffA); PG8_STAGE(PG8_SB(1, 1), cB + hstepB + kstep, voffB);
;         PG8_WAIT_V(6); PG8_BAR;
;     }
.LBB0_420:
	s_add_u32 s14, s78, 0x7c00000
	s_addc_u32 s15, s79, 0
	s_lshl_b32 s0, s0, 5
	s_mov_b64 s[16:17], 0x80
	s_and_b32 s21, s0, 0x60
	s_add_i32 m0, s51, 0x18000
	v_lshl_add_u64 v[8:9], v[8:9], 0, s[16:17]
	s_lshl_b32 s19, s5, 13
	s_lshl_b32 s24, s21, 7
	s_waitcnt vmcnt(2)
	s_barrier
	global_load_lds_dwordx4 v[8:9], off
	v_lshl_add_u64 v[4:5], v[4:5], 0, s[16:17]
	s_add_i32 m0, s51, 0x1a000
	s_add_i32 s56, s51, 0x8000
	s_add_i32 s57, s51, 0xa000
	global_load_lds_dwordx4 v[4:5], off
	v_lshl_add_u64 v[2:3], v[2:3], 0, s[16:17]
	s_mov_b32 m0, s56
	s_add_u32 s22, s42, 0x28080
	global_load_lds_dwordx4 v[2:3], off
	v_lshl_add_u64 v[2:3], v[6:7], 0, s[16:17]
	s_mov_b32 m0, s57
	s_addc_u32 s23, s43, 0
	global_load_lds_dwordx4 v[2:3], off
	s_add_i32 m0, s51, 0x1c000
	v_lshl_add_u64 v[2:3], s[22:23], 0, v[150:151]
	global_load_lds_dwordx4 v[2:3], off
	v_lshl_add_u64 v[2:3], s[22:23], 0, v[146:147]
	s_add_i32 m0, s51, 0x1e000
	s_cmpk_lt_u32 s2, 0x100
	global_load_lds_dwordx4 v[2:3], off
	v_lshrrev_b32_e32 v3, 1, v10
	v_and_b32_e32 v4, 24, v3
	v_and_b32_e32 v2, 15, v10
	v_lshlrev_b32_e32 v5, 1, v4
	v_lshl_or_b32 v1, s5, 6, v2
	v_lshl_or_b32 v2, v2, 6, v5
	v_lshlrev_b32_e32 v5, 2, v10
	v_and_b32_e32 v5, 32, v5
	v_bitop3_b32 v6, v2, s19, v5 bitop3:0xde
	v_bitop3_b32 v166, v2, s24, v5 bitop3:0xde
	v_and_b32_e32 v2, 8, v3
	v_lshlrev_b32_e32 v154, 2, v2
	v_or_b32_e32 v167, s21, v4
	v_lshrrev_b32_e32 v3, 1, v16
	v_mul_lo_u32 v4, v15, s20
	s_movk_i32 s2, 0x2800
	s_waitcnt lgkmcnt(0)
	v_lshl_add_u64 v[156:157], s[6:7], 0, v[154:155]
	v_mad_u64_u32 v[4:5], s[6:7], v3, s2, v[4:5]
	v_or_b32_e32 v3, v4, v17
	v_add_lshl_u32 v154, v3, v18, 1
	v_lshrrev_b32_e32 v3, 1, v11
	v_mul_lo_u32 v4, v12, s20
	v_mad_u64_u32 v[4:5], s[6:7], v3, s2, v[4:5]
	s_mov_b64 s[22:23], 0x28080
	s_waitcnt vmcnt(6)
	v_or_b32_e32 v3, v4, v13
	s_sext_i32_i8 s0, s1
	s_sext_i32_i8 s1, s18
	s_cselect_b64 s[18:19], -1, 0
	v_lshl_add_u64 v[158:159], v[154:155], 0, s[22:23]
	v_add_lshl_u32 v154, v3, v14, 1
	s_add_i32 s59, 0, 0x10000
	s_add_i32 s60, 0, 0x14000
	s_mov_b32 s58, 0xa000
	v_lshl_add_u64 v[160:161], v[154:155], 0, s[22:23]
	v_add_u32_e32 v168, s59, v166
	v_add_u32_e32 v169, s60, v166
	v_add_u32_e32 v170, 0, v6
	s_movk_i32 s61, 0x500
	v_lshlrev_b32_e32 v154, 1, v2
	s_mov_b64 s[20:21], 0x5000
	s_movk_i32 s62, 0x5000
	s_mov_b64 s[22:23], 0xa000
	s_mov_b64 s[24:25], 0xf000
	s_mov_b32 s63, 0xf000
	s_mov_b32 s64, 0x28000
	s_mov_b64 s[26:27], 0x2d000
	s_mov_b32 s65, 0x2d000
	s_mov_b64 s[28:29], 0x400000
	s_mov_b64 s[30:31], 0x32000
	s_mov_b32 s66, 0x32000
	s_mov_b64 s[34:35], 0x37000
	s_mov_b32 s67, 0x37000
	v_mov_b32_e32 v171, 0xffffff70
	s_barrier
	s_mov_b32 s98, 0
	s_branch .LBB0_423

; #define PG8_STAGE(bufoff, gbase, voff) do { _Pragma("unroll") for (int _i = 0; _i < 2; ++_i) \
;         __builtin_amdgcn_global_load_lds((const unsigned*)((const char*)(gbase) + (voff)[_i]), (PG8_LAS unsigned*)(lds + (bufoff) + ldsw + _i * 8192), 16, 0, 0); } while (0)
; #define PG8_LDA(dst, b, h) do { _Pragma("unroll") for (int m = 0; m < 4; ++m) _Pragma("unroll") for (int k = 0; k < 2; ++k) dst[m][k] = *(const PG8_LAS bf16x8*)(lds + PG8_SA(b, h) + aoff + m * 2048 + k * 1024); } while (0)
; #define PG8_LDB(dst, b, h) do { _Pragma("unroll") for (int n = 0; n < 2; ++n) _Pragma("unroll") for (int k = 0; k < 2; ++k) dst[n][k] = *(const PG8_LAS bf16x8*)(lds + PG8_SB(b, h) + boff + n * 2048 + k * 1024); } while (0)
; #define PG8_MMA(ai, bj, At, Bt) do { __builtin_amdgcn_s_setprio(1); _Pragma("unroll") for (int m = 0; m < 4; ++m) _Pragma("unroll") for (int n = 0; n < 2; ++n) _Pragma("unroll") for (int k = 0; k < 2; ++k) \
;         acc[ai][bj][m][n] = __builtin_amdgcn_mfma_f32_16x16x32_bf16(Bt[n][k], At[m][k], acc[ai][bj][m][n], 0, 0, 0); __builtin_amdgcn_s_setprio(0); } while (0)
; #define PG8_WAIT_V(n) asm volatile("s_waitcnt vmcnt(" #n ")" ::: "memory")
; #define PG8_WAIT_L(n) asm volatile("s_waitcnt lgkmcnt(" #n ")" ::: "memory")
; #define PG8_BAR __builtin_amdgcn_s_barrier()
; #define PG8_SCHED __builtin_amdgcn_sched_barrier(0)
; template <class Epi, class Sched, bool ALIGN_EPI = false, bool SP2 = false>
; __device__ __forceinline__ void gemm_phase(PG8_LAS unsigned char* lds, const Gemm g, const Sched& S, const Epi& E) {
;     ...
;             if constexpr (SP2) {
;             PG8_LDB(B0, 0, 0); PG8_LDB(B1, 0, 1); PG8_SCHED; PG8_LDA(At, 0, 0); PG8_STAGE(PG8_SA(1, 1), a1 + hstepA, voffA);
;             PG8_WAIT_V(8); PG8_WAIT_L(0); PG8_BAR; PG8_MMA(0, 0, At, B0); PG8_MMA(0, 1, At, B1); PG8_BAR; PG8_SCHED;
;             PG8_LDA(At, 0, 1); PG8_STAGE(PG8_SB(0, 0), b2, voffB); PG8_STAGE(PG8_SB(0, 1), b2 + hstepB, voffB); PG8_STAGE(PG8_SA(0, 0), a2, voffA);
;             PG8_WAIT_V(8); PG8_WAIT_L(0); PG8_BAR; PG8_MMA(1, 0, At, B0); PG8_MMA(1, 1, At, B1); PG8_BAR; PG8_SCHED;
;     ...
;         if constexpr (ALIGN_EPI) { if (wr == 1) PG8_BAR; }
.LBB0_429:
	s_add_u32 s2, s42, 0x100
	s_addc_u32 s5, s43, 0
	s_mov_b32 s33, -2
	s_cmp_eq_u32 s98, 1
	s_cbranch_scc0 .Lhb_13632
	s_mov_b32 s98, 0
	s_barrier
.Lhb_13632:
	ds_read_b128 v[62:65], v168
	ds_read_b128 v[66:69], v168 offset:1024
	ds_read_b128 v[138:141], v168 offset:2048
	ds_read_b128 v[142:145], v168 offset:3072
	ds_read_b128 v[162:165], v169
	ds_read_b128 v[172:175], v169 offset:1024
	ds_read_b128 v[176:179], v169 offset:2048
	ds_read_b128 v[180:183], v169 offset:3072
	s_add_u32 s42, s40, 0x100
	s_addc_u32 s43, s41, 0
	s_cmp_eq_u32 s33, 6
	s_cselect_b32 s47, s37, s43
	s_cselect_b32 s46, s36, s42
	s_cselect_b32 s45, s39, s5
	s_cselect_b32 s44, s38, s2
	v_lshl_add_u64 v[216:217], s[40:41], 0, v[158:159]
	s_add_i32 m0, s51, 0xc000
	ds_read_b128 v[184:187], v170
	ds_read_b128 v[188:191], v170 offset:1024
	ds_read_b128 v[192:195], v170 offset:2048
	ds_read_b128 v[196:199], v170 offset:3072
	ds_read_b128 v[200:203], v170 offset:4096
	ds_read_b128 v[204:207], v170 offset:5120
	ds_read_b128 v[208:211], v170 offset:6144
	ds_read_b128 v[212:215], v170 offset:7168
	global_load_lds_dwordx4 v[216:217], off
	v_lshl_add_u64 v[216:217], s[40:41], 0, v[160:161]
	s_add_i32 m0, s51, 0xe000
	s_nop 0
	global_load_lds_dwordx4 v[216:217], off
	s_waitcnt vmcnt(8)
	s_waitcnt lgkmcnt(0)
	s_barrier
	s_setprio 1
	s_waitcnt lgkmcnt(0)
	v_mfma_f32_16x16x32_bf16 v[134:137], v[62:65], v[184:187], 0
	v_mfma_f32_16x16x32_bf16 v[130:133], v[138:141], v[184:187], 0
	v_mfma_f32_16x16x32_bf16 v[118:121], v[62:65], v[192:195], 0
	v_mfma_f32_16x16x32_bf16 v[114:117], v[138:141], v[192:195], 0
	v_mfma_f32_16x16x32_bf16 v[102:105], v[62:65], v[200:203], 0
	v_mfma_f32_16x16x32_bf16 v[98:101], v[138:141], v[200:203], 0
	v_mfma_f32_16x16x32_bf16 v[86:89], v[62:65], v[208:211], 0
	v_mfma_f32_16x16x32_bf16 v[82:85], v[138:141], v[208:211], 0
	v_mfma_f32_16x16x32_bf16 v[134:137], v[66:69], v[188:191], v[134:137]
	v_mfma_f32_16x16x32_bf16 v[130:133], v[142:145], v[188:191], v[130:133]
	v_mfma_f32_16x16x32_bf16 v[118:121], v[66:69], v[196:199], v[118:121]
	v_mfma_f32_16x16x32_bf16 v[114:117], v[142:145], v[196:199], v[114:117]
	v_mfma_f32_16x16x32_bf16 v[102:105], v[66:69], v[204:207], v[102:105]
	v_mfma_f32_16x16x32_bf16 v[98:101], v[142:145], v[204:207], v[98:101]
	v_mfma_f32_16x16x32_bf16 v[86:89], v[66:69], v[212:215], v[86:89]
	v_mfma_f32_16x16x32_bf16 v[82:85], v[142:145], v[212:215], v[82:85]
	s_setprio 0
	s_setprio 1
	v_mfma_f32_16x16x32_bf16 v[126:129], v[162:165], v[184:187], 0
	v_mfma_f32_16x16x32_bf16 v[122:125], v[176:179], v[184:187], 0
	v_mfma_f32_16x16x32_bf16 v[110:113], v[162:165], v[192:195], 0
	v_mfma_f32_16x16x32_bf16 v[106:109], v[176:179], v[192:195], 0
	v_mfma_f32_16x16x32_bf16 v[94:97], v[162:165], v[200:203], 0
	v_mfma_f32_16x16x32_bf16 v[90:93], v[176:179], v[200:203], 0
	v_mfma_f32_16x16x32_bf16 v[78:81], v[162:165], v[208:211], 0
	v_mfma_f32_16x16x32_bf16 v[74:77], v[176:179], v[208:211], 0
	v_mfma_f32_16x16x32_bf16 v[126:129], v[172:175], v[188:191], v[126:129]
	v_mfma_f32_16x16x32_bf16 v[122:125], v[180:183], v[188:191], v[122:125]
	v_mfma_f32_16x16x32_bf16 v[110:113], v[172:175], v[196:199], v[110:113]
	v_mfma_f32_16x16x32_bf16 v[106:109], v[180:183], v[196:199], v[106:109]
	v_mfma_f32_16x16x32_bf16 v[94:97], v[172:175], v[204:207], v[94:97]
	v_mfma_f32_16x16x32_bf16 v[90:93], v[180:183], v[204:207], v[90:93]
	v_mfma_f32_16x16x32_bf16 v[78:81], v[172:175], v[212:215], v[78:81]
	v_mfma_f32_16x16x32_bf16 v[74:77], v[180:183], v[212:215], v[74:77]
	s_setprio 0
	s_barrier
	s_add_i32 s40, s59, s48
	v_lshl_add_u64 v[216:217], s[44:45], 0, v[150:151]
	s_mov_b32 m0, s40
	ds_read_b128 v[184:187], v170 offset:16384
	ds_read_b128 v[188:191], v170 offset:17408
	ds_read_b128 v[192:195], v170 offset:18432
	ds_read_b128 v[196:199], v170 offset:19456
	ds_read_b128 v[200:203], v170 offset:20480
	ds_read_b128 v[204:207], v170 offset:21504
	ds_read_b128 v[208:211], v170 offset:22528
	ds_read_b128 v[212:215], v170 offset:23552
	global_load_lds_dwordx4 v[216:217], off
	s_add_i32 m0, s40, 0x2000
	s_add_u32 s40, s44, 0x28000
	v_lshl_add_u64 v[218:219], s[44:45], 0, v[146:147]
	s_addc_u32 s41, s45, 0
	s_add_i32 s71, s60, s48
	global_load_lds_dwordx4 v[218:219], off
	v_lshl_add_u64 v[220:221], s[40:41], 0, v[150:151]
	s_mov_b32 m0, s71
	v_lshl_add_u64 v[222:223], s[46:47], 0, v[148:149]
	global_load_lds_dwordx4 v[220:221], off
	v_lshl_add_u64 v[220:221], s[40:41], 0, v[146:147]
	s_add_i32 m0, s71, 0x2000
	s_nop 0
	global_load_lds_dwordx4 v[220:221], off
	v_lshl_add_u64 v[220:221], s[46:47], 0, v[152:153]
	s_mov_b32 m0, s51
	s_nop 0
	global_load_lds_dwordx4 v[220:221], off
	s_mov_b32 m0, s52
	s_nop 0
	global_load_lds_dwordx4 v[222:223], off
	s_waitcnt vmcnt(8)
	s_waitcnt lgkmcnt(0)
	s_barrier
; #define PG8_STAGE(bufoff, gbase, voff) do { _Pragma("unroll") for (int _i = 0; _i < 2; ++_i) \
;         __builtin_amdgcn_global_load_lds((const unsigned*)((const char*)(gbase) + (voff)[_i]), (PG8_LAS unsigned*)(lds + (bufoff) + ldsw + _i * 8192), 16, 0, 0); } while (0)
; #define PG8_LDA(dst, b, h) do { _Pragma("unroll") for (int m = 0; m < 4; ++m) _Pragma("unroll") for (int k = 0; k < 2; ++k) dst[m][k] = *(const PG8_LAS bf16x8*)(lds + PG8_SA(b, h) + aoff + m * 2048 + k * 1024); } while (0)
; #define PG8_LDB(dst, b, h) do { _Pragma("unroll") for (int n = 0; n < 2; ++n) _Pragma("unroll") for (int k = 0; k < 2; ++k) dst[n][k] = *(const PG8_LAS bf16x8*)(lds + PG8_SB(b, h) + boff + n * 2048 + k * 1024); } while (0)
; #define PG8_MMA(ai, bj, At, Bt) do { __builtin_amdgcn_s_setprio(1); _Pragma("unroll") for (int m = 0; m < 4; ++m) _Pragma("unroll") for (int n = 0; n < 2; ++n) _Pragma("unroll") for (int k = 0; k < 2; ++k) \
;         acc[ai][bj][m][n] = __builtin_amdgcn_mfma_f32_16x16x32_bf16(Bt[n][k], At[m][k], acc[ai][bj][m][n], 0, 0, 0); __builtin_amdgcn_s_setprio(0); } while (0)
; #define PG8_WAIT_V(n) asm volatile("s_waitcnt vmcnt(" #n ")" ::: "memory")
; #define PG8_WAIT_L(n) asm volatile("s_waitcnt lgkmcnt(" #n ")" ::: "memory")
; #define PG8_BAR __builtin_amdgcn_s_barrier()
; #define PG8_SCHED __builtin_amdgcn_sched_barrier(0)
; template <class Epi, class Sched, bool ALIGN_EPI = false, bool SP2 = false>
; __device__ __forceinline__ void gemm_phase(PG8_LAS unsigned char* lds, const Gemm g, const Sched& S, const Epi& E) {
;     ...
;             PG8_WAIT_V(8); PG8_WAIT_L(0); PG8_BAR; PG8_MMA(1, 0, At, B0); PG8_MMA(1, 1, At, B1); PG8_BAR; PG8_SCHED;
;             PG8_LDB(B0, 1, 0); PG8_LDB(B1, 1, 1); PG8_SCHED; PG8_LDA(At, 1, 0); PG8_STAGE(PG8_SA(0, 1), a2 + hstepA, voffA);
;             PG8_WAIT_V(8); PG8_WAIT_L(0); PG8_BAR; PG8_MMA(0, 0, At, B0); PG8_MMA(0, 1, At, B1); PG8_BAR; PG8_SCHED;
	s_setprio 1
	s_waitcnt lgkmcnt(0)
	v_mfma_f32_16x16x32_bf16 v[70:73], v[62:65], v[184:187], 0
	v_mfma_f32_16x16x32_bf16 v[58:61], v[138:141], v[184:187], 0
	v_mfma_f32_16x16x32_bf16 v[46:49], v[62:65], v[192:195], 0
	v_mfma_f32_16x16x32_bf16 v[42:45], v[138:141], v[192:195], 0
	v_mfma_f32_16x16x32_bf16 v[30:33], v[62:65], v[200:203], 0
	v_mfma_f32_16x16x32_bf16 v[26:29], v[138:141], v[200:203], 0
	v_mfma_f32_16x16x32_bf16 v[14:17], v[62:65], v[208:211], 0
	v_mfma_f32_16x16x32_bf16 v[10:13], v[138:141], v[208:211], 0
	v_mfma_f32_16x16x32_bf16 v[70:73], v[66:69], v[188:191], v[70:73]
	v_mfma_f32_16x16x32_bf16 v[58:61], v[142:145], v[188:191], v[58:61]
	v_mfma_f32_16x16x32_bf16 v[46:49], v[66:69], v[196:199], v[46:49]
	v_mfma_f32_16x16x32_bf16 v[42:45], v[142:145], v[196:199], v[42:45]
	v_mfma_f32_16x16x32_bf16 v[30:33], v[66:69], v[204:207], v[30:33]
	v_mfma_f32_16x16x32_bf16 v[26:29], v[142:145], v[204:207], v[26:29]
	v_mfma_f32_16x16x32_bf16 v[14:17], v[66:69], v[212:215], v[14:17]
	v_mfma_f32_16x16x32_bf16 v[10:13], v[142:145], v[212:215], v[10:13]
	s_setprio 0
	s_setprio 1
	v_mfma_f32_16x16x32_bf16 v[54:57], v[162:165], v[184:187], 0
	v_mfma_f32_16x16x32_bf16 v[50:53], v[176:179], v[184:187], 0
	v_mfma_f32_16x16x32_bf16 v[38:41], v[162:165], v[192:195], 0
	v_mfma_f32_16x16x32_bf16 v[34:37], v[176:179], v[192:195], 0
	v_mfma_f32_16x16x32_bf16 v[22:25], v[162:165], v[200:203], 0
	v_mfma_f32_16x16x32_bf16 v[18:21], v[176:179], v[200:203], 0
	v_mfma_f32_16x16x32_bf16 v[6:9], v[162:165], v[208:211], 0
	v_mfma_f32_16x16x32_bf16 v[2:5], v[176:179], v[208:211], 0
	v_mfma_f32_16x16x32_bf16 v[54:57], v[172:175], v[188:191], v[54:57]
	v_mfma_f32_16x16x32_bf16 v[50:53], v[180:183], v[188:191], v[50:53]
	v_mfma_f32_16x16x32_bf16 v[38:41], v[172:175], v[196:199], v[38:41]
	v_mfma_f32_16x16x32_bf16 v[34:37], v[180:183], v[196:199], v[34:37]
	v_mfma_f32_16x16x32_bf16 v[22:25], v[172:175], v[204:207], v[22:25]
	v_mfma_f32_16x16x32_bf16 v[18:21], v[180:183], v[204:207], v[18:21]
	v_mfma_f32_16x16x32_bf16 v[6:9], v[172:175], v[212:215], v[6:9]
	v_mfma_f32_16x16x32_bf16 v[2:5], v[180:183], v[212:215], v[2:5]
	s_setprio 0
	s_barrier
	s_add_i32 s71, 0, 0x18000
	s_add_i32 s72, 0, 0x1c000
	v_add_u32_e32 v142, s71, v166
	v_add_u32_e32 v180, s72, v166
	ds_read_b128 v[62:65], v142
	ds_read_b128 v[66:69], v142 offset:1024
	ds_read_b128 v[138:141], v142 offset:2048
	ds_read_b128 v[142:145], v142 offset:3072
	ds_read_b128 v[162:165], v180
	ds_read_b128 v[172:175], v180 offset:1024
	ds_read_b128 v[176:179], v180 offset:2048
	ds_read_b128 v[180:183], v180 offset:3072
	s_add_u32 s40, s46, 0x28000
	s_addc_u32 s41, s47, 0
	s_mov_b32 m0, s53
	v_lshl_add_u64 v[224:225], s[40:41], 0, v[152:153]
	ds_read_b128 v[184:187], v170 offset:32768
	ds_read_b128 v[188:191], v170 offset:33792
	ds_read_b128 v[192:195], v170 offset:34816
	ds_read_b128 v[196:199], v170 offset:35840
	ds_read_b128 v[200:203], v170 offset:36864
	ds_read_b128 v[204:207], v170 offset:37888
	ds_read_b128 v[208:211], v170 offset:38912
	ds_read_b128 v[212:215], v170 offset:39936
	global_load_lds_dwordx4 v[224:225], off
	v_lshl_add_u64 v[224:225], s[40:41], 0, v[148:149]
	s_mov_b32 m0, s54
	s_nop 0
	global_load_lds_dwordx4 v[224:225], off
	s_waitcnt vmcnt(8)
	s_waitcnt lgkmcnt(0)
	s_barrier
	s_setprio 1
	s_waitcnt lgkmcnt(0)
	v_mfma_f32_16x16x32_bf16 v[134:137], v[62:65], v[184:187], v[134:137]
	v_mfma_f32_16x16x32_bf16 v[130:133], v[138:141], v[184:187], v[130:133]
	v_mfma_f32_16x16x32_bf16 v[118:121], v[62:65], v[192:195], v[118:121]
	v_mfma_f32_16x16x32_bf16 v[114:117], v[138:141], v[192:195], v[114:117]
	v_mfma_f32_16x16x32_bf16 v[102:105], v[62:65], v[200:203], v[102:105]
	v_mfma_f32_16x16x32_bf16 v[98:101], v[138:141], v[200:203], v[98:101]
	v_mfma_f32_16x16x32_bf16 v[86:89], v[62:65], v[208:211], v[86:89]
	v_mfma_f32_16x16x32_bf16 v[82:85], v[138:141], v[208:211], v[82:85]
	v_mfma_f32_16x16x32_bf16 v[134:137], v[66:69], v[188:191], v[134:137]
	v_mfma_f32_16x16x32_bf16 v[130:133], v[142:145], v[188:191], v[130:133]
	v_mfma_f32_16x16x32_bf16 v[118:121], v[66:69], v[196:199], v[118:121]
	v_mfma_f32_16x16x32_bf16 v[114:117], v[142:145], v[196:199], v[114:117]
	v_mfma_f32_16x16x32_bf16 v[102:105], v[66:69], v[204:207], v[102:105]
	v_mfma_f32_16x16x32_bf16 v[98:101], v[142:145], v[204:207], v[98:101]
	v_mfma_f32_16x16x32_bf16 v[86:89], v[66:69], v[212:215], v[86:89]
	v_mfma_f32_16x16x32_bf16 v[82:85], v[142:145], v[212:215], v[82:85]
	s_setprio 0
	s_setprio 1
	v_mfma_f32_16x16x32_bf16 v[126:129], v[162:165], v[184:187], v[126:129]
	v_mfma_f32_16x16x32_bf16 v[122:125], v[176:179], v[184:187], v[122:125]
	v_mfma_f32_16x16x32_bf16 v[110:113], v[162:165], v[192:195], v[110:113]
	v_mfma_f32_16x16x32_bf16 v[106:109], v[176:179], v[192:195], v[106:109]
	v_mfma_f32_16x16x32_bf16 v[94:97], v[162:165], v[200:203], v[94:97]
	v_mfma_f32_16x16x32_bf16 v[90:93], v[176:179], v[200:203], v[90:93]
	v_mfma_f32_16x16x32_bf16 v[78:81], v[162:165], v[208:211], v[78:81]
	v_mfma_f32_16x16x32_bf16 v[74:77], v[176:179], v[208:211], v[74:77]
	v_mfma_f32_16x16x32_bf16 v[126:129], v[172:175], v[188:191], v[126:129]
	v_mfma_f32_16x16x32_bf16 v[122:125], v[180:183], v[188:191], v[122:125]
	v_mfma_f32_16x16x32_bf16 v[110:113], v[172:175], v[196:199], v[110:113]
	v_mfma_f32_16x16x32_bf16 v[106:109], v[180:183], v[196:199], v[106:109]
	v_mfma_f32_16x16x32_bf16 v[94:97], v[172:175], v[204:207], v[94:97]
	v_mfma_f32_16x16x32_bf16 v[90:93], v[180:183], v[204:207], v[90:93]
	v_mfma_f32_16x16x32_bf16 v[78:81], v[172:175], v[212:215], v[78:81]
	v_mfma_f32_16x16x32_bf16 v[74:77], v[180:183], v[212:215], v[74:77]
	s_setprio 0
	s_barrier
; #define PG8_STAGE(bufoff, gbase, voff) do { _Pragma("unroll") for (int _i = 0; _i < 2; ++_i) \
;         __builtin_amdgcn_global_load_lds((const unsigned*)((const char*)(gbase) + (voff)[_i]), (PG8_LAS unsigned*)(lds + (bufoff) + ldsw + _i * 8192), 16, 0, 0); } while (0)
; #define PG8_LDA(dst, b, h) do { _Pragma("unroll") for (int m = 0; m < 4; ++m) _Pragma("unroll") for (int k = 0; k < 2; ++k) dst[m][k] = *(const PG8_LAS bf16x8*)(lds + PG8_SA(b, h) + aoff + m * 2048 + k * 1024); } while (0)
; #define PG8_MMA(ai, bj, At, Bt) do { __builtin_amdgcn_s_setprio(1); _Pragma("unroll") for (int m = 0; m < 4; ++m) _Pragma("unroll") for (int n = 0; n < 2; ++n) _Pragma("unroll") for (int k = 0; k < 2; ++k) \
;         acc[ai][bj][m][n] = __builtin_amdgcn_mfma_f32_16x16x32_bf16(Bt[n][k], At[m][k], acc[ai][bj][m][n], 0, 0, 0); __builtin_amdgcn_s_setprio(0); } while (0)
; #define PG8_WAIT_V(n) asm volatile("s_waitcnt vmcnt(" #n ")" ::: "memory")
; #define PG8_WAIT_L(n) asm volatile("s_waitcnt lgkmcnt(" #n ")" ::: "memory")
; #define PG8_BAR __builtin_amdgcn_s_barrier()
; #define PG8_SCHED __builtin_amdgcn_sched_barrier(0)
; template <class Epi, class Sched, bool ALIGN_EPI = false, bool SP2 = false>
; __device__ __forceinline__ void gemm_phase(PG8_LAS unsigned char* lds, const Gemm g, const Sched& S, const Epi& E) {
;     ...
;         for (int t = 0; t < nt; t += 2) {
;     ...
;             PG8_LDA(At, 1, 1); PG8_STAGE(PG8_SB(1, 0), b3, voffB); PG8_STAGE(PG8_SB(1, 1), b3 + hstepB, voffB); PG8_STAGE(PG8_SA(1, 0), a3, voffA);
;             PG8_WAIT_V(8); PG8_WAIT_L(0); PG8_BAR; PG8_MMA(1, 0, At, B0); PG8_MMA(1, 1, At, B1); PG8_BAR; PG8_SCHED;
	s_add_i32 s40, s71, s48
	v_lshl_add_u64 v[216:217], v[216:217], 0, s[16:17]
	s_mov_b32 m0, s40
	ds_read_b128 v[184:187], v170 offset:49152
	ds_read_b128 v[188:191], v170 offset:50176
	ds_read_b128 v[192:195], v170 offset:51200
	ds_read_b128 v[196:199], v170 offset:52224
	ds_read_b128 v[200:203], v170 offset:53248
	ds_read_b128 v[204:207], v170 offset:54272
	ds_read_b128 v[208:211], v170 offset:55296
	ds_read_b128 v[212:215], v170 offset:56320
	global_load_lds_dwordx4 v[216:217], off
	s_add_i32 m0, s40, 0x2000
	s_add_u32 s40, s44, 0x28080
	v_lshl_add_u64 v[216:217], v[218:219], 0, s[16:17]
	s_addc_u32 s41, s45, 0
	s_add_i32 s44, s72, s48
	global_load_lds_dwordx4 v[216:217], off
	v_lshl_add_u64 v[216:217], s[40:41], 0, v[150:151]
	s_mov_b32 m0, s44
	s_nop 0
	global_load_lds_dwordx4 v[216:217], off
	v_lshl_add_u64 v[216:217], s[40:41], 0, v[146:147]
	s_add_i32 m0, s44, 0x2000
	s_nop 0
	global_load_lds_dwordx4 v[216:217], off
	v_lshl_add_u64 v[216:217], v[220:221], 0, s[16:17]
	s_mov_b32 m0, s56
	s_nop 0
	global_load_lds_dwordx4 v[216:217], off
	v_lshl_add_u64 v[216:217], v[222:223], 0, s[16:17]
	s_mov_b32 m0, s57
	s_nop 0
	global_load_lds_dwordx4 v[216:217], off
	s_waitcnt vmcnt(8)
	s_waitcnt lgkmcnt(0)
	s_barrier
	s_setprio 1
	s_waitcnt lgkmcnt(0)
	v_mfma_f32_16x16x32_bf16 v[70:73], v[62:65], v[184:187], v[70:73]
	v_mfma_f32_16x16x32_bf16 v[58:61], v[138:141], v[184:187], v[58:61]
	v_mfma_f32_16x16x32_bf16 v[46:49], v[62:65], v[192:195], v[46:49]
	v_mfma_f32_16x16x32_bf16 v[42:45], v[138:141], v[192:195], v[42:45]
	v_mfma_f32_16x16x32_bf16 v[30:33], v[62:65], v[200:203], v[30:33]
	v_mfma_f32_16x16x32_bf16 v[26:29], v[138:141], v[200:203], v[26:29]
	v_mfma_f32_16x16x32_bf16 v[14:17], v[62:65], v[208:211], v[14:17]
	v_mfma_f32_16x16x32_bf16 v[10:13], v[138:141], v[208:211], v[10:13]
	v_mfma_f32_16x16x32_bf16 v[70:73], v[66:69], v[188:191], v[70:73]
	v_mfma_f32_16x16x32_bf16 v[58:61], v[142:145], v[188:191], v[58:61]
	v_mfma_f32_16x16x32_bf16 v[46:49], v[66:69], v[196:199], v[46:49]
	v_mfma_f32_16x16x32_bf16 v[42:45], v[142:145], v[196:199], v[42:45]
	v_mfma_f32_16x16x32_bf16 v[30:33], v[66:69], v[204:207], v[30:33]
	v_mfma_f32_16x16x32_bf16 v[26:29], v[142:145], v[204:207], v[26:29]
	v_mfma_f32_16x16x32_bf16 v[14:17], v[66:69], v[212:215], v[14:17]
	v_mfma_f32_16x16x32_bf16 v[10:13], v[142:145], v[212:215], v[10:13]
	s_setprio 0
	s_setprio 1
	v_mfma_f32_16x16x32_bf16 v[54:57], v[162:165], v[184:187], v[54:57]
	v_mfma_f32_16x16x32_bf16 v[50:53], v[176:179], v[184:187], v[50:53]
	v_mfma_f32_16x16x32_bf16 v[38:41], v[162:165], v[192:195], v[38:41]
	v_mfma_f32_16x16x32_bf16 v[34:37], v[176:179], v[192:195], v[34:37]
	v_mfma_f32_16x16x32_bf16 v[22:25], v[162:165], v[200:203], v[22:25]
	v_mfma_f32_16x16x32_bf16 v[18:21], v[176:179], v[200:203], v[18:21]
	v_mfma_f32_16x16x32_bf16 v[6:9], v[162:165], v[208:211], v[6:9]
	v_mfma_f32_16x16x32_bf16 v[2:5], v[176:179], v[208:211], v[2:5]
	v_mfma_f32_16x16x32_bf16 v[54:57], v[172:175], v[188:191], v[54:57]
	v_mfma_f32_16x16x32_bf16 v[50:53], v[180:183], v[188:191], v[50:53]
	v_mfma_f32_16x16x32_bf16 v[38:41], v[172:175], v[196:199], v[38:41]
	v_mfma_f32_16x16x32_bf16 v[34:37], v[180:183], v[196:199], v[34:37]
	v_mfma_f32_16x16x32_bf16 v[22:25], v[172:175], v[204:207], v[22:25]
	v_mfma_f32_16x16x32_bf16 v[18:21], v[180:183], v[204:207], v[18:21]
	v_mfma_f32_16x16x32_bf16 v[6:9], v[172:175], v[212:215], v[6:9]
	v_mfma_f32_16x16x32_bf16 v[2:5], v[180:183], v[212:215], v[2:5]
	s_setprio 0
	s_barrier
	s_add_i32 s33, s33, 2
	s_add_u32 s2, s2, 0x100
	s_addc_u32 s5, s5, 0
	s_cmp_gt_u32 s33, 7
	s_mov_b64 s[40:41], s[42:43]

; __device__ __forceinline__ unsigned cvt_pk_bf16(float lo, float hi) { unsigned r; asm volatile("v_cvt_pk_bf16_f32 %0, %1, %2" : "=v"(r) : "v"(lo), "v"(hi)); return r; }
; __device__ __forceinline__ float bflo(unsigned w) { return __uint_as_float(w << 16); }
; __device__ __forceinline__ float bfhi(unsigned w) { return __uint_as_float(w & 0xffff0000u); }
; __device__ __forceinline__ float gelu_tanh(float v) { const float z = 1.5957691216057308f * (v + 0.044715f * v * v * v); return v * sigm(z); }
;     __device__ __forceinline__ void operator()(const pg8::f32x4 (&acc)[2][2][4][2], const Unit& u, int wr, int wc, int fr, int fq) const {
;         const int row0 = u.pm * BM + wr * 64 + fr; const int c0 = 8 * (fq & 1);
;         const f32x4 d0 = *(const f32x4*)(dsk + u.g * 16 + c0), d1 = *(const f32x4*)(dsk + u.g * 16 + c0 + 4);
;         const int colb = u.pn * BM + wc * 32 + 8 * fq;
;         v4u nu[2];
; #pragma unroll
;         for (int bj = 0; bj < 2; ++bj) nu[bj] = *(const v4u*)(UX + ((size_t)u.g * 1024 + row0) * 640 + ((colb + bj * HALF) >> 4) * 16 + c0);
; #pragma unroll
;         for (int k = 0; k < 8; ++k) { const int ai = k >> 2, m = k & 3; const int row = row0 + ai * HALF + m * 16; v4u cu[2];
; #pragma unroll
;             for (int bj = 0; bj < 2; ++bj) cu[bj] = nu[bj];
;             if (k < 7) {
; #pragma unroll
;                 for (int bj = 0; bj < 2; ++bj) nu[bj] = *(const v4u*)(UX + ((size_t)u.g * 1024 + row0 + ((k + 1) >> 2) * HALF + ((k + 1) & 3) * 16) * 640 + ((colb + bj * HALF) >> 4) * 16 + c0); }
; #pragma unroll
;             for (int bj = 0; bj < 2; ++bj) { const int tau = (colb + bj * HALF) >> 4;
;                 const v4u uw = cu[bj]; const f32x4 a0 = acc[ai][bj][m][0], a1 = acc[ai][bj][m][1];
;                 float r[8]; r[0] = a0[0] + d0[0] * bflo(uw.x); r[1] = a0[1] + d0[1] * bfhi(uw.x); r[2] = a0[2] + d0[2] * bflo(uw.y); r[3] = a0[3] + d0[3] * bfhi(uw.y);
;                 r[4] = a1[0] + d1[0] * bflo(uw.z); r[5] = a1[1] + d1[1] * bfhi(uw.z); r[6] = a1[2] + d1[2] * bflo(uw.w); r[7] = a1[3] + d1[3] * bfhi(uw.w);
; #pragma unroll
;                 for (int e = 0; e < 8; ++e) r[e] = gelu_tanh(r[e]);
;                 v4u w; w.x = cvt_pk_bf16(r[0], r[1]); w.y = cvt_pk_bf16(r[2], r[3]); w.z = cvt_pk_bf16(r[4], r[5]); w.w = cvt_pk_bf16(r[6], r[7]);
;                 *(v4u*)(Y + ((size_t)row * 32 + tau) * 512 + u.g * 16 + c0) = w; } }
.LBB0_433:
	v_lshl_add_u32 v162, s1, 8, v1
	s_ashr_i32 s5, s4, 31
	s_lshl_b32 s2, s0, 8
	s_lshl_b64 s[0:1], s[4:5], 10
	v_ashrrev_i32_e32 v163, 31, v162
	v_lshl_add_u64 v[62:63], s[0:1], 0, v[162:163]
	v_mov_b64_e32 v[64:65], s[8:9]
	v_mad_u64_u32 v[64:65], s[0:1], v62, s61, v[64:65]
	v_mad_i32_i24 v65, v63, s61, v65
	v_bitop3_b32 v62, s2, v171, v167 bitop3:0xc8
	v_lshl_add_u64 v[64:65], v[64:65], 0, v[154:155]
	v_ashrrev_i32_e32 v63, 31, v62
	v_lshl_add_u64 v[164:165], v[62:63], 1, v[64:65]
	s_lshl_b32 s4, s4, 4
	global_load_dwordx4 v[172:175], v[164:165], off
	s_ashr_i32 s5, s4, 31
	v_lshl_add_u64 v[62:63], s[4:5], 2, v[156:157]
	global_load_dwordx4 v[66:69], v[62:63], off
	s_nop 0
	global_load_dwordx4 v[62:65], v[62:63], off offset:16
	v_add_co_u32_e32 v142, vcc, s62, v164
	global_load_dwordx4 v[176:179], v[164:165], off offset:256
	v_lshl_add_u64 v[138:139], v[164:165], 0, s[20:21]
	v_addc_co_u32_e32 v143, vcc, 0, v165, vcc
	global_load_dwordx4 v[138:141], v[138:139], off offset:256
	s_nop 0
	global_load_dwordx4 v[142:145], v[142:143], off
	v_lshlrev_b64 v[180:181], 15, v[162:163]
	v_or_b32_e32 v182, s2, v167
	s_lshl_b64 s[4:5], s[4:5], 1
	s_waitcnt vmcnt(0)
	v_lshlrev_b32_e32 v163, 16, v172
	v_lshlrev_b32_e32 v183, 16, v173
	v_fma_f32 v134, v66, v163, v134
	v_mul_f32_e32 v163, 0x3d372713, v134
	v_mul_f32_e32 v163, v134, v163
	v_fma_f32 v163, v134, v163, v134
	v_mul_f32_e32 v163, 0x3fcc422a, v163
	v_mul_f32_e32 v163, 0xbfb8aa3b, v163
	v_exp_f32_e32 v163, v163
	v_and_b32_e32 v173, 0xffff0000, v173
	v_fma_f32 v136, v68, v183, v136
	v_and_b32_e32 v172, 0xffff0000, v172
	v_fmac_f32_e32 v137, v69, v173
	v_mul_f32_e32 v173, 0x3d372713, v136
	v_fma_f32 v135, v67, v172, v135
	v_mul_f32_e32 v173, v136, v173
	v_add_f32_e32 v163, 1.0, v163
	v_mul_f32_e32 v172, 0x3d372713, v135
	v_fma_f32 v173, v136, v173, v136
	v_rcp_f32_e32 v163, v163
	v_lshlrev_b32_e32 v184, 16, v174
	v_lshlrev_b32_e32 v185, 16, v175
	v_and_b32_e32 v175, 0xffff0000, v175
	v_mul_f32_e32 v172, v135, v172
	v_mul_f32_e32 v173, 0x3fcc422a, v173
	v_and_b32_e32 v174, 0xffff0000, v174
	v_fma_f32 v130, v62, v184, v130
	v_fma_f32 v132, v64, v185, v132
	v_fmac_f32_e32 v133, v65, v175
	v_fma_f32 v172, v135, v172, v135
	v_mul_f32_e32 v173, 0xbfb8aa3b, v173
	v_fma_f32 v131, v63, v174, v131
	v_mul_f32_e32 v175, 0x3d372713, v130
	v_mul_f32_e32 v184, 0x3d372713, v132
	v_mul_f32_e32 v185, 0x3d372713, v133
	v_mul_f32_e32 v172, 0x3fcc422a, v172
	v_exp_f32_e32 v173, v173
	v_mul_f32_e32 v174, 0x3d372713, v137
	v_mul_f32_e32 v183, 0x3d372713, v131
	v_mul_f32_e32 v175, v130, v175
	v_mul_f32_e32 v184, v132, v184
	v_mul_f32_e32 v172, 0xbfb8aa3b, v172
	v_mul_f32_e32 v134, v134, v163
	v_mul_f32_e32 v163, v133, v185
	v_mul_f32_e32 v174, v137, v174
	v_mul_f32_e32 v183, v131, v183
	v_fma_f32 v175, v130, v175, v130
	v_fma_f32 v184, v132, v184, v132
	v_exp_f32_e32 v172, v172
	v_fma_f32 v163, v133, v163, v133
	v_fma_f32 v174, v137, v174, v137
	v_fma_f32 v183, v131, v183, v131
	v_mul_f32_e32 v175, 0x3fcc422a, v175
	v_mul_f32_e32 v184, 0x3fcc422a, v184
	v_mul_f32_e32 v163, 0x3fcc422a, v163
	v_mul_f32_e32 v174, 0x3fcc422a, v174
	v_mul_f32_e32 v183, 0x3fcc422a, v183
	v_mul_f32_e32 v175, 0xbfb8aa3b, v175
	v_mul_f32_e32 v184, 0xbfb8aa3b, v184
	v_add_f32_e32 v173, 1.0, v173
	v_mul_f32_e32 v163, 0xbfb8aa3b, v163
	v_mul_f32_e32 v174, 0xbfb8aa3b, v174
	v_mul_f32_e32 v183, 0xbfb8aa3b, v183
	v_exp_f32_e32 v175, v175
	v_exp_f32_e32 v184, v184
	v_rcp_f32_e32 v173, v173
	v_exp_f32_e32 v163, v163
	v_exp_f32_e32 v174, v174
	v_exp_f32_e32 v183, v183
	v_add_f32_e32 v172, 1.0, v172
	v_rcp_f32_e32 v172, v172
	v_add_f32_e32 v175, 1.0, v175
	v_mul_f32_e32 v136, v136, v173
	v_add_f32_e32 v173, 1.0, v184
	v_add_f32_e32 v163, 1.0, v163
	v_add_f32_e32 v174, 1.0, v174
	v_add_f32_e32 v183, 1.0, v183
	v_rcp_f32_e32 v175, v175
	v_rcp_f32_e32 v173, v173
	v_rcp_f32_e32 v163, v163
	v_rcp_f32_e32 v174, v174
	v_mul_f32_e32 v135, v135, v172
	v_rcp_f32_e32 v172, v183
	v_mul_f32_e32 v130, v130, v175
	v_mul_f32_e32 v175, v132, v173
	v_mul_f32_e32 v133, v133, v163
	v_ashrrev_i32_e32 v132, 4, v182
	v_mul_f32_e32 v137, v137, v174
	v_mul_f32_e32 v131, v131, v172
	v_cvt_pk_bf16_f32 v172, v134, v135
	v_cvt_pk_bf16_f32 v173, v136, v137
	v_cvt_pk_bf16_f32 v174, v130, v131
	v_cvt_pk_bf16_f32 v175, v175, v133
	v_ashrrev_i32_e32 v133, 31, v132
	v_lshl_add_u64 v[134:135], s[14:15], 0, v[180:181]
	v_lshlrev_b64 v[130:131], 10, v[132:133]
	v_lshl_add_u64 v[136:137], v[134:135], 0, v[130:131]
	v_lshl_add_u64 v[136:137], v[136:137], 0, s[4:5]
	v_lshlrev_b32_e32 v133, 16, v176
	v_lshl_add_u64 v[136:137], v[136:137], 0, v[154:155]
	v_fma_f32 v126, v66, v133, v126
	global_store_dwordx4 v[136:137], v[172:175], off
	v_mul_f32_e32 v136, 0x3d372713, v126
	v_mul_f32_e32 v136, v126, v136
	v_and_b32_e32 v133, 0xffff0000, v176
	v_fma_f32 v136, v126, v136, v126
	v_fma_f32 v127, v67, v133, v127
	v_lshlrev_b32_e32 v133, 16, v177
	v_mul_f32_e32 v136, 0x3fcc422a, v136
	v_fma_f32 v128, v68, v133, v128
	v_and_b32_e32 v133, 0xffff0000, v177
	v_mul_f32_e32 v136, 0xbfb8aa3b, v136
	v_fmac_f32_e32 v129, v69, v133
	v_lshlrev_b32_e32 v133, 16, v178
	v_exp_f32_e32 v136, v136
	v_fma_f32 v122, v62, v133, v122
	v_and_b32_e32 v133, 0xffff0000, v178
	v_fma_f32 v123, v63, v133, v123
	v_lshlrev_b32_e32 v133, 16, v179
	v_fma_f32 v124, v64, v133, v124
	v_and_b32_e32 v133, 0xffff0000, v179
	v_mul_f32_e32 v163, 0x3d372713, v129
	v_fmac_f32_e32 v125, v65, v133
	v_add_f32_e32 v133, 1.0, v136
	v_mul_f32_e32 v136, 0x3d372713, v127
	v_mul_f32_e32 v137, 0x3d372713, v128
	v_mul_f32_e32 v163, v129, v163
	v_mul_f32_e32 v136, v127, v136
	v_mul_f32_e32 v137, v128, v137
	v_fma_f32 v163, v129, v163, v129
; __device__ __forceinline__ unsigned cvt_pk_bf16(float lo, float hi) { unsigned r; asm volatile("v_cvt_pk_bf16_f32 %0, %1, %2" : "=v"(r) : "v"(lo), "v"(hi)); return r; }
; __device__ __forceinline__ float bflo(unsigned w) { return __uint_as_float(w << 16); }
; __device__ __forceinline__ float bfhi(unsigned w) { return __uint_as_float(w & 0xffff0000u); }
; __device__ __forceinline__ float gelu_tanh(float v) { const float z = 1.5957691216057308f * (v + 0.044715f * v * v * v); return v * sigm(z); }
;     __device__ __forceinline__ void operator()(const pg8::f32x4 (&acc)[2][2][4][2], const Unit& u, int wr, int wc, int fr, int fq) const {
;     ...
;             for (int bj = 0; bj < 2; ++bj) { const int tau = (colb + bj * HALF) >> 4;
;                 const v4u uw = cu[bj]; const f32x4 a0 = acc[ai][bj][m][0], a1 = acc[ai][bj][m][1];
;                 float r[8]; r[0] = a0[0] + d0[0] * bflo(uw.x); r[1] = a0[1] + d0[1] * bfhi(uw.x); r[2] = a0[2] + d0[2] * bflo(uw.y); r[3] = a0[3] + d0[3] * bfhi(uw.y);
;                 r[4] = a1[0] + d1[0] * bflo(uw.z); r[5] = a1[1] + d1[1] * bfhi(uw.z); r[6] = a1[2] + d1[2] * bflo(uw.w); r[7] = a1[3] + d1[3] * bfhi(uw.w);
; #pragma unroll
;                 for (int e = 0; e < 8; ++e) r[e] = gelu_tanh(r[e]);
;                 v4u w; w.x = cvt_pk_bf16(r[0], r[1]); w.y = cvt_pk_bf16(r[2], r[3]); w.z = cvt_pk_bf16(r[4], r[5]); w.w = cvt_pk_bf16(r[6], r[7]);
;                 *(v4u*)(Y + ((size_t)row * 32 + tau) * 512 + u.g * 16 + c0) = w; } }
	v_fma_f32 v136, v127, v136, v127
	v_fma_f32 v137, v128, v137, v128
	v_mul_f32_e32 v163, 0x3fcc422a, v163
	v_mul_f32_e32 v136, 0x3fcc422a, v136
	v_mul_f32_e32 v137, 0x3fcc422a, v137
	v_mul_f32_e32 v163, 0xbfb8aa3b, v163
	v_mul_f32_e32 v136, 0xbfb8aa3b, v136
	v_mul_f32_e32 v137, 0xbfb8aa3b, v137
	v_rcp_f32_e32 v133, v133
	v_exp_f32_e32 v163, v163
	v_exp_f32_e32 v136, v136
	v_exp_f32_e32 v137, v137
	v_mul_f32_e32 v133, v126, v133
	v_add_f32_e32 v126, 1.0, v163
	v_mul_f32_e32 v163, 0x3d372713, v125
	v_add_f32_e32 v136, 1.0, v136
	v_add_f32_e32 v137, 1.0, v137
	v_mul_f32_e32 v163, v125, v163
	v_rcp_f32_e32 v136, v136
	v_rcp_f32_e32 v137, v137
	v_fma_f32 v163, v125, v163, v125
	v_mul_f32_e32 v163, 0x3fcc422a, v163
	v_mul_f32_e32 v163, 0xbfb8aa3b, v163
	v_exp_f32_e32 v163, v163
	v_mul_f32_e32 v127, v127, v136
	v_mul_f32_e32 v128, v128, v137
	v_mul_f32_e32 v136, 0x3d372713, v122
	v_mul_f32_e32 v137, 0x3d372713, v123
	v_mul_f32_e32 v136, v122, v136
	v_mul_f32_e32 v137, v123, v137
	v_fma_f32 v136, v122, v136, v122
	v_fma_f32 v137, v123, v137, v123
	v_mul_f32_e32 v136, 0x3fcc422a, v136
	v_mul_f32_e32 v137, 0x3fcc422a, v137
	v_add_f32_e32 v163, 1.0, v163
	v_mul_f32_e32 v136, 0xbfb8aa3b, v136
	v_mul_f32_e32 v137, 0xbfb8aa3b, v137
	v_rcp_f32_e32 v163, v163
	v_rcp_f32_e32 v126, v126
	v_exp_f32_e32 v136, v136
	v_exp_f32_e32 v137, v137
	v_mul_f32_e32 v125, v125, v163
	v_lshlrev_b32_e32 v163, 16, v142
	v_and_b32_e32 v142, 0xffff0000, v142
	v_mul_f32_e32 v129, v129, v126
	v_add_f32_e32 v126, 1.0, v136
	v_add_f32_e32 v136, 1.0, v137
	v_mul_f32_e32 v137, 0x3d372713, v124
	v_fma_f32 v118, v66, v163, v118
	v_fma_f32 v119, v67, v142, v119
	v_lshlrev_b32_e32 v142, 16, v143
	v_mul_f32_e32 v137, v124, v137
	v_fma_f32 v120, v68, v142, v120
	v_and_b32_e32 v142, 0xffff0000, v143
	v_mul_f32_e32 v143, 0x3d372713, v118
	v_fma_f32 v137, v124, v137, v124
	v_mul_f32_e32 v143, v118, v143
	v_mul_f32_e32 v137, 0x3fcc422a, v137
	v_fma_f32 v143, v118, v143, v118
	v_rcp_f32_e32 v126, v126
	v_mul_f32_e32 v137, 0xbfb8aa3b, v137
	v_mul_f32_e32 v143, 0x3fcc422a, v143
	v_exp_f32_e32 v137, v137
	v_mul_f32_e32 v143, 0xbfb8aa3b, v143
	v_fmac_f32_e32 v121, v69, v142
	v_lshlrev_b32_e32 v142, 16, v144
	v_exp_f32_e32 v143, v143
	v_fma_f32 v114, v62, v142, v114
	v_and_b32_e32 v142, 0xffff0000, v144
	v_mul_f32_e32 v172, v122, v126
	v_or_b32_e32 v126, 8, v132
	v_fma_f32 v115, v63, v142, v115
	v_lshlrev_b32_e32 v142, 16, v145
	v_add_f32_e32 v137, 1.0, v137
	v_cvt_pk_bf16_f32 v122, v133, v127
	v_ashrrev_i32_e32 v127, 31, v126
	v_fma_f32 v116, v64, v142, v116
	v_and_b32_e32 v142, 0xffff0000, v145
	v_rcp_f32_e32 v136, v136
	v_rcp_f32_e32 v137, v137
	v_lshlrev_b64 v[132:133], 10, v[126:127]
	v_fmac_f32_e32 v117, v65, v142
	v_add_f32_e32 v142, 1.0, v143
	v_mul_f32_e32 v143, 0x3d372713, v119
	v_mul_f32_e32 v144, 0x3d372713, v120
	v_lshl_add_u64 v[126:127], v[134:135], 0, v[132:133]
	v_mul_f32_e32 v143, v119, v143
	v_mul_f32_e32 v144, v120, v144
	v_lshl_add_u64 v[126:127], v[126:127], 0, s[4:5]
	v_fma_f32 v143, v119, v143, v119
	v_fma_f32 v144, v120, v144, v120
	v_lshl_add_u64 v[126:127], v[126:127], 0, v[154:155]
	v_mul_f32_e32 v143, 0x3fcc422a, v143
	v_mul_f32_e32 v144, 0x3fcc422a, v144
	v_mul_f32_e32 v136, v123, v136
	v_mul_f32_e32 v137, v124, v137
	v_cvt_pk_bf16_f32 v123, v128, v129
	v_cvt_pk_bf16_f32 v124, v172, v136
	v_cvt_pk_bf16_f32 v125, v137, v125
	global_store_dwordx4 v[126:127], v[122:125], off
	v_add_co_u32_e32 v126, vcc, s58, v164
	v_mul_f32_e32 v143, 0xbfb8aa3b, v143
	v_mul_f32_e32 v144, 0xbfb8aa3b, v144
	v_lshl_add_u64 v[122:123], v[164:165], 0, s[22:23]
	v_addc_co_u32_e32 v127, vcc, 0, v165, vcc
	v_exp_f32_e32 v143, v143
	v_exp_f32_e32 v144, v144
	global_load_dwordx4 v[122:125], v[122:123], off offset:256
	s_nop 0
	global_load_dwordx4 v[126:129], v[126:127], off
	v_mul_f32_e32 v145, 0x3d372713, v121
	v_add_f32_e32 v143, 1.0, v143
	v_add_f32_e32 v144, 1.0, v144
	v_rcp_f32_e32 v143, v143
	v_rcp_f32_e32 v144, v144
	v_mul_f32_e32 v145, v121, v145
	v_fma_f32 v145, v121, v145, v121
	v_mul_f32_e32 v145, 0x3fcc422a, v145
	v_mul_f32_e32 v145, 0xbfb8aa3b, v145
	v_rcp_f32_e32 v142, v142
	v_exp_f32_e32 v145, v145
	v_mul_f32_e32 v119, v119, v143
	v_mul_f32_e32 v120, v120, v144
	v_mul_f32_e32 v143, 0x3d372713, v114
	v_mul_f32_e32 v144, 0x3d372713, v115
	v_mul_f32_e32 v143, v114, v143
	v_mul_f32_e32 v144, v115, v144
	v_fma_f32 v143, v114, v143, v114
	v_fma_f32 v144, v115, v144, v115
	v_mul_f32_e32 v143, 0x3fcc422a, v143
	v_mul_f32_e32 v144, 0x3fcc422a, v144
	v_mul_f32_e32 v118, v118, v142
	v_add_f32_e32 v142, 1.0, v145
	v_mul_f32_e32 v143, 0xbfb8aa3b, v143
	v_mul_f32_e32 v144, 0xbfb8aa3b, v144
	v_rcp_f32_e32 v142, v142
	v_exp_f32_e32 v143, v143
	v_exp_f32_e32 v144, v144
	v_mul_f32_e32 v145, 0x3d372713, v117
	v_mul_f32_e32 v121, v121, v142
	v_add_f32_e32 v142, 1.0, v143
	v_add_f32_e32 v143, 1.0, v144
	v_mul_f32_e32 v144, 0x3d372713, v116
	v_mul_f32_e32 v145, v117, v145
	v_mul_f32_e32 v144, v116, v144
	v_fma_f32 v145, v117, v145, v117
	v_fma_f32 v144, v116, v144, v116
	v_mul_f32_e32 v145, 0x3fcc422a, v145
	v_mul_f32_e32 v144, 0x3fcc422a, v144
	v_mul_f32_e32 v145, 0xbfb8aa3b, v145
	v_mul_f32_e32 v144, 0xbfb8aa3b, v144
	v_exp_f32_e32 v145, v145
	v_exp_f32_e32 v144, v144
	v_rcp_f32_e32 v142, v142
	v_or_b32_e32 v136, 16, v162
	v_rcp_f32_e32 v143, v143
	v_ashrrev_i32_e32 v137, 31, v136
	v_add_f32_e32 v145, 1.0, v145
	v_lshlrev_b64 v[136:137], 15, v[136:137]
	v_add_f32_e32 v144, 1.0, v144
	v_rcp_f32_e32 v145, v145
	v_rcp_f32_e32 v144, v144
	v_mul_f32_e32 v142, v114, v142
	v_cvt_pk_bf16_f32 v114, v118, v119
	v_lshl_add_u64 v[118:119], s[14:15], 0, v[136:137]
	v_mul_f32_e32 v143, v115, v143
; __device__ __forceinline__ unsigned cvt_pk_bf16(float lo, float hi) { unsigned r; asm volatile("v_cvt_pk_bf16_f32 %0, %1, %2" : "=v"(r) : "v"(lo), "v"(hi)); return r; }
; __device__ __forceinline__ float bflo(unsigned w) { return __uint_as_float(w << 16); }
; __device__ __forceinline__ float bfhi(unsigned w) { return __uint_as_float(w & 0xffff0000u); }
; __device__ __forceinline__ float gelu_tanh(float v) { const float z = 1.5957691216057308f * (v + 0.044715f * v * v * v); return v * sigm(z); }
;     __device__ __forceinline__ void operator()(const pg8::f32x4 (&acc)[2][2][4][2], const Unit& u, int wr, int wc, int fr, int fq) const {
;     ...
;         for (int k = 0; k < 8; ++k) { const int ai = k >> 2, m = k & 3; const int row = row0 + ai * HALF + m * 16; v4u cu[2];
; #pragma unroll
;             for (int bj = 0; bj < 2; ++bj) cu[bj] = nu[bj];
;             if (k < 7) {
; #pragma unroll
;                 for (int bj = 0; bj < 2; ++bj) nu[bj] = *(const v4u*)(UX + ((size_t)u.g * 1024 + row0 + ((k + 1) >> 2) * HALF + ((k + 1) & 3) * 16) * 640 + ((colb + bj * HALF) >> 4) * 16 + c0); }
; #pragma unroll
;             for (int bj = 0; bj < 2; ++bj) { const int tau = (colb + bj * HALF) >> 4;
;                 const v4u uw = cu[bj]; const f32x4 a0 = acc[ai][bj][m][0], a1 = acc[ai][bj][m][1];
;                 float r[8]; r[0] = a0[0] + d0[0] * bflo(uw.x); r[1] = a0[1] + d0[1] * bfhi(uw.x); r[2] = a0[2] + d0[2] * bflo(uw.y); r[3] = a0[3] + d0[3] * bfhi(uw.y);
;                 r[4] = a1[0] + d1[0] * bflo(uw.z); r[5] = a1[1] + d1[1] * bfhi(uw.z); r[6] = a1[2] + d1[2] * bflo(uw.w); r[7] = a1[3] + d1[3] * bfhi(uw.w);
; #pragma unroll
;                 for (int e = 0; e < 8; ++e) r[e] = gelu_tanh(r[e]);
;                 v4u w; w.x = cvt_pk_bf16(r[0], r[1]); w.y = cvt_pk_bf16(r[2], r[3]); w.z = cvt_pk_bf16(r[4], r[5]); w.w = cvt_pk_bf16(r[6], r[7]);
;                 *(v4u*)(Y + ((size_t)row * 32 + tau) * 512 + u.g * 16 + c0) = w; } }
	v_cvt_pk_bf16_f32 v115, v120, v121
	v_lshl_add_u64 v[120:121], v[118:119], 0, v[130:131]
	v_lshl_add_u64 v[120:121], v[120:121], 0, s[4:5]
	v_mul_f32_e32 v117, v117, v145
	v_lshl_add_u64 v[120:121], v[120:121], 0, v[154:155]
	v_mul_f32_e32 v144, v116, v144
	v_cvt_pk_bf16_f32 v116, v142, v143
	v_cvt_pk_bf16_f32 v117, v144, v117
	global_store_dwordx4 v[120:121], v[114:117], off
	s_nop 1
	v_lshlrev_b32_e32 v114, 16, v138
	v_fma_f32 v110, v66, v114, v110
	v_mul_f32_e32 v115, 0x3d372713, v110
	v_mul_f32_e32 v115, v110, v115
	v_and_b32_e32 v114, 0xffff0000, v138
	v_fma_f32 v115, v110, v115, v110
	v_fma_f32 v111, v67, v114, v111
	v_lshlrev_b32_e32 v114, 16, v139
	v_mul_f32_e32 v115, 0x3fcc422a, v115
	v_fma_f32 v112, v68, v114, v112
	v_and_b32_e32 v114, 0xffff0000, v139
	v_mul_f32_e32 v115, 0xbfb8aa3b, v115
	v_fmac_f32_e32 v113, v69, v114
	v_lshlrev_b32_e32 v114, 16, v140
	v_exp_f32_e32 v115, v115
	v_fma_f32 v106, v62, v114, v106
	v_and_b32_e32 v114, 0xffff0000, v140
	v_fma_f32 v107, v63, v114, v107
	v_lshlrev_b32_e32 v114, 16, v141
	v_fma_f32 v108, v64, v114, v108
	v_and_b32_e32 v114, 0xffff0000, v141
	v_fmac_f32_e32 v109, v65, v114
	v_add_f32_e32 v114, 1.0, v115
	v_mul_f32_e32 v115, 0x3d372713, v111
	v_mul_f32_e32 v116, 0x3d372713, v112
	v_mul_f32_e32 v115, v111, v115
	v_mul_f32_e32 v116, v112, v116
	v_fma_f32 v115, v111, v115, v111
	v_fma_f32 v116, v112, v116, v112
	v_mul_f32_e32 v115, 0x3fcc422a, v115
	v_mul_f32_e32 v116, 0x3fcc422a, v116
	v_mul_f32_e32 v115, 0xbfb8aa3b, v115
	v_mul_f32_e32 v116, 0xbfb8aa3b, v116
	v_exp_f32_e32 v115, v115
	v_exp_f32_e32 v116, v116
	v_mul_f32_e32 v117, 0x3d372713, v113
	v_mul_f32_e32 v117, v113, v117
	v_add_f32_e32 v115, 1.0, v115
	v_add_f32_e32 v116, 1.0, v116
	v_rcp_f32_e32 v115, v115
	v_rcp_f32_e32 v116, v116
	v_fma_f32 v117, v113, v117, v113
	v_mul_f32_e32 v117, 0x3fcc422a, v117
	v_mul_f32_e32 v117, 0xbfb8aa3b, v117
	v_rcp_f32_e32 v114, v114
	v_exp_f32_e32 v117, v117
	v_mul_f32_e32 v111, v111, v115
	v_mul_f32_e32 v112, v112, v116
	v_mul_f32_e32 v115, 0x3d372713, v106
	v_mul_f32_e32 v116, 0x3d372713, v107
	v_mul_f32_e32 v115, v106, v115
	v_mul_f32_e32 v116, v107, v116
	v_fma_f32 v115, v106, v115, v106
	v_fma_f32 v116, v107, v116, v107
	v_mul_f32_e32 v115, 0x3fcc422a, v115
	v_mul_f32_e32 v116, 0x3fcc422a, v116
	v_mul_f32_e32 v110, v110, v114
	v_add_f32_e32 v114, 1.0, v117
	v_mul_f32_e32 v115, 0xbfb8aa3b, v115
	v_mul_f32_e32 v116, 0xbfb8aa3b, v116
	v_rcp_f32_e32 v114, v114
	v_exp_f32_e32 v115, v115
	v_exp_f32_e32 v116, v116
	v_mul_f32_e32 v117, 0x3d372713, v109
	v_mul_f32_e32 v113, v113, v114
	v_add_f32_e32 v114, 1.0, v115
	v_add_f32_e32 v115, 1.0, v116
	v_mul_f32_e32 v116, 0x3d372713, v108
	v_mul_f32_e32 v116, v108, v116
	v_mul_f32_e32 v117, v109, v117
	v_fma_f32 v116, v108, v116, v108
	v_fma_f32 v117, v109, v117, v109
	v_mul_f32_e32 v116, 0x3fcc422a, v116
	v_mul_f32_e32 v117, 0x3fcc422a, v117
	v_mul_f32_e32 v116, 0xbfb8aa3b, v116
	v_mul_f32_e32 v117, 0xbfb8aa3b, v117
	v_exp_f32_e32 v116, v116
	v_exp_f32_e32 v117, v117
	v_rcp_f32_e32 v114, v114
	v_rcp_f32_e32 v115, v115
	v_add_f32_e32 v116, 1.0, v116
	v_add_f32_e32 v117, 1.0, v117
	v_rcp_f32_e32 v116, v116
	v_rcp_f32_e32 v117, v117
	v_mul_f32_e32 v114, v106, v114
	v_mul_f32_e32 v115, v107, v115
	v_mul_f32_e32 v116, v108, v116
	v_mul_f32_e32 v109, v109, v117
	v_cvt_pk_bf16_f32 v106, v110, v111
	v_cvt_pk_bf16_f32 v107, v112, v113
	v_cvt_pk_bf16_f32 v108, v114, v115
	v_cvt_pk_bf16_f32 v109, v116, v109
	s_waitcnt vmcnt(1)
	v_lshlrev_b32_e32 v116, 16, v126
	v_fma_f32 v102, v66, v116, v102
	v_mul_f32_e32 v117, 0x3d372713, v102
	v_mul_f32_e32 v117, v102, v117
	v_and_b32_e32 v116, 0xffff0000, v126
	v_fma_f32 v117, v102, v117, v102
	v_fma_f32 v103, v67, v116, v103
	v_lshlrev_b32_e32 v116, 16, v127
	v_mul_f32_e32 v117, 0x3fcc422a, v117
	v_fma_f32 v104, v68, v116, v104
	v_and_b32_e32 v116, 0xffff0000, v127
	v_mul_f32_e32 v117, 0xbfb8aa3b, v117
	v_fmac_f32_e32 v105, v69, v116
	v_lshlrev_b32_e32 v116, 16, v128
	v_exp_f32_e32 v117, v117
	v_fma_f32 v98, v62, v116, v98
	v_and_b32_e32 v116, 0xffff0000, v128
	v_fma_f32 v99, v63, v116, v99
	v_lshlrev_b32_e32 v116, 16, v129
	v_fma_f32 v100, v64, v116, v100
	v_and_b32_e32 v116, 0xffff0000, v129
	v_lshl_add_u64 v[110:111], v[118:119], 0, v[132:133]
	v_fmac_f32_e32 v101, v65, v116
	v_add_f32_e32 v116, 1.0, v117
	v_mul_f32_e32 v117, 0x3d372713, v103
	v_mul_f32_e32 v118, 0x3d372713, v104
	v_mul_f32_e32 v117, v103, v117
	v_mul_f32_e32 v118, v104, v118
	v_lshl_add_u64 v[110:111], v[110:111], 0, s[4:5]
	v_fma_f32 v117, v103, v117, v103
	v_fma_f32 v118, v104, v118, v104
	v_lshl_add_u64 v[110:111], v[110:111], 0, v[154:155]
	v_mul_f32_e32 v117, 0x3fcc422a, v117
	v_mul_f32_e32 v118, 0x3fcc422a, v118
	global_store_dwordx4 v[110:111], v[106:109], off
	v_add_co_u32_e32 v110, vcc, s63, v164
	v_mul_f32_e32 v117, 0xbfb8aa3b, v117
	v_mul_f32_e32 v118, 0xbfb8aa3b, v118
	v_lshl_add_u64 v[106:107], v[164:165], 0, s[24:25]
	v_addc_co_u32_e32 v111, vcc, 0, v165, vcc
	v_exp_f32_e32 v117, v117
	v_exp_f32_e32 v118, v118
	global_load_dwordx4 v[106:109], v[106:107], off offset:256
	s_nop 0
	global_load_dwordx4 v[110:113], v[110:111], off
	v_mul_f32_e32 v119, 0x3d372713, v105
	v_add_f32_e32 v117, 1.0, v117
	v_add_f32_e32 v118, 1.0, v118
	v_rcp_f32_e32 v117, v117
	v_rcp_f32_e32 v118, v118
	v_mul_f32_e32 v119, v105, v119
	v_fma_f32 v119, v105, v119, v105
	v_mul_f32_e32 v119, 0x3fcc422a, v119
	v_mul_f32_e32 v119, 0xbfb8aa3b, v119
	v_rcp_f32_e32 v116, v116
	v_exp_f32_e32 v119, v119
	v_mul_f32_e32 v103, v103, v117
	v_mul_f32_e32 v104, v104, v118
	v_mul_f32_e32 v117, 0x3d372713, v98
	v_mul_f32_e32 v118, 0x3d372713, v99
	v_mul_f32_e32 v117, v98, v117
; __device__ __forceinline__ unsigned cvt_pk_bf16(float lo, float hi) { unsigned r; asm volatile("v_cvt_pk_bf16_f32 %0, %1, %2" : "=v"(r) : "v"(lo), "v"(hi)); return r; }
; __device__ __forceinline__ float bflo(unsigned w) { return __uint_as_float(w << 16); }
; __device__ __forceinline__ float bfhi(unsigned w) { return __uint_as_float(w & 0xffff0000u); }
; __device__ __forceinline__ float gelu_tanh(float v) { const float z = 1.5957691216057308f * (v + 0.044715f * v * v * v); return v * sigm(z); }
;     __device__ __forceinline__ void operator()(const pg8::f32x4 (&acc)[2][2][4][2], const Unit& u, int wr, int wc, int fr, int fq) const {
;     ...
;         for (int k = 0; k < 8; ++k) { const int ai = k >> 2, m = k & 3; const int row = row0 + ai * HALF + m * 16; v4u cu[2];
; #pragma unroll
;             for (int bj = 0; bj < 2; ++bj) cu[bj] = nu[bj];
;             if (k < 7) {
; #pragma unroll
;                 for (int bj = 0; bj < 2; ++bj) nu[bj] = *(const v4u*)(UX + ((size_t)u.g * 1024 + row0 + ((k + 1) >> 2) * HALF + ((k + 1) & 3) * 16) * 640 + ((colb + bj * HALF) >> 4) * 16 + c0); }
; #pragma unroll
;             for (int bj = 0; bj < 2; ++bj) { const int tau = (colb + bj * HALF) >> 4;
;                 const v4u uw = cu[bj]; const f32x4 a0 = acc[ai][bj][m][0], a1 = acc[ai][bj][m][1];
;                 float r[8]; r[0] = a0[0] + d0[0] * bflo(uw.x); r[1] = a0[1] + d0[1] * bfhi(uw.x); r[2] = a0[2] + d0[2] * bflo(uw.y); r[3] = a0[3] + d0[3] * bfhi(uw.y);
;                 r[4] = a1[0] + d1[0] * bflo(uw.z); r[5] = a1[1] + d1[1] * bfhi(uw.z); r[6] = a1[2] + d1[2] * bflo(uw.w); r[7] = a1[3] + d1[3] * bfhi(uw.w);
; #pragma unroll
;                 for (int e = 0; e < 8; ++e) r[e] = gelu_tanh(r[e]);
;                 v4u w; w.x = cvt_pk_bf16(r[0], r[1]); w.y = cvt_pk_bf16(r[2], r[3]); w.z = cvt_pk_bf16(r[4], r[5]); w.w = cvt_pk_bf16(r[6], r[7]);
;                 *(v4u*)(Y + ((size_t)row * 32 + tau) * 512 + u.g * 16 + c0) = w; } }
	v_mul_f32_e32 v118, v99, v118
	v_fma_f32 v117, v98, v117, v98
	v_fma_f32 v118, v99, v118, v99
	v_mul_f32_e32 v117, 0x3fcc422a, v117
	v_mul_f32_e32 v118, 0x3fcc422a, v118
	v_mul_f32_e32 v102, v102, v116
	v_add_f32_e32 v116, 1.0, v119
	v_mul_f32_e32 v117, 0xbfb8aa3b, v117
	v_mul_f32_e32 v118, 0xbfb8aa3b, v118
	v_rcp_f32_e32 v116, v116
	v_exp_f32_e32 v117, v117
	v_exp_f32_e32 v118, v118
	v_mul_f32_e32 v119, 0x3d372713, v101
	v_mul_f32_e32 v105, v105, v116
	v_add_f32_e32 v116, 1.0, v117
	v_add_f32_e32 v117, 1.0, v118
	v_mul_f32_e32 v118, 0x3d372713, v100
	v_mul_f32_e32 v119, v101, v119
	v_mul_f32_e32 v118, v100, v118
	v_fma_f32 v119, v101, v119, v101
	v_fma_f32 v118, v100, v118, v100
	v_mul_f32_e32 v119, 0x3fcc422a, v119
	v_mul_f32_e32 v118, 0x3fcc422a, v118
	v_mul_f32_e32 v119, 0xbfb8aa3b, v119
	v_mul_f32_e32 v118, 0xbfb8aa3b, v118
	v_exp_f32_e32 v119, v119
	v_exp_f32_e32 v118, v118
	v_rcp_f32_e32 v116, v116
	v_or_b32_e32 v114, 32, v162
	v_rcp_f32_e32 v117, v117
	v_ashrrev_i32_e32 v115, 31, v114
	v_add_f32_e32 v119, 1.0, v119
	v_lshlrev_b64 v[114:115], 15, v[114:115]
	v_add_f32_e32 v118, 1.0, v118
	v_rcp_f32_e32 v119, v119
	v_rcp_f32_e32 v118, v118
	v_mul_f32_e32 v116, v98, v116
	v_cvt_pk_bf16_f32 v98, v102, v103
	v_lshl_add_u64 v[102:103], s[14:15], 0, v[114:115]
	v_mul_f32_e32 v117, v99, v117
	v_cvt_pk_bf16_f32 v99, v104, v105
	v_lshl_add_u64 v[104:105], v[102:103], 0, v[130:131]
	v_lshl_add_u64 v[104:105], v[104:105], 0, s[4:5]
	v_mul_f32_e32 v101, v101, v119
	v_lshl_add_u64 v[104:105], v[104:105], 0, v[154:155]
	v_mul_f32_e32 v118, v100, v118
	v_cvt_pk_bf16_f32 v100, v116, v117
	v_cvt_pk_bf16_f32 v101, v118, v101
	global_store_dwordx4 v[104:105], v[98:101], off
	s_nop 1
	v_lshlrev_b32_e32 v98, 16, v122
	v_fma_f32 v94, v66, v98, v94
	v_mul_f32_e32 v99, 0x3d372713, v94
	v_mul_f32_e32 v99, v94, v99
	v_and_b32_e32 v98, 0xffff0000, v122
	v_fma_f32 v99, v94, v99, v94
	v_fma_f32 v95, v67, v98, v95
	v_lshlrev_b32_e32 v98, 16, v123
	v_mul_f32_e32 v99, 0x3fcc422a, v99
	v_fma_f32 v96, v68, v98, v96
	v_and_b32_e32 v98, 0xffff0000, v123
	v_mul_f32_e32 v99, 0xbfb8aa3b, v99
	v_fmac_f32_e32 v97, v69, v98
	v_lshlrev_b32_e32 v98, 16, v124
	v_exp_f32_e32 v99, v99
	v_fma_f32 v90, v62, v98, v90
	v_and_b32_e32 v98, 0xffff0000, v124
	v_fma_f32 v91, v63, v98, v91
	v_lshlrev_b32_e32 v98, 16, v125
	v_fma_f32 v92, v64, v98, v92
	v_and_b32_e32 v98, 0xffff0000, v125
	v_fmac_f32_e32 v93, v65, v98
	v_add_f32_e32 v98, 1.0, v99
	v_mul_f32_e32 v99, 0x3d372713, v95
	v_mul_f32_e32 v100, 0x3d372713, v96
	v_mul_f32_e32 v99, v95, v99
	v_mul_f32_e32 v100, v96, v100
	v_fma_f32 v99, v95, v99, v95
	v_fma_f32 v100, v96, v100, v96
	v_mul_f32_e32 v99, 0x3fcc422a, v99
	v_mul_f32_e32 v100, 0x3fcc422a, v100
	v_mul_f32_e32 v99, 0xbfb8aa3b, v99
	v_mul_f32_e32 v100, 0xbfb8aa3b, v100
	v_exp_f32_e32 v99, v99
	v_exp_f32_e32 v100, v100
	v_mul_f32_e32 v101, 0x3d372713, v97
	v_mul_f32_e32 v101, v97, v101
	v_add_f32_e32 v99, 1.0, v99
	v_add_f32_e32 v100, 1.0, v100
	v_rcp_f32_e32 v99, v99
	v_rcp_f32_e32 v100, v100
	v_fma_f32 v101, v97, v101, v97
	v_mul_f32_e32 v101, 0x3fcc422a, v101
	v_mul_f32_e32 v101, 0xbfb8aa3b, v101
	v_rcp_f32_e32 v98, v98
	v_exp_f32_e32 v101, v101
	v_mul_f32_e32 v95, v95, v99
	v_mul_f32_e32 v96, v96, v100
	v_mul_f32_e32 v99, 0x3d372713, v90
	v_mul_f32_e32 v100, 0x3d372713, v91
	v_mul_f32_e32 v99, v90, v99
	v_mul_f32_e32 v100, v91, v100
	v_fma_f32 v99, v90, v99, v90
	v_fma_f32 v100, v91, v100, v91
	v_mul_f32_e32 v99, 0x3fcc422a, v99
	v_mul_f32_e32 v100, 0x3fcc422a, v100
	v_mul_f32_e32 v94, v94, v98
	v_add_f32_e32 v98, 1.0, v101
	v_mul_f32_e32 v99, 0xbfb8aa3b, v99
	v_mul_f32_e32 v100, 0xbfb8aa3b, v100
	v_rcp_f32_e32 v98, v98
	v_exp_f32_e32 v99, v99
	v_exp_f32_e32 v100, v100
	v_mul_f32_e32 v101, 0x3d372713, v93
	v_mul_f32_e32 v97, v97, v98
	v_add_f32_e32 v98, 1.0, v99
	v_add_f32_e32 v99, 1.0, v100
	v_mul_f32_e32 v100, 0x3d372713, v92
	v_mul_f32_e32 v100, v92, v100
	v_mul_f32_e32 v101, v93, v101
	v_fma_f32 v100, v92, v100, v92
	v_fma_f32 v101, v93, v101, v93
	v_mul_f32_e32 v100, 0x3fcc422a, v100
	v_mul_f32_e32 v101, 0x3fcc422a, v101
	v_mul_f32_e32 v100, 0xbfb8aa3b, v100
	v_mul_f32_e32 v101, 0xbfb8aa3b, v101
	v_exp_f32_e32 v100, v100
	v_exp_f32_e32 v101, v101
	v_rcp_f32_e32 v98, v98
	v_rcp_f32_e32 v99, v99
	v_add_f32_e32 v100, 1.0, v100
	v_add_f32_e32 v101, 1.0, v101
	v_rcp_f32_e32 v100, v100
	v_rcp_f32_e32 v101, v101
	v_mul_f32_e32 v98, v90, v98
	v_mul_f32_e32 v99, v91, v99
	v_mul_f32_e32 v100, v92, v100
	v_mul_f32_e32 v93, v93, v101
	v_cvt_pk_bf16_f32 v90, v94, v95
	v_cvt_pk_bf16_f32 v91, v96, v97
	v_cvt_pk_bf16_f32 v92, v98, v99
	v_cvt_pk_bf16_f32 v93, v100, v93
	s_waitcnt vmcnt(1)
; __device__ __forceinline__ unsigned cvt_pk_bf16(float lo, float hi) { unsigned r; asm volatile("v_cvt_pk_bf16_f32 %0, %1, %2" : "=v"(r) : "v"(lo), "v"(hi)); return r; }
; __device__ __forceinline__ float bflo(unsigned w) { return __uint_as_float(w << 16); }
; __device__ __forceinline__ float bfhi(unsigned w) { return __uint_as_float(w & 0xffff0000u); }
; __device__ __forceinline__ float gelu_tanh(float v) { const float z = 1.5957691216057308f * (v + 0.044715f * v * v * v); return v * sigm(z); }
;     __device__ __forceinline__ void operator()(const pg8::f32x4 (&acc)[2][2][4][2], const Unit& u, int wr, int wc, int fr, int fq) const {
;     ...
;         for (int k = 0; k < 8; ++k) { const int ai = k >> 2, m = k & 3; const int row = row0 + ai * HALF + m * 16; v4u cu[2];
; #pragma unroll
;             for (int bj = 0; bj < 2; ++bj) cu[bj] = nu[bj];
;             if (k < 7) {
; #pragma unroll
;                 for (int bj = 0; bj < 2; ++bj) nu[bj] = *(const v4u*)(UX + ((size_t)u.g * 1024 + row0 + ((k + 1) >> 2) * HALF + ((k + 1) & 3) * 16) * 640 + ((colb + bj * HALF) >> 4) * 16 + c0); }
; #pragma unroll
;             for (int bj = 0; bj < 2; ++bj) { const int tau = (colb + bj * HALF) >> 4;
;                 const v4u uw = cu[bj]; const f32x4 a0 = acc[ai][bj][m][0], a1 = acc[ai][bj][m][1];
;                 float r[8]; r[0] = a0[0] + d0[0] * bflo(uw.x); r[1] = a0[1] + d0[1] * bfhi(uw.x); r[2] = a0[2] + d0[2] * bflo(uw.y); r[3] = a0[3] + d0[3] * bfhi(uw.y);
;                 r[4] = a1[0] + d1[0] * bflo(uw.z); r[5] = a1[1] + d1[1] * bfhi(uw.z); r[6] = a1[2] + d1[2] * bflo(uw.w); r[7] = a1[3] + d1[3] * bfhi(uw.w);
; #pragma unroll
;                 for (int e = 0; e < 8; ++e) r[e] = gelu_tanh(r[e]);
;                 v4u w; w.x = cvt_pk_bf16(r[0], r[1]); w.y = cvt_pk_bf16(r[2], r[3]); w.z = cvt_pk_bf16(r[4], r[5]); w.w = cvt_pk_bf16(r[6], r[7]);
;                 *(v4u*)(Y + ((size_t)row * 32 + tau) * 512 + u.g * 16 + c0) = w; } }
	v_lshlrev_b32_e32 v100, 16, v110
	v_fma_f32 v86, v66, v100, v86
	v_mul_f32_e32 v101, 0x3d372713, v86
	v_mul_f32_e32 v101, v86, v101
	v_and_b32_e32 v100, 0xffff0000, v110
	v_fma_f32 v101, v86, v101, v86
	v_fma_f32 v87, v67, v100, v87
	v_lshlrev_b32_e32 v100, 16, v111
	v_mul_f32_e32 v101, 0x3fcc422a, v101
	v_fma_f32 v88, v68, v100, v88
	v_and_b32_e32 v100, 0xffff0000, v111
	v_mul_f32_e32 v101, 0xbfb8aa3b, v101
	v_fmac_f32_e32 v89, v69, v100
	v_lshlrev_b32_e32 v100, 16, v112
	v_exp_f32_e32 v101, v101
	v_fma_f32 v82, v62, v100, v82
	v_and_b32_e32 v100, 0xffff0000, v112
	v_fma_f32 v83, v63, v100, v83
	v_lshlrev_b32_e32 v100, 16, v113
	v_fma_f32 v84, v64, v100, v84
	v_and_b32_e32 v100, 0xffff0000, v113
	v_lshl_add_u64 v[94:95], v[102:103], 0, v[132:133]
	v_fmac_f32_e32 v85, v65, v100
	v_add_f32_e32 v100, 1.0, v101
	v_mul_f32_e32 v101, 0x3d372713, v87
	v_mul_f32_e32 v102, 0x3d372713, v88
	v_lshl_add_u64 v[94:95], v[94:95], 0, s[4:5]
	v_mul_f32_e32 v101, v87, v101
	v_mul_f32_e32 v102, v88, v102
	v_lshl_add_u64 v[94:95], v[94:95], 0, v[154:155]
	v_fma_f32 v101, v87, v101, v87
	v_fma_f32 v102, v88, v102, v88
	global_store_dwordx4 v[94:95], v[90:93], off
	v_add_co_u32_e32 v94, vcc, s64, v164
	v_mul_f32_e32 v101, 0x3fcc422a, v101
	v_mul_f32_e32 v102, 0x3fcc422a, v102
	v_lshl_add_u64 v[90:91], v[164:165], 0, s[10:11]
	v_addc_co_u32_e32 v95, vcc, 0, v165, vcc
	v_mul_f32_e32 v101, 0xbfb8aa3b, v101
	v_mul_f32_e32 v102, 0xbfb8aa3b, v102
	global_load_dwordx4 v[90:93], v[90:91], off offset:256
	s_nop 0
	global_load_dwordx4 v[94:97], v[94:95], off
	v_exp_f32_e32 v101, v101
	v_exp_f32_e32 v102, v102
	v_mul_f32_e32 v103, 0x3d372713, v89
	v_mul_f32_e32 v103, v89, v103
	v_add_f32_e32 v101, 1.0, v101
	v_add_f32_e32 v102, 1.0, v102
	v_rcp_f32_e32 v101, v101
	v_rcp_f32_e32 v102, v102
	v_fma_f32 v103, v89, v103, v89
	v_mul_f32_e32 v103, 0x3fcc422a, v103
	v_mul_f32_e32 v103, 0xbfb8aa3b, v103
	v_rcp_f32_e32 v100, v100
	v_exp_f32_e32 v103, v103
	v_mul_f32_e32 v87, v87, v101
	v_mul_f32_e32 v88, v88, v102
	v_mul_f32_e32 v101, 0x3d372713, v82
	v_mul_f32_e32 v102, 0x3d372713, v83
	v_mul_f32_e32 v101, v82, v101
	v_mul_f32_e32 v102, v83, v102
	v_fma_f32 v101, v82, v101, v82
	v_fma_f32 v102, v83, v102, v83
	v_mul_f32_e32 v101, 0x3fcc422a, v101
	v_mul_f32_e32 v102, 0x3fcc422a, v102
	v_mul_f32_e32 v86, v86, v100
	v_add_f32_e32 v100, 1.0, v103
	v_mul_f32_e32 v101, 0xbfb8aa3b, v101
	v_mul_f32_e32 v102, 0xbfb8aa3b, v102
	v_rcp_f32_e32 v100, v100
	v_exp_f32_e32 v101, v101
	v_exp_f32_e32 v102, v102
	v_mul_f32_e32 v103, 0x3d372713, v85
	v_mul_f32_e32 v89, v89, v100
	v_add_f32_e32 v100, 1.0, v101
	v_add_f32_e32 v101, 1.0, v102
	v_mul_f32_e32 v102, 0x3d372713, v84
	v_mul_f32_e32 v103, v85, v103
	v_mul_f32_e32 v102, v84, v102
	v_fma_f32 v103, v85, v103, v85
	v_fma_f32 v102, v84, v102, v84
	v_mul_f32_e32 v103, 0x3fcc422a, v103
	v_mul_f32_e32 v102, 0x3fcc422a, v102
	v_mul_f32_e32 v103, 0xbfb8aa3b, v103
	v_mul_f32_e32 v102, 0xbfb8aa3b, v102
	v_exp_f32_e32 v103, v103
	v_exp_f32_e32 v102, v102
	v_rcp_f32_e32 v100, v100
	v_or_b32_e32 v98, 48, v162
	v_rcp_f32_e32 v101, v101
	v_ashrrev_i32_e32 v99, 31, v98
	v_add_f32_e32 v103, 1.0, v103
	v_lshlrev_b64 v[98:99], 15, v[98:99]
	v_add_f32_e32 v102, 1.0, v102
	v_rcp_f32_e32 v103, v103
	v_rcp_f32_e32 v102, v102
	v_mul_f32_e32 v100, v82, v100
	v_cvt_pk_bf16_f32 v82, v86, v87
	v_lshl_add_u64 v[86:87], s[14:15], 0, v[98:99]
	v_mul_f32_e32 v101, v83, v101
	v_cvt_pk_bf16_f32 v83, v88, v89
	v_lshl_add_u64 v[88:89], v[86:87], 0, v[130:131]
	v_lshl_add_u64 v[88:89], v[88:89], 0, s[4:5]
	v_mul_f32_e32 v85, v85, v103
	v_lshl_add_u64 v[88:89], v[88:89], 0, v[154:155]
	v_mul_f32_e32 v102, v84, v102
	v_cvt_pk_bf16_f32 v84, v100, v101
	v_cvt_pk_bf16_f32 v85, v102, v85
	global_store_dwordx4 v[88:89], v[82:85], off
	s_nop 1
	v_lshlrev_b32_e32 v82, 16, v106
	v_fma_f32 v78, v66, v82, v78
	v_mul_f32_e32 v83, 0x3d372713, v78
	v_mul_f32_e32 v83, v78, v83
	v_and_b32_e32 v82, 0xffff0000, v106
	v_fma_f32 v83, v78, v83, v78
	v_fma_f32 v79, v67, v82, v79
	v_lshlrev_b32_e32 v82, 16, v107
	v_mul_f32_e32 v83, 0x3fcc422a, v83
	v_fma_f32 v80, v68, v82, v80
	v_and_b32_e32 v82, 0xffff0000, v107
	v_mul_f32_e32 v83, 0xbfb8aa3b, v83
	v_fmac_f32_e32 v81, v69, v82
	v_lshlrev_b32_e32 v82, 16, v108
	v_exp_f32_e32 v83, v83
	v_fma_f32 v74, v62, v82, v74
	v_and_b32_e32 v82, 0xffff0000, v108
	v_fma_f32 v75, v63, v82, v75
	v_lshlrev_b32_e32 v82, 16, v109
	v_fma_f32 v76, v64, v82, v76
	v_and_b32_e32 v82, 0xffff0000, v109
	v_fmac_f32_e32 v77, v65, v82
	v_add_f32_e32 v82, 1.0, v83
	v_mul_f32_e32 v83, 0x3d372713, v79
	v_mul_f32_e32 v84, 0x3d372713, v80
	v_mul_f32_e32 v83, v79, v83
	v_mul_f32_e32 v84, v80, v84
	v_fma_f32 v83, v79, v83, v79
	v_fma_f32 v84, v80, v84, v80
	v_mul_f32_e32 v83, 0x3fcc422a, v83
	v_mul_f32_e32 v84, 0x3fcc422a, v84
	v_mul_f32_e32 v83, 0xbfb8aa3b, v83
	v_mul_f32_e32 v84, 0xbfb8aa3b, v84
	v_exp_f32_e32 v83, v83
	v_exp_f32_e32 v84, v84
	v_mul_f32_e32 v85, 0x3d372713, v81
	v_mul_f32_e32 v85, v81, v85
	v_add_f32_e32 v83, 1.0, v83
	v_add_f32_e32 v84, 1.0, v84
	v_rcp_f32_e32 v83, v83
	v_rcp_f32_e32 v84, v84
	v_fma_f32 v85, v81, v85, v81
	v_mul_f32_e32 v85, 0x3fcc422a, v85
	v_mul_f32_e32 v85, 0xbfb8aa3b, v85
	v_rcp_f32_e32 v82, v82
	v_exp_f32_e32 v85, v85
	v_mul_f32_e32 v79, v79, v83
	v_mul_f32_e32 v80, v80, v84
	v_mul_f32_e32 v83, 0x3d372713, v74
	v_mul_f32_e32 v84, 0x3d372713, v75
	v_mul_f32_e32 v83, v74, v83
	v_mul_f32_e32 v84, v75, v84
	v_fma_f32 v83, v74, v83, v74
	v_fma_f32 v84, v75, v84, v75
	v_mul_f32_e32 v83, 0x3fcc422a, v83
	v_mul_f32_e32 v84, 0x3fcc422a, v84
	v_mul_f32_e32 v78, v78, v82
	v_add_f32_e32 v82, 1.0, v85
	v_mul_f32_e32 v83, 0xbfb8aa3b, v83
	v_mul_f32_e32 v84, 0xbfb8aa3b, v84
	v_rcp_f32_e32 v82, v82
	v_exp_f32_e32 v83, v83
	v_exp_f32_e32 v84, v84
	v_mul_f32_e32 v85, 0x3d372713, v77
	v_mul_f32_e32 v81, v81, v82
	v_add_f32_e32 v82, 1.0, v83
	v_add_f32_e32 v83, 1.0, v84
	v_mul_f32_e32 v84, 0x3d372713, v76
	v_mul_f32_e32 v84, v76, v84
	v_fma_f32 v84, v76, v84, v76
	v_mul_f32_e32 v84, 0x3fcc422a, v84
	v_mul_f32_e32 v84, 0xbfb8aa3b, v84
	v_exp_f32_e32 v84, v84
	v_rcp_f32_e32 v82, v82
	v_rcp_f32_e32 v83, v83
	v_mul_f32_e32 v85, v77, v85
	v_add_f32_e32 v84, 1.0, v84
	v_rcp_f32_e32 v84, v84
	v_fma_f32 v85, v77, v85, v77
	v_mul_f32_e32 v85, 0x3fcc422a, v85
	v_mul_f32_e32 v82, v74, v82
	v_mul_f32_e32 v85, 0xbfb8aa3b, v85
	v_mul_f32_e32 v83, v75, v83
	v_mul_f32_e32 v84, v76, v84
	v_cvt_pk_bf16_f32 v74, v78, v79
	v_cvt_pk_bf16_f32 v75, v80, v81
	v_cvt_pk_bf16_f32 v76, v82, v83
	s_waitcnt vmcnt(1)
; __device__ __forceinline__ unsigned cvt_pk_bf16(float lo, float hi) { unsigned r; asm volatile("v_cvt_pk_bf16_f32 %0, %1, %2" : "=v"(r) : "v"(lo), "v"(hi)); return r; }
; __device__ __forceinline__ float bflo(unsigned w) { return __uint_as_float(w << 16); }
; __device__ __forceinline__ float bfhi(unsigned w) { return __uint_as_float(w & 0xffff0000u); }
; __device__ __forceinline__ float gelu_tanh(float v) { const float z = 1.5957691216057308f * (v + 0.044715f * v * v * v); return v * sigm(z); }
;     __device__ __forceinline__ void operator()(const pg8::f32x4 (&acc)[2][2][4][2], const Unit& u, int wr, int wc, int fr, int fq) const {
;     ...
;         for (int k = 0; k < 8; ++k) { const int ai = k >> 2, m = k & 3; const int row = row0 + ai * HALF + m * 16; v4u cu[2];
; #pragma unroll
;             for (int bj = 0; bj < 2; ++bj) cu[bj] = nu[bj];
;             if (k < 7) {
; #pragma unroll
;                 for (int bj = 0; bj < 2; ++bj) nu[bj] = *(const v4u*)(UX + ((size_t)u.g * 1024 + row0 + ((k + 1) >> 2) * HALF + ((k + 1) & 3) * 16) * 640 + ((colb + bj * HALF) >> 4) * 16 + c0); }
; #pragma unroll
;             for (int bj = 0; bj < 2; ++bj) { const int tau = (colb + bj * HALF) >> 4;
;                 const v4u uw = cu[bj]; const f32x4 a0 = acc[ai][bj][m][0], a1 = acc[ai][bj][m][1];
;                 float r[8]; r[0] = a0[0] + d0[0] * bflo(uw.x); r[1] = a0[1] + d0[1] * bfhi(uw.x); r[2] = a0[2] + d0[2] * bflo(uw.y); r[3] = a0[3] + d0[3] * bfhi(uw.y);
;                 r[4] = a1[0] + d1[0] * bflo(uw.z); r[5] = a1[1] + d1[1] * bfhi(uw.z); r[6] = a1[2] + d1[2] * bflo(uw.w); r[7] = a1[3] + d1[3] * bfhi(uw.w);
; #pragma unroll
;                 for (int e = 0; e < 8; ++e) r[e] = gelu_tanh(r[e]);
;                 v4u w; w.x = cvt_pk_bf16(r[0], r[1]); w.y = cvt_pk_bf16(r[2], r[3]); w.z = cvt_pk_bf16(r[4], r[5]); w.w = cvt_pk_bf16(r[6], r[7]);
;                 *(v4u*)(Y + ((size_t)row * 32 + tau) * 512 + u.g * 16 + c0) = w; } }
	v_lshlrev_b32_e32 v82, 16, v94
	v_exp_f32_e32 v85, v85
	v_fma_f32 v70, v66, v82, v70
	v_mul_f32_e32 v83, 0x3d372713, v70
	v_mul_f32_e32 v83, v70, v83
	v_and_b32_e32 v82, 0xffff0000, v94
	v_fma_f32 v83, v70, v83, v70
	v_add_f32_e32 v85, 1.0, v85
	v_fma_f32 v71, v67, v82, v71
	v_lshlrev_b32_e32 v82, 16, v95
	v_mul_f32_e32 v83, 0x3fcc422a, v83
	v_rcp_f32_e32 v85, v85
	v_fma_f32 v72, v68, v82, v72
	v_and_b32_e32 v82, 0xffff0000, v95
	v_mul_f32_e32 v83, 0xbfb8aa3b, v83
	v_fmac_f32_e32 v73, v69, v82
	v_lshlrev_b32_e32 v82, 16, v96
	v_exp_f32_e32 v83, v83
	v_fma_f32 v58, v62, v82, v58
	v_and_b32_e32 v82, 0xffff0000, v96
	v_fma_f32 v59, v63, v82, v59
	v_lshlrev_b32_e32 v82, 16, v97
	v_mul_f32_e32 v77, v77, v85
	v_fma_f32 v60, v64, v82, v60
	v_and_b32_e32 v82, 0xffff0000, v97
	v_cvt_pk_bf16_f32 v77, v84, v77
	v_fmac_f32_e32 v61, v65, v82
	v_add_f32_e32 v82, 1.0, v83
	v_mul_f32_e32 v83, 0x3d372713, v71
	v_mul_f32_e32 v84, 0x3d372713, v72
	v_lshl_add_u64 v[78:79], v[86:87], 0, v[132:133]
	v_mul_f32_e32 v83, v71, v83
	v_mul_f32_e32 v84, v72, v84
	v_lshl_add_u64 v[78:79], v[78:79], 0, s[4:5]
	v_fma_f32 v83, v71, v83, v71
	v_fma_f32 v84, v72, v84, v72
	v_lshl_add_u64 v[78:79], v[78:79], 0, v[154:155]
	v_mul_f32_e32 v83, 0x3fcc422a, v83
	v_mul_f32_e32 v84, 0x3fcc422a, v84
	global_store_dwordx4 v[78:79], v[74:77], off
	v_add_co_u32_e32 v78, vcc, s65, v164
	v_mul_f32_e32 v83, 0xbfb8aa3b, v83
	v_mul_f32_e32 v84, 0xbfb8aa3b, v84
	v_lshl_add_u64 v[74:75], v[164:165], 0, s[26:27]
	v_addc_co_u32_e32 v79, vcc, 0, v165, vcc
	v_exp_f32_e32 v83, v83
	v_exp_f32_e32 v84, v84
	global_load_dwordx4 v[74:77], v[74:75], off offset:256
	s_nop 0
	global_load_dwordx4 v[78:81], v[78:79], off
	v_mul_f32_e32 v85, 0x3d372713, v73
	v_add_f32_e32 v83, 1.0, v83
	v_add_f32_e32 v84, 1.0, v84
	v_rcp_f32_e32 v83, v83
	v_rcp_f32_e32 v84, v84
	v_mul_f32_e32 v85, v73, v85
	v_fma_f32 v85, v73, v85, v73
	v_mul_f32_e32 v85, 0x3fcc422a, v85
	v_mul_f32_e32 v85, 0xbfb8aa3b, v85
	v_rcp_f32_e32 v82, v82
	v_exp_f32_e32 v85, v85
	v_mul_f32_e32 v71, v71, v83
	v_mul_f32_e32 v72, v72, v84
	v_mul_f32_e32 v83, 0x3d372713, v58
	v_mul_f32_e32 v84, 0x3d372713, v59
	v_mul_f32_e32 v83, v58, v83
	v_mul_f32_e32 v84, v59, v84
	v_fma_f32 v83, v58, v83, v58
	v_fma_f32 v84, v59, v84, v59
	v_mul_f32_e32 v83, 0x3fcc422a, v83
	v_mul_f32_e32 v84, 0x3fcc422a, v84
	v_mul_f32_e32 v70, v70, v82
	v_add_f32_e32 v82, 1.0, v85
	v_mul_f32_e32 v83, 0xbfb8aa3b, v83
	v_mul_f32_e32 v84, 0xbfb8aa3b, v84
	v_rcp_f32_e32 v82, v82
	v_exp_f32_e32 v83, v83
	v_exp_f32_e32 v84, v84
	v_mul_f32_e32 v85, 0x3d372713, v61
	v_mul_f32_e32 v73, v73, v82
	v_add_f32_e32 v82, 1.0, v83
	v_add_f32_e32 v83, 1.0, v84
	v_mul_f32_e32 v84, 0x3d372713, v60
	v_mul_f32_e32 v85, v61, v85
	v_mul_f32_e32 v84, v60, v84
	v_fma_f32 v85, v61, v85, v61
	v_fma_f32 v84, v60, v84, v60
	v_mul_f32_e32 v85, 0x3fcc422a, v85
	v_mul_f32_e32 v84, 0x3fcc422a, v84
	v_mul_f32_e32 v85, 0xbfb8aa3b, v85
	v_mul_f32_e32 v84, 0xbfb8aa3b, v84
	v_exp_f32_e32 v85, v85
	v_exp_f32_e32 v84, v84
	v_rcp_f32_e32 v82, v82
	v_rcp_f32_e32 v83, v83
	v_add_f32_e32 v85, 1.0, v85
	v_add_f32_e32 v84, 1.0, v84
	v_rcp_f32_e32 v85, v85
	v_rcp_f32_e32 v84, v84
	v_mul_f32_e32 v82, v58, v82
	v_cvt_pk_bf16_f32 v58, v70, v71
	v_lshl_add_u64 v[70:71], v[134:135], 0, s[28:29]
	v_mul_f32_e32 v83, v59, v83
	v_cvt_pk_bf16_f32 v59, v72, v73
	v_lshl_add_u64 v[72:73], v[70:71], 0, v[130:131]
	v_lshl_add_u64 v[72:73], v[72:73], 0, s[4:5]
	v_mul_f32_e32 v61, v61, v85
	v_lshl_add_u64 v[72:73], v[72:73], 0, v[154:155]
	v_mul_f32_e32 v84, v60, v84
	v_cvt_pk_bf16_f32 v60, v82, v83
	v_cvt_pk_bf16_f32 v61, v84, v61
	global_store_dwordx4 v[72:73], v[58:61], off
	s_nop 1
	v_lshlrev_b32_e32 v58, 16, v90
	v_fma_f32 v54, v66, v58, v54
	v_mul_f32_e32 v59, 0x3d372713, v54
	v_mul_f32_e32 v59, v54, v59
	v_and_b32_e32 v58, 0xffff0000, v90
	v_fma_f32 v59, v54, v59, v54
	v_fma_f32 v55, v67, v58, v55
	v_lshlrev_b32_e32 v58, 16, v91
	v_mul_f32_e32 v59, 0x3fcc422a, v59
	v_fma_f32 v56, v68, v58, v56
	v_and_b32_e32 v58, 0xffff0000, v91
	v_mul_f32_e32 v59, 0xbfb8aa3b, v59
	v_fmac_f32_e32 v57, v69, v58
	v_lshlrev_b32_e32 v58, 16, v92
	v_exp_f32_e32 v59, v59
	v_fma_f32 v50, v62, v58, v50
	v_and_b32_e32 v58, 0xffff0000, v92
	v_fma_f32 v51, v63, v58, v51
	v_lshlrev_b32_e32 v58, 16, v93
	v_fma_f32 v52, v64, v58, v52
	v_and_b32_e32 v58, 0xffff0000, v93
	v_fmac_f32_e32 v53, v65, v58
	v_add_f32_e32 v58, 1.0, v59
	v_mul_f32_e32 v59, 0x3d372713, v55
	v_mul_f32_e32 v60, 0x3d372713, v56
	v_mul_f32_e32 v59, v55, v59
	v_mul_f32_e32 v60, v56, v60
	v_fma_f32 v59, v55, v59, v55
	v_fma_f32 v60, v56, v60, v56
	v_mul_f32_e32 v59, 0x3fcc422a, v59
	v_mul_f32_e32 v60, 0x3fcc422a, v60
	v_mul_f32_e32 v59, 0xbfb8aa3b, v59
	v_mul_f32_e32 v60, 0xbfb8aa3b, v60
	v_exp_f32_e32 v59, v59
	v_exp_f32_e32 v60, v60
	v_mul_f32_e32 v61, 0x3d372713, v57
	v_mul_f32_e32 v61, v57, v61
	v_add_f32_e32 v59, 1.0, v59
	v_add_f32_e32 v60, 1.0, v60
	v_rcp_f32_e32 v59, v59
	v_rcp_f32_e32 v60, v60
	v_fma_f32 v61, v57, v61, v57
	v_mul_f32_e32 v61, 0x3fcc422a, v61
	v_mul_f32_e32 v61, 0xbfb8aa3b, v61
	v_rcp_f32_e32 v58, v58
	v_exp_f32_e32 v61, v61
	v_mul_f32_e32 v55, v55, v59
	v_mul_f32_e32 v56, v56, v60
	v_mul_f32_e32 v59, 0x3d372713, v50
	v_mul_f32_e32 v60, 0x3d372713, v51
	v_mul_f32_e32 v59, v50, v59
	v_mul_f32_e32 v60, v51, v60
	v_fma_f32 v59, v50, v59, v50
	v_fma_f32 v60, v51, v60, v51
	v_mul_f32_e32 v59, 0x3fcc422a, v59
	v_mul_f32_e32 v60, 0x3fcc422a, v60
	v_mul_f32_e32 v54, v54, v58
	v_add_f32_e32 v58, 1.0, v61
	v_mul_f32_e32 v59, 0xbfb8aa3b, v59
	v_mul_f32_e32 v60, 0xbfb8aa3b, v60
	v_rcp_f32_e32 v58, v58
	v_exp_f32_e32 v59, v59
	v_exp_f32_e32 v60, v60
	v_mul_f32_e32 v61, 0x3d372713, v53
	v_mul_f32_e32 v57, v57, v58
	v_add_f32_e32 v58, 1.0, v59
	v_add_f32_e32 v59, 1.0, v60
	v_mul_f32_e32 v60, 0x3d372713, v52
	v_mul_f32_e32 v60, v52, v60
	v_mul_f32_e32 v61, v53, v61
	v_fma_f32 v60, v52, v60, v52
	v_fma_f32 v61, v53, v61, v53
	v_mul_f32_e32 v60, 0x3fcc422a, v60
	v_mul_f32_e32 v61, 0x3fcc422a, v61
	v_mul_f32_e32 v60, 0xbfb8aa3b, v60
	v_mul_f32_e32 v61, 0xbfb8aa3b, v61
	v_exp_f32_e32 v60, v60
	v_exp_f32_e32 v61, v61
	v_rcp_f32_e32 v58, v58
	v_rcp_f32_e32 v59, v59
	v_add_f32_e32 v60, 1.0, v60
	v_add_f32_e32 v61, 1.0, v61
	v_rcp_f32_e32 v60, v60
	v_rcp_f32_e32 v61, v61
	v_mul_f32_e32 v58, v50, v58
	v_mul_f32_e32 v59, v51, v59
	v_mul_f32_e32 v60, v52, v60
	v_mul_f32_e32 v53, v53, v61
	v_cvt_pk_bf16_f32 v50, v54, v55
	v_cvt_pk_bf16_f32 v51, v56, v57
	v_cvt_pk_bf16_f32 v52, v58, v59
	v_cvt_pk_bf16_f32 v53, v60, v53
	s_waitcnt vmcnt(1)
; __device__ __forceinline__ unsigned cvt_pk_bf16(float lo, float hi) { unsigned r; asm volatile("v_cvt_pk_bf16_f32 %0, %1, %2" : "=v"(r) : "v"(lo), "v"(hi)); return r; }
; __device__ __forceinline__ float bflo(unsigned w) { return __uint_as_float(w << 16); }
; __device__ __forceinline__ float bfhi(unsigned w) { return __uint_as_float(w & 0xffff0000u); }
; __device__ __forceinline__ float gelu_tanh(float v) { const float z = 1.5957691216057308f * (v + 0.044715f * v * v * v); return v * sigm(z); }
;     __device__ __forceinline__ void operator()(const pg8::f32x4 (&acc)[2][2][4][2], const Unit& u, int wr, int wc, int fr, int fq) const {
;     ...
;         for (int k = 0; k < 8; ++k) { const int ai = k >> 2, m = k & 3; const int row = row0 + ai * HALF + m * 16; v4u cu[2];
; #pragma unroll
;             for (int bj = 0; bj < 2; ++bj) cu[bj] = nu[bj];
;             if (k < 7) {
; #pragma unroll
;                 for (int bj = 0; bj < 2; ++bj) nu[bj] = *(const v4u*)(UX + ((size_t)u.g * 1024 + row0 + ((k + 1) >> 2) * HALF + ((k + 1) & 3) * 16) * 640 + ((colb + bj * HALF) >> 4) * 16 + c0); }
; #pragma unroll
;             for (int bj = 0; bj < 2; ++bj) { const int tau = (colb + bj * HALF) >> 4;
;                 const v4u uw = cu[bj]; const f32x4 a0 = acc[ai][bj][m][0], a1 = acc[ai][bj][m][1];
;                 float r[8]; r[0] = a0[0] + d0[0] * bflo(uw.x); r[1] = a0[1] + d0[1] * bfhi(uw.x); r[2] = a0[2] + d0[2] * bflo(uw.y); r[3] = a0[3] + d0[3] * bfhi(uw.y);
;                 r[4] = a1[0] + d1[0] * bflo(uw.z); r[5] = a1[1] + d1[1] * bfhi(uw.z); r[6] = a1[2] + d1[2] * bflo(uw.w); r[7] = a1[3] + d1[3] * bfhi(uw.w);
; #pragma unroll
;                 for (int e = 0; e < 8; ++e) r[e] = gelu_tanh(r[e]);
;                 v4u w; w.x = cvt_pk_bf16(r[0], r[1]); w.y = cvt_pk_bf16(r[2], r[3]); w.z = cvt_pk_bf16(r[4], r[5]); w.w = cvt_pk_bf16(r[6], r[7]);
;                 *(v4u*)(Y + ((size_t)row * 32 + tau) * 512 + u.g * 16 + c0) = w; } }
	v_lshlrev_b32_e32 v60, 16, v78
	v_fma_f32 v46, v66, v60, v46
	v_mul_f32_e32 v61, 0x3d372713, v46
	v_mul_f32_e32 v61, v46, v61
	v_and_b32_e32 v60, 0xffff0000, v78
	v_fma_f32 v61, v46, v61, v46
	v_fma_f32 v47, v67, v60, v47
	v_lshlrev_b32_e32 v60, 16, v79
	v_mul_f32_e32 v61, 0x3fcc422a, v61
	v_fma_f32 v48, v68, v60, v48
	v_and_b32_e32 v60, 0xffff0000, v79
	v_mul_f32_e32 v61, 0xbfb8aa3b, v61
	v_fmac_f32_e32 v49, v69, v60
	v_lshlrev_b32_e32 v60, 16, v80
	v_exp_f32_e32 v61, v61
	v_fma_f32 v42, v62, v60, v42
	v_and_b32_e32 v60, 0xffff0000, v80
	v_fma_f32 v43, v63, v60, v43
	v_lshlrev_b32_e32 v60, 16, v81
	v_fma_f32 v44, v64, v60, v44
	v_and_b32_e32 v60, 0xffff0000, v81
	v_lshl_add_u64 v[54:55], v[70:71], 0, v[132:133]
	v_fmac_f32_e32 v45, v65, v60
	v_add_f32_e32 v60, 1.0, v61
	v_mul_f32_e32 v61, 0x3d372713, v47
	v_mul_f32_e32 v70, 0x3d372713, v48
	v_mul_f32_e32 v61, v47, v61
	v_mul_f32_e32 v70, v48, v70
	v_lshl_add_u64 v[54:55], v[54:55], 0, s[4:5]
	v_fma_f32 v61, v47, v61, v47
	v_fma_f32 v70, v48, v70, v48
	v_lshl_add_u64 v[54:55], v[54:55], 0, v[154:155]
	v_mul_f32_e32 v61, 0x3fcc422a, v61
	v_mul_f32_e32 v70, 0x3fcc422a, v70
	global_store_dwordx4 v[54:55], v[50:53], off
	v_add_co_u32_e32 v54, vcc, s66, v164
	v_mul_f32_e32 v61, 0xbfb8aa3b, v61
	v_mul_f32_e32 v70, 0xbfb8aa3b, v70
	v_lshl_add_u64 v[50:51], v[164:165], 0, s[30:31]
	v_addc_co_u32_e32 v55, vcc, 0, v165, vcc
	v_exp_f32_e32 v61, v61
	v_exp_f32_e32 v70, v70
	global_load_dwordx4 v[50:53], v[50:51], off offset:256
	s_nop 0
	global_load_dwordx4 v[54:57], v[54:55], off
	v_mul_f32_e32 v71, 0x3d372713, v49
	v_add_f32_e32 v61, 1.0, v61
	v_add_f32_e32 v70, 1.0, v70
	v_rcp_f32_e32 v61, v61
	v_rcp_f32_e32 v70, v70
	v_mul_f32_e32 v71, v49, v71
	v_fma_f32 v71, v49, v71, v49
	v_mul_f32_e32 v71, 0x3fcc422a, v71
	v_mul_f32_e32 v71, 0xbfb8aa3b, v71
	v_rcp_f32_e32 v60, v60
	v_exp_f32_e32 v71, v71
	v_mul_f32_e32 v47, v47, v61
	v_mul_f32_e32 v48, v48, v70
	v_mul_f32_e32 v61, 0x3d372713, v42
	v_mul_f32_e32 v70, 0x3d372713, v43
	v_mul_f32_e32 v61, v42, v61
	v_mul_f32_e32 v70, v43, v70
	v_fma_f32 v61, v42, v61, v42
	v_fma_f32 v70, v43, v70, v43
	v_mul_f32_e32 v61, 0x3fcc422a, v61
	v_mul_f32_e32 v70, 0x3fcc422a, v70
	v_mul_f32_e32 v46, v46, v60
	v_add_f32_e32 v60, 1.0, v71
	v_mul_f32_e32 v61, 0xbfb8aa3b, v61
	v_mul_f32_e32 v70, 0xbfb8aa3b, v70
	v_rcp_f32_e32 v60, v60
	v_exp_f32_e32 v61, v61
	v_exp_f32_e32 v70, v70
	v_mul_f32_e32 v71, 0x3d372713, v45
	v_mul_f32_e32 v49, v49, v60
	v_add_f32_e32 v60, 1.0, v61
	v_add_f32_e32 v61, 1.0, v70
	v_mul_f32_e32 v70, 0x3d372713, v44
	v_mul_f32_e32 v71, v45, v71
	v_mul_f32_e32 v70, v44, v70
	v_fma_f32 v71, v45, v71, v45
	v_fma_f32 v70, v44, v70, v44
	v_mul_f32_e32 v71, 0x3fcc422a, v71
	v_mul_f32_e32 v70, 0x3fcc422a, v70
	v_mul_f32_e32 v71, 0xbfb8aa3b, v71
	v_mul_f32_e32 v70, 0xbfb8aa3b, v70
	v_exp_f32_e32 v71, v71
	v_exp_f32_e32 v70, v70
	v_rcp_f32_e32 v60, v60
	v_add_u32_e32 v58, 0x90, v162
	v_rcp_f32_e32 v61, v61
	v_ashrrev_i32_e32 v59, 31, v58
	v_add_f32_e32 v71, 1.0, v71
	v_lshlrev_b64 v[58:59], 15, v[58:59]
	v_add_f32_e32 v70, 1.0, v70
	v_rcp_f32_e32 v71, v71
	v_rcp_f32_e32 v70, v70
	v_mul_f32_e32 v60, v42, v60
	v_cvt_pk_bf16_f32 v42, v46, v47
	v_lshl_add_u64 v[46:47], s[14:15], 0, v[58:59]
	v_mul_f32_e32 v61, v43, v61
	v_cvt_pk_bf16_f32 v43, v48, v49
	v_lshl_add_u64 v[48:49], v[46:47], 0, v[130:131]
	v_lshl_add_u64 v[48:49], v[48:49], 0, s[4:5]
	v_mul_f32_e32 v45, v45, v71
	v_lshl_add_u64 v[48:49], v[48:49], 0, v[154:155]
	v_mul_f32_e32 v70, v44, v70
	v_cvt_pk_bf16_f32 v44, v60, v61
	v_cvt_pk_bf16_f32 v45, v70, v45
	global_store_dwordx4 v[48:49], v[42:45], off
	s_nop 1
	v_lshlrev_b32_e32 v42, 16, v74
	v_fma_f32 v38, v66, v42, v38
	v_mul_f32_e32 v43, 0x3d372713, v38
	v_mul_f32_e32 v43, v38, v43
	v_and_b32_e32 v42, 0xffff0000, v74
	v_fma_f32 v43, v38, v43, v38
	v_fma_f32 v39, v67, v42, v39
	v_lshlrev_b32_e32 v42, 16, v75
	v_mul_f32_e32 v43, 0x3fcc422a, v43
	v_fma_f32 v40, v68, v42, v40
	v_and_b32_e32 v42, 0xffff0000, v75
	v_mul_f32_e32 v43, 0xbfb8aa3b, v43
	v_fmac_f32_e32 v41, v69, v42
	v_lshlrev_b32_e32 v42, 16, v76
	v_exp_f32_e32 v43, v43
	v_fma_f32 v34, v62, v42, v34
	v_and_b32_e32 v42, 0xffff0000, v76
	v_fma_f32 v35, v63, v42, v35
	v_lshlrev_b32_e32 v42, 16, v77
	v_fma_f32 v36, v64, v42, v36
	v_and_b32_e32 v42, 0xffff0000, v77
	v_fmac_f32_e32 v37, v65, v42
	v_add_f32_e32 v42, 1.0, v43
	v_mul_f32_e32 v43, 0x3d372713, v39
	v_mul_f32_e32 v44, 0x3d372713, v40
	v_mul_f32_e32 v43, v39, v43
	v_mul_f32_e32 v44, v40, v44
	v_fma_f32 v43, v39, v43, v39
	v_fma_f32 v44, v40, v44, v40
	v_mul_f32_e32 v43, 0x3fcc422a, v43
	v_mul_f32_e32 v44, 0x3fcc422a, v44
	v_mul_f32_e32 v43, 0xbfb8aa3b, v43
	v_mul_f32_e32 v44, 0xbfb8aa3b, v44
	v_exp_f32_e32 v43, v43
	v_exp_f32_e32 v44, v44
	v_mul_f32_e32 v45, 0x3d372713, v41
	v_mul_f32_e32 v45, v41, v45
	v_add_f32_e32 v43, 1.0, v43
	v_add_f32_e32 v44, 1.0, v44
	v_rcp_f32_e32 v43, v43
	v_rcp_f32_e32 v44, v44
	v_fma_f32 v45, v41, v45, v41
	v_mul_f32_e32 v45, 0x3fcc422a, v45
	v_mul_f32_e32 v45, 0xbfb8aa3b, v45
	v_rcp_f32_e32 v42, v42
	v_exp_f32_e32 v45, v45
	v_mul_f32_e32 v39, v39, v43
	v_mul_f32_e32 v40, v40, v44
	v_mul_f32_e32 v43, 0x3d372713, v34
	v_mul_f32_e32 v44, 0x3d372713, v35
	v_mul_f32_e32 v43, v34, v43
	v_mul_f32_e32 v44, v35, v44
	v_fma_f32 v43, v34, v43, v34
	v_fma_f32 v44, v35, v44, v35
	v_mul_f32_e32 v43, 0x3fcc422a, v43
	v_mul_f32_e32 v44, 0x3fcc422a, v44
	v_mul_f32_e32 v38, v38, v42
	v_add_f32_e32 v42, 1.0, v45
	v_mul_f32_e32 v43, 0xbfb8aa3b, v43
	v_mul_f32_e32 v44, 0xbfb8aa3b, v44
	v_rcp_f32_e32 v42, v42
	v_exp_f32_e32 v43, v43
	v_exp_f32_e32 v44, v44
	v_mul_f32_e32 v45, 0x3d372713, v37
	v_mul_f32_e32 v41, v41, v42
	v_add_f32_e32 v42, 1.0, v43
	v_add_f32_e32 v43, 1.0, v44
	v_mul_f32_e32 v44, 0x3d372713, v36
	v_mul_f32_e32 v44, v36, v44
	v_mul_f32_e32 v45, v37, v45
	v_fma_f32 v44, v36, v44, v36
	v_fma_f32 v45, v37, v45, v37
	v_mul_f32_e32 v44, 0x3fcc422a, v44
	v_mul_f32_e32 v45, 0x3fcc422a, v45
	v_mul_f32_e32 v44, 0xbfb8aa3b, v44
	v_mul_f32_e32 v45, 0xbfb8aa3b, v45
	v_exp_f32_e32 v44, v44
	v_exp_f32_e32 v45, v45
	v_rcp_f32_e32 v42, v42
	v_rcp_f32_e32 v43, v43
	v_add_f32_e32 v44, 1.0, v44
	v_add_f32_e32 v45, 1.0, v45
	v_rcp_f32_e32 v44, v44
	v_rcp_f32_e32 v45, v45
	v_mul_f32_e32 v42, v34, v42
	v_mul_f32_e32 v43, v35, v43
	v_mul_f32_e32 v44, v36, v44
	v_mul_f32_e32 v37, v37, v45
	v_cvt_pk_bf16_f32 v34, v38, v39
	v_cvt_pk_bf16_f32 v35, v40, v41
	v_cvt_pk_bf16_f32 v36, v42, v43
	v_cvt_pk_bf16_f32 v37, v44, v37
	s_waitcnt vmcnt(1)
; __device__ __forceinline__ unsigned cvt_pk_bf16(float lo, float hi) { unsigned r; asm volatile("v_cvt_pk_bf16_f32 %0, %1, %2" : "=v"(r) : "v"(lo), "v"(hi)); return r; }
; __device__ __forceinline__ float bflo(unsigned w) { return __uint_as_float(w << 16); }
; __device__ __forceinline__ float bfhi(unsigned w) { return __uint_as_float(w & 0xffff0000u); }
; __device__ __forceinline__ float gelu_tanh(float v) { const float z = 1.5957691216057308f * (v + 0.044715f * v * v * v); return v * sigm(z); }
; template <class Epi, class Sched, bool ALIGN_EPI = false, bool SP2 = false>
; __device__ __forceinline__ void gemm_phase(PG8_LAS unsigned char* lds, const Gemm g, const Sched& S, const Epi& E) {
;     ...
;         if (!has_next) break;
;     __device__ __forceinline__ void operator()(const pg8::f32x4 (&acc)[2][2][4][2], const Unit& u, int wr, int wc, int fr, int fq) const {
;     ...
;         for (int k = 0; k < 8; ++k) { const int ai = k >> 2, m = k & 3; const int row = row0 + ai * HALF + m * 16; v4u cu[2];
; #pragma unroll
;             for (int bj = 0; bj < 2; ++bj) cu[bj] = nu[bj];
;             if (k < 7) {
; #pragma unroll
;                 for (int bj = 0; bj < 2; ++bj) nu[bj] = *(const v4u*)(UX + ((size_t)u.g * 1024 + row0 + ((k + 1) >> 2) * HALF + ((k + 1) & 3) * 16) * 640 + ((colb + bj * HALF) >> 4) * 16 + c0); }
; #pragma unroll
;             for (int bj = 0; bj < 2; ++bj) { const int tau = (colb + bj * HALF) >> 4;
;                 const v4u uw = cu[bj]; const f32x4 a0 = acc[ai][bj][m][0], a1 = acc[ai][bj][m][1];
;                 float r[8]; r[0] = a0[0] + d0[0] * bflo(uw.x); r[1] = a0[1] + d0[1] * bfhi(uw.x); r[2] = a0[2] + d0[2] * bflo(uw.y); r[3] = a0[3] + d0[3] * bfhi(uw.y);
;                 r[4] = a1[0] + d1[0] * bflo(uw.z); r[5] = a1[1] + d1[1] * bfhi(uw.z); r[6] = a1[2] + d1[2] * bflo(uw.w); r[7] = a1[3] + d1[3] * bfhi(uw.w);
; #pragma unroll
;                 for (int e = 0; e < 8; ++e) r[e] = gelu_tanh(r[e]);
;                 v4u w; w.x = cvt_pk_bf16(r[0], r[1]); w.y = cvt_pk_bf16(r[2], r[3]); w.z = cvt_pk_bf16(r[4], r[5]); w.w = cvt_pk_bf16(r[6], r[7]);
;                 *(v4u*)(Y + ((size_t)row * 32 + tau) * 512 + u.g * 16 + c0) = w; } }
	v_lshlrev_b32_e32 v44, 16, v54
	v_fma_f32 v30, v66, v44, v30
	v_mul_f32_e32 v45, 0x3d372713, v30
	v_mul_f32_e32 v45, v30, v45
	v_and_b32_e32 v44, 0xffff0000, v54
	v_fma_f32 v45, v30, v45, v30
	v_fma_f32 v31, v67, v44, v31
	v_lshlrev_b32_e32 v44, 16, v55
	v_mul_f32_e32 v45, 0x3fcc422a, v45
	v_fma_f32 v32, v68, v44, v32
	v_and_b32_e32 v44, 0xffff0000, v55
	v_mul_f32_e32 v45, 0xbfb8aa3b, v45
	v_fmac_f32_e32 v33, v69, v44
	v_lshlrev_b32_e32 v44, 16, v56
	v_exp_f32_e32 v45, v45
	v_fma_f32 v26, v62, v44, v26
	v_and_b32_e32 v44, 0xffff0000, v56
	v_fma_f32 v27, v63, v44, v27
	v_lshlrev_b32_e32 v44, 16, v57
	v_fma_f32 v28, v64, v44, v28
	v_and_b32_e32 v44, 0xffff0000, v57
	v_lshl_add_u64 v[38:39], v[46:47], 0, v[132:133]
	v_fmac_f32_e32 v29, v65, v44
	v_add_f32_e32 v44, 1.0, v45
	v_mul_f32_e32 v45, 0x3d372713, v31
	v_mul_f32_e32 v46, 0x3d372713, v32
	v_mul_f32_e32 v45, v31, v45
	v_mul_f32_e32 v46, v32, v46
	v_lshl_add_u64 v[38:39], v[38:39], 0, s[4:5]
	v_fma_f32 v45, v31, v45, v31
	v_fma_f32 v46, v32, v46, v32
	v_lshl_add_u64 v[38:39], v[38:39], 0, v[154:155]
	v_mul_f32_e32 v45, 0x3fcc422a, v45
	v_mul_f32_e32 v46, 0x3fcc422a, v46
	global_store_dwordx4 v[38:39], v[34:37], off
	v_add_co_u32_e32 v38, vcc, s67, v164
	v_mul_f32_e32 v45, 0xbfb8aa3b, v45
	v_mul_f32_e32 v46, 0xbfb8aa3b, v46
	v_lshl_add_u64 v[34:35], v[164:165], 0, s[34:35]
	v_addc_co_u32_e32 v39, vcc, 0, v165, vcc
	v_exp_f32_e32 v45, v45
	v_exp_f32_e32 v46, v46
	global_load_dwordx4 v[34:37], v[34:35], off offset:256
	s_nop 0
	global_load_dwordx4 v[38:41], v[38:39], off
	v_mul_f32_e32 v47, 0x3d372713, v33
	v_add_f32_e32 v45, 1.0, v45
	v_add_f32_e32 v46, 1.0, v46
	v_rcp_f32_e32 v45, v45
	v_rcp_f32_e32 v46, v46
	v_mul_f32_e32 v47, v33, v47
	v_fma_f32 v47, v33, v47, v33
	v_mul_f32_e32 v47, 0x3fcc422a, v47
	v_mul_f32_e32 v47, 0xbfb8aa3b, v47
	v_rcp_f32_e32 v44, v44
	v_exp_f32_e32 v47, v47
	v_mul_f32_e32 v31, v31, v45
	v_mul_f32_e32 v32, v32, v46
	v_mul_f32_e32 v45, 0x3d372713, v26
	v_mul_f32_e32 v46, 0x3d372713, v27
	v_mul_f32_e32 v45, v26, v45
	v_mul_f32_e32 v46, v27, v46
	v_fma_f32 v45, v26, v45, v26
	v_fma_f32 v46, v27, v46, v27
	v_mul_f32_e32 v45, 0x3fcc422a, v45
	v_mul_f32_e32 v46, 0x3fcc422a, v46
	v_mul_f32_e32 v30, v30, v44
	v_add_f32_e32 v44, 1.0, v47
	v_mul_f32_e32 v45, 0xbfb8aa3b, v45
	v_mul_f32_e32 v46, 0xbfb8aa3b, v46
	v_rcp_f32_e32 v44, v44
	v_exp_f32_e32 v45, v45
	v_exp_f32_e32 v46, v46
	v_mul_f32_e32 v47, 0x3d372713, v29
	v_mul_f32_e32 v33, v33, v44
	v_add_f32_e32 v44, 1.0, v45
	v_add_f32_e32 v45, 1.0, v46
	v_mul_f32_e32 v46, 0x3d372713, v28
	v_mul_f32_e32 v47, v29, v47
	v_mul_f32_e32 v46, v28, v46
	v_fma_f32 v47, v29, v47, v29
	v_fma_f32 v46, v28, v46, v28
	v_mul_f32_e32 v47, 0x3fcc422a, v47
	v_mul_f32_e32 v46, 0x3fcc422a, v46
	v_mul_f32_e32 v47, 0xbfb8aa3b, v47
	v_mul_f32_e32 v46, 0xbfb8aa3b, v46
	v_exp_f32_e32 v47, v47
	v_exp_f32_e32 v46, v46
	v_rcp_f32_e32 v44, v44
	v_add_u32_e32 v42, 0xa0, v162
	v_rcp_f32_e32 v45, v45
	v_ashrrev_i32_e32 v43, 31, v42
	v_add_f32_e32 v47, 1.0, v47
	v_lshlrev_b64 v[42:43], 15, v[42:43]
	v_add_f32_e32 v46, 1.0, v46
	v_rcp_f32_e32 v47, v47
	v_rcp_f32_e32 v46, v46
	v_mul_f32_e32 v44, v26, v44
	v_cvt_pk_bf16_f32 v26, v30, v31
	v_lshl_add_u64 v[30:31], s[14:15], 0, v[42:43]
	v_mul_f32_e32 v45, v27, v45
	v_cvt_pk_bf16_f32 v27, v32, v33
	v_lshl_add_u64 v[32:33], v[30:31], 0, v[130:131]
	v_lshl_add_u64 v[32:33], v[32:33], 0, s[4:5]
	v_mul_f32_e32 v29, v29, v47
	v_lshl_add_u64 v[32:33], v[32:33], 0, v[154:155]
	v_mul_f32_e32 v46, v28, v46
	v_cvt_pk_bf16_f32 v28, v44, v45
	v_cvt_pk_bf16_f32 v29, v46, v29
	global_store_dwordx4 v[32:33], v[26:29], off
	s_and_b64 vcc, exec, s[6:7]
	s_nop 0
	v_lshlrev_b32_e32 v26, 16, v50
	v_fma_f32 v22, v66, v26, v22
	v_mul_f32_e32 v27, 0x3d372713, v22
	v_mul_f32_e32 v27, v22, v27
	v_and_b32_e32 v26, 0xffff0000, v50
	v_fma_f32 v27, v22, v27, v22
	v_fma_f32 v23, v67, v26, v23
	v_lshlrev_b32_e32 v26, 16, v51
	v_mul_f32_e32 v27, 0x3fcc422a, v27
	v_fma_f32 v24, v68, v26, v24
	v_and_b32_e32 v26, 0xffff0000, v51
	v_mul_f32_e32 v27, 0xbfb8aa3b, v27
	v_fmac_f32_e32 v25, v69, v26
	v_lshlrev_b32_e32 v26, 16, v52
	v_exp_f32_e32 v27, v27
	v_fma_f32 v18, v62, v26, v18
	v_and_b32_e32 v26, 0xffff0000, v52
	v_fma_f32 v19, v63, v26, v19
	v_lshlrev_b32_e32 v26, 16, v53
	v_fma_f32 v20, v64, v26, v20
	v_and_b32_e32 v26, 0xffff0000, v53
	v_fmac_f32_e32 v21, v65, v26
	v_add_f32_e32 v26, 1.0, v27
	v_mul_f32_e32 v27, 0x3d372713, v23
	v_mul_f32_e32 v28, 0x3d372713, v24
	v_mul_f32_e32 v27, v23, v27
	v_mul_f32_e32 v28, v24, v28
	v_fma_f32 v27, v23, v27, v23
	v_fma_f32 v28, v24, v28, v24
	v_mul_f32_e32 v27, 0x3fcc422a, v27
	v_mul_f32_e32 v28, 0x3fcc422a, v28
	v_mul_f32_e32 v27, 0xbfb8aa3b, v27
	v_mul_f32_e32 v28, 0xbfb8aa3b, v28
	v_exp_f32_e32 v27, v27
	v_exp_f32_e32 v28, v28
	v_mul_f32_e32 v29, 0x3d372713, v25
	v_mul_f32_e32 v29, v25, v29
	v_add_f32_e32 v27, 1.0, v27
	v_add_f32_e32 v28, 1.0, v28
	v_rcp_f32_e32 v27, v27
	v_rcp_f32_e32 v28, v28
	v_fma_f32 v29, v25, v29, v25
	v_mul_f32_e32 v29, 0x3fcc422a, v29
	v_mul_f32_e32 v29, 0xbfb8aa3b, v29
	v_rcp_f32_e32 v26, v26
	v_exp_f32_e32 v29, v29
	v_mul_f32_e32 v23, v23, v27
	v_mul_f32_e32 v24, v24, v28
	v_mul_f32_e32 v27, 0x3d372713, v18
	v_mul_f32_e32 v28, 0x3d372713, v19
	v_mul_f32_e32 v27, v18, v27
	v_mul_f32_e32 v28, v19, v28
	v_fma_f32 v27, v18, v27, v18
	v_fma_f32 v28, v19, v28, v19
	v_mul_f32_e32 v27, 0x3fcc422a, v27
	v_mul_f32_e32 v28, 0x3fcc422a, v28
	v_mul_f32_e32 v22, v22, v26
	v_add_f32_e32 v26, 1.0, v29
	v_mul_f32_e32 v27, 0xbfb8aa3b, v27
	v_mul_f32_e32 v28, 0xbfb8aa3b, v28
	v_rcp_f32_e32 v26, v26
	v_exp_f32_e32 v27, v27
	v_exp_f32_e32 v28, v28
	v_mul_f32_e32 v29, 0x3d372713, v21
	v_mul_f32_e32 v25, v25, v26
	v_add_f32_e32 v26, 1.0, v27
	v_add_f32_e32 v27, 1.0, v28
	v_mul_f32_e32 v28, 0x3d372713, v20
	v_mul_f32_e32 v28, v20, v28
	v_mul_f32_e32 v29, v21, v29
	v_fma_f32 v28, v20, v28, v20
	v_fma_f32 v29, v21, v29, v21
	v_mul_f32_e32 v28, 0x3fcc422a, v28
	v_mul_f32_e32 v29, 0x3fcc422a, v29
	v_mul_f32_e32 v28, 0xbfb8aa3b, v28
	v_mul_f32_e32 v29, 0xbfb8aa3b, v29
	v_exp_f32_e32 v28, v28
	v_exp_f32_e32 v29, v29
	v_rcp_f32_e32 v26, v26
	v_rcp_f32_e32 v27, v27
	v_add_f32_e32 v28, 1.0, v28
	v_add_f32_e32 v29, 1.0, v29
	v_rcp_f32_e32 v28, v28
	v_rcp_f32_e32 v29, v29
	v_mul_f32_e32 v26, v18, v26
	v_cvt_pk_bf16_f32 v18, v22, v23
	v_lshl_add_u64 v[22:23], v[30:31], 0, v[132:133]
	v_lshl_add_u64 v[22:23], v[22:23], 0, s[4:5]
	v_mul_f32_e32 v27, v19, v27
	v_mul_f32_e32 v28, v20, v28
	v_mul_f32_e32 v21, v21, v29
	v_cvt_pk_bf16_f32 v19, v24, v25
	v_cvt_pk_bf16_f32 v20, v26, v27
	v_lshl_add_u64 v[22:23], v[22:23], 0, v[154:155]
	v_cvt_pk_bf16_f32 v21, v28, v21
	global_store_dwordx4 v[22:23], v[18:21], off
	s_waitcnt vmcnt(2)
; __device__ __forceinline__ unsigned cvt_pk_bf16(float lo, float hi) { unsigned r; asm volatile("v_cvt_pk_bf16_f32 %0, %1, %2" : "=v"(r) : "v"(lo), "v"(hi)); return r; }
; template <class Epi, class Sched, bool ALIGN_EPI = false, bool SP2 = false>
; __device__ __forceinline__ void gemm_phase(PG8_LAS unsigned char* lds, const Gemm g, const Sched& S, const Epi& E) {
;     ...
;         if constexpr (ALIGN_EPI) { if (wr == 0) PG8_BAR; }
;         if constexpr (!Epi::AFTER_DRAIN) { E(acc, cur, wr, wc, fr, fq); S.done(cur); }
;         if (!has_next) break;
; #pragma unroll
;         for (int a = 0; a < 2; ++a)
; #pragma unroll
;             for (int b = 0; b < 2; ++b)
; #pragma unroll
;                 for (int m = 0; m < 4; ++m)
; #pragma unroll
;                     for (int n = 0; n < 2; ++n) acc[a][b][m][n] = (f32x4){0.f, 0.f, 0.f, 0.f};
;         cur = nxt; cA = nA; cB = nB; ++ui;
;         if constexpr (ALIGN_EPI) { if (wr == 1) PG8_BAR; }
;     __device__ __forceinline__ void operator()(const pg8::f32x4 (&acc)[2][2][4][2], const Unit& u, int wr, int wc, int fr, int fq) const {
;     ...
;         for (int k = 0; k < 8; ++k) { const int ai = k >> 2, m = k & 3; const int row = row0 + ai * HALF + m * 16; v4u cu[2];
; #pragma unroll
;             for (int bj = 0; bj < 2; ++bj) cu[bj] = nu[bj];
;             if (k < 7) {
; #pragma unroll
;                 for (int bj = 0; bj < 2; ++bj) nu[bj] = *(const v4u*)(UX + ((size_t)u.g * 1024 + row0 + ((k + 1) >> 2) * HALF + ((k + 1) & 3) * 16) * 640 + ((colb + bj * HALF) >> 4) * 16 + c0); }
; #pragma unroll
;             for (int bj = 0; bj < 2; ++bj) { const int tau = (colb + bj * HALF) >> 4;
;                 const v4u uw = cu[bj]; const f32x4 a0 = acc[ai][bj][m][0], a1 = acc[ai][bj][m][1];
;                 float r[8]; r[0] = a0[0] + d0[0] * bflo(uw.x); r[1] = a0[1] + d0[1] * bfhi(uw.x); r[2] = a0[2] + d0[2] * bflo(uw.y); r[3] = a0[3] + d0[3] * bfhi(uw.y);
;                 r[4] = a1[0] + d1[0] * bflo(uw.z); r[5] = a1[1] + d1[1] * bfhi(uw.z); r[6] = a1[2] + d1[2] * bflo(uw.w); r[7] = a1[3] + d1[3] * bfhi(uw.w);
; #pragma unroll
;                 for (int e = 0; e < 8; ++e) r[e] = gelu_tanh(r[e]);
;                 v4u w; w.x = cvt_pk_bf16(r[0], r[1]); w.y = cvt_pk_bf16(r[2], r[3]); w.z = cvt_pk_bf16(r[4], r[5]); w.w = cvt_pk_bf16(r[6], r[7]);
;                 *(v4u*)(Y + ((size_t)row * 32 + tau) * 512 + u.g * 16 + c0) = w; } }
	s_nop 0
	v_lshlrev_b32_e32 v20, 16, v38
	v_fma_f32 v14, v66, v20, v14
	v_mul_f32_e32 v21, 0x3d372713, v14
	v_mul_f32_e32 v21, v14, v21
	v_and_b32_e32 v20, 0xffff0000, v38
	v_fma_f32 v21, v14, v21, v14
	v_fma_f32 v15, v67, v20, v15
	v_lshlrev_b32_e32 v20, 16, v39
	v_mul_f32_e32 v21, 0x3fcc422a, v21
	v_fma_f32 v16, v68, v20, v16
	v_and_b32_e32 v20, 0xffff0000, v39
	v_mul_f32_e32 v21, 0xbfb8aa3b, v21
	v_fmac_f32_e32 v17, v69, v20
	v_lshlrev_b32_e32 v20, 16, v40
	v_exp_f32_e32 v21, v21
	v_fma_f32 v10, v62, v20, v10
	v_and_b32_e32 v20, 0xffff0000, v40
	v_fma_f32 v11, v63, v20, v11
	v_lshlrev_b32_e32 v20, 16, v41
	v_fma_f32 v12, v64, v20, v12
	v_and_b32_e32 v20, 0xffff0000, v41
	v_fmac_f32_e32 v13, v65, v20
	v_add_f32_e32 v20, 1.0, v21
	v_mul_f32_e32 v21, 0x3d372713, v15
	v_mul_f32_e32 v22, 0x3d372713, v16
	v_mul_f32_e32 v21, v15, v21
	v_mul_f32_e32 v22, v16, v22
	v_fma_f32 v21, v15, v21, v15
	v_fma_f32 v22, v16, v22, v16
	v_mul_f32_e32 v21, 0x3fcc422a, v21
	v_mul_f32_e32 v22, 0x3fcc422a, v22
	v_mul_f32_e32 v21, 0xbfb8aa3b, v21
	v_mul_f32_e32 v22, 0xbfb8aa3b, v22
	v_exp_f32_e32 v21, v21
	v_exp_f32_e32 v22, v22
	v_mul_f32_e32 v23, 0x3d372713, v17
	v_mul_f32_e32 v23, v17, v23
	v_add_f32_e32 v21, 1.0, v21
	v_add_f32_e32 v22, 1.0, v22
	v_rcp_f32_e32 v21, v21
	v_rcp_f32_e32 v22, v22
	v_fma_f32 v23, v17, v23, v17
	v_mul_f32_e32 v23, 0x3fcc422a, v23
	v_mul_f32_e32 v23, 0xbfb8aa3b, v23
	v_rcp_f32_e32 v20, v20
	v_exp_f32_e32 v23, v23
	v_mul_f32_e32 v15, v15, v21
	v_mul_f32_e32 v16, v16, v22
	v_mul_f32_e32 v21, 0x3d372713, v10
	v_mul_f32_e32 v22, 0x3d372713, v11
	v_mul_f32_e32 v21, v10, v21
	v_mul_f32_e32 v22, v11, v22
	v_fma_f32 v21, v10, v21, v10
	v_fma_f32 v22, v11, v22, v11
	v_mul_f32_e32 v21, 0x3fcc422a, v21
	v_mul_f32_e32 v22, 0x3fcc422a, v22
	v_mul_f32_e32 v14, v14, v20
	v_add_f32_e32 v20, 1.0, v23
	v_mul_f32_e32 v21, 0xbfb8aa3b, v21
	v_mul_f32_e32 v22, 0xbfb8aa3b, v22
	v_rcp_f32_e32 v20, v20
	v_exp_f32_e32 v21, v21
	v_exp_f32_e32 v22, v22
	v_mul_f32_e32 v23, 0x3d372713, v13
	v_mul_f32_e32 v17, v17, v20
	v_add_f32_e32 v20, 1.0, v21
	v_add_f32_e32 v21, 1.0, v22
	v_mul_f32_e32 v22, 0x3d372713, v12
	v_mul_f32_e32 v23, v13, v23
	v_mul_f32_e32 v22, v12, v22
	v_fma_f32 v23, v13, v23, v13
	v_fma_f32 v22, v12, v22, v12
	v_mul_f32_e32 v23, 0x3fcc422a, v23
	v_mul_f32_e32 v22, 0x3fcc422a, v22
	v_mul_f32_e32 v23, 0xbfb8aa3b, v23
	v_mul_f32_e32 v22, 0xbfb8aa3b, v22
	v_exp_f32_e32 v23, v23
	v_exp_f32_e32 v22, v22
	v_rcp_f32_e32 v20, v20
	v_add_u32_e32 v18, 0xb0, v162
	v_rcp_f32_e32 v21, v21
	v_ashrrev_i32_e32 v19, 31, v18
	v_add_f32_e32 v23, 1.0, v23
	v_lshlrev_b64 v[18:19], 15, v[18:19]
	v_add_f32_e32 v22, 1.0, v22
	v_rcp_f32_e32 v23, v23
	v_rcp_f32_e32 v22, v22
	v_mul_f32_e32 v20, v10, v20
	v_cvt_pk_bf16_f32 v10, v14, v15
	v_lshl_add_u64 v[14:15], s[14:15], 0, v[18:19]
	v_mul_f32_e32 v21, v11, v21
	v_cvt_pk_bf16_f32 v11, v16, v17
	v_lshl_add_u64 v[16:17], v[14:15], 0, v[130:131]
	v_lshl_add_u64 v[16:17], v[16:17], 0, s[4:5]
	v_mul_f32_e32 v13, v13, v23
	v_lshl_add_u64 v[16:17], v[16:17], 0, v[154:155]
	v_mul_f32_e32 v22, v12, v22
	v_cvt_pk_bf16_f32 v12, v20, v21
	v_cvt_pk_bf16_f32 v13, v22, v13
	global_store_dwordx4 v[16:17], v[10:13], off
	s_nop 1
	v_lshlrev_b32_e32 v10, 16, v34
	v_fma_f32 v6, v66, v10, v6
	v_mul_f32_e32 v11, 0x3d372713, v6
	v_mul_f32_e32 v11, v6, v11
	v_and_b32_e32 v10, 0xffff0000, v34
	v_fma_f32 v11, v6, v11, v6
	v_fma_f32 v7, v67, v10, v7
	v_lshlrev_b32_e32 v10, 16, v35
	v_mul_f32_e32 v11, 0x3fcc422a, v11
	v_fma_f32 v8, v68, v10, v8
	v_and_b32_e32 v10, 0xffff0000, v35
	v_mul_f32_e32 v11, 0xbfb8aa3b, v11
	v_fmac_f32_e32 v9, v69, v10
	v_lshlrev_b32_e32 v10, 16, v36
	v_exp_f32_e32 v11, v11
	v_fma_f32 v2, v62, v10, v2
	v_and_b32_e32 v10, 0xffff0000, v36
	v_fma_f32 v3, v63, v10, v3
	v_lshlrev_b32_e32 v10, 16, v37
	v_fma_f32 v4, v64, v10, v4
	v_and_b32_e32 v10, 0xffff0000, v37
	v_fmac_f32_e32 v5, v65, v10
	v_add_f32_e32 v10, 1.0, v11
	v_mul_f32_e32 v11, 0x3d372713, v7
	v_mul_f32_e32 v12, 0x3d372713, v8
	v_mul_f32_e32 v11, v7, v11
	v_mul_f32_e32 v12, v8, v12
	v_fma_f32 v11, v7, v11, v7
	v_fma_f32 v12, v8, v12, v8
	v_mul_f32_e32 v11, 0x3fcc422a, v11
	v_mul_f32_e32 v12, 0x3fcc422a, v12
	v_mul_f32_e32 v11, 0xbfb8aa3b, v11
	v_mul_f32_e32 v12, 0xbfb8aa3b, v12
	v_exp_f32_e32 v11, v11
	v_exp_f32_e32 v12, v12
	v_mul_f32_e32 v13, 0x3d372713, v9
	v_mul_f32_e32 v13, v9, v13
	v_add_f32_e32 v11, 1.0, v11
	v_add_f32_e32 v12, 1.0, v12
	v_rcp_f32_e32 v11, v11
	v_rcp_f32_e32 v12, v12
	v_fma_f32 v13, v9, v13, v9
	v_mul_f32_e32 v13, 0x3fcc422a, v13
	v_mul_f32_e32 v13, 0xbfb8aa3b, v13
	v_rcp_f32_e32 v10, v10
	v_exp_f32_e32 v13, v13
	v_mul_f32_e32 v7, v7, v11
	v_mul_f32_e32 v8, v8, v12
	v_mul_f32_e32 v11, 0x3d372713, v2
	v_mul_f32_e32 v12, 0x3d372713, v3
	v_mul_f32_e32 v11, v2, v11
	v_mul_f32_e32 v12, v3, v12
	v_fma_f32 v11, v2, v11, v2
	v_fma_f32 v12, v3, v12, v3
	v_mul_f32_e32 v11, 0x3fcc422a, v11
	v_mul_f32_e32 v12, 0x3fcc422a, v12
	v_mul_f32_e32 v6, v6, v10
	v_add_f32_e32 v10, 1.0, v13
	v_mul_f32_e32 v11, 0xbfb8aa3b, v11
	v_mul_f32_e32 v12, 0xbfb8aa3b, v12
	v_rcp_f32_e32 v10, v10
	v_exp_f32_e32 v11, v11
	v_exp_f32_e32 v12, v12
	v_mul_f32_e32 v13, 0x3d372713, v5
	v_mul_f32_e32 v9, v9, v10
	v_add_f32_e32 v10, 1.0, v11
	v_add_f32_e32 v11, 1.0, v12
	v_mul_f32_e32 v12, 0x3d372713, v4
	v_mul_f32_e32 v13, v5, v13
	v_mul_f32_e32 v12, v4, v12
	v_fma_f32 v13, v5, v13, v5
	v_fma_f32 v12, v4, v12, v4
	v_mul_f32_e32 v13, 0x3fcc422a, v13
	v_mul_f32_e32 v12, 0x3fcc422a, v12
	v_mul_f32_e32 v13, 0xbfb8aa3b, v13
	v_mul_f32_e32 v12, 0xbfb8aa3b, v12
	v_exp_f32_e32 v13, v13
	v_exp_f32_e32 v12, v12
	v_rcp_f32_e32 v10, v10
	v_rcp_f32_e32 v11, v11
	v_add_f32_e32 v13, 1.0, v13
	v_add_f32_e32 v12, 1.0, v12
	v_rcp_f32_e32 v13, v13
	v_rcp_f32_e32 v12, v12
	v_mul_f32_e32 v10, v2, v10
	v_cvt_pk_bf16_f32 v2, v6, v7
	v_lshl_add_u64 v[6:7], v[14:15], 0, v[132:133]
	v_lshl_add_u64 v[6:7], v[6:7], 0, s[4:5]
	v_mul_f32_e32 v5, v5, v13
	v_lshl_add_u64 v[6:7], v[6:7], 0, v[154:155]
	s_mov_b64 s[4:5], -1
	v_mul_f32_e32 v11, v3, v11
	v_mul_f32_e32 v12, v4, v12
	v_cvt_pk_bf16_f32 v3, v8, v9
	v_cvt_pk_bf16_f32 v4, v10, v11
	v_cvt_pk_bf16_f32 v5, v12, v5
	global_store_dwordx4 v[6:7], v[2:5], off
	s_cbranch_vccnz .LBB0_422
	s_andn2_b64 vcc, exec, s[12:13]
	s_cbranch_vccnz .LBB0_421
	s_mov_b32 s98, 1
	s_branch .LBB0_421

; #define PG8_STAGE(bufoff, gbase, voff) do { _Pragma("unroll") for (int _i = 0; _i < 2; ++_i) \
;         __builtin_amdgcn_global_load_lds((const unsigned*)((const char*)(gbase) + (voff)[_i]), (PG8_LAS unsigned*)(lds + (bufoff) + ldsw + _i * 8192), 16, 0, 0); } while (0)
; #define PG8_WAIT_V(n) asm volatile("s_waitcnt vmcnt(" #n ")" ::: "memory")
; #define PG8_BAR __builtin_amdgcn_s_barrier()
; template <class Epi, class Sched, bool ALIGN_EPI = false, bool SP2 = false>
; __device__ __forceinline__ void gemm_phase(PG8_LAS unsigned char* lds, const Gemm g, const Sched& S, const Epi& E) {
;     ...
;     const int aoff = lds_byte(wr * 64 + fr, fq * 8), boff = lds_byte(wc * 32 + fr, fq * 8);
;     ...
;         PG8_STAGE(PG8_SB(0, 0), cB, voffB); PG8_STAGE(PG8_SB(0, 1), cB + hstepB, voffB); PG8_STAGE(PG8_SA(0, 0), cA, voffA); PG8_STAGE(PG8_SA(0, 1), cA + hstepA, voffA);
;         if (wr == 1) PG8_BAR;
;         PG8_WAIT_V(2); PG8_BAR;
;         PG8_STAGE(PG8_SB(1, 0), cB + kstep, voffB); PG8_STAGE(PG8_SA(1, 0), cA + kstep, voffA); PG8_STAGE(PG8_SB(1, 1), cB + hstepB + kstep, voffB);
;         PG8_WAIT_V(6); PG8_BAR;
;     } else {
;         PG8_STAGE(PG8_SB(0, 0), cB, voffB); PG8_STAGE(PG8_SA(0, 0), cA, voffA); PG8_STAGE(PG8_SB(0, 1), cB + hstepB, voffB); PG8_STAGE(PG8_SA(0, 1), cA + hstepA, voffA);
;         if (wr == 1) PG8_BAR;
;         PG8_WAIT_V(4); PG8_BAR;
;         PG8_STAGE(PG8_SB(1, 0), cB + kstep, voffB); PG8_STAGE(PG8_SA(1, 0), cA + kstep, voffA); PG8_STAGE(PG8_SB(1, 1), cB + hstepB + kstep, voffB);
;         PG8_WAIT_V(6); PG8_BAR;
.LBB0_513:
	s_add_u32 s12, s78, 0xfc00000
	s_addc_u32 s13, s79, 0
	s_lshl_b32 s5, s5, 5
	s_mov_b64 s[14:15], 0x80
	s_and_b32 s17, s5, 0x60
	s_add_i32 m0, s25, 0x18000
	v_lshl_add_u64 v[8:9], v[8:9], 0, s[14:15]
	s_lshl_b32 s16, s1, 13
	s_lshl_b32 s5, s17, 7
	s_waitcnt vmcnt(2)
	s_barrier
	global_load_lds_dwordx4 v[8:9], off
	v_lshl_add_u64 v[6:7], v[6:7], 0, s[14:15]
	s_add_i32 m0, s25, 0x1a000
	s_add_i32 s39, s25, 0x8000
	s_add_i32 s40, s25, 0xa000
	global_load_lds_dwordx4 v[6:7], off
	v_lshl_add_u64 v[2:3], v[2:3], 0, s[14:15]
	s_mov_b32 m0, s39
	s_add_u32 s6, s28, 0x20080
	global_load_lds_dwordx4 v[2:3], off
	v_lshl_add_u64 v[2:3], v[4:5], 0, s[14:15]
	s_mov_b32 m0, s40
	s_addc_u32 s7, s29, 0
	global_load_lds_dwordx4 v[2:3], off
	s_add_i32 m0, s25, 0x1c000
	v_lshl_add_u64 v[2:3], s[6:7], 0, v[132:133]
	global_load_lds_dwordx4 v[2:3], off
	v_lshl_add_u64 v[2:3], s[6:7], 0, v[136:137]
	s_add_i32 m0, s25, 0x1e000
	s_cmpk_lt_u32 s0, 0x100
	global_load_lds_dwordx4 v[2:3], off
	v_lshrrev_b32_e32 v3, 1, v10
	v_and_b32_e32 v3, 24, v3
	v_and_b32_e32 v2, 15, v10
	v_lshlrev_b32_e32 v4, 1, v3
	v_lshl_or_b32 v1, s1, 6, v2
	v_lshl_or_b32 v2, v2, 6, v4
	v_lshlrev_b32_e32 v4, 2, v10
	v_and_b32_e32 v4, 32, v4
	v_bitop3_b32 v5, v2, s16, v4 bitop3:0xde
	v_bitop3_b32 v150, v2, s5, v4 bitop3:0xde
	v_lshlrev_b32_e32 v2, 13, v11
	v_and_b32_e32 v2, 0xffffc000, v2
	v_or_b32_e32 v151, s17, v3
	v_lshl_add_u32 v2, v12, 10, v2
	v_and_b32_e32 v3, 1, v11
	v_lshl_or_b32 v2, v3, 6, v2
	v_lshl_add_u32 v138, v13, 1, v2
	v_lshlrev_b32_e32 v2, 13, v14
	v_and_b32_e32 v2, 0xffffc000, v2
	s_waitcnt vmcnt(6)
	v_lshl_add_u32 v2, v15, 10, v2
	v_and_b32_e32 v3, 1, v14
	s_sext_i32_i8 s43, s4
	s_cselect_b64 s[4:5], -1, 0
	v_lshl_or_b32 v2, v3, 6, v2
	s_add_i32 s41, 0, 0x10000
	s_add_i32 s42, 0, 0x14000
	s_ashr_i32 s0, s82, 31
	s_mov_b32 s1, s82
	v_mov_b32_e32 v139, v133
	v_lshl_add_u32 v140, v16, 1, v2
	v_mov_b32_e32 v141, v133
	v_mov_b64_e32 v[142:143], 0x100
	v_mov_b64_e32 v[144:145], 0xff
	v_add_u32_e32 v152, s41, v150
	v_add_u32_e32 v153, s42, v150
	v_add_u32_e32 v154, 0, v5
	s_barrier
	s_mov_b32 s98, 0
	s_branch .LBB0_516

; #define PG8_STAGE(bufoff, gbase, voff) do { _Pragma("unroll") for (int _i = 0; _i < 2; ++_i) \
;         __builtin_amdgcn_global_load_lds((const unsigned*)((const char*)(gbase) + (voff)[_i]), (PG8_LAS unsigned*)(lds + (bufoff) + ldsw + _i * 8192), 16, 0, 0); } while (0)
; #define PG8_LDA(dst, b, h) do { _Pragma("unroll") for (int m = 0; m < 4; ++m) _Pragma("unroll") for (int k = 0; k < 2; ++k) dst[m][k] = *(const PG8_LAS bf16x8*)(lds + PG8_SA(b, h) + aoff + m * 2048 + k * 1024); } while (0)
; #define PG8_LDB(dst, b, h) do { _Pragma("unroll") for (int n = 0; n < 2; ++n) _Pragma("unroll") for (int k = 0; k < 2; ++k) dst[n][k] = *(const PG8_LAS bf16x8*)(lds + PG8_SB(b, h) + boff + n * 2048 + k * 1024); } while (0)
; #define PG8_WAIT_V(n) asm volatile("s_waitcnt vmcnt(" #n ")" ::: "memory")
; #define PG8_WAIT_L(n) asm volatile("s_waitcnt lgkmcnt(" #n ")" ::: "memory")
; #define PG8_BAR __builtin_amdgcn_s_barrier()
; template <class Epi, class Sched, bool ALIGN_EPI = false, bool SP2 = false>
; __device__ __forceinline__ void gemm_phase(PG8_LAS unsigned char* lds, const Gemm g, const Sched& S, const Epi& E) {
;     ...
;         const bool has_next = S.next(ui + 1, nxt);
;         const char* nA = has_next ? (const char*)g.A + (size_t)nxt.g * g.gsA * 2 + (size_t)nxt.pm * tstepA : cA; const char* nB = has_next ? (const char*)g.Bt + (size_t)nxt.g * g.gsB * 2 + (size_t)nxt.pn * tstepB : cB;
;         for (int t = 0; t < nt; t += 2) {
;             const bool last = (t == nt - 2);
;             const char* a1 = cA + (size_t)(t + 1) * kstep;
;             const char* a2 = last ? nA : cA + (size_t)(t + 2) * kstep; const char* b2 = last ? nB : cB + (size_t)(t + 2) * kstep;
;             const char* a3 = a2 + kstep; const char* b3 = b2 + kstep;
;             if (last && has_next) S.a_ready(nxt);
;             if constexpr (SP2) {
;             PG8_LDB(B0, 0, 0); PG8_LDB(B1, 0, 1); PG8_SCHED; PG8_LDA(At, 0, 0); PG8_STAGE(PG8_SA(1, 1), a1 + hstepA, voffA);
;             PG8_WAIT_V(8); PG8_WAIT_L(0); PG8_BAR; PG8_MMA(0, 0, At, B0); PG8_MMA(0, 1, At, B1); PG8_BAR; PG8_SCHED;
;             PG8_LDA(At, 0, 1); PG8_STAGE(PG8_SB(0, 0), b2, voffB); PG8_STAGE(PG8_SB(0, 1), b2 + hstepB, voffB); PG8_STAGE(PG8_SA(0, 0), a2, voffA);
;             PG8_WAIT_V(8); PG8_WAIT_L(0); PG8_BAR; PG8_MMA(1, 0, At, B0); PG8_MMA(1, 1, At, B1); PG8_BAR; PG8_SCHED;
.LBB0_522:
	s_ashr_i32 s19, s18, 31
	s_lshl_b64 s[20:21], s[18:19], 18
	s_add_u32 s20, s8, s20
	s_addc_u32 s21, s9, s21
	s_and_b64 s[22:23], s[6:7], exec
	s_cselect_b32 s19, s21, s27
	s_cselect_b32 s44, s20, s26
	s_ashr_i32 s17, s16, 31
	s_lshl_b64 s[22:23], s[16:17], 18
	s_add_u32 s22, s33, s22
	s_addc_u32 s23, s34, s23
	s_and_b64 s[30:31], s[6:7], exec
	s_cselect_b32 s17, s23, s29
	s_cselect_b32 s45, s22, s28
	s_add_u32 s26, s26, 0x20080
	s_addc_u32 s27, s27, 0
	s_add_u32 s46, s28, 0x100
	s_addc_u32 s47, s29, 0
	s_mov_b32 s48, -2
	s_waitcnt lgkmcnt(0)
	s_cmp_eq_u32 s98, 1
	s_cbranch_scc0 .Lhb_18148
	s_mov_b32 s98, 0
	s_barrier
.Lhb_18148:
	ds_read_b128 v[146:149], v152
	ds_read_b128 v[156:159], v152 offset:1024
	ds_read_b128 v[160:163], v152 offset:2048
	ds_read_b128 v[164:167], v152 offset:3072
	ds_read_b128 v[168:171], v153
	ds_read_b128 v[172:175], v153 offset:1024
	ds_read_b128 v[176:179], v153 offset:2048
	ds_read_b128 v[180:183], v153 offset:3072
	s_add_u32 s28, s26, 0xfffe0080
	s_addc_u32 s29, s27, -1
	s_cmp_eq_u32 s48, 4
	s_cselect_b32 s31, s19, s29
	s_cselect_b32 s30, s44, s28
	s_cselect_b32 s29, s17, s47
	s_cselect_b32 s28, s45, s46
	v_lshl_add_u64 v[216:217], s[26:27], 0, v[138:139]
	s_add_i32 m0, s25, 0xc000
	ds_read_b128 v[184:187], v154
	ds_read_b128 v[188:191], v154 offset:1024
	ds_read_b128 v[192:195], v154 offset:2048
	ds_read_b128 v[196:199], v154 offset:3072
	ds_read_b128 v[200:203], v154 offset:4096
	ds_read_b128 v[204:207], v154 offset:5120
	ds_read_b128 v[208:211], v154 offset:6144
	ds_read_b128 v[212:215], v154 offset:7168
	global_load_lds_dwordx4 v[216:217], off
	v_lshl_add_u64 v[216:217], s[26:27], 0, v[140:141]
	s_add_i32 m0, s25, 0xe000
	s_nop 0
	global_load_lds_dwordx4 v[216:217], off
	s_waitcnt vmcnt(8)
	s_waitcnt lgkmcnt(0)
	s_barrier
	s_setprio 1
	s_waitcnt lgkmcnt(0)
	v_mfma_f32_16x16x32_bf16 v[126:129], v[146:149], v[184:187], 0
	v_mfma_f32_16x16x32_bf16 v[122:125], v[160:163], v[184:187], 0
	v_mfma_f32_16x16x32_bf16 v[110:113], v[146:149], v[192:195], 0
	v_mfma_f32_16x16x32_bf16 v[106:109], v[160:163], v[192:195], 0
	v_mfma_f32_16x16x32_bf16 v[94:97], v[146:149], v[200:203], 0
	v_mfma_f32_16x16x32_bf16 v[90:93], v[160:163], v[200:203], 0
	v_mfma_f32_16x16x32_bf16 v[78:81], v[146:149], v[208:211], 0
	v_mfma_f32_16x16x32_bf16 v[74:77], v[160:163], v[208:211], 0
	v_mfma_f32_16x16x32_bf16 v[126:129], v[156:159], v[188:191], v[126:129]
	v_mfma_f32_16x16x32_bf16 v[122:125], v[164:167], v[188:191], v[122:125]
	v_mfma_f32_16x16x32_bf16 v[110:113], v[156:159], v[196:199], v[110:113]
	v_mfma_f32_16x16x32_bf16 v[106:109], v[164:167], v[196:199], v[106:109]
	v_mfma_f32_16x16x32_bf16 v[94:97], v[156:159], v[204:207], v[94:97]
	v_mfma_f32_16x16x32_bf16 v[90:93], v[164:167], v[204:207], v[90:93]
	v_mfma_f32_16x16x32_bf16 v[78:81], v[156:159], v[212:215], v[78:81]
	v_mfma_f32_16x16x32_bf16 v[74:77], v[164:167], v[212:215], v[74:77]
	s_setprio 0
	s_setprio 1
	v_mfma_f32_16x16x32_bf16 v[118:121], v[168:171], v[184:187], 0
	v_mfma_f32_16x16x32_bf16 v[114:117], v[176:179], v[184:187], 0
	v_mfma_f32_16x16x32_bf16 v[102:105], v[168:171], v[192:195], 0
	v_mfma_f32_16x16x32_bf16 v[98:101], v[176:179], v[192:195], 0
	v_mfma_f32_16x16x32_bf16 v[86:89], v[168:171], v[200:203], 0
	v_mfma_f32_16x16x32_bf16 v[82:85], v[176:179], v[200:203], 0
	v_mfma_f32_16x16x32_bf16 v[70:73], v[168:171], v[208:211], 0
	v_mfma_f32_16x16x32_bf16 v[66:69], v[176:179], v[208:211], 0
	v_mfma_f32_16x16x32_bf16 v[118:121], v[172:175], v[188:191], v[118:121]
	v_mfma_f32_16x16x32_bf16 v[114:117], v[180:183], v[188:191], v[114:117]
	v_mfma_f32_16x16x32_bf16 v[102:105], v[172:175], v[196:199], v[102:105]
	v_mfma_f32_16x16x32_bf16 v[98:101], v[180:183], v[196:199], v[98:101]
	v_mfma_f32_16x16x32_bf16 v[86:89], v[172:175], v[204:207], v[86:89]
	v_mfma_f32_16x16x32_bf16 v[82:85], v[180:183], v[204:207], v[82:85]
	v_mfma_f32_16x16x32_bf16 v[70:73], v[172:175], v[212:215], v[70:73]
	v_mfma_f32_16x16x32_bf16 v[66:69], v[180:183], v[212:215], v[66:69]
	s_setprio 0
	s_barrier
	s_add_i32 s49, s41, s2
	v_lshl_add_u64 v[216:217], s[28:29], 0, v[132:133]
	s_mov_b32 m0, s49
	ds_read_b128 v[184:187], v154 offset:16384
	ds_read_b128 v[188:191], v154 offset:17408
	ds_read_b128 v[192:195], v154 offset:18432
	ds_read_b128 v[196:199], v154 offset:19456
	ds_read_b128 v[200:203], v154 offset:20480
	ds_read_b128 v[204:207], v154 offset:21504
	ds_read_b128 v[208:211], v154 offset:22528
	ds_read_b128 v[212:215], v154 offset:23552
	global_load_lds_dwordx4 v[216:217], off
	s_add_i32 m0, s49, 0x2000
	s_add_u32 s50, s28, 0x20000
	v_lshl_add_u64 v[218:219], s[28:29], 0, v[136:137]
	s_addc_u32 s51, s29, 0
	s_add_i32 s49, s42, s2
	global_load_lds_dwordx4 v[218:219], off
	v_lshl_add_u64 v[220:221], s[50:51], 0, v[132:133]
	s_mov_b32 m0, s49
	v_lshl_add_u64 v[222:223], s[30:31], 0, v[134:135]
	global_load_lds_dwordx4 v[220:221], off
	v_lshl_add_u64 v[220:221], s[50:51], 0, v[136:137]
	s_add_i32 m0, s49, 0x2000
	s_nop 0
	global_load_lds_dwordx4 v[220:221], off
	v_lshl_add_u64 v[220:221], s[30:31], 0, v[130:131]
	s_mov_b32 m0, s25
	s_nop 0
	global_load_lds_dwordx4 v[220:221], off
	s_mov_b32 m0, s35
	s_nop 0
	global_load_lds_dwordx4 v[222:223], off
	s_waitcnt vmcnt(8)
	s_waitcnt lgkmcnt(0)
	s_barrier
; #define PG8_STAGE(bufoff, gbase, voff) do { _Pragma("unroll") for (int _i = 0; _i < 2; ++_i) \
;         __builtin_amdgcn_global_load_lds((const unsigned*)((const char*)(gbase) + (voff)[_i]), (PG8_LAS unsigned*)(lds + (bufoff) + ldsw + _i * 8192), 16, 0, 0); } while (0)
; #define PG8_LDA(dst, b, h) do { _Pragma("unroll") for (int m = 0; m < 4; ++m) _Pragma("unroll") for (int k = 0; k < 2; ++k) dst[m][k] = *(const PG8_LAS bf16x8*)(lds + PG8_SA(b, h) + aoff + m * 2048 + k * 1024); } while (0)
; #define PG8_LDB(dst, b, h) do { _Pragma("unroll") for (int n = 0; n < 2; ++n) _Pragma("unroll") for (int k = 0; k < 2; ++k) dst[n][k] = *(const PG8_LAS bf16x8*)(lds + PG8_SB(b, h) + boff + n * 2048 + k * 1024); } while (0)
; #define PG8_MMA(ai, bj, At, Bt) do { __builtin_amdgcn_s_setprio(1); _Pragma("unroll") for (int m = 0; m < 4; ++m) _Pragma("unroll") for (int n = 0; n < 2; ++n) _Pragma("unroll") for (int k = 0; k < 2; ++k) \
;         acc[ai][bj][m][n] = __builtin_amdgcn_mfma_f32_16x16x32_bf16(Bt[n][k], At[m][k], acc[ai][bj][m][n], 0, 0, 0); __builtin_amdgcn_s_setprio(0); } while (0)
; #define PG8_WAIT_V(n) asm volatile("s_waitcnt vmcnt(" #n ")" ::: "memory")
; #define PG8_WAIT_L(n) asm volatile("s_waitcnt lgkmcnt(" #n ")" ::: "memory")
; #define PG8_BAR __builtin_amdgcn_s_barrier()
; #define PG8_SCHED __builtin_amdgcn_sched_barrier(0)
; template <class Epi, class Sched, bool ALIGN_EPI = false, bool SP2 = false>
; __device__ __forceinline__ void gemm_phase(PG8_LAS unsigned char* lds, const Gemm g, const Sched& S, const Epi& E) {
;     ...
;             PG8_WAIT_V(8); PG8_WAIT_L(0); PG8_BAR; PG8_MMA(1, 0, At, B0); PG8_MMA(1, 1, At, B1); PG8_BAR; PG8_SCHED;
;             PG8_LDB(B0, 1, 0); PG8_LDB(B1, 1, 1); PG8_SCHED; PG8_LDA(At, 1, 0); PG8_STAGE(PG8_SA(0, 1), a2 + hstepA, voffA);
;             PG8_WAIT_V(8); PG8_WAIT_L(0); PG8_BAR; PG8_MMA(0, 0, At, B0); PG8_MMA(0, 1, At, B1); PG8_BAR; PG8_SCHED;
;             PG8_LDA(At, 1, 1); PG8_STAGE(PG8_SB(1, 0), b3, voffB); PG8_STAGE(PG8_SB(1, 1), b3 + hstepB, voffB); PG8_STAGE(PG8_SA(1, 0), a3, voffA);
	s_setprio 1
	s_waitcnt lgkmcnt(0)
	v_mfma_f32_16x16x32_bf16 v[62:65], v[146:149], v[184:187], 0
	v_mfma_f32_16x16x32_bf16 v[58:61], v[160:163], v[184:187], 0
	v_mfma_f32_16x16x32_bf16 v[46:49], v[146:149], v[192:195], 0
	v_mfma_f32_16x16x32_bf16 v[42:45], v[160:163], v[192:195], 0
	v_mfma_f32_16x16x32_bf16 v[30:33], v[146:149], v[200:203], 0
	v_mfma_f32_16x16x32_bf16 v[26:29], v[160:163], v[200:203], 0
	v_mfma_f32_16x16x32_bf16 v[14:17], v[146:149], v[208:211], 0
	v_mfma_f32_16x16x32_bf16 v[10:13], v[160:163], v[208:211], 0
	v_mfma_f32_16x16x32_bf16 v[62:65], v[156:159], v[188:191], v[62:65]
	v_mfma_f32_16x16x32_bf16 v[58:61], v[164:167], v[188:191], v[58:61]
	v_mfma_f32_16x16x32_bf16 v[46:49], v[156:159], v[196:199], v[46:49]
	v_mfma_f32_16x16x32_bf16 v[42:45], v[164:167], v[196:199], v[42:45]
	v_mfma_f32_16x16x32_bf16 v[30:33], v[156:159], v[204:207], v[30:33]
	v_mfma_f32_16x16x32_bf16 v[26:29], v[164:167], v[204:207], v[26:29]
	v_mfma_f32_16x16x32_bf16 v[14:17], v[156:159], v[212:215], v[14:17]
	v_mfma_f32_16x16x32_bf16 v[10:13], v[164:167], v[212:215], v[10:13]
	s_setprio 0
	s_setprio 1
	v_mfma_f32_16x16x32_bf16 v[54:57], v[168:171], v[184:187], 0
	v_mfma_f32_16x16x32_bf16 v[50:53], v[176:179], v[184:187], 0
	v_mfma_f32_16x16x32_bf16 v[38:41], v[168:171], v[192:195], 0
	v_mfma_f32_16x16x32_bf16 v[34:37], v[176:179], v[192:195], 0
	v_mfma_f32_16x16x32_bf16 v[22:25], v[168:171], v[200:203], 0
	v_mfma_f32_16x16x32_bf16 v[18:21], v[176:179], v[200:203], 0
	v_mfma_f32_16x16x32_bf16 v[6:9], v[168:171], v[208:211], 0
	v_mfma_f32_16x16x32_bf16 v[2:5], v[176:179], v[208:211], 0
	v_mfma_f32_16x16x32_bf16 v[54:57], v[172:175], v[188:191], v[54:57]
	v_mfma_f32_16x16x32_bf16 v[50:53], v[180:183], v[188:191], v[50:53]
	v_mfma_f32_16x16x32_bf16 v[38:41], v[172:175], v[196:199], v[38:41]
	v_mfma_f32_16x16x32_bf16 v[34:37], v[180:183], v[196:199], v[34:37]
	v_mfma_f32_16x16x32_bf16 v[22:25], v[172:175], v[204:207], v[22:25]
	v_mfma_f32_16x16x32_bf16 v[18:21], v[180:183], v[204:207], v[18:21]
	v_mfma_f32_16x16x32_bf16 v[6:9], v[172:175], v[212:215], v[6:9]
	v_mfma_f32_16x16x32_bf16 v[2:5], v[180:183], v[212:215], v[2:5]
	s_setprio 0
	s_barrier
	s_add_i32 s49, 0, 0x18000
	v_add_u32_e32 v155, s49, v150
	s_add_i32 s50, 0, 0x1c000
	ds_read_b128 v[146:149], v155
	ds_read_b128 v[156:159], v155 offset:1024
	ds_read_b128 v[160:163], v155 offset:2048
	ds_read_b128 v[164:167], v155 offset:3072
	v_add_u32_e32 v155, s50, v150
	ds_read_b128 v[168:171], v155
	ds_read_b128 v[172:175], v155 offset:1024
	ds_read_b128 v[176:179], v155 offset:2048
	ds_read_b128 v[180:183], v155 offset:3072
	s_add_u32 s30, s30, 0x20000
	s_addc_u32 s31, s31, 0
	s_mov_b32 m0, s36
	v_lshl_add_u64 v[224:225], s[30:31], 0, v[130:131]
	ds_read_b128 v[184:187], v154 offset:32768
	ds_read_b128 v[188:191], v154 offset:33792
	ds_read_b128 v[192:195], v154 offset:34816
	ds_read_b128 v[196:199], v154 offset:35840
	ds_read_b128 v[200:203], v154 offset:36864
	ds_read_b128 v[204:207], v154 offset:37888
	ds_read_b128 v[208:211], v154 offset:38912
	ds_read_b128 v[212:215], v154 offset:39936
	global_load_lds_dwordx4 v[224:225], off
	v_lshl_add_u64 v[224:225], s[30:31], 0, v[134:135]
	s_mov_b32 m0, s37
	s_nop 0
	global_load_lds_dwordx4 v[224:225], off
	s_waitcnt vmcnt(8)
	s_waitcnt lgkmcnt(0)
	s_barrier
	s_setprio 1
	s_waitcnt lgkmcnt(0)
	v_mfma_f32_16x16x32_bf16 v[126:129], v[146:149], v[184:187], v[126:129]
	v_mfma_f32_16x16x32_bf16 v[122:125], v[160:163], v[184:187], v[122:125]
	v_mfma_f32_16x16x32_bf16 v[110:113], v[146:149], v[192:195], v[110:113]
	v_mfma_f32_16x16x32_bf16 v[106:109], v[160:163], v[192:195], v[106:109]
	v_mfma_f32_16x16x32_bf16 v[94:97], v[146:149], v[200:203], v[94:97]
	v_mfma_f32_16x16x32_bf16 v[90:93], v[160:163], v[200:203], v[90:93]
	v_mfma_f32_16x16x32_bf16 v[78:81], v[146:149], v[208:211], v[78:81]
	v_mfma_f32_16x16x32_bf16 v[74:77], v[160:163], v[208:211], v[74:77]
	v_mfma_f32_16x16x32_bf16 v[126:129], v[156:159], v[188:191], v[126:129]
	v_mfma_f32_16x16x32_bf16 v[122:125], v[164:167], v[188:191], v[122:125]
	v_mfma_f32_16x16x32_bf16 v[110:113], v[156:159], v[196:199], v[110:113]
	v_mfma_f32_16x16x32_bf16 v[106:109], v[164:167], v[196:199], v[106:109]
	v_mfma_f32_16x16x32_bf16 v[94:97], v[156:159], v[204:207], v[94:97]
	v_mfma_f32_16x16x32_bf16 v[90:93], v[164:167], v[204:207], v[90:93]
	v_mfma_f32_16x16x32_bf16 v[78:81], v[156:159], v[212:215], v[78:81]
	v_mfma_f32_16x16x32_bf16 v[74:77], v[164:167], v[212:215], v[74:77]
	s_setprio 0
	s_setprio 1
	v_mfma_f32_16x16x32_bf16 v[118:121], v[168:171], v[184:187], v[118:121]
	v_mfma_f32_16x16x32_bf16 v[114:117], v[176:179], v[184:187], v[114:117]
	v_mfma_f32_16x16x32_bf16 v[102:105], v[168:171], v[192:195], v[102:105]
	v_mfma_f32_16x16x32_bf16 v[98:101], v[176:179], v[192:195], v[98:101]
	v_mfma_f32_16x16x32_bf16 v[86:89], v[168:171], v[200:203], v[86:89]
	v_mfma_f32_16x16x32_bf16 v[82:85], v[176:179], v[200:203], v[82:85]
	v_mfma_f32_16x16x32_bf16 v[70:73], v[168:171], v[208:211], v[70:73]
	v_mfma_f32_16x16x32_bf16 v[66:69], v[176:179], v[208:211], v[66:69]
	v_mfma_f32_16x16x32_bf16 v[118:121], v[172:175], v[188:191], v[118:121]
	v_mfma_f32_16x16x32_bf16 v[114:117], v[180:183], v[188:191], v[114:117]
	v_mfma_f32_16x16x32_bf16 v[102:105], v[172:175], v[196:199], v[102:105]
	v_mfma_f32_16x16x32_bf16 v[98:101], v[180:183], v[196:199], v[98:101]
	v_mfma_f32_16x16x32_bf16 v[86:89], v[172:175], v[204:207], v[86:89]
	v_mfma_f32_16x16x32_bf16 v[82:85], v[180:183], v[204:207], v[82:85]
	v_mfma_f32_16x16x32_bf16 v[70:73], v[172:175], v[212:215], v[70:73]
	v_mfma_f32_16x16x32_bf16 v[66:69], v[180:183], v[212:215], v[66:69]
	s_setprio 0
	s_barrier
; #define PG8_STAGE(bufoff, gbase, voff) do { _Pragma("unroll") for (int _i = 0; _i < 2; ++_i) \
;         __builtin_amdgcn_global_load_lds((const unsigned*)((const char*)(gbase) + (voff)[_i]), (PG8_LAS unsigned*)(lds + (bufoff) + ldsw + _i * 8192), 16, 0, 0); } while (0)
; #define PG8_LDA(dst, b, h) do { _Pragma("unroll") for (int m = 0; m < 4; ++m) _Pragma("unroll") for (int k = 0; k < 2; ++k) dst[m][k] = *(const PG8_LAS bf16x8*)(lds + PG8_SA(b, h) + aoff + m * 2048 + k * 1024); } while (0)
; #define PG8_MMA(ai, bj, At, Bt) do { __builtin_amdgcn_s_setprio(1); _Pragma("unroll") for (int m = 0; m < 4; ++m) _Pragma("unroll") for (int n = 0; n < 2; ++n) _Pragma("unroll") for (int k = 0; k < 2; ++k) \
;         acc[ai][bj][m][n] = __builtin_amdgcn_mfma_f32_16x16x32_bf16(Bt[n][k], At[m][k], acc[ai][bj][m][n], 0, 0, 0); __builtin_amdgcn_s_setprio(0); } while (0)
; #define PG8_WAIT_V(n) asm volatile("s_waitcnt vmcnt(" #n ")" ::: "memory")
; #define PG8_WAIT_L(n) asm volatile("s_waitcnt lgkmcnt(" #n ")" ::: "memory")
; #define PG8_BAR __builtin_amdgcn_s_barrier()
; #define PG8_SCHED __builtin_amdgcn_sched_barrier(0)
; template <class Epi, class Sched, bool ALIGN_EPI = false, bool SP2 = false>
; __device__ __forceinline__ void gemm_phase(PG8_LAS unsigned char* lds, const Gemm g, const Sched& S, const Epi& E) {
;     ...
;         for (int t = 0; t < nt; t += 2) {
;     ...
;             PG8_LDA(At, 1, 1); PG8_STAGE(PG8_SB(1, 0), b3, voffB); PG8_STAGE(PG8_SB(1, 1), b3 + hstepB, voffB); PG8_STAGE(PG8_SA(1, 0), a3, voffA);
;             PG8_WAIT_V(8); PG8_WAIT_L(0); PG8_BAR; PG8_MMA(1, 0, At, B0); PG8_MMA(1, 1, At, B1); PG8_BAR; PG8_SCHED;
	s_add_i32 s30, s49, s2
	v_lshl_add_u64 v[216:217], v[216:217], 0, s[14:15]
	s_mov_b32 m0, s30
	ds_read_b128 v[184:187], v154 offset:49152
	ds_read_b128 v[188:191], v154 offset:50176
	ds_read_b128 v[192:195], v154 offset:51200
	ds_read_b128 v[196:199], v154 offset:52224
	ds_read_b128 v[200:203], v154 offset:53248
	ds_read_b128 v[204:207], v154 offset:54272
	ds_read_b128 v[208:211], v154 offset:55296
	ds_read_b128 v[212:215], v154 offset:56320
	global_load_lds_dwordx4 v[216:217], off
	s_add_i32 m0, s30, 0x2000
	s_add_u32 s28, s28, 0x20080
	v_lshl_add_u64 v[216:217], v[218:219], 0, s[14:15]
	s_addc_u32 s29, s29, 0
	s_add_i32 s30, s50, s2
	global_load_lds_dwordx4 v[216:217], off
	v_lshl_add_u64 v[216:217], s[28:29], 0, v[132:133]
	s_mov_b32 m0, s30
	s_nop 0
	global_load_lds_dwordx4 v[216:217], off
	v_lshl_add_u64 v[216:217], s[28:29], 0, v[136:137]
	s_add_i32 m0, s30, 0x2000
	s_nop 0
	global_load_lds_dwordx4 v[216:217], off
	v_lshl_add_u64 v[216:217], v[220:221], 0, s[14:15]
	s_mov_b32 m0, s39
	s_nop 0
	global_load_lds_dwordx4 v[216:217], off
	v_lshl_add_u64 v[216:217], v[222:223], 0, s[14:15]
	s_mov_b32 m0, s40
	s_nop 0
	global_load_lds_dwordx4 v[216:217], off
	s_waitcnt vmcnt(8)
	s_waitcnt lgkmcnt(0)
	s_barrier
	s_setprio 1
	s_waitcnt lgkmcnt(0)
	v_mfma_f32_16x16x32_bf16 v[62:65], v[146:149], v[184:187], v[62:65]
	v_mfma_f32_16x16x32_bf16 v[58:61], v[160:163], v[184:187], v[58:61]
	v_mfma_f32_16x16x32_bf16 v[46:49], v[146:149], v[192:195], v[46:49]
	v_mfma_f32_16x16x32_bf16 v[42:45], v[160:163], v[192:195], v[42:45]
	v_mfma_f32_16x16x32_bf16 v[30:33], v[146:149], v[200:203], v[30:33]
	v_mfma_f32_16x16x32_bf16 v[26:29], v[160:163], v[200:203], v[26:29]
	v_mfma_f32_16x16x32_bf16 v[14:17], v[146:149], v[208:211], v[14:17]
	v_mfma_f32_16x16x32_bf16 v[10:13], v[160:163], v[208:211], v[10:13]
	v_mfma_f32_16x16x32_bf16 v[62:65], v[156:159], v[188:191], v[62:65]
	v_mfma_f32_16x16x32_bf16 v[58:61], v[164:167], v[188:191], v[58:61]
	v_mfma_f32_16x16x32_bf16 v[46:49], v[156:159], v[196:199], v[46:49]
	v_mfma_f32_16x16x32_bf16 v[42:45], v[164:167], v[196:199], v[42:45]
	v_mfma_f32_16x16x32_bf16 v[30:33], v[156:159], v[204:207], v[30:33]
	v_mfma_f32_16x16x32_bf16 v[26:29], v[164:167], v[204:207], v[26:29]
	v_mfma_f32_16x16x32_bf16 v[14:17], v[156:159], v[212:215], v[14:17]
	v_mfma_f32_16x16x32_bf16 v[10:13], v[164:167], v[212:215], v[10:13]
	s_setprio 0
	s_setprio 1
	v_mfma_f32_16x16x32_bf16 v[54:57], v[168:171], v[184:187], v[54:57]
	v_mfma_f32_16x16x32_bf16 v[50:53], v[176:179], v[184:187], v[50:53]
	v_mfma_f32_16x16x32_bf16 v[38:41], v[168:171], v[192:195], v[38:41]
	v_mfma_f32_16x16x32_bf16 v[34:37], v[176:179], v[192:195], v[34:37]
	v_mfma_f32_16x16x32_bf16 v[22:25], v[168:171], v[200:203], v[22:25]
	v_mfma_f32_16x16x32_bf16 v[18:21], v[176:179], v[200:203], v[18:21]
	v_mfma_f32_16x16x32_bf16 v[6:9], v[168:171], v[208:211], v[6:9]
	v_mfma_f32_16x16x32_bf16 v[2:5], v[176:179], v[208:211], v[2:5]
	v_mfma_f32_16x16x32_bf16 v[54:57], v[172:175], v[188:191], v[54:57]
	v_mfma_f32_16x16x32_bf16 v[50:53], v[180:183], v[188:191], v[50:53]
	v_mfma_f32_16x16x32_bf16 v[38:41], v[172:175], v[196:199], v[38:41]
	v_mfma_f32_16x16x32_bf16 v[34:37], v[180:183], v[196:199], v[34:37]
	v_mfma_f32_16x16x32_bf16 v[22:25], v[172:175], v[204:207], v[22:25]
	v_mfma_f32_16x16x32_bf16 v[18:21], v[180:183], v[204:207], v[18:21]
	v_mfma_f32_16x16x32_bf16 v[6:9], v[172:175], v[212:215], v[6:9]
	v_mfma_f32_16x16x32_bf16 v[2:5], v[180:183], v[212:215], v[2:5]
	s_setprio 0
	s_barrier
	s_add_i32 s48, s48, 2
	s_add_u32 s26, s26, 0x100
	s_addc_u32 s27, s27, 0
	s_add_u32 s46, s46, 0x100
	s_addc_u32 s47, s47, 0
	s_cmp_gt_u32 s48, 5

; __device__ __forceinline__ unsigned cvt_pk_bf16(float lo, float hi) { unsigned r; asm volatile("v_cvt_pk_bf16_f32 %0, %1, %2" : "=v"(r) : "v"(lo), "v"(hi)); return r; }
; __device__ __forceinline__ float bflo(unsigned w) { return __uint_as_float(w << 16); }
; __device__ __forceinline__ float bfhi(unsigned w) { return __uint_as_float(w & 0xffff0000u); }
; __device__ __forceinline__ float sigm(float x) { return __builtin_amdgcn_rcpf(1.f + __expf(-x)); }
;     __device__ __forceinline__ void operator()(const pg8::f32x4 (&acc)[2][2][4][2], const Unit& u, int wr, int wc, int fr, int fq) const {
;         const int row0 = u.pm * BM + wr * 64 + fr, col0 = u.pn * BM + wc * 32 + 8 * fq;
;         v4u ny[2];
; #pragma unroll
;         for (int bj = 0; bj < 2; ++bj) ny[bj] = *(const v4u*)(Y + (size_t)row0 * 512 + col0 + bj * HALF);
; #pragma unroll
;         for (int k = 0; k < 8; ++k) { const int ai = k >> 2, m = k & 3; const int row = row0 + ai * HALF + m * 16; v4u cy[2];
; #pragma unroll
;             for (int bj = 0; bj < 2; ++bj) cy[bj] = ny[bj];
;             if (k < 7) {
; #pragma unroll
;                 for (int bj = 0; bj < 2; ++bj) ny[bj] = *(const v4u*)(Y + (size_t)(row0 + ((k + 1) >> 2) * HALF + ((k + 1) & 3) * 16) * 512 + col0 + bj * HALF); }
; #pragma unroll
;             for (int bj = 0; bj < 2; ++bj) { const int col = col0 + bj * HALF; const v4u yw = cy[bj]; const f32x4 a0 = acc[ai][bj][m][0], a1 = acc[ai][bj][m][1];
;                 v4u w; w.x = cvt_pk_bf16(bflo(yw.x) * sigm(a0[0]), bfhi(yw.x) * sigm(a0[1])); w.y = cvt_pk_bf16(bflo(yw.y) * sigm(a0[2]), bfhi(yw.y) * sigm(a0[3]));
;                 w.z = cvt_pk_bf16(bflo(yw.z) * sigm(a1[0]), bfhi(yw.z) * sigm(a1[1])); w.w = cvt_pk_bf16(bflo(yw.w) * sigm(a1[2]), bfhi(yw.w) * sigm(a1[3]));
;                 *(v4u*)(O + (size_t)row * DM_ + 512 + col) = w; } }
.LBB0_526:
	v_lshl_add_u32 v148, s24, 8, v1
	v_lshl_or_b32 v146, s43, 8, v151
	v_ashrrev_i32_e32 v149, 31, v148
	v_lshlrev_b64 v[156:157], 10, v[148:149]
	v_ashrrev_i32_e32 v147, 31, v146
	v_lshl_add_u64 v[156:157], s[8:9], 0, v[156:157]
	v_lshlrev_b64 v[146:147], 1, v[146:147]
	v_lshl_add_u64 v[160:161], v[156:157], 0, v[146:147]
	global_load_dwordx4 v[156:159], v[160:161], off
	s_nop 0
	global_load_dwordx4 v[160:163], v[160:161], off offset:256
	v_mul_f32_e32 v122, 0xbfb8aa3b, v122
	v_mul_f32_e32 v123, 0xbfb8aa3b, v123
	v_mul_f32_e32 v124, 0xbfb8aa3b, v124
	v_mul_f32_e32 v125, 0xbfb8aa3b, v125
	v_or_b32_e32 v164, 16, v148
	v_mul_f32_e32 v120, 0xbfb8aa3b, v120
	v_mul_f32_e32 v121, 0xbfb8aa3b, v121
	v_exp_f32_e32 v155, v122
	v_exp_f32_e32 v168, v123
	v_exp_f32_e32 v124, v124
	v_exp_f32_e32 v125, v125
	v_ashrrev_i32_e32 v165, 31, v164
	v_mul_f32_e32 v118, 0xbfb8aa3b, v118
	v_mul_f32_e32 v119, 0xbfb8aa3b, v119
	v_exp_f32_e32 v171, v120
	v_exp_f32_e32 v172, v121
	v_lshlrev_b64 v[120:121], 10, v[164:165]
	v_exp_f32_e32 v169, v118
	v_exp_f32_e32 v170, v119
	v_lshlrev_b64 v[118:119], 11, v[148:149]
	v_lshl_add_u64 v[120:121], s[8:9], 0, v[120:121]
	v_lshl_add_u64 v[118:119], s[12:13], 0, v[118:119]
	v_lshl_add_u64 v[122:123], v[120:121], 0, v[146:147]
	v_lshl_add_u64 v[166:167], v[118:119], 0, v[146:147]
	v_add_f32_e32 v149, 1.0, v155
	v_add_f32_e32 v155, 1.0, v168
	v_add_f32_e32 v168, 1.0, v124
	v_add_f32_e32 v173, 1.0, v125
	global_load_dwordx4 v[118:121], v[122:123], off offset:256
	s_nop 0
	global_load_dwordx4 v[122:125], v[122:123], off
	v_mul_f32_e32 v126, 0xbfb8aa3b, v126
	v_mul_f32_e32 v127, 0xbfb8aa3b, v127
	v_mul_f32_e32 v128, 0xbfb8aa3b, v128
	v_mul_f32_e32 v129, 0xbfb8aa3b, v129
	v_exp_f32_e32 v126, v126
	v_exp_f32_e32 v127, v127
	v_exp_f32_e32 v128, v128
	v_exp_f32_e32 v129, v129
	v_add_f32_e32 v126, 1.0, v126
	v_add_f32_e32 v127, 1.0, v127
	v_add_f32_e32 v128, 1.0, v128
	v_add_f32_e32 v129, 1.0, v129
	v_rcp_f32_e32 v126, v126
	v_rcp_f32_e32 v127, v127
	v_rcp_f32_e32 v128, v128
	v_rcp_f32_e32 v129, v129
	v_rcp_f32_e32 v149, v149
	v_rcp_f32_e32 v155, v155
	v_rcp_f32_e32 v168, v168
	v_rcp_f32_e32 v173, v173
	v_mul_f32_e32 v114, 0xbfb8aa3b, v114
	v_exp_f32_e32 v114, v114
	v_mul_f32_e32 v115, 0xbfb8aa3b, v115
	v_exp_f32_e32 v115, v115
	v_add_f32_e32 v169, 1.0, v169
	v_add_f32_e32 v170, 1.0, v170
	v_rcp_f32_e32 v169, v169
	v_rcp_f32_e32 v170, v170
	v_add_f32_e32 v114, 1.0, v114
	v_rcp_f32_e32 v114, v114
	v_add_f32_e32 v115, 1.0, v115
	v_mul_f32_e32 v116, 0xbfb8aa3b, v116
	v_rcp_f32_e32 v115, v115
	v_exp_f32_e32 v116, v116
	v_mul_f32_e32 v117, 0xbfb8aa3b, v117
	v_exp_f32_e32 v117, v117
	v_mul_f32_e32 v110, 0xbfb8aa3b, v110
	v_mul_f32_e32 v111, 0xbfb8aa3b, v111
	v_exp_f32_e32 v110, v110
	v_exp_f32_e32 v111, v111
	v_mul_f32_e32 v112, 0xbfb8aa3b, v112
	v_exp_f32_e32 v112, v112
	v_add_f32_e32 v110, 1.0, v110
	v_add_f32_e32 v111, 1.0, v111
	v_rcp_f32_e32 v110, v110
	v_rcp_f32_e32 v111, v111
	v_mul_f32_e32 v113, 0xbfb8aa3b, v113
	v_exp_f32_e32 v113, v113
	v_mul_f32_e32 v106, 0xbfb8aa3b, v106
	s_waitcnt vmcnt(0)
	v_lshlrev_b32_e32 v174, 16, v156
	v_and_b32_e32 v156, 0xffff0000, v156
	v_lshlrev_b32_e32 v175, 16, v157
	v_and_b32_e32 v157, 0xffff0000, v157
	v_mul_f32_e32 v126, v126, v174
	v_mul_f32_e32 v127, v127, v156
	v_lshlrev_b32_e32 v176, 16, v158
	v_and_b32_e32 v158, 0xffff0000, v158
	v_lshlrev_b32_e32 v177, 16, v159
	v_and_b32_e32 v159, 0xffff0000, v159
	v_mul_f32_e32 v128, v128, v175
	v_mul_f32_e32 v129, v129, v157
	v_cvt_pk_bf16_f32 v126, v126, v127
	v_cvt_pk_bf16_f32 v127, v128, v129
	v_mul_f32_e32 v149, v149, v176
	v_mul_f32_e32 v155, v155, v158
	v_mul_f32_e32 v156, v168, v177
	v_mul_f32_e32 v157, v173, v159
	v_cvt_pk_bf16_f32 v128, v149, v155
	v_cvt_pk_bf16_f32 v129, v156, v157
	global_store_dwordx4 v[166:167], v[126:129], off offset:1024
	v_lshlrev_b32_e32 v178, 16, v160
	v_and_b32_e32 v160, 0xffff0000, v160
	v_add_f32_e32 v127, 1.0, v171
	v_rcp_f32_e32 v127, v127
	v_add_f32_e32 v128, 1.0, v172
	v_rcp_f32_e32 v128, v128
	v_lshlrev_b32_e32 v129, 16, v161
	v_mul_f32_e32 v127, v127, v129
	v_and_b32_e32 v129, 0xffff0000, v161
	v_mul_f32_e32 v128, v128, v129
	v_mul_f32_e32 v158, v169, v178
	v_mul_f32_e32 v159, v170, v160
	v_cvt_pk_bf16_f32 v126, v158, v159
	v_cvt_pk_bf16_f32 v127, v127, v128
	v_lshlrev_b32_e32 v128, 16, v162
	v_mul_f32_e32 v114, v114, v128
	v_and_b32_e32 v128, 0xffff0000, v162
	v_mul_f32_e32 v115, v115, v128
	v_cvt_pk_bf16_f32 v128, v114, v115
	v_add_f32_e32 v114, 1.0, v116
	v_rcp_f32_e32 v114, v114
	v_add_f32_e32 v115, 1.0, v117
	v_rcp_f32_e32 v115, v115
	v_lshlrev_b32_e32 v116, 16, v163
	v_mul_f32_e32 v114, v114, v116
	v_and_b32_e32 v116, 0xffff0000, v163
	v_or_b32_e32 v156, 32, v148
	v_mul_f32_e32 v115, v115, v116
	v_ashrrev_i32_e32 v157, 31, v156
	v_cvt_pk_bf16_f32 v129, v114, v115
	v_lshlrev_b64 v[114:115], 10, v[156:157]
	v_lshl_add_u64 v[114:115], s[8:9], 0, v[114:115]
	v_lshlrev_b32_e32 v149, 16, v122
	v_and_b32_e32 v122, 0xffff0000, v122
	global_store_dwordx4 v[166:167], v[126:129], off offset:1280
	v_mul_f32_e32 v110, v110, v149
	v_mul_f32_e32 v111, v111, v122
	v_lshl_add_u64 v[126:127], v[114:115], 0, v[146:147]
	v_exp_f32_e32 v106, v106
	v_mul_f32_e32 v107, 0xbfb8aa3b, v107
	global_load_dwordx4 v[114:117], v[126:127], off offset:256
	s_nop 0
	global_load_dwordx4 v[126:129], v[126:127], off
	v_cvt_pk_bf16_f32 v110, v110, v111
	v_add_f32_e32 v111, 1.0, v112
	v_exp_f32_e32 v107, v107
	v_rcp_f32_e32 v111, v111
	v_add_f32_e32 v112, 1.0, v113
	v_rcp_f32_e32 v112, v112
	v_add_f32_e32 v106, 1.0, v106
	v_lshlrev_b32_e32 v113, 16, v123
	v_rcp_f32_e32 v106, v106
	v_add_f32_e32 v107, 1.0, v107
	v_mul_f32_e32 v108, 0xbfb8aa3b, v108
; __device__ __forceinline__ unsigned cvt_pk_bf16(float lo, float hi) { unsigned r; asm volatile("v_cvt_pk_bf16_f32 %0, %1, %2" : "=v"(r) : "v"(lo), "v"(hi)); return r; }
; __device__ __forceinline__ float bflo(unsigned w) { return __uint_as_float(w << 16); }
; __device__ __forceinline__ float bfhi(unsigned w) { return __uint_as_float(w & 0xffff0000u); }
; __device__ __forceinline__ float sigm(float x) { return __builtin_amdgcn_rcpf(1.f + __expf(-x)); }
;     __device__ __forceinline__ void operator()(const pg8::f32x4 (&acc)[2][2][4][2], const Unit& u, int wr, int wc, int fr, int fq) const {
;         const int row0 = u.pm * BM + wr * 64 + fr, col0 = u.pn * BM + wc * 32 + 8 * fq;
;         v4u ny[2];
; #pragma unroll
;         for (int bj = 0; bj < 2; ++bj) ny[bj] = *(const v4u*)(Y + (size_t)row0 * 512 + col0 + bj * HALF);
; #pragma unroll
;         for (int k = 0; k < 8; ++k) { const int ai = k >> 2, m = k & 3; const int row = row0 + ai * HALF + m * 16; v4u cy[2];
; #pragma unroll
;             for (int bj = 0; bj < 2; ++bj) cy[bj] = ny[bj];
;             if (k < 7) {
; #pragma unroll
;                 for (int bj = 0; bj < 2; ++bj) ny[bj] = *(const v4u*)(Y + (size_t)(row0 + ((k + 1) >> 2) * HALF + ((k + 1) & 3) * 16) * 512 + col0 + bj * HALF); }
; #pragma unroll
;             for (int bj = 0; bj < 2; ++bj) { const int col = col0 + bj * HALF; const v4u yw = cy[bj]; const f32x4 a0 = acc[ai][bj][m][0], a1 = acc[ai][bj][m][1];
;                 v4u w; w.x = cvt_pk_bf16(bflo(yw.x) * sigm(a0[0]), bfhi(yw.x) * sigm(a0[1])); w.y = cvt_pk_bf16(bflo(yw.y) * sigm(a0[2]), bfhi(yw.y) * sigm(a0[3]));
;                 w.z = cvt_pk_bf16(bflo(yw.z) * sigm(a1[0]), bfhi(yw.z) * sigm(a1[1])); w.w = cvt_pk_bf16(bflo(yw.w) * sigm(a1[2]), bfhi(yw.w) * sigm(a1[3]));
;                 *(v4u*)(O + (size_t)row * DM_ + 512 + col) = w; } }
	v_mul_f32_e32 v111, v111, v113
	v_and_b32_e32 v113, 0xffff0000, v123
	v_rcp_f32_e32 v107, v107
	v_exp_f32_e32 v108, v108
	v_mul_f32_e32 v109, 0xbfb8aa3b, v109
	v_mul_f32_e32 v112, v112, v113
	v_exp_f32_e32 v109, v109
	v_mul_f32_e32 v102, 0xbfb8aa3b, v102
	v_cvt_pk_bf16_f32 v111, v111, v112
	v_lshlrev_b32_e32 v112, 16, v124
	v_exp_f32_e32 v102, v102
	v_mul_f32_e32 v103, 0xbfb8aa3b, v103
	v_mul_f32_e32 v106, v106, v112
	v_and_b32_e32 v112, 0xffff0000, v124
	v_exp_f32_e32 v103, v103
	v_mul_f32_e32 v107, v107, v112
	v_cvt_pk_bf16_f32 v112, v106, v107
	v_add_f32_e32 v106, 1.0, v108
	v_rcp_f32_e32 v106, v106
	v_add_f32_e32 v107, 1.0, v109
	v_rcp_f32_e32 v107, v107
	v_add_f32_e32 v102, 1.0, v102
	v_rcp_f32_e32 v102, v102
	v_add_f32_e32 v103, 1.0, v103
	v_lshlrev_b32_e32 v108, 16, v125
	v_rcp_f32_e32 v103, v103
	v_mul_f32_e32 v104, 0xbfb8aa3b, v104
	v_mul_f32_e32 v106, v106, v108
	v_and_b32_e32 v108, 0xffff0000, v125
	v_exp_f32_e32 v104, v104
	v_mul_f32_e32 v105, 0xbfb8aa3b, v105
	v_lshlrev_b64 v[158:159], 11, v[164:165]
	v_mul_f32_e32 v107, v107, v108
	v_lshlrev_b32_e32 v108, 16, v118
	v_exp_f32_e32 v105, v105
	v_cvt_pk_bf16_f32 v113, v106, v107
	v_lshl_add_u64 v[106:107], s[12:13], 0, v[158:159]
	v_mul_f32_e32 v102, v102, v108
	v_and_b32_e32 v108, 0xffff0000, v118
	v_mul_f32_e32 v98, 0xbfb8aa3b, v98
	v_lshl_add_u64 v[106:107], v[106:107], 0, v[146:147]
	v_mul_f32_e32 v103, v103, v108
	v_exp_f32_e32 v98, v98
	v_mul_f32_e32 v99, 0xbfb8aa3b, v99
	global_store_dwordx4 v[106:107], v[110:113], off offset:1024
	v_cvt_pk_bf16_f32 v102, v102, v103
	v_add_f32_e32 v103, 1.0, v104
	v_exp_f32_e32 v99, v99
	v_rcp_f32_e32 v103, v103
	v_add_f32_e32 v104, 1.0, v105
	v_rcp_f32_e32 v104, v104
	v_add_f32_e32 v98, 1.0, v98
	v_lshlrev_b32_e32 v105, 16, v119
	v_rcp_f32_e32 v98, v98
	v_add_f32_e32 v99, 1.0, v99
	v_mul_f32_e32 v100, 0xbfb8aa3b, v100
	v_mul_f32_e32 v103, v103, v105
	v_and_b32_e32 v105, 0xffff0000, v119
	v_rcp_f32_e32 v99, v99
	v_exp_f32_e32 v100, v100
	v_mul_f32_e32 v101, 0xbfb8aa3b, v101
	v_mul_f32_e32 v104, v104, v105
	v_exp_f32_e32 v101, v101
	v_cvt_pk_bf16_f32 v103, v103, v104
	v_lshlrev_b32_e32 v104, 16, v120
	v_mul_f32_e32 v98, v98, v104
	v_and_b32_e32 v104, 0xffff0000, v120
	v_mul_f32_e32 v99, v99, v104
	v_cvt_pk_bf16_f32 v104, v98, v99
	v_add_f32_e32 v98, 1.0, v100
	v_rcp_f32_e32 v98, v98
	v_add_f32_e32 v99, 1.0, v101
	v_rcp_f32_e32 v99, v99
	v_lshlrev_b32_e32 v100, 16, v121
	v_mul_f32_e32 v98, v98, v100
	v_and_b32_e32 v100, 0xffff0000, v121
	v_mul_f32_e32 v99, v99, v100
	v_cvt_pk_bf16_f32 v105, v98, v99
	global_store_dwordx4 v[106:107], v[102:105], off offset:1280
	v_or_b32_e32 v106, 48, v148
	v_ashrrev_i32_e32 v107, 31, v106
	v_lshlrev_b64 v[98:99], 10, v[106:107]
	v_lshl_add_u64 v[98:99], s[8:9], 0, v[98:99]
	v_lshl_add_u64 v[102:103], v[98:99], 0, v[146:147]
	global_load_dwordx4 v[98:101], v[102:103], off offset:256
	s_nop 0
	global_load_dwordx4 v[102:105], v[102:103], off
	v_mul_f32_e32 v94, 0xbfb8aa3b, v94
	v_exp_f32_e32 v94, v94
	v_mul_f32_e32 v95, 0xbfb8aa3b, v95
	v_exp_f32_e32 v95, v95
	v_mul_f32_e32 v96, 0xbfb8aa3b, v96
	v_add_f32_e32 v94, 1.0, v94
	v_rcp_f32_e32 v94, v94
	v_add_f32_e32 v95, 1.0, v95
	v_rcp_f32_e32 v95, v95
	v_exp_f32_e32 v96, v96
	v_mul_f32_e32 v97, 0xbfb8aa3b, v97
	s_waitcnt vmcnt(4)
	v_lshlrev_b32_e32 v110, 16, v126
	v_exp_f32_e32 v97, v97
	v_mul_f32_e32 v94, v94, v110
	v_and_b32_e32 v110, 0xffff0000, v126
	v_mul_f32_e32 v90, 0xbfb8aa3b, v90
	v_mul_f32_e32 v95, v95, v110
	v_exp_f32_e32 v90, v90
	v_mul_f32_e32 v91, 0xbfb8aa3b, v91
	v_cvt_pk_bf16_f32 v94, v94, v95
	v_add_f32_e32 v95, 1.0, v96
	v_exp_f32_e32 v91, v91
	v_rcp_f32_e32 v95, v95
	v_add_f32_e32 v96, 1.0, v97
	v_rcp_f32_e32 v96, v96
	v_add_f32_e32 v90, 1.0, v90
	v_lshlrev_b32_e32 v97, 16, v127
	v_rcp_f32_e32 v90, v90
	v_add_f32_e32 v91, 1.0, v91
	v_mul_f32_e32 v92, 0xbfb8aa3b, v92
	v_mul_f32_e32 v95, v95, v97
	v_and_b32_e32 v97, 0xffff0000, v127
	v_rcp_f32_e32 v91, v91
	v_exp_f32_e32 v92, v92
	v_mul_f32_e32 v93, 0xbfb8aa3b, v93
	v_mul_f32_e32 v96, v96, v97
	v_exp_f32_e32 v93, v93
	v_mul_f32_e32 v86, 0xbfb8aa3b, v86
	v_cvt_pk_bf16_f32 v95, v95, v96
	v_lshlrev_b32_e32 v96, 16, v128
	v_exp_f32_e32 v86, v86
	v_mul_f32_e32 v87, 0xbfb8aa3b, v87
	v_mul_f32_e32 v90, v90, v96
	v_and_b32_e32 v96, 0xffff0000, v128
	v_exp_f32_e32 v87, v87
	v_mul_f32_e32 v91, v91, v96
	v_cvt_pk_bf16_f32 v96, v90, v91
	v_add_f32_e32 v90, 1.0, v92
	v_rcp_f32_e32 v90, v90
	v_add_f32_e32 v91, 1.0, v93
	v_rcp_f32_e32 v91, v91
	v_add_f32_e32 v86, 1.0, v86
	v_rcp_f32_e32 v86, v86
	v_add_f32_e32 v87, 1.0, v87
	v_lshlrev_b32_e32 v92, 16, v129
	v_rcp_f32_e32 v87, v87
	v_mul_f32_e32 v88, 0xbfb8aa3b, v88
	v_mul_f32_e32 v90, v90, v92
	v_and_b32_e32 v92, 0xffff0000, v129
	v_exp_f32_e32 v88, v88
	v_mul_f32_e32 v89, 0xbfb8aa3b, v89
	v_lshlrev_b64 v[108:109], 11, v[156:157]
	v_mul_f32_e32 v91, v91, v92
	v_lshlrev_b32_e32 v92, 16, v114
	v_exp_f32_e32 v89, v89
	v_cvt_pk_bf16_f32 v97, v90, v91
	v_lshl_add_u64 v[90:91], s[12:13], 0, v[108:109]
	v_mul_f32_e32 v86, v86, v92
	v_and_b32_e32 v92, 0xffff0000, v114
	v_mul_f32_e32 v82, 0xbfb8aa3b, v82
	v_lshl_add_u64 v[90:91], v[90:91], 0, v[146:147]
	v_mul_f32_e32 v87, v87, v92
	v_exp_f32_e32 v82, v82
	v_mul_f32_e32 v83, 0xbfb8aa3b, v83
	global_store_dwordx4 v[90:91], v[94:97], off offset:1024
	v_cvt_pk_bf16_f32 v86, v86, v87
	v_add_f32_e32 v87, 1.0, v88
	v_exp_f32_e32 v83, v83
	v_rcp_f32_e32 v87, v87
	v_add_f32_e32 v88, 1.0, v89
	v_rcp_f32_e32 v88, v88
	v_add_f32_e32 v82, 1.0, v82
	v_lshlrev_b32_e32 v89, 16, v115
	v_rcp_f32_e32 v82, v82
	v_add_f32_e32 v83, 1.0, v83
	v_mul_f32_e32 v84, 0xbfb8aa3b, v84
	v_mul_f32_e32 v87, v87, v89
	v_and_b32_e32 v89, 0xffff0000, v115
	v_rcp_f32_e32 v83, v83
	v_exp_f32_e32 v84, v84
	v_mul_f32_e32 v85, 0xbfb8aa3b, v85
	v_mul_f32_e32 v88, v88, v89
	v_exp_f32_e32 v85, v85
	v_cvt_pk_bf16_f32 v87, v87, v88
	v_lshlrev_b32_e32 v88, 16, v116
	v_mul_f32_e32 v82, v82, v88
	v_and_b32_e32 v88, 0xffff0000, v116
	v_mul_f32_e32 v78, 0xbfb8aa3b, v78
	v_mul_f32_e32 v83, v83, v88
	v_cvt_pk_bf16_f32 v88, v82, v83
	v_add_f32_e32 v82, 1.0, v84
	v_exp_f32_e32 v78, v78
	v_mul_f32_e32 v79, 0xbfb8aa3b, v79
	v_rcp_f32_e32 v82, v82
	v_add_f32_e32 v83, 1.0, v85
	v_exp_f32_e32 v79, v79
	v_rcp_f32_e32 v83, v83
	v_lshlrev_b32_e32 v84, 16, v117
	v_add_f32_e32 v78, 1.0, v78
	v_mul_f32_e32 v82, v82, v84
	v_and_b32_e32 v84, 0xffff0000, v117
	v_rcp_f32_e32 v78, v78
	v_add_f32_e32 v79, 1.0, v79
	v_mul_f32_e32 v83, v83, v84
	v_cvt_pk_bf16_f32 v89, v82, v83
	global_store_dwordx4 v[90:91], v[86:89], off offset:1280
	v_add_u32_e32 v90, 0x80, v148
	v_rcp_f32_e32 v79, v79
	v_mul_f32_e32 v80, 0xbfb8aa3b, v80
	v_ashrrev_i32_e32 v91, 31, v90
	v_exp_f32_e32 v80, v80
	v_mul_f32_e32 v81, 0xbfb8aa3b, v81
	v_lshlrev_b64 v[82:83], 10, v[90:91]
	s_waitcnt vmcnt(2)
; __device__ __forceinline__ unsigned cvt_pk_bf16(float lo, float hi) { unsigned r; asm volatile("v_cvt_pk_bf16_f32 %0, %1, %2" : "=v"(r) : "v"(lo), "v"(hi)); return r; }
; __device__ __forceinline__ float bflo(unsigned w) { return __uint_as_float(w << 16); }
; __device__ __forceinline__ float bfhi(unsigned w) { return __uint_as_float(w & 0xffff0000u); }
; __device__ __forceinline__ float sigm(float x) { return __builtin_amdgcn_rcpf(1.f + __expf(-x)); }
;     __device__ __forceinline__ void operator()(const pg8::f32x4 (&acc)[2][2][4][2], const Unit& u, int wr, int wc, int fr, int fq) const {
;         const int row0 = u.pm * BM + wr * 64 + fr, col0 = u.pn * BM + wc * 32 + 8 * fq;
;         v4u ny[2];
; #pragma unroll
;         for (int bj = 0; bj < 2; ++bj) ny[bj] = *(const v4u*)(Y + (size_t)row0 * 512 + col0 + bj * HALF);
; #pragma unroll
;         for (int k = 0; k < 8; ++k) { const int ai = k >> 2, m = k & 3; const int row = row0 + ai * HALF + m * 16; v4u cy[2];
; #pragma unroll
;             for (int bj = 0; bj < 2; ++bj) cy[bj] = ny[bj];
;             if (k < 7) {
; #pragma unroll
;                 for (int bj = 0; bj < 2; ++bj) ny[bj] = *(const v4u*)(Y + (size_t)(row0 + ((k + 1) >> 2) * HALF + ((k + 1) & 3) * 16) * 512 + col0 + bj * HALF); }
; #pragma unroll
;             for (int bj = 0; bj < 2; ++bj) { const int col = col0 + bj * HALF; const v4u yw = cy[bj]; const f32x4 a0 = acc[ai][bj][m][0], a1 = acc[ai][bj][m][1];
;                 v4u w; w.x = cvt_pk_bf16(bflo(yw.x) * sigm(a0[0]), bfhi(yw.x) * sigm(a0[1])); w.y = cvt_pk_bf16(bflo(yw.y) * sigm(a0[2]), bfhi(yw.y) * sigm(a0[3]));
;                 w.z = cvt_pk_bf16(bflo(yw.z) * sigm(a1[0]), bfhi(yw.z) * sigm(a1[1])); w.w = cvt_pk_bf16(bflo(yw.w) * sigm(a1[2]), bfhi(yw.w) * sigm(a1[3]));
;                 *(v4u*)(O + (size_t)row * DM_ + 512 + col) = w; } }
	v_lshlrev_b32_e32 v94, 16, v102
	v_exp_f32_e32 v81, v81
	v_lshl_add_u64 v[82:83], s[8:9], 0, v[82:83]
	v_mul_f32_e32 v78, v78, v94
	v_and_b32_e32 v94, 0xffff0000, v102
	v_mul_f32_e32 v74, 0xbfb8aa3b, v74
	v_lshl_add_u64 v[86:87], v[82:83], 0, v[146:147]
	v_mul_f32_e32 v79, v79, v94
	v_exp_f32_e32 v74, v74
	v_mul_f32_e32 v75, 0xbfb8aa3b, v75
	global_load_dwordx4 v[82:85], v[86:87], off offset:256
	s_nop 0
	global_load_dwordx4 v[86:89], v[86:87], off
	v_cvt_pk_bf16_f32 v78, v78, v79
	v_add_f32_e32 v79, 1.0, v80
	v_exp_f32_e32 v75, v75
	v_rcp_f32_e32 v79, v79
	v_add_f32_e32 v80, 1.0, v81
	v_rcp_f32_e32 v80, v80
	v_add_f32_e32 v74, 1.0, v74
	v_lshlrev_b32_e32 v81, 16, v103
	v_rcp_f32_e32 v74, v74
	v_add_f32_e32 v75, 1.0, v75
	v_mul_f32_e32 v76, 0xbfb8aa3b, v76
	v_mul_f32_e32 v79, v79, v81
	v_and_b32_e32 v81, 0xffff0000, v103
	v_rcp_f32_e32 v75, v75
	v_exp_f32_e32 v76, v76
	v_mul_f32_e32 v77, 0xbfb8aa3b, v77
	v_mul_f32_e32 v80, v80, v81
	v_exp_f32_e32 v77, v77
	v_mul_f32_e32 v70, 0xbfb8aa3b, v70
	v_cvt_pk_bf16_f32 v79, v79, v80
	v_lshlrev_b32_e32 v80, 16, v104
	v_exp_f32_e32 v70, v70
	v_mul_f32_e32 v71, 0xbfb8aa3b, v71
	v_mul_f32_e32 v74, v74, v80
	v_and_b32_e32 v80, 0xffff0000, v104
	v_exp_f32_e32 v71, v71
	v_mul_f32_e32 v75, v75, v80
	v_cvt_pk_bf16_f32 v80, v74, v75
	v_add_f32_e32 v74, 1.0, v76
	v_rcp_f32_e32 v74, v74
	v_add_f32_e32 v75, 1.0, v77
	v_rcp_f32_e32 v75, v75
	v_add_f32_e32 v70, 1.0, v70
	v_rcp_f32_e32 v70, v70
	v_add_f32_e32 v71, 1.0, v71
	v_lshlrev_b32_e32 v76, 16, v105
	v_rcp_f32_e32 v71, v71
	v_mul_f32_e32 v72, 0xbfb8aa3b, v72
	v_mul_f32_e32 v74, v74, v76
	v_and_b32_e32 v76, 0xffff0000, v105
	v_exp_f32_e32 v72, v72
	v_mul_f32_e32 v73, 0xbfb8aa3b, v73
	v_lshlrev_b64 v[92:93], 11, v[106:107]
	v_mul_f32_e32 v75, v75, v76
	v_lshlrev_b32_e32 v76, 16, v98
	v_exp_f32_e32 v73, v73
	v_cvt_pk_bf16_f32 v81, v74, v75
	v_lshl_add_u64 v[74:75], s[12:13], 0, v[92:93]
	v_mul_f32_e32 v70, v70, v76
	v_and_b32_e32 v76, 0xffff0000, v98
	v_mul_f32_e32 v66, 0xbfb8aa3b, v66
	v_lshl_add_u64 v[74:75], v[74:75], 0, v[146:147]
	v_mul_f32_e32 v71, v71, v76
	v_exp_f32_e32 v66, v66
	v_mul_f32_e32 v67, 0xbfb8aa3b, v67
	global_store_dwordx4 v[74:75], v[78:81], off offset:1024
	v_cvt_pk_bf16_f32 v70, v70, v71
	v_add_f32_e32 v71, 1.0, v72
	v_exp_f32_e32 v67, v67
	v_rcp_f32_e32 v71, v71
	v_add_f32_e32 v72, 1.0, v73
	v_rcp_f32_e32 v72, v72
	v_add_f32_e32 v66, 1.0, v66
	v_lshlrev_b32_e32 v73, 16, v99
	v_rcp_f32_e32 v66, v66
	v_add_f32_e32 v67, 1.0, v67
	v_mul_f32_e32 v68, 0xbfb8aa3b, v68
	v_mul_f32_e32 v71, v71, v73
	v_and_b32_e32 v73, 0xffff0000, v99
	v_rcp_f32_e32 v67, v67
	v_exp_f32_e32 v68, v68
	v_mul_f32_e32 v69, 0xbfb8aa3b, v69
	v_mul_f32_e32 v72, v72, v73
	v_exp_f32_e32 v69, v69
	v_cvt_pk_bf16_f32 v71, v71, v72
	v_lshlrev_b32_e32 v72, 16, v100
	v_mul_f32_e32 v66, v66, v72
	v_and_b32_e32 v72, 0xffff0000, v100
	v_mul_f32_e32 v67, v67, v72
	v_cvt_pk_bf16_f32 v72, v66, v67
	v_add_f32_e32 v66, 1.0, v68
	v_rcp_f32_e32 v66, v66
	v_add_f32_e32 v67, 1.0, v69
	v_rcp_f32_e32 v67, v67
	v_lshlrev_b32_e32 v68, 16, v101
	v_mul_f32_e32 v66, v66, v68
	v_and_b32_e32 v68, 0xffff0000, v101
	v_mul_f32_e32 v67, v67, v68
	v_cvt_pk_bf16_f32 v73, v66, v67
	global_store_dwordx4 v[74:75], v[70:73], off offset:1280
	v_add_u32_e32 v74, 0x90, v148
	v_ashrrev_i32_e32 v75, 31, v74
	v_lshlrev_b64 v[66:67], 10, v[74:75]
	v_lshl_add_u64 v[66:67], s[8:9], 0, v[66:67]
	v_lshl_add_u64 v[70:71], v[66:67], 0, v[146:147]
	global_load_dwordx4 v[66:69], v[70:71], off offset:256
	s_nop 0
	global_load_dwordx4 v[70:73], v[70:71], off
	v_mul_f32_e32 v62, 0xbfb8aa3b, v62
	v_exp_f32_e32 v62, v62
	v_mul_f32_e32 v63, 0xbfb8aa3b, v63
	v_exp_f32_e32 v63, v63
	v_mul_f32_e32 v64, 0xbfb8aa3b, v64
	v_add_f32_e32 v62, 1.0, v62
	v_rcp_f32_e32 v62, v62
	v_add_f32_e32 v63, 1.0, v63
	v_rcp_f32_e32 v63, v63
	v_exp_f32_e32 v64, v64
	v_mul_f32_e32 v65, 0xbfb8aa3b, v65
	s_waitcnt vmcnt(4)
	v_lshlrev_b32_e32 v78, 16, v86
	v_exp_f32_e32 v65, v65
	v_mul_f32_e32 v62, v62, v78
	v_and_b32_e32 v78, 0xffff0000, v86
	v_mul_f32_e32 v58, 0xbfb8aa3b, v58
	v_mul_f32_e32 v63, v63, v78
	v_exp_f32_e32 v58, v58
	v_mul_f32_e32 v59, 0xbfb8aa3b, v59
	v_cvt_pk_bf16_f32 v62, v62, v63
	v_add_f32_e32 v63, 1.0, v64
	v_exp_f32_e32 v59, v59
	v_rcp_f32_e32 v63, v63
	v_add_f32_e32 v64, 1.0, v65
	v_rcp_f32_e32 v64, v64
	v_add_f32_e32 v58, 1.0, v58
	v_lshlrev_b32_e32 v65, 16, v87
	v_rcp_f32_e32 v58, v58
	v_add_f32_e32 v59, 1.0, v59
	v_mul_f32_e32 v60, 0xbfb8aa3b, v60
	v_mul_f32_e32 v63, v63, v65
	v_and_b32_e32 v65, 0xffff0000, v87
	v_rcp_f32_e32 v59, v59
	v_exp_f32_e32 v60, v60
	v_mul_f32_e32 v61, 0xbfb8aa3b, v61
	v_mul_f32_e32 v64, v64, v65
	v_exp_f32_e32 v61, v61
	v_mul_f32_e32 v54, 0xbfb8aa3b, v54
	v_cvt_pk_bf16_f32 v63, v63, v64
	v_lshlrev_b32_e32 v64, 16, v88
	v_exp_f32_e32 v54, v54
	v_mul_f32_e32 v55, 0xbfb8aa3b, v55
	v_mul_f32_e32 v58, v58, v64
	v_and_b32_e32 v64, 0xffff0000, v88
	v_exp_f32_e32 v55, v55
	v_mul_f32_e32 v59, v59, v64
	v_cvt_pk_bf16_f32 v64, v58, v59
	v_add_f32_e32 v58, 1.0, v60
	v_rcp_f32_e32 v58, v58
	v_add_f32_e32 v59, 1.0, v61
	v_rcp_f32_e32 v59, v59
	v_add_f32_e32 v54, 1.0, v54
	v_rcp_f32_e32 v54, v54
	v_add_f32_e32 v55, 1.0, v55
	v_lshlrev_b32_e32 v60, 16, v89
	v_rcp_f32_e32 v55, v55
	v_mul_f32_e32 v56, 0xbfb8aa3b, v56
	v_mul_f32_e32 v58, v58, v60
	v_and_b32_e32 v60, 0xffff0000, v89
	v_exp_f32_e32 v56, v56
	v_mul_f32_e32 v57, 0xbfb8aa3b, v57
	v_lshlrev_b64 v[76:77], 11, v[90:91]
	v_mul_f32_e32 v59, v59, v60
	v_lshlrev_b32_e32 v60, 16, v82
	v_exp_f32_e32 v57, v57
	v_cvt_pk_bf16_f32 v65, v58, v59
	v_lshl_add_u64 v[58:59], s[12:13], 0, v[76:77]
	v_mul_f32_e32 v54, v54, v60
	v_and_b32_e32 v60, 0xffff0000, v82
; __device__ __forceinline__ unsigned cvt_pk_bf16(float lo, float hi) { unsigned r; asm volatile("v_cvt_pk_bf16_f32 %0, %1, %2" : "=v"(r) : "v"(lo), "v"(hi)); return r; }
; __device__ __forceinline__ float bflo(unsigned w) { return __uint_as_float(w << 16); }
; __device__ __forceinline__ float bfhi(unsigned w) { return __uint_as_float(w & 0xffff0000u); }
; __device__ __forceinline__ float sigm(float x) { return __builtin_amdgcn_rcpf(1.f + __expf(-x)); }
;     __device__ __forceinline__ void operator()(const pg8::f32x4 (&acc)[2][2][4][2], const Unit& u, int wr, int wc, int fr, int fq) const {
;         const int row0 = u.pm * BM + wr * 64 + fr, col0 = u.pn * BM + wc * 32 + 8 * fq;
;         v4u ny[2];
; #pragma unroll
;         for (int bj = 0; bj < 2; ++bj) ny[bj] = *(const v4u*)(Y + (size_t)row0 * 512 + col0 + bj * HALF);
; #pragma unroll
;         for (int k = 0; k < 8; ++k) { const int ai = k >> 2, m = k & 3; const int row = row0 + ai * HALF + m * 16; v4u cy[2];
; #pragma unroll
;             for (int bj = 0; bj < 2; ++bj) cy[bj] = ny[bj];
;             if (k < 7) {
; #pragma unroll
;                 for (int bj = 0; bj < 2; ++bj) ny[bj] = *(const v4u*)(Y + (size_t)(row0 + ((k + 1) >> 2) * HALF + ((k + 1) & 3) * 16) * 512 + col0 + bj * HALF); }
; #pragma unroll
;             for (int bj = 0; bj < 2; ++bj) { const int col = col0 + bj * HALF; const v4u yw = cy[bj]; const f32x4 a0 = acc[ai][bj][m][0], a1 = acc[ai][bj][m][1];
;                 v4u w; w.x = cvt_pk_bf16(bflo(yw.x) * sigm(a0[0]), bfhi(yw.x) * sigm(a0[1])); w.y = cvt_pk_bf16(bflo(yw.y) * sigm(a0[2]), bfhi(yw.y) * sigm(a0[3]));
;                 w.z = cvt_pk_bf16(bflo(yw.z) * sigm(a1[0]), bfhi(yw.z) * sigm(a1[1])); w.w = cvt_pk_bf16(bflo(yw.w) * sigm(a1[2]), bfhi(yw.w) * sigm(a1[3]));
;                 *(v4u*)(O + (size_t)row * DM_ + 512 + col) = w; } }
	v_mul_f32_e32 v50, 0xbfb8aa3b, v50
	v_lshl_add_u64 v[58:59], v[58:59], 0, v[146:147]
	v_mul_f32_e32 v55, v55, v60
	v_exp_f32_e32 v50, v50
	v_mul_f32_e32 v51, 0xbfb8aa3b, v51
	global_store_dwordx4 v[58:59], v[62:65], off offset:1024
	v_cvt_pk_bf16_f32 v54, v54, v55
	v_add_f32_e32 v55, 1.0, v56
	v_exp_f32_e32 v51, v51
	v_rcp_f32_e32 v55, v55
	v_add_f32_e32 v56, 1.0, v57
	v_rcp_f32_e32 v56, v56
	v_add_f32_e32 v50, 1.0, v50
	v_lshlrev_b32_e32 v57, 16, v83
	v_rcp_f32_e32 v50, v50
	v_add_f32_e32 v51, 1.0, v51
	v_mul_f32_e32 v52, 0xbfb8aa3b, v52
	v_mul_f32_e32 v55, v55, v57
	v_and_b32_e32 v57, 0xffff0000, v83
	v_rcp_f32_e32 v51, v51
	v_exp_f32_e32 v52, v52
	v_mul_f32_e32 v53, 0xbfb8aa3b, v53
	v_mul_f32_e32 v56, v56, v57
	v_exp_f32_e32 v53, v53
	v_cvt_pk_bf16_f32 v55, v55, v56
	v_lshlrev_b32_e32 v56, 16, v84
	v_mul_f32_e32 v50, v50, v56
	v_and_b32_e32 v56, 0xffff0000, v84
	v_mul_f32_e32 v46, 0xbfb8aa3b, v46
	v_mul_f32_e32 v51, v51, v56
	v_cvt_pk_bf16_f32 v56, v50, v51
	v_add_f32_e32 v50, 1.0, v52
	v_exp_f32_e32 v46, v46
	v_mul_f32_e32 v47, 0xbfb8aa3b, v47
	v_rcp_f32_e32 v50, v50
	v_add_f32_e32 v51, 1.0, v53
	v_exp_f32_e32 v47, v47
	v_rcp_f32_e32 v51, v51
	v_lshlrev_b32_e32 v52, 16, v85
	v_add_f32_e32 v46, 1.0, v46
	v_mul_f32_e32 v50, v50, v52
	v_and_b32_e32 v52, 0xffff0000, v85
	v_rcp_f32_e32 v46, v46
	v_add_f32_e32 v47, 1.0, v47
	v_mul_f32_e32 v51, v51, v52
	v_cvt_pk_bf16_f32 v57, v50, v51
	global_store_dwordx4 v[58:59], v[54:57], off offset:1280
	v_add_u32_e32 v58, 0xa0, v148
	v_rcp_f32_e32 v47, v47
	v_mul_f32_e32 v48, 0xbfb8aa3b, v48
	v_ashrrev_i32_e32 v59, 31, v58
	v_exp_f32_e32 v48, v48
	v_mul_f32_e32 v49, 0xbfb8aa3b, v49
	v_lshlrev_b64 v[50:51], 10, v[58:59]
	s_waitcnt vmcnt(2)
	v_lshlrev_b32_e32 v62, 16, v70
	v_exp_f32_e32 v49, v49
	v_lshl_add_u64 v[50:51], s[8:9], 0, v[50:51]
	v_mul_f32_e32 v46, v46, v62
	v_and_b32_e32 v62, 0xffff0000, v70
	v_mul_f32_e32 v42, 0xbfb8aa3b, v42
	v_lshl_add_u64 v[54:55], v[50:51], 0, v[146:147]
	v_mul_f32_e32 v47, v47, v62
	v_exp_f32_e32 v42, v42
	v_mul_f32_e32 v43, 0xbfb8aa3b, v43
	global_load_dwordx4 v[50:53], v[54:55], off offset:256
	s_nop 0
	global_load_dwordx4 v[54:57], v[54:55], off
	v_cvt_pk_bf16_f32 v46, v46, v47
	v_add_f32_e32 v47, 1.0, v48
	v_exp_f32_e32 v43, v43
	v_rcp_f32_e32 v47, v47
	v_add_f32_e32 v48, 1.0, v49
	v_rcp_f32_e32 v48, v48
	v_add_f32_e32 v42, 1.0, v42
	v_lshlrev_b32_e32 v49, 16, v71
	v_rcp_f32_e32 v42, v42
	v_add_f32_e32 v43, 1.0, v43
	v_mul_f32_e32 v44, 0xbfb8aa3b, v44
	v_mul_f32_e32 v47, v47, v49
	v_and_b32_e32 v49, 0xffff0000, v71
	v_rcp_f32_e32 v43, v43
	v_exp_f32_e32 v44, v44
	v_mul_f32_e32 v45, 0xbfb8aa3b, v45
	v_mul_f32_e32 v48, v48, v49
	v_exp_f32_e32 v45, v45
	v_mul_f32_e32 v38, 0xbfb8aa3b, v38
	v_cvt_pk_bf16_f32 v47, v47, v48
	v_lshlrev_b32_e32 v48, 16, v72
	v_exp_f32_e32 v38, v38
	v_mul_f32_e32 v39, 0xbfb8aa3b, v39
	v_mul_f32_e32 v42, v42, v48
	v_and_b32_e32 v48, 0xffff0000, v72
	v_exp_f32_e32 v39, v39
	v_mul_f32_e32 v43, v43, v48
	v_cvt_pk_bf16_f32 v48, v42, v43
	v_add_f32_e32 v42, 1.0, v44
	v_rcp_f32_e32 v42, v42
	v_add_f32_e32 v43, 1.0, v45
	v_rcp_f32_e32 v43, v43
	v_add_f32_e32 v38, 1.0, v38
	v_rcp_f32_e32 v38, v38
	v_add_f32_e32 v39, 1.0, v39
	v_lshlrev_b32_e32 v44, 16, v73
	v_rcp_f32_e32 v39, v39
	v_mul_f32_e32 v40, 0xbfb8aa3b, v40
	v_mul_f32_e32 v42, v42, v44
	v_and_b32_e32 v44, 0xffff0000, v73
	v_exp_f32_e32 v40, v40
	v_mul_f32_e32 v41, 0xbfb8aa3b, v41
	v_lshlrev_b64 v[60:61], 11, v[74:75]
	v_mul_f32_e32 v43, v43, v44
	v_lshlrev_b32_e32 v44, 16, v66
	v_exp_f32_e32 v41, v41
	v_cvt_pk_bf16_f32 v49, v42, v43
	v_lshl_add_u64 v[42:43], s[12:13], 0, v[60:61]
	v_mul_f32_e32 v38, v38, v44
	v_and_b32_e32 v44, 0xffff0000, v66
	v_mul_f32_e32 v34, 0xbfb8aa3b, v34
	v_lshl_add_u64 v[42:43], v[42:43], 0, v[146:147]
	v_mul_f32_e32 v39, v39, v44
	v_exp_f32_e32 v34, v34
	v_mul_f32_e32 v35, 0xbfb8aa3b, v35
	global_store_dwordx4 v[42:43], v[46:49], off offset:1024
	v_cvt_pk_bf16_f32 v38, v38, v39
	v_add_f32_e32 v39, 1.0, v40
	v_exp_f32_e32 v35, v35
	v_rcp_f32_e32 v39, v39
	v_add_f32_e32 v40, 1.0, v41
	v_rcp_f32_e32 v40, v40
	v_add_f32_e32 v34, 1.0, v34
	v_lshlrev_b32_e32 v41, 16, v67
	v_rcp_f32_e32 v34, v34
	v_add_f32_e32 v35, 1.0, v35
	v_mul_f32_e32 v36, 0xbfb8aa3b, v36
	v_mul_f32_e32 v39, v39, v41
	v_and_b32_e32 v41, 0xffff0000, v67
	v_rcp_f32_e32 v35, v35
	v_exp_f32_e32 v36, v36
	v_mul_f32_e32 v37, 0xbfb8aa3b, v37
	v_mul_f32_e32 v40, v40, v41
	v_exp_f32_e32 v37, v37
	v_cvt_pk_bf16_f32 v39, v39, v40
	v_lshlrev_b32_e32 v40, 16, v68
	v_mul_f32_e32 v34, v34, v40
	v_and_b32_e32 v40, 0xffff0000, v68
	v_mul_f32_e32 v35, v35, v40
	v_cvt_pk_bf16_f32 v40, v34, v35
	v_add_f32_e32 v34, 1.0, v36
	v_rcp_f32_e32 v34, v34
	v_add_f32_e32 v35, 1.0, v37
	v_rcp_f32_e32 v35, v35
	v_lshlrev_b32_e32 v36, 16, v69
	v_mul_f32_e32 v34, v34, v36
	v_and_b32_e32 v36, 0xffff0000, v69
	v_mul_f32_e32 v35, v35, v36
	v_cvt_pk_bf16_f32 v41, v34, v35
	global_store_dwordx4 v[42:43], v[38:41], off offset:1280
	v_add_u32_e32 v42, 0xb0, v148
	v_ashrrev_i32_e32 v43, 31, v42
	v_lshlrev_b64 v[34:35], 10, v[42:43]
	v_lshl_add_u64 v[34:35], s[8:9], 0, v[34:35]
	v_lshl_add_u64 v[38:39], v[34:35], 0, v[146:147]
	global_load_dwordx4 v[34:37], v[38:39], off offset:256
	s_nop 0
	global_load_dwordx4 v[38:41], v[38:39], off
	v_mul_f32_e32 v30, 0xbfb8aa3b, v30
	v_exp_f32_e32 v30, v30
	v_mul_f32_e32 v31, 0xbfb8aa3b, v31
	v_exp_f32_e32 v31, v31
	v_mul_f32_e32 v32, 0xbfb8aa3b, v32
	v_add_f32_e32 v30, 1.0, v30
	v_rcp_f32_e32 v30, v30
	v_add_f32_e32 v31, 1.0, v31
	v_rcp_f32_e32 v31, v31
	v_exp_f32_e32 v32, v32
	v_mul_f32_e32 v33, 0xbfb8aa3b, v33
	s_waitcnt vmcnt(4)
; __device__ __forceinline__ unsigned cvt_pk_bf16(float lo, float hi) { unsigned r; asm volatile("v_cvt_pk_bf16_f32 %0, %1, %2" : "=v"(r) : "v"(lo), "v"(hi)); return r; }
; #define PG8_BAR __builtin_amdgcn_s_barrier()
; __device__ __forceinline__ float bflo(unsigned w) { return __uint_as_float(w << 16); }
; __device__ __forceinline__ float bfhi(unsigned w) { return __uint_as_float(w & 0xffff0000u); }
; __device__ __forceinline__ float sigm(float x) { return __builtin_amdgcn_rcpf(1.f + __expf(-x)); }
; template <class Epi, class Sched, bool ALIGN_EPI = false, bool SP2 = false>
; __device__ __forceinline__ void gemm_phase(PG8_LAS unsigned char* lds, const Gemm g, const Sched& S, const Epi& E) {
;     ...
;         if constexpr (ALIGN_EPI) { if (wr == 0) PG8_BAR; }
;         if constexpr (!Epi::AFTER_DRAIN) { E(acc, cur, wr, wc, fr, fq); S.done(cur); }
;         if (!has_next) break;
; #pragma unroll
;         for (int a = 0; a < 2; ++a)
; #pragma unroll
;             for (int b = 0; b < 2; ++b)
; #pragma unroll
;                 for (int m = 0; m < 4; ++m)
; #pragma unroll
;                     for (int n = 0; n < 2; ++n) acc[a][b][m][n] = (f32x4){0.f, 0.f, 0.f, 0.f};
;         cur = nxt; cA = nA; cB = nB; ++ui;
;         if constexpr (ALIGN_EPI) { if (wr == 1) PG8_BAR; }
;     __device__ __forceinline__ void operator()(const pg8::f32x4 (&acc)[2][2][4][2], const Unit& u, int wr, int wc, int fr, int fq) const {
;     ...
;             for (int bj = 0; bj < 2; ++bj) { const int col = col0 + bj * HALF; const v4u yw = cy[bj]; const f32x4 a0 = acc[ai][bj][m][0], a1 = acc[ai][bj][m][1];
;                 v4u w; w.x = cvt_pk_bf16(bflo(yw.x) * sigm(a0[0]), bfhi(yw.x) * sigm(a0[1])); w.y = cvt_pk_bf16(bflo(yw.y) * sigm(a0[2]), bfhi(yw.y) * sigm(a0[3]));
;                 w.z = cvt_pk_bf16(bflo(yw.z) * sigm(a1[0]), bfhi(yw.z) * sigm(a1[1])); w.w = cvt_pk_bf16(bflo(yw.w) * sigm(a1[2]), bfhi(yw.w) * sigm(a1[3]));
;                 *(v4u*)(O + (size_t)row * DM_ + 512 + col) = w; } }
	v_lshlrev_b32_e32 v46, 16, v54
	v_exp_f32_e32 v33, v33
	v_mul_f32_e32 v30, v30, v46
	v_and_b32_e32 v46, 0xffff0000, v54
	v_mul_f32_e32 v26, 0xbfb8aa3b, v26
	v_mul_f32_e32 v31, v31, v46
	v_exp_f32_e32 v26, v26
	v_mul_f32_e32 v27, 0xbfb8aa3b, v27
	v_cvt_pk_bf16_f32 v30, v30, v31
	v_add_f32_e32 v31, 1.0, v32
	v_exp_f32_e32 v27, v27
	v_rcp_f32_e32 v31, v31
	v_add_f32_e32 v32, 1.0, v33
	v_rcp_f32_e32 v32, v32
	v_add_f32_e32 v26, 1.0, v26
	v_lshlrev_b32_e32 v33, 16, v55
	v_rcp_f32_e32 v26, v26
	v_add_f32_e32 v27, 1.0, v27
	v_mul_f32_e32 v28, 0xbfb8aa3b, v28
	v_mul_f32_e32 v31, v31, v33
	v_and_b32_e32 v33, 0xffff0000, v55
	v_rcp_f32_e32 v27, v27
	v_exp_f32_e32 v28, v28
	v_mul_f32_e32 v29, 0xbfb8aa3b, v29
	v_mul_f32_e32 v32, v32, v33
	v_exp_f32_e32 v29, v29
	v_mul_f32_e32 v22, 0xbfb8aa3b, v22
	v_cvt_pk_bf16_f32 v31, v31, v32
	v_lshlrev_b32_e32 v32, 16, v56
	v_exp_f32_e32 v22, v22
	v_mul_f32_e32 v23, 0xbfb8aa3b, v23
	v_mul_f32_e32 v26, v26, v32
	v_and_b32_e32 v32, 0xffff0000, v56
	v_exp_f32_e32 v23, v23
	v_mul_f32_e32 v27, v27, v32
	v_cvt_pk_bf16_f32 v32, v26, v27
	v_add_f32_e32 v26, 1.0, v28
	v_rcp_f32_e32 v26, v26
	v_add_f32_e32 v27, 1.0, v29
	v_rcp_f32_e32 v27, v27
	v_add_f32_e32 v22, 1.0, v22
	v_rcp_f32_e32 v22, v22
	v_add_f32_e32 v23, 1.0, v23
	v_lshlrev_b32_e32 v28, 16, v57
	v_rcp_f32_e32 v23, v23
	v_mul_f32_e32 v24, 0xbfb8aa3b, v24
	v_mul_f32_e32 v26, v26, v28
	v_and_b32_e32 v28, 0xffff0000, v57
	v_exp_f32_e32 v24, v24
	v_mul_f32_e32 v25, 0xbfb8aa3b, v25
	v_lshlrev_b64 v[44:45], 11, v[58:59]
	v_mul_f32_e32 v27, v27, v28
	v_lshlrev_b32_e32 v28, 16, v50
	v_exp_f32_e32 v25, v25
	v_cvt_pk_bf16_f32 v33, v26, v27
	v_lshl_add_u64 v[26:27], s[12:13], 0, v[44:45]
	v_mul_f32_e32 v22, v22, v28
	v_and_b32_e32 v28, 0xffff0000, v50
	v_mul_f32_e32 v18, 0xbfb8aa3b, v18
	v_lshl_add_u64 v[26:27], v[26:27], 0, v[146:147]
	v_mul_f32_e32 v23, v23, v28
	v_exp_f32_e32 v18, v18
	v_mul_f32_e32 v19, 0xbfb8aa3b, v19
	global_store_dwordx4 v[26:27], v[30:33], off offset:1024
	v_cvt_pk_bf16_f32 v22, v22, v23
	v_add_f32_e32 v23, 1.0, v24
	v_exp_f32_e32 v19, v19
	v_rcp_f32_e32 v23, v23
	v_add_f32_e32 v24, 1.0, v25
	v_rcp_f32_e32 v24, v24
	v_add_f32_e32 v18, 1.0, v18
	v_lshlrev_b32_e32 v25, 16, v51
	v_rcp_f32_e32 v18, v18
	v_add_f32_e32 v19, 1.0, v19
	v_mul_f32_e32 v20, 0xbfb8aa3b, v20
	v_mul_f32_e32 v23, v23, v25
	v_and_b32_e32 v25, 0xffff0000, v51
	v_rcp_f32_e32 v19, v19
	v_exp_f32_e32 v20, v20
	v_mul_f32_e32 v21, 0xbfb8aa3b, v21
	v_mul_f32_e32 v24, v24, v25
	v_exp_f32_e32 v21, v21
	v_mul_f32_e32 v14, 0xbfb8aa3b, v14
	v_cvt_pk_bf16_f32 v23, v23, v24
	v_lshlrev_b32_e32 v24, 16, v52
	v_exp_f32_e32 v14, v14
	v_mul_f32_e32 v15, 0xbfb8aa3b, v15
	v_mul_f32_e32 v18, v18, v24
	v_and_b32_e32 v24, 0xffff0000, v52
	v_exp_f32_e32 v15, v15
	v_mul_f32_e32 v19, v19, v24
	v_cvt_pk_bf16_f32 v24, v18, v19
	v_add_f32_e32 v18, 1.0, v20
	v_rcp_f32_e32 v18, v18
	v_add_f32_e32 v19, 1.0, v21
	v_rcp_f32_e32 v19, v19
	v_add_f32_e32 v14, 1.0, v14
	v_rcp_f32_e32 v14, v14
	v_add_f32_e32 v15, 1.0, v15
	v_lshlrev_b32_e32 v20, 16, v53
	v_rcp_f32_e32 v15, v15
	v_mul_f32_e32 v16, 0xbfb8aa3b, v16
	v_mul_f32_e32 v18, v18, v20
	v_and_b32_e32 v20, 0xffff0000, v53
	v_exp_f32_e32 v16, v16
	v_mul_f32_e32 v17, 0xbfb8aa3b, v17
	v_mul_f32_e32 v19, v19, v20
	s_waitcnt vmcnt(1)
	v_lshlrev_b32_e32 v20, 16, v38
	v_exp_f32_e32 v17, v17
	v_mul_f32_e32 v14, v14, v20
	v_and_b32_e32 v20, 0xffff0000, v38
	v_mul_f32_e32 v10, 0xbfb8aa3b, v10
	v_mul_f32_e32 v15, v15, v20
	v_exp_f32_e32 v10, v10
	v_mul_f32_e32 v11, 0xbfb8aa3b, v11
	v_cvt_pk_bf16_f32 v25, v18, v19
	global_store_dwordx4 v[26:27], v[22:25], off offset:1280
	v_cvt_pk_bf16_f32 v14, v14, v15
	v_add_f32_e32 v15, 1.0, v16
	v_exp_f32_e32 v11, v11
	v_rcp_f32_e32 v15, v15
	v_add_f32_e32 v16, 1.0, v17
	v_rcp_f32_e32 v16, v16
	v_add_f32_e32 v10, 1.0, v10
	v_lshlrev_b32_e32 v17, 16, v39
	v_rcp_f32_e32 v10, v10
	v_add_f32_e32 v11, 1.0, v11
	v_mul_f32_e32 v12, 0xbfb8aa3b, v12
	v_mul_f32_e32 v15, v15, v17
	v_and_b32_e32 v17, 0xffff0000, v39
	v_rcp_f32_e32 v11, v11
	v_exp_f32_e32 v12, v12
	v_mul_f32_e32 v13, 0xbfb8aa3b, v13
	v_mul_f32_e32 v16, v16, v17
	v_exp_f32_e32 v13, v13
	v_mul_f32_e32 v6, 0xbfb8aa3b, v6
	v_cvt_pk_bf16_f32 v15, v15, v16
	v_lshlrev_b32_e32 v16, 16, v40
	v_exp_f32_e32 v6, v6
	v_mul_f32_e32 v7, 0xbfb8aa3b, v7
	v_mul_f32_e32 v10, v10, v16
	v_and_b32_e32 v16, 0xffff0000, v40
	v_exp_f32_e32 v7, v7
	v_mul_f32_e32 v11, v11, v16
	v_cvt_pk_bf16_f32 v16, v10, v11
	v_add_f32_e32 v10, 1.0, v12
	v_rcp_f32_e32 v10, v10
	v_add_f32_e32 v11, 1.0, v13
	v_rcp_f32_e32 v11, v11
	v_add_f32_e32 v6, 1.0, v6
	v_rcp_f32_e32 v6, v6
	v_add_f32_e32 v7, 1.0, v7
	v_lshlrev_b32_e32 v12, 16, v41
	v_rcp_f32_e32 v7, v7
	v_mul_f32_e32 v8, 0xbfb8aa3b, v8
	v_mul_f32_e32 v10, v10, v12
	v_and_b32_e32 v12, 0xffff0000, v41
	v_exp_f32_e32 v8, v8
	v_mul_f32_e32 v9, 0xbfb8aa3b, v9
	v_lshlrev_b64 v[18:19], 11, v[42:43]
	v_mul_f32_e32 v11, v11, v12
	v_lshlrev_b32_e32 v12, 16, v34
	v_exp_f32_e32 v9, v9
	v_cvt_pk_bf16_f32 v17, v10, v11
	v_lshl_add_u64 v[10:11], s[12:13], 0, v[18:19]
	v_mul_f32_e32 v6, v6, v12
	v_and_b32_e32 v12, 0xffff0000, v34
	v_mul_f32_e32 v2, 0xbfb8aa3b, v2
	v_lshl_add_u64 v[10:11], v[10:11], 0, v[146:147]
	v_mul_f32_e32 v7, v7, v12
	v_exp_f32_e32 v2, v2
	v_mul_f32_e32 v3, 0xbfb8aa3b, v3
	global_store_dwordx4 v[10:11], v[14:17], off offset:1024
	v_cvt_pk_bf16_f32 v6, v6, v7
	v_add_f32_e32 v7, 1.0, v8
	v_exp_f32_e32 v3, v3
	v_rcp_f32_e32 v7, v7
	v_add_f32_e32 v8, 1.0, v9
	v_rcp_f32_e32 v8, v8
	v_add_f32_e32 v2, 1.0, v2
	v_lshlrev_b32_e32 v9, 16, v35
	v_rcp_f32_e32 v2, v2
	v_add_f32_e32 v3, 1.0, v3
	v_mul_f32_e32 v4, 0xbfb8aa3b, v4
	v_mul_f32_e32 v7, v7, v9
	v_and_b32_e32 v9, 0xffff0000, v35
	v_rcp_f32_e32 v3, v3
	v_exp_f32_e32 v4, v4
	v_mul_f32_e32 v5, 0xbfb8aa3b, v5
	v_mul_f32_e32 v8, v8, v9
	v_exp_f32_e32 v5, v5
	v_cvt_pk_bf16_f32 v7, v7, v8
	v_lshlrev_b32_e32 v8, 16, v36
	v_mul_f32_e32 v2, v2, v8
	v_and_b32_e32 v8, 0xffff0000, v36
	v_mul_f32_e32 v3, v3, v8
	v_cvt_pk_bf16_f32 v8, v2, v3
	v_add_f32_e32 v2, 1.0, v4
	v_rcp_f32_e32 v2, v2
	v_add_f32_e32 v3, 1.0, v5
	v_rcp_f32_e32 v3, v3
	v_lshlrev_b32_e32 v4, 16, v37
	v_mul_f32_e32 v2, v2, v4
	v_and_b32_e32 v4, 0xffff0000, v37
	s_andn2_b64 vcc, exec, s[6:7]
	s_mov_b64 s[6:7], -1
	v_mul_f32_e32 v3, v3, v4
	v_cvt_pk_bf16_f32 v9, v2, v3
	global_store_dwordx4 v[10:11], v[6:9], off offset:1280
	s_cbranch_vccnz .LBB0_515
	s_andn2_b64 vcc, exec, s[10:11]
	s_cbranch_vccnz .LBB0_514
	s_mov_b32 s98, 1
	s_branch .LBB0_514

; #define PG8_STAGE(bufoff, gbase, voff) do { _Pragma("unroll") for (int _i = 0; _i < 2; ++_i) \
;         __builtin_amdgcn_global_load_lds((const unsigned*)((const char*)(gbase) + (voff)[_i]), (PG8_LAS unsigned*)(lds + (bufoff) + ldsw + _i * 8192), 16, 0, 0); } while (0)
; #define PG8_WAIT_V(n) asm volatile("s_waitcnt vmcnt(" #n ")" ::: "memory")
; #define PG8_BAR __builtin_amdgcn_s_barrier()
; template <class Epi, class Sched, bool ALIGN_EPI = false, bool SP2 = false>
; __device__ __forceinline__ void gemm_phase(PG8_LAS unsigned char* lds, const Gemm g, const Sched& S, const Epi& E) {
;     ...
;     const int aoff = lds_byte(wr * 64 + fr, fq * 8), boff = lds_byte(wc * 32 + fr, fq * 8);
;     ...
;         PG8_STAGE(PG8_SB(0, 0), cB, voffB); PG8_STAGE(PG8_SB(0, 1), cB + hstepB, voffB); PG8_STAGE(PG8_SA(0, 0), cA, voffA); PG8_STAGE(PG8_SA(0, 1), cA + hstepA, voffA);
;         if (wr == 1) PG8_BAR;
;         PG8_WAIT_V(2); PG8_BAR;
;         PG8_STAGE(PG8_SB(1, 0), cB + kstep, voffB); PG8_STAGE(PG8_SA(1, 0), cA + kstep, voffA); PG8_STAGE(PG8_SB(1, 1), cB + hstepB + kstep, voffB);
;         PG8_WAIT_V(6); PG8_BAR;
;     } else {
;         PG8_STAGE(PG8_SB(0, 0), cB, voffB); PG8_STAGE(PG8_SA(0, 0), cA, voffA); PG8_STAGE(PG8_SB(0, 1), cB + hstepB, voffB); PG8_STAGE(PG8_SA(0, 1), cA + hstepA, voffA);
;         if (wr == 1) PG8_BAR;
;         PG8_WAIT_V(4); PG8_BAR;
;         PG8_STAGE(PG8_SB(1, 0), cB + kstep, voffB); PG8_STAGE(PG8_SA(1, 0), cA + kstep, voffA); PG8_STAGE(PG8_SB(1, 1), cB + hstepB + kstep, voffB);
;         PG8_WAIT_V(6); PG8_BAR;
.LBB0_595:
	s_add_u32 s14, s78, 0x7c00000
	s_addc_u32 s15, s79, 0
	s_add_u32 s16, s78, 0x5a00000
	s_mov_b64 s[18:19], 0x80
	s_addc_u32 s17, s79, 0
	s_and_b32 s44, s6, 3
	s_add_i32 m0, s40, 0x18000
	v_lshl_add_u64 v[8:9], v[8:9], 0, s[18:19]
	s_lshl_b32 s6, s7, 13
	s_lshl_b32 s21, s44, 12
	s_waitcnt vmcnt(2)
	s_barrier
	global_load_lds_dwordx4 v[8:9], off
	v_lshl_add_u64 v[6:7], v[6:7], 0, s[18:19]
	s_add_i32 m0, s40, 0x1a000
	s_add_i32 s45, s40, 0x8000
	s_add_i32 s46, s40, 0xa000
	global_load_lds_dwordx4 v[6:7], off
	v_lshl_add_u64 v[2:3], v[2:3], 0, s[18:19]
	s_mov_b32 m0, s45
	s_add_u32 s8, s36, 0x40080
	global_load_lds_dwordx4 v[2:3], off
	v_lshl_add_u64 v[2:3], v[4:5], 0, s[18:19]
	s_mov_b32 m0, s46
	s_addc_u32 s9, s37, 0
	global_load_lds_dwordx4 v[2:3], off
	s_add_i32 m0, s40, 0x1c000
	v_lshl_add_u64 v[2:3], s[8:9], 0, v[148:149]
	global_load_lds_dwordx4 v[2:3], off
	v_lshl_add_u64 v[2:3], s[8:9], 0, v[152:153]
	s_add_i32 m0, s40, 0x1e000
	s_cmpk_lt_u32 s20, 0x100
	global_load_lds_dwordx4 v[2:3], off
	v_bfe_u32 v3, v10, 4, 2
	v_and_b32_e32 v2, 15, v10
	v_lshlrev_b32_e32 v5, 4, v3
	v_lshl_or_b32 v1, s7, 6, v2
	v_lshl_or_b32 v2, v2, 6, v5
	v_lshlrev_b32_e32 v5, 2, v10
	v_and_b32_e32 v5, 32, v5
	v_bitop3_b32 v6, v2, s6, v5 bitop3:0xde
	v_bitop3_b32 v170, v2, s21, v5 bitop3:0xde
	v_lshlrev_b32_e32 v2, 14, v11
	v_and_b32_e32 v2, 0xffff8000, v2
	v_lshlrev_b32_e32 v4, 3, v3
	v_cmp_eq_u32_e64 s[6:7], 0, v3
	v_lshl_add_u32 v2, v12, 11, v2
	v_and_b32_e32 v3, 1, v11
	v_lshl_or_b32 v2, v3, 6, v2
	v_lshl_add_u32 v154, v13, 1, v2
	v_lshlrev_b32_e32 v2, 14, v14
	v_and_b32_e32 v2, 0xffff8000, v2
	v_lshl_add_u32 v2, v15, 11, v2
	v_and_b32_e32 v3, 1, v14
	s_waitcnt vmcnt(6)
	v_lshl_or_b32 v2, v3, 6, v2
	s_cselect_b64 s[20:21], -1, 0
	v_lshl_add_u32 v156, v16, 1, v2
	s_add_i32 s50, 0, 0x10000
	s_add_i32 s51, 0, 0x14000
	v_mbcnt_lo_u32_b32 v2, -1, 0
	v_lshl_or_b32 v171, s44, 5, v4
	s_ashr_i32 s47, s82, 31
	s_mov_b32 s48, s82
	s_ashr_i32 s49, s96, 31
	v_mov_b32_e32 v155, v149
	v_mov_b32_e32 v157, v149
	v_mov_b64_e32 v[158:159], 0x200
	v_mov_b64_e32 v[160:161], 0x1ff
	v_add_u32_e32 v172, s50, v170
	v_add_u32_e32 v173, s51, v170
	v_add_u32_e32 v174, 0, v6
	v_mbcnt_hi_u32_b32 v175, -1, v2
	s_mov_b32 s52, 0
	s_barrier
	s_mov_b32 s98, 0
	s_branch .LBB0_598

; #define PG8_STAGE(bufoff, gbase, voff) do { _Pragma("unroll") for (int _i = 0; _i < 2; ++_i) \
;         __builtin_amdgcn_global_load_lds((const unsigned*)((const char*)(gbase) + (voff)[_i]), (PG8_LAS unsigned*)(lds + (bufoff) + ldsw + _i * 8192), 16, 0, 0); } while (0)
; #define PG8_LDA(dst, b, h) do { _Pragma("unroll") for (int m = 0; m < 4; ++m) _Pragma("unroll") for (int k = 0; k < 2; ++k) dst[m][k] = *(const PG8_LAS bf16x8*)(lds + PG8_SA(b, h) + aoff + m * 2048 + k * 1024); } while (0)
; #define PG8_LDB(dst, b, h) do { _Pragma("unroll") for (int n = 0; n < 2; ++n) _Pragma("unroll") for (int k = 0; k < 2; ++k) dst[n][k] = *(const PG8_LAS bf16x8*)(lds + PG8_SB(b, h) + boff + n * 2048 + k * 1024); } while (0)
; #define PG8_WAIT_V(n) asm volatile("s_waitcnt vmcnt(" #n ")" ::: "memory")
; #define PG8_WAIT_L(n) asm volatile("s_waitcnt lgkmcnt(" #n ")" ::: "memory")
; #define PG8_BAR __builtin_amdgcn_s_barrier()
; template <class Epi, class Sched, bool ALIGN_EPI = false, bool SP2 = false>
; __device__ __forceinline__ void gemm_phase(PG8_LAS unsigned char* lds, const Gemm g, const Sched& S, const Epi& E) {
;     ...
;         const bool has_next = S.next(ui + 1, nxt);
;         const char* nA = has_next ? (const char*)g.A + (size_t)nxt.g * g.gsA * 2 + (size_t)nxt.pm * tstepA : cA; const char* nB = has_next ? (const char*)g.Bt + (size_t)nxt.g * g.gsB * 2 + (size_t)nxt.pn * tstepB : cB;
;         for (int t = 0; t < nt; t += 2) {
;             const bool last = (t == nt - 2);
;             const char* a1 = cA + (size_t)(t + 1) * kstep;
;             const char* a2 = last ? nA : cA + (size_t)(t + 2) * kstep; const char* b2 = last ? nB : cB + (size_t)(t + 2) * kstep;
;             const char* a3 = a2 + kstep; const char* b3 = b2 + kstep;
;             if (last && has_next) S.a_ready(nxt);
;             if constexpr (SP2) {
;             PG8_LDB(B0, 0, 0); PG8_LDB(B1, 0, 1); PG8_SCHED; PG8_LDA(At, 0, 0); PG8_STAGE(PG8_SA(1, 1), a1 + hstepA, voffA);
;             PG8_WAIT_V(8); PG8_WAIT_L(0); PG8_BAR; PG8_MMA(0, 0, At, B0); PG8_MMA(0, 1, At, B1); PG8_BAR; PG8_SCHED;
;             PG8_LDA(At, 0, 1); PG8_STAGE(PG8_SB(0, 0), b2, voffB); PG8_STAGE(PG8_SB(0, 1), b2 + hstepB, voffB); PG8_STAGE(PG8_SA(0, 0), a2, voffA);
;             PG8_WAIT_V(8); PG8_WAIT_L(0); PG8_BAR; PG8_MMA(1, 0, At, B0); PG8_MMA(1, 1, At, B1); PG8_BAR; PG8_SCHED;
.LBB0_604:
	s_ashr_i32 s25, s24, 31
	s_lshl_b64 s[26:27], s[24:25], 19
	s_add_u32 s26, s0, s26
	s_addc_u32 s27, s1, s27
	s_and_b64 s[28:29], s[8:9], exec
	s_cselect_b32 s25, s27, s35
	s_cselect_b32 s31, s26, s34
	s_ashr_i32 s23, s22, 31
	s_lshl_b64 s[28:29], s[22:23], 19
	s_add_u32 s28, s2, s28
	s_addc_u32 s29, s3, s29
	s_and_b64 s[38:39], s[8:9], exec
	s_cselect_b32 s23, s29, s37
	s_cselect_b32 s53, s28, s36
	s_add_u32 s34, s34, 0x40080
	s_addc_u32 s35, s35, 0
	s_add_u32 s54, s36, 0x100
	s_addc_u32 s55, s37, 0
	s_mov_b32 s56, -2
	s_waitcnt lgkmcnt(0)
	s_waitcnt lgkmcnt(0)
	s_cmp_eq_u32 s98, 1
	s_cbranch_scc0 .Lhb_20635
	s_mov_b32 s98, 0
	s_barrier
.Lhb_20635:
	ds_read_b128 v[130:133], v172
	ds_read_b128 v[134:137], v172 offset:1024
	ds_read_b128 v[138:141], v172 offset:2048
	ds_read_b128 v[142:145], v172 offset:3072
	ds_read_b128 v[162:165], v173
	ds_read_b128 v[166:169], v173 offset:1024
	ds_read_b128 v[176:179], v173 offset:2048
	ds_read_b128 v[180:183], v173 offset:3072
	s_add_u32 s36, s34, 0xfffc0080
	s_addc_u32 s37, s35, -1
	s_cmp_eq_u32 s56, 12
	s_cselect_b32 s39, s25, s37
	s_cselect_b32 s38, s31, s36
	s_cselect_b32 s37, s23, s55
	s_cselect_b32 s36, s53, s54
	v_lshl_add_u64 v[216:217], s[34:35], 0, v[154:155]
	s_add_i32 m0, s40, 0xc000
	ds_read_b128 v[184:187], v174
	ds_read_b128 v[188:191], v174 offset:1024
	ds_read_b128 v[192:195], v174 offset:2048
	ds_read_b128 v[196:199], v174 offset:3072
	ds_read_b128 v[200:203], v174 offset:4096
	ds_read_b128 v[204:207], v174 offset:5120
	ds_read_b128 v[208:211], v174 offset:6144
	ds_read_b128 v[212:215], v174 offset:7168
	global_load_lds_dwordx4 v[216:217], off
	v_lshl_add_u64 v[216:217], s[34:35], 0, v[156:157]
	s_add_i32 m0, s40, 0xe000
	s_nop 0
	global_load_lds_dwordx4 v[216:217], off
	s_waitcnt vmcnt(8)
	s_waitcnt lgkmcnt(0)
	s_barrier
	s_setprio 1
	s_waitcnt lgkmcnt(0)
	v_mfma_f32_16x16x32_bf16 v[126:129], v[130:133], v[184:187], 0
	v_mfma_f32_16x16x32_bf16 v[122:125], v[138:141], v[184:187], 0
	v_mfma_f32_16x16x32_bf16 v[110:113], v[130:133], v[192:195], 0
	v_mfma_f32_16x16x32_bf16 v[106:109], v[138:141], v[192:195], 0
	v_mfma_f32_16x16x32_bf16 v[94:97], v[130:133], v[200:203], 0
	v_mfma_f32_16x16x32_bf16 v[90:93], v[138:141], v[200:203], 0
	v_mfma_f32_16x16x32_bf16 v[78:81], v[130:133], v[208:211], 0
	v_mfma_f32_16x16x32_bf16 v[74:77], v[138:141], v[208:211], 0
	v_mfma_f32_16x16x32_bf16 v[126:129], v[134:137], v[188:191], v[126:129]
	v_mfma_f32_16x16x32_bf16 v[122:125], v[142:145], v[188:191], v[122:125]
	v_mfma_f32_16x16x32_bf16 v[110:113], v[134:137], v[196:199], v[110:113]
	v_mfma_f32_16x16x32_bf16 v[106:109], v[142:145], v[196:199], v[106:109]
	v_mfma_f32_16x16x32_bf16 v[94:97], v[134:137], v[204:207], v[94:97]
	v_mfma_f32_16x16x32_bf16 v[90:93], v[142:145], v[204:207], v[90:93]
	v_mfma_f32_16x16x32_bf16 v[78:81], v[134:137], v[212:215], v[78:81]
	v_mfma_f32_16x16x32_bf16 v[74:77], v[142:145], v[212:215], v[74:77]
	s_setprio 0
	s_setprio 1
	v_mfma_f32_16x16x32_bf16 v[118:121], v[162:165], v[184:187], 0
	v_mfma_f32_16x16x32_bf16 v[114:117], v[176:179], v[184:187], 0
	v_mfma_f32_16x16x32_bf16 v[102:105], v[162:165], v[192:195], 0
	v_mfma_f32_16x16x32_bf16 v[98:101], v[176:179], v[192:195], 0
	v_mfma_f32_16x16x32_bf16 v[86:89], v[162:165], v[200:203], 0
	v_mfma_f32_16x16x32_bf16 v[82:85], v[176:179], v[200:203], 0
	v_mfma_f32_16x16x32_bf16 v[70:73], v[162:165], v[208:211], 0
	v_mfma_f32_16x16x32_bf16 v[66:69], v[176:179], v[208:211], 0
	v_mfma_f32_16x16x32_bf16 v[118:121], v[166:169], v[188:191], v[118:121]
	v_mfma_f32_16x16x32_bf16 v[114:117], v[180:183], v[188:191], v[114:117]
	v_mfma_f32_16x16x32_bf16 v[102:105], v[166:169], v[196:199], v[102:105]
	v_mfma_f32_16x16x32_bf16 v[98:101], v[180:183], v[196:199], v[98:101]
	v_mfma_f32_16x16x32_bf16 v[86:89], v[166:169], v[204:207], v[86:89]
	v_mfma_f32_16x16x32_bf16 v[82:85], v[180:183], v[204:207], v[82:85]
	v_mfma_f32_16x16x32_bf16 v[70:73], v[166:169], v[212:215], v[70:73]
	v_mfma_f32_16x16x32_bf16 v[66:69], v[180:183], v[212:215], v[66:69]
	s_setprio 0
	s_barrier
	s_add_i32 s57, s50, s33
	v_lshl_add_u64 v[216:217], s[36:37], 0, v[148:149]
	s_mov_b32 m0, s57
	ds_read_b128 v[184:187], v174 offset:16384
	ds_read_b128 v[188:191], v174 offset:17408
	ds_read_b128 v[192:195], v174 offset:18432
	ds_read_b128 v[196:199], v174 offset:19456
	ds_read_b128 v[200:203], v174 offset:20480
	ds_read_b128 v[204:207], v174 offset:21504
	ds_read_b128 v[208:211], v174 offset:22528
	ds_read_b128 v[212:215], v174 offset:23552
	global_load_lds_dwordx4 v[216:217], off
	s_add_i32 m0, s57, 0x2000
	s_add_u32 s58, s36, 0x40000
	v_lshl_add_u64 v[218:219], s[36:37], 0, v[152:153]
	s_addc_u32 s59, s37, 0
	s_add_i32 s57, s51, s33
	global_load_lds_dwordx4 v[218:219], off
	v_lshl_add_u64 v[220:221], s[58:59], 0, v[148:149]
	s_mov_b32 m0, s57
	v_lshl_add_u64 v[222:223], s[38:39], 0, v[150:151]
	global_load_lds_dwordx4 v[220:221], off
	v_lshl_add_u64 v[220:221], s[58:59], 0, v[152:153]
	s_add_i32 m0, s57, 0x2000
	s_nop 0
	global_load_lds_dwordx4 v[220:221], off
	v_lshl_add_u64 v[220:221], s[38:39], 0, v[146:147]
	s_mov_b32 m0, s40
	s_nop 0
	global_load_lds_dwordx4 v[220:221], off
	s_mov_b32 m0, s41
	s_nop 0
	global_load_lds_dwordx4 v[222:223], off
	s_waitcnt vmcnt(8)
	s_waitcnt lgkmcnt(0)
	s_barrier
; #define PG8_STAGE(bufoff, gbase, voff) do { _Pragma("unroll") for (int _i = 0; _i < 2; ++_i) \
;         __builtin_amdgcn_global_load_lds((const unsigned*)((const char*)(gbase) + (voff)[_i]), (PG8_LAS unsigned*)(lds + (bufoff) + ldsw + _i * 8192), 16, 0, 0); } while (0)
; #define PG8_LDA(dst, b, h) do { _Pragma("unroll") for (int m = 0; m < 4; ++m) _Pragma("unroll") for (int k = 0; k < 2; ++k) dst[m][k] = *(const PG8_LAS bf16x8*)(lds + PG8_SA(b, h) + aoff + m * 2048 + k * 1024); } while (0)
; #define PG8_LDB(dst, b, h) do { _Pragma("unroll") for (int n = 0; n < 2; ++n) _Pragma("unroll") for (int k = 0; k < 2; ++k) dst[n][k] = *(const PG8_LAS bf16x8*)(lds + PG8_SB(b, h) + boff + n * 2048 + k * 1024); } while (0)
; #define PG8_MMA(ai, bj, At, Bt) do { __builtin_amdgcn_s_setprio(1); _Pragma("unroll") for (int m = 0; m < 4; ++m) _Pragma("unroll") for (int n = 0; n < 2; ++n) _Pragma("unroll") for (int k = 0; k < 2; ++k) \
;         acc[ai][bj][m][n] = __builtin_amdgcn_mfma_f32_16x16x32_bf16(Bt[n][k], At[m][k], acc[ai][bj][m][n], 0, 0, 0); __builtin_amdgcn_s_setprio(0); } while (0)
; #define PG8_WAIT_V(n) asm volatile("s_waitcnt vmcnt(" #n ")" ::: "memory")
; #define PG8_WAIT_L(n) asm volatile("s_waitcnt lgkmcnt(" #n ")" ::: "memory")
; #define PG8_BAR __builtin_amdgcn_s_barrier()
; #define PG8_SCHED __builtin_amdgcn_sched_barrier(0)
; template <class Epi, class Sched, bool ALIGN_EPI = false, bool SP2 = false>
; __device__ __forceinline__ void gemm_phase(PG8_LAS unsigned char* lds, const Gemm g, const Sched& S, const Epi& E) {
;     ...
;             PG8_WAIT_V(8); PG8_WAIT_L(0); PG8_BAR; PG8_MMA(1, 0, At, B0); PG8_MMA(1, 1, At, B1); PG8_BAR; PG8_SCHED;
;             PG8_LDB(B0, 1, 0); PG8_LDB(B1, 1, 1); PG8_SCHED; PG8_LDA(At, 1, 0); PG8_STAGE(PG8_SA(0, 1), a2 + hstepA, voffA);
;             PG8_WAIT_V(8); PG8_WAIT_L(0); PG8_BAR; PG8_MMA(0, 0, At, B0); PG8_MMA(0, 1, At, B1); PG8_BAR; PG8_SCHED;
;             PG8_LDA(At, 1, 1); PG8_STAGE(PG8_SB(1, 0), b3, voffB); PG8_STAGE(PG8_SB(1, 1), b3 + hstepB, voffB); PG8_STAGE(PG8_SA(1, 0), a3, voffA);
	s_setprio 1
	s_waitcnt lgkmcnt(0)
	v_mfma_f32_16x16x32_bf16 v[62:65], v[130:133], v[184:187], 0
	v_mfma_f32_16x16x32_bf16 v[58:61], v[138:141], v[184:187], 0
	v_mfma_f32_16x16x32_bf16 v[46:49], v[130:133], v[192:195], 0
	v_mfma_f32_16x16x32_bf16 v[42:45], v[138:141], v[192:195], 0
	v_mfma_f32_16x16x32_bf16 v[30:33], v[130:133], v[200:203], 0
	v_mfma_f32_16x16x32_bf16 v[26:29], v[138:141], v[200:203], 0
	v_mfma_f32_16x16x32_bf16 v[14:17], v[130:133], v[208:211], 0
	v_mfma_f32_16x16x32_bf16 v[10:13], v[138:141], v[208:211], 0
	v_mfma_f32_16x16x32_bf16 v[62:65], v[134:137], v[188:191], v[62:65]
	v_mfma_f32_16x16x32_bf16 v[58:61], v[142:145], v[188:191], v[58:61]
	v_mfma_f32_16x16x32_bf16 v[46:49], v[134:137], v[196:199], v[46:49]
	v_mfma_f32_16x16x32_bf16 v[42:45], v[142:145], v[196:199], v[42:45]
	v_mfma_f32_16x16x32_bf16 v[30:33], v[134:137], v[204:207], v[30:33]
	v_mfma_f32_16x16x32_bf16 v[26:29], v[142:145], v[204:207], v[26:29]
	v_mfma_f32_16x16x32_bf16 v[14:17], v[134:137], v[212:215], v[14:17]
	v_mfma_f32_16x16x32_bf16 v[10:13], v[142:145], v[212:215], v[10:13]
	s_setprio 0
	s_setprio 1
	v_mfma_f32_16x16x32_bf16 v[54:57], v[162:165], v[184:187], 0
	v_mfma_f32_16x16x32_bf16 v[50:53], v[176:179], v[184:187], 0
	v_mfma_f32_16x16x32_bf16 v[38:41], v[162:165], v[192:195], 0
	v_mfma_f32_16x16x32_bf16 v[34:37], v[176:179], v[192:195], 0
	v_mfma_f32_16x16x32_bf16 v[22:25], v[162:165], v[200:203], 0
	v_mfma_f32_16x16x32_bf16 v[18:21], v[176:179], v[200:203], 0
	v_mfma_f32_16x16x32_bf16 v[6:9], v[162:165], v[208:211], 0
	v_mfma_f32_16x16x32_bf16 v[2:5], v[176:179], v[208:211], 0
	v_mfma_f32_16x16x32_bf16 v[54:57], v[166:169], v[188:191], v[54:57]
	v_mfma_f32_16x16x32_bf16 v[50:53], v[180:183], v[188:191], v[50:53]
	v_mfma_f32_16x16x32_bf16 v[38:41], v[166:169], v[196:199], v[38:41]
	v_mfma_f32_16x16x32_bf16 v[34:37], v[180:183], v[196:199], v[34:37]
	v_mfma_f32_16x16x32_bf16 v[22:25], v[166:169], v[204:207], v[22:25]
	v_mfma_f32_16x16x32_bf16 v[18:21], v[180:183], v[204:207], v[18:21]
	v_mfma_f32_16x16x32_bf16 v[6:9], v[166:169], v[212:215], v[6:9]
	v_mfma_f32_16x16x32_bf16 v[2:5], v[180:183], v[212:215], v[2:5]
	s_setprio 0
	s_barrier
	s_add_i32 s57, 0, 0x18000
	s_add_i32 s58, 0, 0x1c000
	v_add_u32_e32 v142, s57, v170
	v_add_u32_e32 v180, s58, v170
	ds_read_b128 v[130:133], v142
	ds_read_b128 v[134:137], v142 offset:1024
	ds_read_b128 v[138:141], v142 offset:2048
	ds_read_b128 v[142:145], v142 offset:3072
	ds_read_b128 v[162:165], v180
	ds_read_b128 v[166:169], v180 offset:1024
	ds_read_b128 v[176:179], v180 offset:2048
	ds_read_b128 v[180:183], v180 offset:3072
	s_add_u32 s38, s38, 0x40000
	s_addc_u32 s39, s39, 0
	s_mov_b32 m0, s42
	v_lshl_add_u64 v[224:225], s[38:39], 0, v[146:147]
	ds_read_b128 v[184:187], v174 offset:32768
	ds_read_b128 v[188:191], v174 offset:33792
	ds_read_b128 v[192:195], v174 offset:34816
	ds_read_b128 v[196:199], v174 offset:35840
	ds_read_b128 v[200:203], v174 offset:36864
	ds_read_b128 v[204:207], v174 offset:37888
	ds_read_b128 v[208:211], v174 offset:38912
	ds_read_b128 v[212:215], v174 offset:39936
	global_load_lds_dwordx4 v[224:225], off
	v_lshl_add_u64 v[224:225], s[38:39], 0, v[150:151]
	s_mov_b32 m0, s43
	s_nop 0
	global_load_lds_dwordx4 v[224:225], off
	s_waitcnt vmcnt(8)
	s_waitcnt lgkmcnt(0)
	s_barrier
	s_setprio 1
	s_waitcnt lgkmcnt(0)
	v_mfma_f32_16x16x32_bf16 v[126:129], v[130:133], v[184:187], v[126:129]
	v_mfma_f32_16x16x32_bf16 v[122:125], v[138:141], v[184:187], v[122:125]
	v_mfma_f32_16x16x32_bf16 v[110:113], v[130:133], v[192:195], v[110:113]
	v_mfma_f32_16x16x32_bf16 v[106:109], v[138:141], v[192:195], v[106:109]
	v_mfma_f32_16x16x32_bf16 v[94:97], v[130:133], v[200:203], v[94:97]
	v_mfma_f32_16x16x32_bf16 v[90:93], v[138:141], v[200:203], v[90:93]
	v_mfma_f32_16x16x32_bf16 v[78:81], v[130:133], v[208:211], v[78:81]
	v_mfma_f32_16x16x32_bf16 v[74:77], v[138:141], v[208:211], v[74:77]
	v_mfma_f32_16x16x32_bf16 v[126:129], v[134:137], v[188:191], v[126:129]
	v_mfma_f32_16x16x32_bf16 v[122:125], v[142:145], v[188:191], v[122:125]
	v_mfma_f32_16x16x32_bf16 v[110:113], v[134:137], v[196:199], v[110:113]
	v_mfma_f32_16x16x32_bf16 v[106:109], v[142:145], v[196:199], v[106:109]
	v_mfma_f32_16x16x32_bf16 v[94:97], v[134:137], v[204:207], v[94:97]
	v_mfma_f32_16x16x32_bf16 v[90:93], v[142:145], v[204:207], v[90:93]
	v_mfma_f32_16x16x32_bf16 v[78:81], v[134:137], v[212:215], v[78:81]
	v_mfma_f32_16x16x32_bf16 v[74:77], v[142:145], v[212:215], v[74:77]
	s_setprio 0
	s_setprio 1
	v_mfma_f32_16x16x32_bf16 v[118:121], v[162:165], v[184:187], v[118:121]
	v_mfma_f32_16x16x32_bf16 v[114:117], v[176:179], v[184:187], v[114:117]
	v_mfma_f32_16x16x32_bf16 v[102:105], v[162:165], v[192:195], v[102:105]
	v_mfma_f32_16x16x32_bf16 v[98:101], v[176:179], v[192:195], v[98:101]
	v_mfma_f32_16x16x32_bf16 v[86:89], v[162:165], v[200:203], v[86:89]
	v_mfma_f32_16x16x32_bf16 v[82:85], v[176:179], v[200:203], v[82:85]
	v_mfma_f32_16x16x32_bf16 v[70:73], v[162:165], v[208:211], v[70:73]
	v_mfma_f32_16x16x32_bf16 v[66:69], v[176:179], v[208:211], v[66:69]
	v_mfma_f32_16x16x32_bf16 v[118:121], v[166:169], v[188:191], v[118:121]
	v_mfma_f32_16x16x32_bf16 v[114:117], v[180:183], v[188:191], v[114:117]
	v_mfma_f32_16x16x32_bf16 v[102:105], v[166:169], v[196:199], v[102:105]
	v_mfma_f32_16x16x32_bf16 v[98:101], v[180:183], v[196:199], v[98:101]
	v_mfma_f32_16x16x32_bf16 v[86:89], v[166:169], v[204:207], v[86:89]
	v_mfma_f32_16x16x32_bf16 v[82:85], v[180:183], v[204:207], v[82:85]
	v_mfma_f32_16x16x32_bf16 v[70:73], v[166:169], v[212:215], v[70:73]
	v_mfma_f32_16x16x32_bf16 v[66:69], v[180:183], v[212:215], v[66:69]
	s_setprio 0
	s_barrier
; #define PG8_STAGE(bufoff, gbase, voff) do { _Pragma("unroll") for (int _i = 0; _i < 2; ++_i) \
;         __builtin_amdgcn_global_load_lds((const unsigned*)((const char*)(gbase) + (voff)[_i]), (PG8_LAS unsigned*)(lds + (bufoff) + ldsw + _i * 8192), 16, 0, 0); } while (0)
; #define PG8_LDA(dst, b, h) do { _Pragma("unroll") for (int m = 0; m < 4; ++m) _Pragma("unroll") for (int k = 0; k < 2; ++k) dst[m][k] = *(const PG8_LAS bf16x8*)(lds + PG8_SA(b, h) + aoff + m * 2048 + k * 1024); } while (0)
; #define PG8_MMA(ai, bj, At, Bt) do { __builtin_amdgcn_s_setprio(1); _Pragma("unroll") for (int m = 0; m < 4; ++m) _Pragma("unroll") for (int n = 0; n < 2; ++n) _Pragma("unroll") for (int k = 0; k < 2; ++k) \
;         acc[ai][bj][m][n] = __builtin_amdgcn_mfma_f32_16x16x32_bf16(Bt[n][k], At[m][k], acc[ai][bj][m][n], 0, 0, 0); __builtin_amdgcn_s_setprio(0); } while (0)
; #define PG8_WAIT_V(n) asm volatile("s_waitcnt vmcnt(" #n ")" ::: "memory")
; #define PG8_WAIT_L(n) asm volatile("s_waitcnt lgkmcnt(" #n ")" ::: "memory")
; #define PG8_BAR __builtin_amdgcn_s_barrier()
; #define PG8_SCHED __builtin_amdgcn_sched_barrier(0)
; template <class Epi, class Sched, bool ALIGN_EPI = false, bool SP2 = false>
; __device__ __forceinline__ void gemm_phase(PG8_LAS unsigned char* lds, const Gemm g, const Sched& S, const Epi& E) {
;     ...
;         for (int t = 0; t < nt; t += 2) {
;     ...
;             PG8_LDA(At, 1, 1); PG8_STAGE(PG8_SB(1, 0), b3, voffB); PG8_STAGE(PG8_SB(1, 1), b3 + hstepB, voffB); PG8_STAGE(PG8_SA(1, 0), a3, voffA);
;             PG8_WAIT_V(8); PG8_WAIT_L(0); PG8_BAR; PG8_MMA(1, 0, At, B0); PG8_MMA(1, 1, At, B1); PG8_BAR; PG8_SCHED;
	s_add_i32 s38, s57, s33
	v_lshl_add_u64 v[216:217], v[216:217], 0, s[18:19]
	s_mov_b32 m0, s38
	ds_read_b128 v[184:187], v174 offset:49152
	ds_read_b128 v[188:191], v174 offset:50176
	ds_read_b128 v[192:195], v174 offset:51200
	ds_read_b128 v[196:199], v174 offset:52224
	ds_read_b128 v[200:203], v174 offset:53248
	ds_read_b128 v[204:207], v174 offset:54272
	ds_read_b128 v[208:211], v174 offset:55296
	ds_read_b128 v[212:215], v174 offset:56320
	global_load_lds_dwordx4 v[216:217], off
	s_add_i32 m0, s38, 0x2000
	s_add_u32 s36, s36, 0x40080
	v_lshl_add_u64 v[216:217], v[218:219], 0, s[18:19]
	s_addc_u32 s37, s37, 0
	s_add_i32 s38, s58, s33
	global_load_lds_dwordx4 v[216:217], off
	v_lshl_add_u64 v[216:217], s[36:37], 0, v[148:149]
	s_mov_b32 m0, s38
	s_nop 0
	global_load_lds_dwordx4 v[216:217], off
	v_lshl_add_u64 v[216:217], s[36:37], 0, v[152:153]
	s_add_i32 m0, s38, 0x2000
	s_nop 0
	global_load_lds_dwordx4 v[216:217], off
	v_lshl_add_u64 v[216:217], v[220:221], 0, s[18:19]
	s_mov_b32 m0, s45
	s_nop 0
	global_load_lds_dwordx4 v[216:217], off
	v_lshl_add_u64 v[216:217], v[222:223], 0, s[18:19]
	s_mov_b32 m0, s46
	s_nop 0
	global_load_lds_dwordx4 v[216:217], off
	s_waitcnt vmcnt(8)
	s_waitcnt lgkmcnt(0)
	s_barrier
	s_setprio 1
	s_waitcnt lgkmcnt(0)
	v_mfma_f32_16x16x32_bf16 v[62:65], v[130:133], v[184:187], v[62:65]
	v_mfma_f32_16x16x32_bf16 v[58:61], v[138:141], v[184:187], v[58:61]
	v_mfma_f32_16x16x32_bf16 v[46:49], v[130:133], v[192:195], v[46:49]
	v_mfma_f32_16x16x32_bf16 v[42:45], v[138:141], v[192:195], v[42:45]
	v_mfma_f32_16x16x32_bf16 v[30:33], v[130:133], v[200:203], v[30:33]
	v_mfma_f32_16x16x32_bf16 v[26:29], v[138:141], v[200:203], v[26:29]
	v_mfma_f32_16x16x32_bf16 v[14:17], v[130:133], v[208:211], v[14:17]
	v_mfma_f32_16x16x32_bf16 v[10:13], v[138:141], v[208:211], v[10:13]
	v_mfma_f32_16x16x32_bf16 v[62:65], v[134:137], v[188:191], v[62:65]
	v_mfma_f32_16x16x32_bf16 v[58:61], v[142:145], v[188:191], v[58:61]
	v_mfma_f32_16x16x32_bf16 v[46:49], v[134:137], v[196:199], v[46:49]
	v_mfma_f32_16x16x32_bf16 v[42:45], v[142:145], v[196:199], v[42:45]
	v_mfma_f32_16x16x32_bf16 v[30:33], v[134:137], v[204:207], v[30:33]
	v_mfma_f32_16x16x32_bf16 v[26:29], v[142:145], v[204:207], v[26:29]
	v_mfma_f32_16x16x32_bf16 v[14:17], v[134:137], v[212:215], v[14:17]
	v_mfma_f32_16x16x32_bf16 v[10:13], v[142:145], v[212:215], v[10:13]
	s_setprio 0
	s_setprio 1
	v_mfma_f32_16x16x32_bf16 v[54:57], v[162:165], v[184:187], v[54:57]
	v_mfma_f32_16x16x32_bf16 v[50:53], v[176:179], v[184:187], v[50:53]
	v_mfma_f32_16x16x32_bf16 v[38:41], v[162:165], v[192:195], v[38:41]
	v_mfma_f32_16x16x32_bf16 v[34:37], v[176:179], v[192:195], v[34:37]
	v_mfma_f32_16x16x32_bf16 v[22:25], v[162:165], v[200:203], v[22:25]
	v_mfma_f32_16x16x32_bf16 v[18:21], v[176:179], v[200:203], v[18:21]
	v_mfma_f32_16x16x32_bf16 v[6:9], v[162:165], v[208:211], v[6:9]
	v_mfma_f32_16x16x32_bf16 v[2:5], v[176:179], v[208:211], v[2:5]
	v_mfma_f32_16x16x32_bf16 v[54:57], v[166:169], v[188:191], v[54:57]
	v_mfma_f32_16x16x32_bf16 v[50:53], v[180:183], v[188:191], v[50:53]
	v_mfma_f32_16x16x32_bf16 v[38:41], v[166:169], v[196:199], v[38:41]
	v_mfma_f32_16x16x32_bf16 v[34:37], v[180:183], v[196:199], v[34:37]
	v_mfma_f32_16x16x32_bf16 v[22:25], v[166:169], v[204:207], v[22:25]
	v_mfma_f32_16x16x32_bf16 v[18:21], v[180:183], v[204:207], v[18:21]
	v_mfma_f32_16x16x32_bf16 v[6:9], v[166:169], v[212:215], v[6:9]
	v_mfma_f32_16x16x32_bf16 v[2:5], v[180:183], v[212:215], v[2:5]
	s_setprio 0
	s_barrier
	s_add_i32 s56, s56, 2
	s_add_u32 s34, s34, 0x100
	s_addc_u32 s35, s35, 0
	s_add_u32 s54, s54, 0x100
	s_addc_u32 s55, s55, 0
	s_cmp_gt_u32 s56, 13

; #define PG8_BAR __builtin_amdgcn_s_barrier()
; template <class Epi, class Sched, bool ALIGN_EPI = false, bool SP2 = false>
; __device__ __forceinline__ void gemm_phase(PG8_LAS unsigned char* lds, const Gemm g, const Sched& S, const Epi& E) {
;     ...
;         if (!has_next) break;
; #pragma unroll
;         for (int a = 0; a < 2; ++a)
; #pragma unroll
;             for (int b = 0; b < 2; ++b)
; #pragma unroll
;                 for (int m = 0; m < 4; ++m)
; #pragma unroll
;                     for (int n = 0; n < 2; ++n) acc[a][b][m][n] = (f32x4){0.f, 0.f, 0.f, 0.f};
;         cur = nxt; cA = nA; cB = nB; ++ui;
;         if constexpr (ALIGN_EPI) { if (wr == 1) PG8_BAR; }
.LBB0_624:
	s_or_b64 exec, exec, s[34:35]
	s_andn2_b64 vcc, exec, s[8:9]
	s_mov_b64 s[8:9], -1
	s_cbranch_vccnz .LBB0_597
	s_andn2_b64 vcc, exec, s[12:13]
	s_cbranch_vccnz .LBB0_596
	s_mov_b32 s98, 1
	s_branch .LBB0_596

; #define PG8_STAGE(bufoff, gbase, voff) do { _Pragma("unroll") for (int _i = 0; _i < 2; ++_i) \
;         __builtin_amdgcn_global_load_lds((const unsigned*)((const char*)(gbase) + (voff)[_i]), (PG8_LAS unsigned*)(lds + (bufoff) + ldsw + _i * 8192), 16, 0, 0); } while (0)
; #define PG8_WAIT_V(n) asm volatile("s_waitcnt vmcnt(" #n ")" ::: "memory")
; #define PG8_BAR __builtin_amdgcn_s_barrier()
; template <class Epi, class Sched, bool ALIGN_EPI = false, bool SP2 = false>
; __device__ __forceinline__ void gemm_phase(PG8_LAS unsigned char* lds, const Gemm g, const Sched& S, const Epi& E) {
;     ...
;     const int aoff = lds_byte(wr * 64 + fr, fq * 8), boff = lds_byte(wc * 32 + fr, fq * 8);
;     ...
;         PG8_STAGE(PG8_SB(0, 0), cB, voffB); PG8_STAGE(PG8_SB(0, 1), cB + hstepB, voffB); PG8_STAGE(PG8_SA(0, 0), cA, voffA); PG8_STAGE(PG8_SA(0, 1), cA + hstepA, voffA);
;         if (wr == 1) PG8_BAR;
;         PG8_WAIT_V(2); PG8_BAR;
;         PG8_STAGE(PG8_SB(1, 0), cB + kstep, voffB); PG8_STAGE(PG8_SA(1, 0), cA + kstep, voffA); PG8_STAGE(PG8_SB(1, 1), cB + hstepB + kstep, voffB);
;         PG8_WAIT_V(6); PG8_BAR;
;     } else {
;         PG8_STAGE(PG8_SB(0, 0), cB, voffB); PG8_STAGE(PG8_SA(0, 0), cA, voffA); PG8_STAGE(PG8_SB(0, 1), cB + hstepB, voffB); PG8_STAGE(PG8_SA(0, 1), cA + hstepA, voffA);
;         if (wr == 1) PG8_BAR;
;         PG8_WAIT_V(4); PG8_BAR;
;         PG8_STAGE(PG8_SB(1, 0), cB + kstep, voffB); PG8_STAGE(PG8_SA(1, 0), cA + kstep, voffA); PG8_STAGE(PG8_SB(1, 1), cB + hstepB + kstep, voffB);
;         PG8_WAIT_V(6); PG8_BAR;
.LBB0_685:
	s_add_u32 s8, s78, 0x13c00000
	s_addc_u32 s9, s79, 0
	s_lshl_b32 s10, s10, 5
	s_and_b32 s16, s10, 0x60
	s_mov_b64 s[10:11], 0x80
	s_add_i32 m0, s23, 0x18000
	v_lshl_add_u64 v[8:9], v[8:9], 0, s[10:11]
	s_lshl_b32 s13, s12, 13
	s_lshl_b32 s17, s16, 7
	s_waitcnt vmcnt(2)
	s_barrier
	global_load_lds_dwordx4 v[8:9], off
	v_lshl_add_u64 v[6:7], v[6:7], 0, s[10:11]
	s_add_i32 m0, s23, 0x1a000
	s_add_i32 s38, s23, 0x8000
	s_add_i32 s39, s23, 0xa000
	global_load_lds_dwordx4 v[6:7], off
	v_lshl_add_u64 v[2:3], v[2:3], 0, s[10:11]
	s_mov_b32 m0, s38
	s_add_u32 s14, s26, 0x40080
	global_load_lds_dwordx4 v[2:3], off
	v_lshl_add_u64 v[2:3], v[4:5], 0, s[10:11]
	s_mov_b32 m0, s39
	s_addc_u32 s15, s27, 0
	global_load_lds_dwordx4 v[2:3], off
	s_add_i32 m0, s23, 0x1c000
	v_lshl_add_u64 v[2:3], s[14:15], 0, v[134:135]
	global_load_lds_dwordx4 v[2:3], off
	v_lshl_add_u64 v[2:3], s[14:15], 0, v[130:131]
	s_add_i32 m0, s23, 0x1e000
	v_bfe_u32 v4, v12, 4, 2
	global_load_lds_dwordx4 v[2:3], off
	v_and_b32_e32 v3, 15, v12
	v_lshlrev_b32_e32 v2, 4, v4
	v_lshlrev_b32_e32 v5, 2, v12
	v_lshl_or_b32 v1, s12, 6, v3
	v_lshl_or_b32 v3, v3, 6, v2
	v_and_b32_e32 v5, 32, v5
	v_bitop3_b32 v6, v3, s13, v5 bitop3:0xde
	v_bitop3_b32 v166, v3, s17, v5 bitop3:0xde
	v_mov_b32_e32 v3, v135
	s_sext_i32_i8 s45, s6
	s_cmpk_lt_u32 s7, 0x100
	v_lshl_add_u64 v[2:3], s[78:79], 0, v[2:3]
	s_mov_b64 s[6:7], 0x5a00000
	v_lshl_add_u64 v[138:139], v[2:3], 0, s[6:7]
	v_lshlrev_b32_e32 v2, 14, v15
	v_and_b32_e32 v2, 0xffff8000, v2
	v_lshl_add_u32 v2, v14, 11, v2
	v_and_b32_e32 v3, 1, v15
	v_lshl_or_b32 v2, v3, 6, v2
	v_lshl_add_u32 v140, v16, 1, v2
	v_lshlrev_b32_e32 v2, 14, v10
	v_and_b32_e32 v2, 0xffff8000, v2
	v_lshl_add_u32 v2, v11, 11, v2
	v_and_b32_e32 v3, 1, v10
	s_waitcnt vmcnt(6)
	v_lshl_or_b32 v2, v3, 6, v2
	s_cselect_b64 s[12:13], -1, 0
	v_lshl_add_u32 v142, v13, 1, v2
	s_add_i32 s42, 0, 0x10000
	s_add_i32 s43, 0, 0x14000
	v_mbcnt_lo_u32_b32 v2, -1, 0
	s_ashr_i32 s40, s82, 31
	s_mov_b32 s41, s82
	v_lshl_or_b32 v167, v4, 3, s16
	v_mov_b32_e32 v141, v135
	v_mov_b32_e32 v143, v135
	v_mov_b64_e32 v[144:145], 0xb00
	v_mov_b64_e32 v[146:147], 0xaff
	v_add_u32_e32 v168, s42, v166
	v_add_u32_e32 v169, s43, v166
	v_add_u32_e32 v170, 0, v6
	v_mbcnt_hi_u32_b32 v171, -1, v2
	v_mov_b32_e32 v172, 0x358637bd
	s_movk_i32 s44, 0x1600
	s_barrier
	s_mov_b32 s98, 0
	s_branch .LBB0_688

; #define PG8_STAGE(bufoff, gbase, voff) do { _Pragma("unroll") for (int _i = 0; _i < 2; ++_i) \
;         __builtin_amdgcn_global_load_lds((const unsigned*)((const char*)(gbase) + (voff)[_i]), (PG8_LAS unsigned*)(lds + (bufoff) + ldsw + _i * 8192), 16, 0, 0); } while (0)
; #define PG8_LDA(dst, b, h) do { _Pragma("unroll") for (int m = 0; m < 4; ++m) _Pragma("unroll") for (int k = 0; k < 2; ++k) dst[m][k] = *(const PG8_LAS bf16x8*)(lds + PG8_SA(b, h) + aoff + m * 2048 + k * 1024); } while (0)
; #define PG8_LDB(dst, b, h) do { _Pragma("unroll") for (int n = 0; n < 2; ++n) _Pragma("unroll") for (int k = 0; k < 2; ++k) dst[n][k] = *(const PG8_LAS bf16x8*)(lds + PG8_SB(b, h) + boff + n * 2048 + k * 1024); } while (0)
; #define PG8_WAIT_V(n) asm volatile("s_waitcnt vmcnt(" #n ")" ::: "memory")
; #define PG8_WAIT_L(n) asm volatile("s_waitcnt lgkmcnt(" #n ")" ::: "memory")
; #define PG8_BAR __builtin_amdgcn_s_barrier()
; template <class Epi, class Sched, bool ALIGN_EPI = false, bool SP2 = false>
; __device__ __forceinline__ void gemm_phase(PG8_LAS unsigned char* lds, const Gemm g, const Sched& S, const Epi& E) {
;     ...
;         const bool has_next = S.next(ui + 1, nxt);
;         const char* nA = has_next ? (const char*)g.A + (size_t)nxt.g * g.gsA * 2 + (size_t)nxt.pm * tstepA : cA; const char* nB = has_next ? (const char*)g.Bt + (size_t)nxt.g * g.gsB * 2 + (size_t)nxt.pn * tstepB : cB;
;         for (int t = 0; t < nt; t += 2) {
;             const bool last = (t == nt - 2);
;             const char* a1 = cA + (size_t)(t + 1) * kstep;
;             const char* a2 = last ? nA : cA + (size_t)(t + 2) * kstep; const char* b2 = last ? nB : cB + (size_t)(t + 2) * kstep;
;             const char* a3 = a2 + kstep; const char* b3 = b2 + kstep;
;             if (last && has_next) S.a_ready(nxt);
;             if constexpr (SP2) {
;             PG8_LDB(B0, 0, 0); PG8_LDB(B1, 0, 1); PG8_SCHED; PG8_LDA(At, 0, 0); PG8_STAGE(PG8_SA(1, 1), a1 + hstepA, voffA);
;             PG8_WAIT_V(8); PG8_WAIT_L(0); PG8_BAR; PG8_MMA(0, 0, At, B0); PG8_MMA(0, 1, At, B1); PG8_BAR; PG8_SCHED;
;             PG8_LDA(At, 0, 1); PG8_STAGE(PG8_SB(0, 0), b2, voffB); PG8_STAGE(PG8_SB(0, 1), b2 + hstepB, voffB); PG8_STAGE(PG8_SA(0, 0), a2, voffA);
;             PG8_WAIT_V(8); PG8_WAIT_L(0); PG8_BAR; PG8_MMA(1, 0, At, B0); PG8_MMA(1, 1, At, B1); PG8_BAR; PG8_SCHED;
.LBB0_690:
	s_ashr_i32 s17, s16, 31
	s_lshl_b64 s[18:19], s[16:17], 19
	s_add_u32 s18, s0, s18
	s_addc_u32 s19, s1, s19
	s_and_b64 s[20:21], s[6:7], exec
	s_cselect_b32 s17, s19, s25
	s_cselect_b32 s46, s18, s24
	s_ashr_i32 s15, s14, 31
	s_lshl_b64 s[20:21], s[14:15], 19
	s_add_u32 s20, s2, s20
	s_addc_u32 s21, s3, s21
	s_and_b64 s[28:29], s[6:7], exec
	s_cselect_b32 s15, s21, s27
	s_cselect_b32 s47, s20, s26
	s_add_u32 s24, s24, 0x40080
	s_addc_u32 s25, s25, 0
	s_add_u32 s48, s26, 0x100
	s_addc_u32 s49, s27, 0
	s_mov_b32 s50, -2
	s_cmp_eq_u32 s98, 1
	s_cbranch_scc0 .Lhb_22739
	s_mov_b32 s98, 0
	s_barrier
.Lhb_22739:
	ds_read_b128 v[148:151], v168
	ds_read_b128 v[152:155], v168 offset:1024
	ds_read_b128 v[156:159], v168 offset:2048
	ds_read_b128 v[160:163], v168 offset:3072
	ds_read_b128 v[174:177], v169
	ds_read_b128 v[178:181], v169 offset:1024
	ds_read_b128 v[182:185], v169 offset:2048
	ds_read_b128 v[186:189], v169 offset:3072
	s_add_u32 s26, s24, 0xfffc0080
	s_addc_u32 s27, s25, -1
	s_cmp_eq_u32 s50, 12
	s_cselect_b32 s29, s17, s27
	s_cselect_b32 s28, s46, s26
	s_cselect_b32 s27, s15, s49
	s_cselect_b32 s26, s47, s48
	v_lshl_add_u64 v[164:165], s[24:25], 0, v[140:141]
	s_add_i32 m0, s23, 0xc000
	ds_read_b128 v[190:193], v170
	ds_read_b128 v[194:197], v170 offset:1024
	ds_read_b128 v[198:201], v170 offset:2048
	ds_read_b128 v[202:205], v170 offset:3072
	ds_read_b128 v[206:209], v170 offset:4096
	ds_read_b128 v[210:213], v170 offset:5120
	ds_read_b128 v[214:217], v170 offset:6144
	ds_read_b128 v[218:221], v170 offset:7168
	global_load_lds_dwordx4 v[164:165], off
	v_lshl_add_u64 v[164:165], s[24:25], 0, v[142:143]
	s_add_i32 m0, s23, 0xe000
	s_nop 0
	global_load_lds_dwordx4 v[164:165], off
	s_waitcnt vmcnt(8)
	s_waitcnt lgkmcnt(0)
	s_barrier
	s_setprio 1
	s_waitcnt lgkmcnt(0)
	v_mfma_f32_16x16x32_bf16 v[126:129], v[148:151], v[190:193], 0
	v_mfma_f32_16x16x32_bf16 v[118:121], v[156:159], v[190:193], 0
	v_mfma_f32_16x16x32_bf16 v[110:113], v[148:151], v[198:201], 0
	v_mfma_f32_16x16x32_bf16 v[102:105], v[156:159], v[198:201], 0
	v_mfma_f32_16x16x32_bf16 v[94:97], v[148:151], v[206:209], 0
	v_mfma_f32_16x16x32_bf16 v[86:89], v[156:159], v[206:209], 0
	v_mfma_f32_16x16x32_bf16 v[78:81], v[148:151], v[214:217], 0
	v_mfma_f32_16x16x32_bf16 v[70:73], v[156:159], v[214:217], 0
	v_mfma_f32_16x16x32_bf16 v[126:129], v[152:155], v[194:197], v[126:129]
	v_mfma_f32_16x16x32_bf16 v[118:121], v[160:163], v[194:197], v[118:121]
	v_mfma_f32_16x16x32_bf16 v[110:113], v[152:155], v[202:205], v[110:113]
	v_mfma_f32_16x16x32_bf16 v[102:105], v[160:163], v[202:205], v[102:105]
	v_mfma_f32_16x16x32_bf16 v[94:97], v[152:155], v[210:213], v[94:97]
	v_mfma_f32_16x16x32_bf16 v[86:89], v[160:163], v[210:213], v[86:89]
	v_mfma_f32_16x16x32_bf16 v[78:81], v[152:155], v[218:221], v[78:81]
	v_mfma_f32_16x16x32_bf16 v[70:73], v[160:163], v[218:221], v[70:73]
	s_setprio 0
	s_setprio 1
	v_mfma_f32_16x16x32_bf16 v[122:125], v[174:177], v[190:193], 0
	v_mfma_f32_16x16x32_bf16 v[114:117], v[182:185], v[190:193], 0
	v_mfma_f32_16x16x32_bf16 v[106:109], v[174:177], v[198:201], 0
	v_mfma_f32_16x16x32_bf16 v[98:101], v[182:185], v[198:201], 0
	v_mfma_f32_16x16x32_bf16 v[90:93], v[174:177], v[206:209], 0
	v_mfma_f32_16x16x32_bf16 v[82:85], v[182:185], v[206:209], 0
	v_mfma_f32_16x16x32_bf16 v[74:77], v[174:177], v[214:217], 0
	v_mfma_f32_16x16x32_bf16 v[66:69], v[182:185], v[214:217], 0
	v_mfma_f32_16x16x32_bf16 v[122:125], v[178:181], v[194:197], v[122:125]
	v_mfma_f32_16x16x32_bf16 v[114:117], v[186:189], v[194:197], v[114:117]
	v_mfma_f32_16x16x32_bf16 v[106:109], v[178:181], v[202:205], v[106:109]
	v_mfma_f32_16x16x32_bf16 v[98:101], v[186:189], v[202:205], v[98:101]
	v_mfma_f32_16x16x32_bf16 v[90:93], v[178:181], v[210:213], v[90:93]
	v_mfma_f32_16x16x32_bf16 v[82:85], v[186:189], v[210:213], v[82:85]
	v_mfma_f32_16x16x32_bf16 v[74:77], v[178:181], v[218:221], v[74:77]
	v_mfma_f32_16x16x32_bf16 v[66:69], v[186:189], v[218:221], v[66:69]
	s_setprio 0
	s_barrier
	s_add_i32 s51, s42, s30
	v_lshl_add_u64 v[164:165], s[26:27], 0, v[134:135]
	s_mov_b32 m0, s51
	ds_read_b128 v[190:193], v170 offset:16384
	ds_read_b128 v[194:197], v170 offset:17408
	ds_read_b128 v[198:201], v170 offset:18432
	ds_read_b128 v[202:205], v170 offset:19456
	ds_read_b128 v[206:209], v170 offset:20480
	ds_read_b128 v[210:213], v170 offset:21504
	ds_read_b128 v[214:217], v170 offset:22528
	ds_read_b128 v[218:221], v170 offset:23552
	global_load_lds_dwordx4 v[164:165], off
	s_add_i32 m0, s51, 0x2000
	s_add_u32 s52, s26, 0x40000
	v_lshl_add_u64 v[222:223], s[26:27], 0, v[130:131]
	s_addc_u32 s53, s27, 0
	s_add_i32 s51, s43, s30
	global_load_lds_dwordx4 v[222:223], off
	v_lshl_add_u64 v[224:225], s[52:53], 0, v[134:135]
	s_mov_b32 m0, s51
	v_lshl_add_u64 v[226:227], s[28:29], 0, v[132:133]
	global_load_lds_dwordx4 v[224:225], off
	v_lshl_add_u64 v[224:225], s[52:53], 0, v[130:131]
	s_add_i32 m0, s51, 0x2000
	s_nop 0
	global_load_lds_dwordx4 v[224:225], off
	v_lshl_add_u64 v[224:225], s[28:29], 0, v[136:137]
	s_mov_b32 m0, s23
	s_nop 0
	global_load_lds_dwordx4 v[224:225], off
	s_mov_b32 m0, s34
	s_nop 0
	global_load_lds_dwordx4 v[226:227], off
	s_waitcnt vmcnt(8)
	s_waitcnt lgkmcnt(0)
	s_barrier
; #define PG8_STAGE(bufoff, gbase, voff) do { _Pragma("unroll") for (int _i = 0; _i < 2; ++_i) \
;         __builtin_amdgcn_global_load_lds((const unsigned*)((const char*)(gbase) + (voff)[_i]), (PG8_LAS unsigned*)(lds + (bufoff) + ldsw + _i * 8192), 16, 0, 0); } while (0)
; #define PG8_LDA(dst, b, h) do { _Pragma("unroll") for (int m = 0; m < 4; ++m) _Pragma("unroll") for (int k = 0; k < 2; ++k) dst[m][k] = *(const PG8_LAS bf16x8*)(lds + PG8_SA(b, h) + aoff + m * 2048 + k * 1024); } while (0)
; #define PG8_LDB(dst, b, h) do { _Pragma("unroll") for (int n = 0; n < 2; ++n) _Pragma("unroll") for (int k = 0; k < 2; ++k) dst[n][k] = *(const PG8_LAS bf16x8*)(lds + PG8_SB(b, h) + boff + n * 2048 + k * 1024); } while (0)
; #define PG8_MMA(ai, bj, At, Bt) do { __builtin_amdgcn_s_setprio(1); _Pragma("unroll") for (int m = 0; m < 4; ++m) _Pragma("unroll") for (int n = 0; n < 2; ++n) _Pragma("unroll") for (int k = 0; k < 2; ++k) \
;         acc[ai][bj][m][n] = __builtin_amdgcn_mfma_f32_16x16x32_bf16(Bt[n][k], At[m][k], acc[ai][bj][m][n], 0, 0, 0); __builtin_amdgcn_s_setprio(0); } while (0)
; #define PG8_WAIT_V(n) asm volatile("s_waitcnt vmcnt(" #n ")" ::: "memory")
; #define PG8_WAIT_L(n) asm volatile("s_waitcnt lgkmcnt(" #n ")" ::: "memory")
; #define PG8_BAR __builtin_amdgcn_s_barrier()
; #define PG8_SCHED __builtin_amdgcn_sched_barrier(0)
; template <class Epi, class Sched, bool ALIGN_EPI = false, bool SP2 = false>
; __device__ __forceinline__ void gemm_phase(PG8_LAS unsigned char* lds, const Gemm g, const Sched& S, const Epi& E) {
;     ...
;             PG8_WAIT_V(8); PG8_WAIT_L(0); PG8_BAR; PG8_MMA(1, 0, At, B0); PG8_MMA(1, 1, At, B1); PG8_BAR; PG8_SCHED;
;             PG8_LDB(B0, 1, 0); PG8_LDB(B1, 1, 1); PG8_SCHED; PG8_LDA(At, 1, 0); PG8_STAGE(PG8_SA(0, 1), a2 + hstepA, voffA);
;             PG8_WAIT_V(8); PG8_WAIT_L(0); PG8_BAR; PG8_MMA(0, 0, At, B0); PG8_MMA(0, 1, At, B1); PG8_BAR; PG8_SCHED;
;             PG8_LDA(At, 1, 1); PG8_STAGE(PG8_SB(1, 0), b3, voffB); PG8_STAGE(PG8_SB(1, 1), b3 + hstepB, voffB); PG8_STAGE(PG8_SA(1, 0), a3, voffA);
	s_setprio 1
	s_waitcnt lgkmcnt(0)
	v_mfma_f32_16x16x32_bf16 v[62:65], v[148:151], v[190:193], 0
	v_mfma_f32_16x16x32_bf16 v[54:57], v[156:159], v[190:193], 0
	v_mfma_f32_16x16x32_bf16 v[46:49], v[148:151], v[198:201], 0
	v_mfma_f32_16x16x32_bf16 v[38:41], v[156:159], v[198:201], 0
	v_mfma_f32_16x16x32_bf16 v[30:33], v[148:151], v[206:209], 0
	v_mfma_f32_16x16x32_bf16 v[22:25], v[156:159], v[206:209], 0
	v_mfma_f32_16x16x32_bf16 v[14:17], v[148:151], v[214:217], 0
	v_mfma_f32_16x16x32_bf16 v[6:9], v[156:159], v[214:217], 0
	v_mfma_f32_16x16x32_bf16 v[62:65], v[152:155], v[194:197], v[62:65]
	v_mfma_f32_16x16x32_bf16 v[54:57], v[160:163], v[194:197], v[54:57]
	v_mfma_f32_16x16x32_bf16 v[46:49], v[152:155], v[202:205], v[46:49]
	v_mfma_f32_16x16x32_bf16 v[38:41], v[160:163], v[202:205], v[38:41]
	v_mfma_f32_16x16x32_bf16 v[30:33], v[152:155], v[210:213], v[30:33]
	v_mfma_f32_16x16x32_bf16 v[22:25], v[160:163], v[210:213], v[22:25]
	v_mfma_f32_16x16x32_bf16 v[14:17], v[152:155], v[218:221], v[14:17]
	v_mfma_f32_16x16x32_bf16 v[6:9], v[160:163], v[218:221], v[6:9]
	s_setprio 0
	s_setprio 1
	v_mfma_f32_16x16x32_bf16 v[58:61], v[174:177], v[190:193], 0
	v_mfma_f32_16x16x32_bf16 v[50:53], v[182:185], v[190:193], 0
	v_mfma_f32_16x16x32_bf16 v[42:45], v[174:177], v[198:201], 0
	v_mfma_f32_16x16x32_bf16 v[34:37], v[182:185], v[198:201], 0
	v_mfma_f32_16x16x32_bf16 v[26:29], v[174:177], v[206:209], 0
	v_mfma_f32_16x16x32_bf16 v[18:21], v[182:185], v[206:209], 0
	v_mfma_f32_16x16x32_bf16 v[10:13], v[174:177], v[214:217], 0
	v_mfma_f32_16x16x32_bf16 v[2:5], v[182:185], v[214:217], 0
	v_mfma_f32_16x16x32_bf16 v[58:61], v[178:181], v[194:197], v[58:61]
	v_mfma_f32_16x16x32_bf16 v[50:53], v[186:189], v[194:197], v[50:53]
	v_mfma_f32_16x16x32_bf16 v[42:45], v[178:181], v[202:205], v[42:45]
	v_mfma_f32_16x16x32_bf16 v[34:37], v[186:189], v[202:205], v[34:37]
	v_mfma_f32_16x16x32_bf16 v[26:29], v[178:181], v[210:213], v[26:29]
	v_mfma_f32_16x16x32_bf16 v[18:21], v[186:189], v[210:213], v[18:21]
	v_mfma_f32_16x16x32_bf16 v[10:13], v[178:181], v[218:221], v[10:13]
	v_mfma_f32_16x16x32_bf16 v[2:5], v[186:189], v[218:221], v[2:5]
	s_setprio 0
	s_barrier
	s_add_i32 s51, 0, 0x18000
	s_add_i32 s52, 0, 0x1c000
	v_add_u32_e32 v160, s51, v166
	v_add_u32_e32 v173, s52, v166
	ds_read_b128 v[148:151], v160
	ds_read_b128 v[152:155], v160 offset:1024
	ds_read_b128 v[156:159], v160 offset:2048
	ds_read_b128 v[160:163], v160 offset:3072
	ds_read_b128 v[174:177], v173
	ds_read_b128 v[178:181], v173 offset:1024
	ds_read_b128 v[182:185], v173 offset:2048
	ds_read_b128 v[186:189], v173 offset:3072
	s_add_u32 s28, s28, 0x40000
	s_addc_u32 s29, s29, 0
	s_mov_b32 m0, s35
	v_lshl_add_u64 v[228:229], s[28:29], 0, v[136:137]
	ds_read_b128 v[190:193], v170 offset:32768
	ds_read_b128 v[194:197], v170 offset:33792
	ds_read_b128 v[198:201], v170 offset:34816
	ds_read_b128 v[202:205], v170 offset:35840
	ds_read_b128 v[206:209], v170 offset:36864
	ds_read_b128 v[210:213], v170 offset:37888
	ds_read_b128 v[214:217], v170 offset:38912
	ds_read_b128 v[218:221], v170 offset:39936
	global_load_lds_dwordx4 v[228:229], off
	v_lshl_add_u64 v[228:229], s[28:29], 0, v[132:133]
	s_mov_b32 m0, s36
	s_nop 0
	global_load_lds_dwordx4 v[228:229], off
	s_waitcnt vmcnt(8)
	s_waitcnt lgkmcnt(0)
	s_barrier
	s_setprio 1
	s_waitcnt lgkmcnt(0)
	v_mfma_f32_16x16x32_bf16 v[126:129], v[148:151], v[190:193], v[126:129]
	v_mfma_f32_16x16x32_bf16 v[118:121], v[156:159], v[190:193], v[118:121]
	v_mfma_f32_16x16x32_bf16 v[110:113], v[148:151], v[198:201], v[110:113]
	v_mfma_f32_16x16x32_bf16 v[102:105], v[156:159], v[198:201], v[102:105]
	v_mfma_f32_16x16x32_bf16 v[94:97], v[148:151], v[206:209], v[94:97]
	v_mfma_f32_16x16x32_bf16 v[86:89], v[156:159], v[206:209], v[86:89]
	v_mfma_f32_16x16x32_bf16 v[78:81], v[148:151], v[214:217], v[78:81]
	v_mfma_f32_16x16x32_bf16 v[70:73], v[156:159], v[214:217], v[70:73]
	v_mfma_f32_16x16x32_bf16 v[126:129], v[152:155], v[194:197], v[126:129]
	v_mfma_f32_16x16x32_bf16 v[118:121], v[160:163], v[194:197], v[118:121]
	v_mfma_f32_16x16x32_bf16 v[110:113], v[152:155], v[202:205], v[110:113]
	v_mfma_f32_16x16x32_bf16 v[102:105], v[160:163], v[202:205], v[102:105]
	v_mfma_f32_16x16x32_bf16 v[94:97], v[152:155], v[210:213], v[94:97]
	v_mfma_f32_16x16x32_bf16 v[86:89], v[160:163], v[210:213], v[86:89]
	v_mfma_f32_16x16x32_bf16 v[78:81], v[152:155], v[218:221], v[78:81]
	v_mfma_f32_16x16x32_bf16 v[70:73], v[160:163], v[218:221], v[70:73]
	s_setprio 0
	s_setprio 1
	v_mfma_f32_16x16x32_bf16 v[122:125], v[174:177], v[190:193], v[122:125]
	v_mfma_f32_16x16x32_bf16 v[114:117], v[182:185], v[190:193], v[114:117]
	v_mfma_f32_16x16x32_bf16 v[106:109], v[174:177], v[198:201], v[106:109]
	v_mfma_f32_16x16x32_bf16 v[98:101], v[182:185], v[198:201], v[98:101]
	v_mfma_f32_16x16x32_bf16 v[90:93], v[174:177], v[206:209], v[90:93]
	v_mfma_f32_16x16x32_bf16 v[82:85], v[182:185], v[206:209], v[82:85]
	v_mfma_f32_16x16x32_bf16 v[74:77], v[174:177], v[214:217], v[74:77]
	v_mfma_f32_16x16x32_bf16 v[66:69], v[182:185], v[214:217], v[66:69]
	v_mfma_f32_16x16x32_bf16 v[122:125], v[178:181], v[194:197], v[122:125]
	v_mfma_f32_16x16x32_bf16 v[114:117], v[186:189], v[194:197], v[114:117]
	v_mfma_f32_16x16x32_bf16 v[106:109], v[178:181], v[202:205], v[106:109]
	v_mfma_f32_16x16x32_bf16 v[98:101], v[186:189], v[202:205], v[98:101]
	v_mfma_f32_16x16x32_bf16 v[90:93], v[178:181], v[210:213], v[90:93]
	v_mfma_f32_16x16x32_bf16 v[82:85], v[186:189], v[210:213], v[82:85]
	v_mfma_f32_16x16x32_bf16 v[74:77], v[178:181], v[218:221], v[74:77]
	v_mfma_f32_16x16x32_bf16 v[66:69], v[186:189], v[218:221], v[66:69]
	s_setprio 0
	s_barrier
; #define PG8_STAGE(bufoff, gbase, voff) do { _Pragma("unroll") for (int _i = 0; _i < 2; ++_i) \
;         __builtin_amdgcn_global_load_lds((const unsigned*)((const char*)(gbase) + (voff)[_i]), (PG8_LAS unsigned*)(lds + (bufoff) + ldsw + _i * 8192), 16, 0, 0); } while (0)
; #define PG8_LDA(dst, b, h) do { _Pragma("unroll") for (int m = 0; m < 4; ++m) _Pragma("unroll") for (int k = 0; k < 2; ++k) dst[m][k] = *(const PG8_LAS bf16x8*)(lds + PG8_SA(b, h) + aoff + m * 2048 + k * 1024); } while (0)
; #define PG8_MMA(ai, bj, At, Bt) do { __builtin_amdgcn_s_setprio(1); _Pragma("unroll") for (int m = 0; m < 4; ++m) _Pragma("unroll") for (int n = 0; n < 2; ++n) _Pragma("unroll") for (int k = 0; k < 2; ++k) \
;         acc[ai][bj][m][n] = __builtin_amdgcn_mfma_f32_16x16x32_bf16(Bt[n][k], At[m][k], acc[ai][bj][m][n], 0, 0, 0); __builtin_amdgcn_s_setprio(0); } while (0)
; #define PG8_WAIT_V(n) asm volatile("s_waitcnt vmcnt(" #n ")" ::: "memory")
; #define PG8_WAIT_L(n) asm volatile("s_waitcnt lgkmcnt(" #n ")" ::: "memory")
; #define PG8_BAR __builtin_amdgcn_s_barrier()
; #define PG8_SCHED __builtin_amdgcn_sched_barrier(0)
; template <class Epi, class Sched, bool ALIGN_EPI = false, bool SP2 = false>
; __device__ __forceinline__ void gemm_phase(PG8_LAS unsigned char* lds, const Gemm g, const Sched& S, const Epi& E) {
;     ...
;         for (int t = 0; t < nt; t += 2) {
;     ...
;             PG8_LDA(At, 1, 1); PG8_STAGE(PG8_SB(1, 0), b3, voffB); PG8_STAGE(PG8_SB(1, 1), b3 + hstepB, voffB); PG8_STAGE(PG8_SA(1, 0), a3, voffA);
;             PG8_WAIT_V(8); PG8_WAIT_L(0); PG8_BAR; PG8_MMA(1, 0, At, B0); PG8_MMA(1, 1, At, B1); PG8_BAR; PG8_SCHED;
	s_add_i32 s28, s51, s30
	v_lshl_add_u64 v[164:165], v[164:165], 0, s[10:11]
	s_mov_b32 m0, s28
	ds_read_b128 v[190:193], v170 offset:49152
	ds_read_b128 v[194:197], v170 offset:50176
	ds_read_b128 v[198:201], v170 offset:51200
	ds_read_b128 v[202:205], v170 offset:52224
	ds_read_b128 v[206:209], v170 offset:53248
	ds_read_b128 v[210:213], v170 offset:54272
	ds_read_b128 v[214:217], v170 offset:55296
	ds_read_b128 v[218:221], v170 offset:56320
	global_load_lds_dwordx4 v[164:165], off
	s_add_i32 m0, s28, 0x2000
	s_add_u32 s26, s26, 0x40080
	v_lshl_add_u64 v[164:165], v[222:223], 0, s[10:11]
	s_addc_u32 s27, s27, 0
	s_add_i32 s28, s52, s30
	global_load_lds_dwordx4 v[164:165], off
	v_lshl_add_u64 v[164:165], s[26:27], 0, v[134:135]
	s_mov_b32 m0, s28
	s_nop 0
	global_load_lds_dwordx4 v[164:165], off
	v_lshl_add_u64 v[164:165], s[26:27], 0, v[130:131]
	s_add_i32 m0, s28, 0x2000
	s_nop 0
	global_load_lds_dwordx4 v[164:165], off
	v_lshl_add_u64 v[164:165], v[224:225], 0, s[10:11]
	s_mov_b32 m0, s38
	s_nop 0
	global_load_lds_dwordx4 v[164:165], off
	v_lshl_add_u64 v[164:165], v[226:227], 0, s[10:11]
	s_mov_b32 m0, s39
	s_nop 0
	global_load_lds_dwordx4 v[164:165], off
	s_waitcnt vmcnt(8)
	s_waitcnt lgkmcnt(0)
	s_barrier
	s_setprio 1
	s_waitcnt lgkmcnt(0)
	v_mfma_f32_16x16x32_bf16 v[62:65], v[148:151], v[190:193], v[62:65]
	v_mfma_f32_16x16x32_bf16 v[54:57], v[156:159], v[190:193], v[54:57]
	v_mfma_f32_16x16x32_bf16 v[46:49], v[148:151], v[198:201], v[46:49]
	v_mfma_f32_16x16x32_bf16 v[38:41], v[156:159], v[198:201], v[38:41]
	v_mfma_f32_16x16x32_bf16 v[30:33], v[148:151], v[206:209], v[30:33]
	v_mfma_f32_16x16x32_bf16 v[22:25], v[156:159], v[206:209], v[22:25]
	v_mfma_f32_16x16x32_bf16 v[14:17], v[148:151], v[214:217], v[14:17]
	v_mfma_f32_16x16x32_bf16 v[6:9], v[156:159], v[214:217], v[6:9]
	v_mfma_f32_16x16x32_bf16 v[62:65], v[152:155], v[194:197], v[62:65]
	v_mfma_f32_16x16x32_bf16 v[54:57], v[160:163], v[194:197], v[54:57]
	v_mfma_f32_16x16x32_bf16 v[46:49], v[152:155], v[202:205], v[46:49]
	v_mfma_f32_16x16x32_bf16 v[38:41], v[160:163], v[202:205], v[38:41]
	v_mfma_f32_16x16x32_bf16 v[30:33], v[152:155], v[210:213], v[30:33]
	v_mfma_f32_16x16x32_bf16 v[22:25], v[160:163], v[210:213], v[22:25]
	v_mfma_f32_16x16x32_bf16 v[14:17], v[152:155], v[218:221], v[14:17]
	v_mfma_f32_16x16x32_bf16 v[6:9], v[160:163], v[218:221], v[6:9]
	s_setprio 0
	s_setprio 1
	v_mfma_f32_16x16x32_bf16 v[58:61], v[174:177], v[190:193], v[58:61]
	v_mfma_f32_16x16x32_bf16 v[50:53], v[182:185], v[190:193], v[50:53]
	v_mfma_f32_16x16x32_bf16 v[42:45], v[174:177], v[198:201], v[42:45]
	v_mfma_f32_16x16x32_bf16 v[34:37], v[182:185], v[198:201], v[34:37]
	v_mfma_f32_16x16x32_bf16 v[26:29], v[174:177], v[206:209], v[26:29]
	v_mfma_f32_16x16x32_bf16 v[18:21], v[182:185], v[206:209], v[18:21]
	v_mfma_f32_16x16x32_bf16 v[10:13], v[174:177], v[214:217], v[10:13]
	v_mfma_f32_16x16x32_bf16 v[2:5], v[182:185], v[214:217], v[2:5]
	v_mfma_f32_16x16x32_bf16 v[58:61], v[178:181], v[194:197], v[58:61]
	v_mfma_f32_16x16x32_bf16 v[50:53], v[186:189], v[194:197], v[50:53]
	v_mfma_f32_16x16x32_bf16 v[42:45], v[178:181], v[202:205], v[42:45]
	v_mfma_f32_16x16x32_bf16 v[34:37], v[186:189], v[202:205], v[34:37]
	v_mfma_f32_16x16x32_bf16 v[26:29], v[178:181], v[210:213], v[26:29]
	v_mfma_f32_16x16x32_bf16 v[18:21], v[186:189], v[210:213], v[18:21]
	v_mfma_f32_16x16x32_bf16 v[10:13], v[178:181], v[218:221], v[10:13]
	v_mfma_f32_16x16x32_bf16 v[2:5], v[186:189], v[218:221], v[2:5]
	s_setprio 0
	s_barrier
	s_add_i32 s50, s50, 2
	s_add_u32 s24, s24, 0x100
	s_addc_u32 s25, s25, 0
	s_add_u32 s48, s48, 0x100
	s_addc_u32 s49, s49, 0
	s_cmp_gt_u32 s50, 13

; __device__ __forceinline__ unsigned cvt_pk_bf16(float lo, float hi) { unsigned r; asm volatile("v_cvt_pk_bf16_f32 %0, %1, %2" : "=v"(r) : "v"(lo), "v"(hi)); return r; }
; __device__ __forceinline__ void rstd8(const float* ss, int row0, int fq, float (&rs)[8]) {
;     f32x4 a[8];
; #pragma unroll
;     for (int k = 0; k < 8; ++k) a[k] = *(const f32x4*)(ss + (size_t)(row0 + (k >> 2) * 128 + (k & 3) * 16) * 16 + 4 * fq);
; #pragma unroll
;     for (int k = 0; k < 8; ++k) { float s = (a[k][0] + a[k][1]) + (a[k][2] + a[k][3]); s += __shfl_xor(s, 16); s += __shfl_xor(s, 32); rs[k] = __builtin_amdgcn_rsqf(s * (1.f / 1024.f) + EPS); }
; }
;     __device__ __forceinline__ void operator()(const pg8::f32x4 (&acc)[2][2][4][2], const Unit& u, int wr, int wc, int fr, int fq) const {
;         const int row0 = u.pm * BM + wr * 64 + fr, col0 = u.pn * HALF + wc * 32 + 8 * fq;
;         float rsv[8]; rstd8(ss, row0, fq, rsv);
; #pragma unroll
;         for (int ai = 0; ai < 2; ++ai)
; #pragma unroll
;             for (int m = 0; m < 4; ++m) { float r[8]; const float rs = rsv[ai * 4 + m]; const float c1 = -1.4426950408889634f * rs, rs2 = rs * rs;
; #pragma unroll
;                 for (int n = 0; n < 2; ++n)
; #pragma unroll
;                     for (int e = 0; e < 4; e += 2) { const f32x2 ag = {acc[ai][0][m][n][e], acc[ai][0][m][n][e + 1]}, au = {acc[ai][1][m][n][e], acc[ai][1][m][n][e + 1]};
;                         const f32x2 t = ag * c1; f32x2 d; d.x = __builtin_amdgcn_exp2f(t.x); d.y = __builtin_amdgcn_exp2f(t.y); d = d + 1.0f;
;                         f32x2 q; q.x = __builtin_amdgcn_rcpf(d.x); q.y = __builtin_amdgcn_rcpf(d.y); const f32x2 o = (ag * au) * rs2 * q; r[4 * n + e] = o.x; r[4 * n + e + 1] = o.y; }
;                 v4u w; w.x = cvt_pk_bf16(r[0], r[1]); w.y = cvt_pk_bf16(r[2], r[3]); w.z = cvt_pk_bf16(r[4], r[5]); w.w = cvt_pk_bf16(r[6], r[7]);
;                 __builtin_nontemporal_store(w, (v4u*)(O + (size_t)(row0 + ai * HALF + m * 16) * FF + col0)); }
.LBB0_694:
	v_lshl_add_u32 v162, s22, 8, v1
	v_ashrrev_i32_e32 v163, 31, v162
	v_or_b32_e32 v160, 16, v162
	v_lshlrev_b64 v[148:149], 6, v[162:163]
	v_ashrrev_i32_e32 v161, 31, v160
	v_or_b32_e32 v158, 32, v162
	v_lshl_add_u64 v[148:149], v[138:139], 0, v[148:149]
	v_lshlrev_b64 v[150:151], 6, v[160:161]
	v_ashrrev_i32_e32 v159, 31, v158
	v_or_b32_e32 v156, 48, v162
	v_lshl_add_u64 v[150:151], v[138:139], 0, v[150:151]
	global_load_dwordx4 v[174:177], v[148:149], off
	global_load_dwordx4 v[178:181], v[150:151], off
	v_lshlrev_b64 v[148:149], 6, v[158:159]
	v_ashrrev_i32_e32 v157, 31, v156
	v_lshl_add_u64 v[148:149], v[138:139], 0, v[148:149]
	v_lshlrev_b64 v[150:151], 6, v[156:157]
	v_lshl_add_u64 v[150:151], v[138:139], 0, v[150:151]
	global_load_dwordx4 v[182:185], v[148:149], off
	global_load_dwordx4 v[186:189], v[150:151], off
	v_add_u32_e32 v154, 0x80, v162
	v_ashrrev_i32_e32 v155, 31, v154
	v_lshlrev_b64 v[148:149], 6, v[154:155]
	v_lshl_add_u64 v[148:149], v[138:139], 0, v[148:149]
	global_load_dwordx4 v[190:193], v[148:149], off
	v_add_u32_e32 v152, 0x90, v162
	v_ashrrev_i32_e32 v153, 31, v152
	v_lshlrev_b64 v[148:149], 6, v[152:153]
	v_add_u32_e32 v150, 0xa0, v162
	v_lshl_add_u64 v[148:149], v[138:139], 0, v[148:149]
	v_ashrrev_i32_e32 v151, 31, v150
	global_load_dwordx4 v[194:197], v[148:149], off
	v_lshlrev_b64 v[148:149], 6, v[150:151]
	v_lshl_add_u64 v[148:149], v[138:139], 0, v[148:149]
	global_load_dwordx4 v[198:201], v[148:149], off
	v_add_u32_e32 v148, 0xb0, v162
	v_ashrrev_i32_e32 v149, 31, v148
	v_lshlrev_b64 v[202:203], 6, v[148:149]
	v_lshl_add_u64 v[202:203], v[138:139], 0, v[202:203]
	global_load_dwordx4 v[202:205], v[202:203], off
	v_and_b32_e32 v151, 64, v171
	v_xor_b32_e32 v149, 16, v171
	v_add_u32_e32 v151, 64, v151
	v_xor_b32_e32 v153, 32, v171
	v_cmp_lt_i32_e32 vcc, v149, v151
	v_pk_mul_f32 v[124:125], v[128:129], v[124:125]
	v_pk_mul_f32 v[122:123], v[126:127], v[122:123]
	v_cndmask_b32_e32 v149, v171, v149, vcc
	v_cmp_lt_i32_e32 vcc, v153, v151
	v_lshlrev_b32_e32 v149, 2, v149
	v_pk_mul_f32 v[114:115], v[118:119], v[114:115]
	v_cndmask_b32_e32 v151, v171, v153, vcc
	v_lshlrev_b32_e32 v151, 2, v151
	v_pk_mul_f32 v[116:117], v[120:121], v[116:117]
	v_lshl_or_b32 v164, s45, 7, v167
	v_pk_mul_f32 v[108:109], v[112:113], v[108:109]
	v_pk_mul_f32 v[106:107], v[110:111], v[106:107]
	v_pk_mul_f32 v[98:99], v[102:103], v[98:99]
	v_pk_mul_f32 v[100:101], v[104:105], v[100:101]
	v_pk_mul_f32 v[92:93], v[96:97], v[92:93]
	v_pk_mul_f32 v[90:91], v[94:95], v[90:91]
	v_pk_mul_f32 v[82:83], v[86:87], v[82:83]
	v_pk_mul_f32 v[84:85], v[88:89], v[84:85]
	v_pk_mul_f32 v[76:77], v[80:81], v[76:77]
	v_pk_mul_f32 v[74:75], v[78:79], v[74:75]
	v_pk_mul_f32 v[66:67], v[70:71], v[66:67]
	v_pk_mul_f32 v[68:69], v[72:73], v[68:69]
	v_pk_mul_f32 v[60:61], v[64:65], v[60:61]
	v_pk_mul_f32 v[58:59], v[62:63], v[58:59]
	v_pk_mul_f32 v[50:51], v[54:55], v[50:51]
	v_pk_mul_f32 v[52:53], v[56:57], v[52:53]
	v_pk_mul_f32 v[44:45], v[48:49], v[44:45]
	v_pk_mul_f32 v[42:43], v[46:47], v[42:43]
	v_pk_mul_f32 v[34:35], v[38:39], v[34:35]
	v_pk_mul_f32 v[36:37], v[40:41], v[36:37]
	v_pk_mul_f32 v[28:29], v[32:33], v[28:29]
	v_pk_mul_f32 v[26:27], v[30:31], v[26:27]
	v_pk_mul_f32 v[18:19], v[22:23], v[18:19]
	v_pk_mul_f32 v[20:21], v[24:25], v[20:21]
	v_pk_mul_f32 v[12:13], v[16:17], v[12:13]
	v_pk_mul_f32 v[10:11], v[14:15], v[10:11]
	v_pk_mul_f32 v[2:3], v[6:7], v[2:3]
	v_pk_mul_f32 v[4:5], v[8:9], v[4:5]
	s_andn2_b64 vcc, exec, s[6:7]
	s_mov_b64 s[6:7], -1
	s_waitcnt vmcnt(0)
	v_mov_b32_e32 v206, v175
	v_mov_b32_e32 v207, v176
	v_mov_b32_e32 v175, v177
	v_pk_add_f32 v[174:175], v[206:207], v[174:175]
	v_mov_b32_e32 v176, v179
	v_mov_b32_e32 v177, v180
	v_mov_b32_e32 v179, v181
	v_mov_b32_e32 v180, v183
	v_mov_b32_e32 v181, v184
	v_mov_b32_e32 v183, v185
	v_mov_b32_e32 v184, v187
	v_mov_b32_e32 v185, v188
	v_mov_b32_e32 v187, v189
	v_add_f32_e32 v153, v174, v175
	v_pk_add_f32 v[174:175], v[176:177], v[178:179]
	v_pk_add_f32 v[176:177], v[180:181], v[182:183]
	v_pk_add_f32 v[178:179], v[184:185], v[186:187]
	v_add_f32_e32 v157, v174, v175
	v_add_f32_e32 v159, v176, v177
	v_add_f32_e32 v161, v178, v179
	ds_bpermute_b32 v155, v149, v153
	ds_bpermute_b32 v165, v149, v157
	ds_bpermute_b32 v173, v149, v159
	ds_bpermute_b32 v174, v149, v161
	v_mov_b32_e32 v188, v191
	v_mov_b32_e32 v189, v192
	v_mov_b32_e32 v191, v193
	v_pk_add_f32 v[180:181], v[188:189], v[190:191]
	s_waitcnt lgkmcnt(3)
	v_add_f32_e32 v153, v153, v155
	v_add_f32_e32 v163, v180, v181
	s_waitcnt lgkmcnt(2)
	v_add_f32_e32 v157, v157, v165
	s_waitcnt lgkmcnt(1)
	v_add_f32_e32 v159, v159, v173
	s_waitcnt lgkmcnt(0)
	v_add_f32_e32 v161, v161, v174
	ds_bpermute_b32 v175, v149, v163
	ds_bpermute_b32 v155, v151, v153
	ds_bpermute_b32 v165, v151, v157
	ds_bpermute_b32 v173, v151, v159
	ds_bpermute_b32 v174, v151, v161
	s_waitcnt lgkmcnt(4)
	v_add_f32_e32 v163, v163, v175
	s_waitcnt lgkmcnt(3)
	v_add_f32_e32 v153, v153, v155
	s_waitcnt lgkmcnt(2)
	v_add_f32_e32 v155, v157, v165
	s_waitcnt lgkmcnt(1)
	v_add_f32_e32 v157, v159, v173
	s_waitcnt lgkmcnt(0)
	v_add_f32_e32 v159, v161, v174
	v_mov_b32_e32 v174, v195
	v_mov_b32_e32 v175, v196
	v_mov_b32_e32 v195, v197
	v_pk_add_f32 v[174:175], v[174:175], v[194:195]
	ds_bpermute_b32 v176, v151, v163
	v_add_f32_e32 v161, v174, v175
	v_mov_b32_e32 v174, v199
	v_mov_b32_e32 v175, v200
	v_mov_b32_e32 v199, v201
	v_pk_add_f32 v[174:175], v[174:175], v[198:199]
	ds_bpermute_b32 v165, v149, v161
	v_add_f32_e32 v173, v174, v175
	v_mov_b32_e32 v174, v203
	v_mov_b32_e32 v175, v204
	v_mov_b32_e32 v203, v205
	v_pk_add_f32 v[174:175], v[174:175], v[202:203]
	s_waitcnt lgkmcnt(1)
; __device__ __forceinline__ unsigned cvt_pk_bf16(float lo, float hi) { unsigned r; asm volatile("v_cvt_pk_bf16_f32 %0, %1, %2" : "=v"(r) : "v"(lo), "v"(hi)); return r; }
;     __device__ __forceinline__ void operator()(const pg8::f32x4 (&acc)[2][2][4][2], const Unit& u, int wr, int wc, int fr, int fq) const {
;         const int row0 = u.pm * BM + wr * 64 + fr, col0 = u.pn * HALF + wc * 32 + 8 * fq;
;         float rsv[8]; rstd8(ss, row0, fq, rsv);
; #pragma unroll
;         for (int ai = 0; ai < 2; ++ai)
; #pragma unroll
;             for (int m = 0; m < 4; ++m) { float r[8]; const float rs = rsv[ai * 4 + m]; const float c1 = -1.4426950408889634f * rs, rs2 = rs * rs;
; #pragma unroll
;                 for (int n = 0; n < 2; ++n)
; #pragma unroll
;                     for (int e = 0; e < 4; e += 2) { const f32x2 ag = {acc[ai][0][m][n][e], acc[ai][0][m][n][e + 1]}, au = {acc[ai][1][m][n][e], acc[ai][1][m][n][e + 1]};
;                         const f32x2 t = ag * c1; f32x2 d; d.x = __builtin_amdgcn_exp2f(t.x); d.y = __builtin_amdgcn_exp2f(t.y); d = d + 1.0f;
;                         f32x2 q; q.x = __builtin_amdgcn_rcpf(d.x); q.y = __builtin_amdgcn_rcpf(d.y); const f32x2 o = (ag * au) * rs2 * q; r[4 * n + e] = o.x; r[4 * n + e + 1] = o.y; }
;                 v4u w; w.x = cvt_pk_bf16(r[0], r[1]); w.y = cvt_pk_bf16(r[2], r[3]); w.z = cvt_pk_bf16(r[4], r[5]); w.w = cvt_pk_bf16(r[6], r[7]);
;                 __builtin_nontemporal_store(w, (v4u*)(O + (size_t)(row0 + ai * HALF + m * 16) * FF + col0)); }
	v_add_f32_e32 v163, v163, v176
	v_add_f32_e32 v174, v174, v175
	ds_bpermute_b32 v176, v149, v173
	ds_bpermute_b32 v149, v149, v174
	v_fmamk_f32 v153, v153, 0x3a800000, v172
	v_rsq_f32_e32 v153, v153
	s_waitcnt lgkmcnt(2)
	v_add_f32_e32 v161, v161, v165
	ds_bpermute_b32 v165, v151, v161
	s_waitcnt lgkmcnt(1)
	v_add_f32_e32 v149, v174, v149
	ds_bpermute_b32 v174, v151, v149
	v_mul_f32_e32 v178, v153, v153
	v_pk_mul_f32 v[124:125], v[124:125], v[178:179] op_sel_hi:[1,0]
	s_waitcnt lgkmcnt(1)
	v_add_f32_e32 v161, v161, v165
	v_add_f32_e32 v165, v173, v176
	s_waitcnt lgkmcnt(0)
	v_add_f32_e32 v149, v149, v174
	v_mul_f32_e32 v174, 0xbfb8aa3b, v153
	v_pk_mul_f32 v[180:181], v[128:129], v[174:175] op_sel_hi:[1,0]
	v_pk_mul_f32 v[176:177], v[126:127], v[174:175] op_sel_hi:[1,0]
	v_exp_f32_e32 v180, v180
	v_exp_f32_e32 v181, v181
	v_pk_mul_f32 v[128:129], v[118:119], v[174:175] op_sel_hi:[1,0]
	v_exp_f32_e32 v176, v176
	v_exp_f32_e32 v128, v128
	v_pk_add_f32 v[126:127], v[180:181], 1.0 op_sel_hi:[1,0]
	v_exp_f32_e32 v129, v129
	v_rcp_f32_e32 v126, v126
	v_rcp_f32_e32 v127, v127
	v_exp_f32_e32 v177, v177
	ds_bpermute_b32 v173, v151, v165
	v_fmamk_f32 v155, v155, 0x3a800000, v172
	v_pk_mul_f32 v[124:125], v[124:125], v[126:127]
	v_pk_add_f32 v[126:127], v[128:129], 1.0 op_sel_hi:[1,0]
	v_pk_mul_f32 v[128:129], v[120:121], v[174:175] op_sel_hi:[1,0]
	v_pk_add_f32 v[176:177], v[176:177], 1.0 op_sel_hi:[1,0]
	v_exp_f32_e32 v128, v128
	v_exp_f32_e32 v129, v129
	v_rcp_f32_e32 v126, v126
	v_rcp_f32_e32 v127, v127
	v_rcp_f32_e32 v176, v176
	v_pk_add_f32 v[118:119], v[128:129], 1.0 op_sel_hi:[1,0]
	v_rcp_f32_e32 v177, v177
	v_rcp_f32_e32 v118, v118
	v_rcp_f32_e32 v119, v119
	v_rsq_f32_e32 v155, v155
	v_pk_mul_f32 v[114:115], v[114:115], v[178:179] op_sel_hi:[1,0]
	v_pk_mul_f32 v[122:123], v[122:123], v[178:179] op_sel_hi:[1,0]
	v_pk_mul_f32 v[114:115], v[114:115], v[126:127]
	v_pk_mul_f32 v[116:117], v[116:117], v[178:179] op_sel_hi:[1,0]
	s_waitcnt lgkmcnt(0)
	v_add_f32_e32 v151, v165, v173
	v_ashrrev_i32_e32 v165, 31, v164
	v_pk_mul_f32 v[122:123], v[122:123], v[176:177]
	v_pk_mul_f32 v[116:117], v[116:117], v[118:119]
	v_cvt_pk_bf16_f32 v118, v122, v123
	v_cvt_pk_bf16_f32 v119, v124, v125
	v_cvt_pk_bf16_f32 v120, v114, v115
	v_mov_b64_e32 v[114:115], s[8:9]
	v_cvt_pk_bf16_f32 v121, v116, v117
	v_mad_i64_i32 v[122:123], s[24:25], v162, s44, v[114:115]
	v_lshlrev_b64 v[116:117], 1, v[164:165]
	v_mul_f32_e32 v124, 0xbfb8aa3b, v155
	v_lshl_add_u64 v[122:123], v[122:123], 0, v[116:117]
	global_store_dwordx4 v[122:123], v[118:121], off nt
	v_pk_mul_f32 v[122:123], v[112:113], v[124:125] op_sel_hi:[1,0]
	v_pk_mul_f32 v[126:127], v[110:111], v[124:125] op_sel_hi:[1,0]
	v_exp_f32_e32 v122, v122
	v_exp_f32_e32 v123, v123
	v_pk_mul_f32 v[112:113], v[102:103], v[124:125] op_sel_hi:[1,0]
	v_mul_f32_e32 v118, v155, v155
	v_exp_f32_e32 v112, v112
	v_pk_add_f32 v[110:111], v[122:123], 1.0 op_sel_hi:[1,0]
	v_exp_f32_e32 v113, v113
	v_rcp_f32_e32 v110, v110
	v_rcp_f32_e32 v111, v111
	v_pk_mul_f32 v[108:109], v[108:109], v[118:119] op_sel_hi:[1,0]
	v_exp_f32_e32 v126, v126
	v_exp_f32_e32 v127, v127
	v_pk_mul_f32 v[108:109], v[108:109], v[110:111]
	v_pk_add_f32 v[110:111], v[112:113], 1.0 op_sel_hi:[1,0]
	v_pk_mul_f32 v[112:113], v[104:105], v[124:125] op_sel_hi:[1,0]
	v_rcp_f32_e32 v110, v110
	v_exp_f32_e32 v112, v112
	v_exp_f32_e32 v113, v113
	v_rcp_f32_e32 v111, v111
	v_pk_add_f32 v[120:121], v[126:127], 1.0 op_sel_hi:[1,0]
	v_fmamk_f32 v157, v157, 0x3a800000, v172
	v_pk_add_f32 v[102:103], v[112:113], 1.0 op_sel_hi:[1,0]
	v_rcp_f32_e32 v120, v120
	v_rcp_f32_e32 v102, v102
	v_rcp_f32_e32 v103, v103
	v_rcp_f32_e32 v121, v121
	v_rsq_f32_e32 v157, v157
	v_pk_mul_f32 v[98:99], v[98:99], v[118:119] op_sel_hi:[1,0]
	v_pk_mul_f32 v[106:107], v[106:107], v[118:119] op_sel_hi:[1,0]
	v_pk_mul_f32 v[104:105], v[98:99], v[110:111]
	v_pk_mul_f32 v[98:99], v[100:101], v[118:119] op_sel_hi:[1,0]
	v_pk_mul_f32 v[106:107], v[106:107], v[120:121]
	v_pk_mul_f32 v[102:103], v[98:99], v[102:103]
	v_cvt_pk_bf16_f32 v98, v106, v107
	v_cvt_pk_bf16_f32 v99, v108, v109
	v_cvt_pk_bf16_f32 v100, v104, v105
	v_mul_f32_e32 v104, 0xbfb8aa3b, v157
	v_cvt_pk_bf16_f32 v101, v102, v103
	v_mad_i64_i32 v[102:103], s[24:25], v160, s44, v[114:115]
	v_lshl_add_u64 v[102:103], v[102:103], 0, v[116:117]
	global_store_dwordx4 v[102:103], v[98:101], off nt
	v_pk_mul_f32 v[102:103], v[96:97], v[104:105] op_sel_hi:[1,0]
	v_pk_mul_f32 v[106:107], v[94:95], v[104:105] op_sel_hi:[1,0]
	v_exp_f32_e32 v102, v102
	v_exp_f32_e32 v103, v103
	v_pk_mul_f32 v[96:97], v[86:87], v[104:105] op_sel_hi:[1,0]
	v_mul_f32_e32 v98, v157, v157
	v_exp_f32_e32 v96, v96
	v_pk_add_f32 v[94:95], v[102:103], 1.0 op_sel_hi:[1,0]
	v_exp_f32_e32 v97, v97
	v_rcp_f32_e32 v94, v94
	v_rcp_f32_e32 v95, v95
	v_pk_mul_f32 v[92:93], v[92:93], v[98:99] op_sel_hi:[1,0]
	v_exp_f32_e32 v106, v106
	v_exp_f32_e32 v107, v107
	v_pk_mul_f32 v[92:93], v[92:93], v[94:95]
	v_pk_add_f32 v[94:95], v[96:97], 1.0 op_sel_hi:[1,0]
	v_pk_mul_f32 v[96:97], v[88:89], v[104:105] op_sel_hi:[1,0]
	v_rcp_f32_e32 v94, v94
	v_exp_f32_e32 v96, v96
	v_exp_f32_e32 v97, v97
	v_rcp_f32_e32 v95, v95
	v_pk_add_f32 v[100:101], v[106:107], 1.0 op_sel_hi:[1,0]
	v_fmamk_f32 v159, v159, 0x3a800000, v172
	v_pk_add_f32 v[86:87], v[96:97], 1.0 op_sel_hi:[1,0]
	v_rcp_f32_e32 v100, v100
	v_rcp_f32_e32 v86, v86
	v_rcp_f32_e32 v87, v87
	v_rcp_f32_e32 v101, v101
	v_rsq_f32_e32 v159, v159
	v_pk_mul_f32 v[82:83], v[82:83], v[98:99] op_sel_hi:[1,0]
	v_pk_mul_f32 v[90:91], v[90:91], v[98:99] op_sel_hi:[1,0]
	v_pk_mul_f32 v[88:89], v[82:83], v[94:95]
	v_pk_mul_f32 v[82:83], v[84:85], v[98:99] op_sel_hi:[1,0]
; __device__ __forceinline__ unsigned cvt_pk_bf16(float lo, float hi) { unsigned r; asm volatile("v_cvt_pk_bf16_f32 %0, %1, %2" : "=v"(r) : "v"(lo), "v"(hi)); return r; }
;     __device__ __forceinline__ void operator()(const pg8::f32x4 (&acc)[2][2][4][2], const Unit& u, int wr, int wc, int fr, int fq) const {
;         const int row0 = u.pm * BM + wr * 64 + fr, col0 = u.pn * HALF + wc * 32 + 8 * fq;
;         float rsv[8]; rstd8(ss, row0, fq, rsv);
; #pragma unroll
;         for (int ai = 0; ai < 2; ++ai)
; #pragma unroll
;             for (int m = 0; m < 4; ++m) { float r[8]; const float rs = rsv[ai * 4 + m]; const float c1 = -1.4426950408889634f * rs, rs2 = rs * rs;
; #pragma unroll
;                 for (int n = 0; n < 2; ++n)
; #pragma unroll
;                     for (int e = 0; e < 4; e += 2) { const f32x2 ag = {acc[ai][0][m][n][e], acc[ai][0][m][n][e + 1]}, au = {acc[ai][1][m][n][e], acc[ai][1][m][n][e + 1]};
;                         const f32x2 t = ag * c1; f32x2 d; d.x = __builtin_amdgcn_exp2f(t.x); d.y = __builtin_amdgcn_exp2f(t.y); d = d + 1.0f;
;                         f32x2 q; q.x = __builtin_amdgcn_rcpf(d.x); q.y = __builtin_amdgcn_rcpf(d.y); const f32x2 o = (ag * au) * rs2 * q; r[4 * n + e] = o.x; r[4 * n + e + 1] = o.y; }
;                 v4u w; w.x = cvt_pk_bf16(r[0], r[1]); w.y = cvt_pk_bf16(r[2], r[3]); w.z = cvt_pk_bf16(r[4], r[5]); w.w = cvt_pk_bf16(r[6], r[7]);
;                 __builtin_nontemporal_store(w, (v4u*)(O + (size_t)(row0 + ai * HALF + m * 16) * FF + col0)); }
	v_pk_mul_f32 v[90:91], v[90:91], v[100:101]
	v_pk_mul_f32 v[86:87], v[82:83], v[86:87]
	v_cvt_pk_bf16_f32 v82, v90, v91
	v_cvt_pk_bf16_f32 v83, v92, v93
	v_cvt_pk_bf16_f32 v84, v88, v89
	v_mul_f32_e32 v88, 0xbfb8aa3b, v159
	v_cvt_pk_bf16_f32 v85, v86, v87
	v_mad_i64_i32 v[86:87], s[24:25], v158, s44, v[114:115]
	v_lshl_add_u64 v[86:87], v[86:87], 0, v[116:117]
	global_store_dwordx4 v[86:87], v[82:85], off nt
	v_pk_mul_f32 v[86:87], v[80:81], v[88:89] op_sel_hi:[1,0]
	v_pk_mul_f32 v[90:91], v[78:79], v[88:89] op_sel_hi:[1,0]
	v_exp_f32_e32 v86, v86
	v_exp_f32_e32 v87, v87
	v_pk_mul_f32 v[80:81], v[70:71], v[88:89] op_sel_hi:[1,0]
	v_mul_f32_e32 v82, v159, v159
	v_exp_f32_e32 v80, v80
	v_pk_add_f32 v[78:79], v[86:87], 1.0 op_sel_hi:[1,0]
	v_exp_f32_e32 v81, v81
	v_rcp_f32_e32 v78, v78
	v_rcp_f32_e32 v79, v79
	v_pk_mul_f32 v[76:77], v[76:77], v[82:83] op_sel_hi:[1,0]
	v_exp_f32_e32 v90, v90
	v_exp_f32_e32 v91, v91
	v_pk_mul_f32 v[76:77], v[76:77], v[78:79]
	v_pk_add_f32 v[78:79], v[80:81], 1.0 op_sel_hi:[1,0]
	v_pk_mul_f32 v[80:81], v[72:73], v[88:89] op_sel_hi:[1,0]
	v_rcp_f32_e32 v78, v78
	v_exp_f32_e32 v80, v80
	v_exp_f32_e32 v81, v81
	v_rcp_f32_e32 v79, v79
	v_pk_add_f32 v[84:85], v[90:91], 1.0 op_sel_hi:[1,0]
	v_fmamk_f32 v163, v163, 0x3a800000, v172
	v_pk_add_f32 v[70:71], v[80:81], 1.0 op_sel_hi:[1,0]
	v_rcp_f32_e32 v84, v84
	v_rcp_f32_e32 v70, v70
	v_rcp_f32_e32 v71, v71
	v_rcp_f32_e32 v85, v85
	v_rsq_f32_e32 v163, v163
	v_pk_mul_f32 v[66:67], v[66:67], v[82:83] op_sel_hi:[1,0]
	v_pk_mul_f32 v[74:75], v[74:75], v[82:83] op_sel_hi:[1,0]
	v_pk_mul_f32 v[72:73], v[66:67], v[78:79]
	v_pk_mul_f32 v[66:67], v[68:69], v[82:83] op_sel_hi:[1,0]
	v_pk_mul_f32 v[74:75], v[74:75], v[84:85]
	v_pk_mul_f32 v[70:71], v[66:67], v[70:71]
	v_cvt_pk_bf16_f32 v66, v74, v75
	v_cvt_pk_bf16_f32 v67, v76, v77
	v_cvt_pk_bf16_f32 v68, v72, v73
	v_mul_f32_e32 v72, 0xbfb8aa3b, v163
	v_cvt_pk_bf16_f32 v69, v70, v71
	v_mad_i64_i32 v[70:71], s[24:25], v156, s44, v[114:115]
	v_lshl_add_u64 v[70:71], v[70:71], 0, v[116:117]
	global_store_dwordx4 v[70:71], v[66:69], off nt
	v_pk_mul_f32 v[70:71], v[64:65], v[72:73] op_sel_hi:[1,0]
	v_pk_mul_f32 v[74:75], v[62:63], v[72:73] op_sel_hi:[1,0]
	v_exp_f32_e32 v70, v70
	v_exp_f32_e32 v71, v71
	v_pk_mul_f32 v[64:65], v[54:55], v[72:73] op_sel_hi:[1,0]
	v_mul_f32_e32 v66, v163, v163
	v_exp_f32_e32 v64, v64
	v_pk_add_f32 v[62:63], v[70:71], 1.0 op_sel_hi:[1,0]
	v_exp_f32_e32 v65, v65
	v_rcp_f32_e32 v62, v62
	v_rcp_f32_e32 v63, v63
	v_pk_mul_f32 v[60:61], v[60:61], v[66:67] op_sel_hi:[1,0]
	v_exp_f32_e32 v74, v74
	v_exp_f32_e32 v75, v75
	v_pk_mul_f32 v[60:61], v[60:61], v[62:63]
	v_pk_add_f32 v[62:63], v[64:65], 1.0 op_sel_hi:[1,0]
	v_pk_mul_f32 v[64:65], v[56:57], v[72:73] op_sel_hi:[1,0]
	v_rcp_f32_e32 v62, v62
	v_exp_f32_e32 v64, v64
	v_exp_f32_e32 v65, v65
	v_rcp_f32_e32 v63, v63
	v_pk_add_f32 v[68:69], v[74:75], 1.0 op_sel_hi:[1,0]
	v_fmamk_f32 v161, v161, 0x3a800000, v172
	v_pk_add_f32 v[54:55], v[64:65], 1.0 op_sel_hi:[1,0]
	v_rcp_f32_e32 v68, v68
	v_rcp_f32_e32 v54, v54
	v_rcp_f32_e32 v55, v55
	v_rcp_f32_e32 v69, v69
	v_rsq_f32_e32 v161, v161
	v_pk_mul_f32 v[50:51], v[50:51], v[66:67] op_sel_hi:[1,0]
	v_pk_mul_f32 v[58:59], v[58:59], v[66:67] op_sel_hi:[1,0]
	v_pk_mul_f32 v[56:57], v[50:51], v[62:63]
	v_pk_mul_f32 v[50:51], v[52:53], v[66:67] op_sel_hi:[1,0]
	v_pk_mul_f32 v[58:59], v[58:59], v[68:69]
	v_pk_mul_f32 v[54:55], v[50:51], v[54:55]
	v_cvt_pk_bf16_f32 v50, v58, v59
	v_cvt_pk_bf16_f32 v51, v60, v61
	v_cvt_pk_bf16_f32 v52, v56, v57
	v_mul_f32_e32 v56, 0xbfb8aa3b, v161
	v_cvt_pk_bf16_f32 v53, v54, v55
	v_mad_i64_i32 v[54:55], s[24:25], v154, s44, v[114:115]
	v_lshl_add_u64 v[54:55], v[54:55], 0, v[116:117]
	global_store_dwordx4 v[54:55], v[50:53], off nt
	v_pk_mul_f32 v[54:55], v[48:49], v[56:57] op_sel_hi:[1,0]
	v_pk_mul_f32 v[58:59], v[46:47], v[56:57] op_sel_hi:[1,0]
	v_exp_f32_e32 v54, v54
	v_exp_f32_e32 v55, v55
	v_pk_mul_f32 v[48:49], v[38:39], v[56:57] op_sel_hi:[1,0]
	v_mul_f32_e32 v50, v161, v161
	v_exp_f32_e32 v48, v48
	v_pk_add_f32 v[46:47], v[54:55], 1.0 op_sel_hi:[1,0]
	v_exp_f32_e32 v49, v49
	v_rcp_f32_e32 v46, v46
	v_rcp_f32_e32 v47, v47
	v_pk_mul_f32 v[44:45], v[44:45], v[50:51] op_sel_hi:[1,0]
	v_exp_f32_e32 v58, v58
	v_exp_f32_e32 v59, v59
	v_pk_mul_f32 v[44:45], v[44:45], v[46:47]
	v_pk_add_f32 v[46:47], v[48:49], 1.0 op_sel_hi:[1,0]
; __device__ __forceinline__ unsigned cvt_pk_bf16(float lo, float hi) { unsigned r; asm volatile("v_cvt_pk_bf16_f32 %0, %1, %2" : "=v"(r) : "v"(lo), "v"(hi)); return r; }
; #define PG8_BAR __builtin_amdgcn_s_barrier()
; template <class Epi, class Sched, bool ALIGN_EPI = false, bool SP2 = false>
; __device__ __forceinline__ void gemm_phase(PG8_LAS unsigned char* lds, const Gemm g, const Sched& S, const Epi& E) {
;     ...
;         if constexpr (!Epi::AFTER_DRAIN) { E(acc, cur, wr, wc, fr, fq); S.done(cur); }
;         if (!has_next) break;
; #pragma unroll
;         for (int a = 0; a < 2; ++a)
; #pragma unroll
;             for (int b = 0; b < 2; ++b)
; #pragma unroll
;                 for (int m = 0; m < 4; ++m)
; #pragma unroll
;                     for (int n = 0; n < 2; ++n) acc[a][b][m][n] = (f32x4){0.f, 0.f, 0.f, 0.f};
;         cur = nxt; cA = nA; cB = nB; ++ui;
;         if constexpr (ALIGN_EPI) { if (wr == 1) PG8_BAR; }
;     __device__ __forceinline__ void operator()(const pg8::f32x4 (&acc)[2][2][4][2], const Unit& u, int wr, int wc, int fr, int fq) const {
;     ...
;             for (int m = 0; m < 4; ++m) { float r[8]; const float rs = rsv[ai * 4 + m]; const float c1 = -1.4426950408889634f * rs, rs2 = rs * rs;
; #pragma unroll
;                 for (int n = 0; n < 2; ++n)
; #pragma unroll
;                     for (int e = 0; e < 4; e += 2) { const f32x2 ag = {acc[ai][0][m][n][e], acc[ai][0][m][n][e + 1]}, au = {acc[ai][1][m][n][e], acc[ai][1][m][n][e + 1]};
;                         const f32x2 t = ag * c1; f32x2 d; d.x = __builtin_amdgcn_exp2f(t.x); d.y = __builtin_amdgcn_exp2f(t.y); d = d + 1.0f;
;                         f32x2 q; q.x = __builtin_amdgcn_rcpf(d.x); q.y = __builtin_amdgcn_rcpf(d.y); const f32x2 o = (ag * au) * rs2 * q; r[4 * n + e] = o.x; r[4 * n + e + 1] = o.y; }
;                 v4u w; w.x = cvt_pk_bf16(r[0], r[1]); w.y = cvt_pk_bf16(r[2], r[3]); w.z = cvt_pk_bf16(r[4], r[5]); w.w = cvt_pk_bf16(r[6], r[7]);
;                 __builtin_nontemporal_store(w, (v4u*)(O + (size_t)(row0 + ai * HALF + m * 16) * FF + col0)); }
	v_pk_mul_f32 v[48:49], v[40:41], v[56:57] op_sel_hi:[1,0]
	v_rcp_f32_e32 v46, v46
	v_exp_f32_e32 v48, v48
	v_exp_f32_e32 v49, v49
	v_rcp_f32_e32 v47, v47
	v_pk_add_f32 v[52:53], v[58:59], 1.0 op_sel_hi:[1,0]
	v_fmamk_f32 v151, v151, 0x3a800000, v172
	v_pk_add_f32 v[38:39], v[48:49], 1.0 op_sel_hi:[1,0]
	v_rcp_f32_e32 v52, v52
	v_rcp_f32_e32 v38, v38
	v_rcp_f32_e32 v39, v39
	v_rcp_f32_e32 v53, v53
	v_rsq_f32_e32 v151, v151
	v_pk_mul_f32 v[34:35], v[34:35], v[50:51] op_sel_hi:[1,0]
	v_pk_mul_f32 v[42:43], v[42:43], v[50:51] op_sel_hi:[1,0]
	v_pk_mul_f32 v[40:41], v[34:35], v[46:47]
	v_pk_mul_f32 v[34:35], v[36:37], v[50:51] op_sel_hi:[1,0]
	v_pk_mul_f32 v[42:43], v[42:43], v[52:53]
	v_pk_mul_f32 v[38:39], v[34:35], v[38:39]
	v_cvt_pk_bf16_f32 v34, v42, v43
	v_cvt_pk_bf16_f32 v35, v44, v45
	v_cvt_pk_bf16_f32 v36, v40, v41
	v_mul_f32_e32 v40, 0xbfb8aa3b, v151
	v_cvt_pk_bf16_f32 v37, v38, v39
	v_mad_i64_i32 v[38:39], s[24:25], v152, s44, v[114:115]
	v_lshl_add_u64 v[38:39], v[38:39], 0, v[116:117]
	global_store_dwordx4 v[38:39], v[34:37], off nt
	v_pk_mul_f32 v[38:39], v[32:33], v[40:41] op_sel_hi:[1,0]
	v_pk_mul_f32 v[42:43], v[30:31], v[40:41] op_sel_hi:[1,0]
	v_exp_f32_e32 v38, v38
	v_exp_f32_e32 v39, v39
	v_pk_mul_f32 v[32:33], v[22:23], v[40:41] op_sel_hi:[1,0]
	v_mul_f32_e32 v34, v151, v151
	v_exp_f32_e32 v32, v32
	v_pk_add_f32 v[30:31], v[38:39], 1.0 op_sel_hi:[1,0]
	v_exp_f32_e32 v33, v33
	v_rcp_f32_e32 v30, v30
	v_rcp_f32_e32 v31, v31
	v_pk_mul_f32 v[28:29], v[28:29], v[34:35] op_sel_hi:[1,0]
	v_exp_f32_e32 v42, v42
	v_exp_f32_e32 v43, v43
	v_pk_mul_f32 v[28:29], v[28:29], v[30:31]
	v_pk_add_f32 v[30:31], v[32:33], 1.0 op_sel_hi:[1,0]
	v_pk_mul_f32 v[32:33], v[24:25], v[40:41] op_sel_hi:[1,0]
	v_rcp_f32_e32 v30, v30
	v_exp_f32_e32 v32, v32
	v_exp_f32_e32 v33, v33
	v_rcp_f32_e32 v31, v31
	v_pk_add_f32 v[36:37], v[42:43], 1.0 op_sel_hi:[1,0]
	v_fmamk_f32 v149, v149, 0x3a800000, v172
	v_pk_add_f32 v[22:23], v[32:33], 1.0 op_sel_hi:[1,0]
	v_rcp_f32_e32 v36, v36
	v_rcp_f32_e32 v22, v22
	v_rcp_f32_e32 v23, v23
	v_rcp_f32_e32 v37, v37
	v_rsq_f32_e32 v149, v149
	v_pk_mul_f32 v[18:19], v[18:19], v[34:35] op_sel_hi:[1,0]
	v_pk_mul_f32 v[26:27], v[26:27], v[34:35] op_sel_hi:[1,0]
	v_pk_mul_f32 v[24:25], v[18:19], v[30:31]
	v_pk_mul_f32 v[18:19], v[20:21], v[34:35] op_sel_hi:[1,0]
	v_pk_mul_f32 v[26:27], v[26:27], v[36:37]
	v_pk_mul_f32 v[22:23], v[18:19], v[22:23]
	v_cvt_pk_bf16_f32 v18, v26, v27
	v_cvt_pk_bf16_f32 v19, v28, v29
	v_cvt_pk_bf16_f32 v20, v24, v25
	v_mul_f32_e32 v24, 0xbfb8aa3b, v149
	v_cvt_pk_bf16_f32 v21, v22, v23
	v_mad_i64_i32 v[22:23], s[24:25], v150, s44, v[114:115]
	v_lshl_add_u64 v[22:23], v[22:23], 0, v[116:117]
	global_store_dwordx4 v[22:23], v[18:21], off nt
	v_pk_mul_f32 v[22:23], v[16:17], v[24:25] op_sel_hi:[1,0]
	v_pk_mul_f32 v[26:27], v[14:15], v[24:25] op_sel_hi:[1,0]
	v_exp_f32_e32 v22, v22
	v_exp_f32_e32 v23, v23
	v_pk_mul_f32 v[16:17], v[6:7], v[24:25] op_sel_hi:[1,0]
	v_mul_f32_e32 v18, v149, v149
	v_exp_f32_e32 v16, v16
	v_pk_add_f32 v[14:15], v[22:23], 1.0 op_sel_hi:[1,0]
	v_exp_f32_e32 v17, v17
	v_rcp_f32_e32 v14, v14
	v_rcp_f32_e32 v15, v15
	v_pk_mul_f32 v[12:13], v[12:13], v[18:19] op_sel_hi:[1,0]
	v_exp_f32_e32 v26, v26
	v_exp_f32_e32 v27, v27
	v_pk_mul_f32 v[12:13], v[12:13], v[14:15]
	v_pk_add_f32 v[14:15], v[16:17], 1.0 op_sel_hi:[1,0]
	v_pk_mul_f32 v[16:17], v[8:9], v[24:25] op_sel_hi:[1,0]
	v_rcp_f32_e32 v14, v14
	v_exp_f32_e32 v16, v16
	v_exp_f32_e32 v17, v17
	v_rcp_f32_e32 v15, v15
	v_pk_add_f32 v[20:21], v[26:27], 1.0 op_sel_hi:[1,0]
	v_pk_mul_f32 v[2:3], v[2:3], v[18:19] op_sel_hi:[1,0]
	v_pk_add_f32 v[6:7], v[16:17], 1.0 op_sel_hi:[1,0]
	v_rcp_f32_e32 v20, v20
	v_rcp_f32_e32 v6, v6
	v_rcp_f32_e32 v7, v7
	v_rcp_f32_e32 v21, v21
	v_pk_mul_f32 v[8:9], v[2:3], v[14:15]
	v_pk_mul_f32 v[2:3], v[4:5], v[18:19] op_sel_hi:[1,0]
	v_pk_mul_f32 v[10:11], v[10:11], v[18:19] op_sel_hi:[1,0]
	v_pk_mul_f32 v[6:7], v[2:3], v[6:7]
	v_pk_mul_f32 v[10:11], v[10:11], v[20:21]
	s_nop 0
	v_cvt_pk_bf16_f32 v2, v10, v11
	v_cvt_pk_bf16_f32 v3, v12, v13
	v_cvt_pk_bf16_f32 v4, v8, v9
	v_cvt_pk_bf16_f32 v5, v6, v7
	v_mad_i64_i32 v[6:7], s[24:25], v148, s44, v[114:115]
	v_lshl_add_u64 v[6:7], v[6:7], 0, v[116:117]
	global_store_dwordx4 v[6:7], v[2:5], off nt
	s_cbranch_vccnz .LBB0_687
	s_andn2_b64 vcc, exec, s[4:5]
	s_cbranch_vccnz .LBB0_686
	s_mov_b32 s98, 1
	s_branch .LBB0_686

; #define PG8_STAGE(bufoff, gbase, voff) do { _Pragma("unroll") for (int _i = 0; _i < 2; ++_i) \
;         __builtin_amdgcn_global_load_lds((const unsigned*)((const char*)(gbase) + (voff)[_i]), (PG8_LAS unsigned*)(lds + (bufoff) + ldsw + _i * 8192), 16, 0, 0); } while (0)
; #define PG8_WAIT_V(n) asm volatile("s_waitcnt vmcnt(" #n ")" ::: "memory")
; #define PG8_BAR __builtin_amdgcn_s_barrier()
; template <class Epi, class Sched, bool ALIGN_EPI = false, bool SP2 = false>
; __device__ __forceinline__ void gemm_phase(PG8_LAS unsigned char* lds, const Gemm g, const Sched& S, const Epi& E) {
;     int tid_ = threadIdx.x; asm volatile("" : "+v"(tid_));
;     const int tid = tid_, wid = __builtin_amdgcn_readfirstlane(tid >> 6), lane = tid & 63, wr = wid >> 2, wc = wid & 3, fr = lane & 15, fq = lane >> 4;
;     const int K = g.K, nt = K / BK;
;     unsigned voffA[2], voffB[2];
; #pragma unroll
;     for (int i = 0; i < 2; ++i) { int R, C; stage_rc(tid * 16 + i * 8192, R, C); const int Rb = Epi::PERM ? ((R & ~31) + perm32(R & 31)) : R;
;         voffA[i] = (unsigned)(R * g.lda + C) * 2u; voffB[i] = (unsigned)(Rb * g.ldb + C) * 2u; }
;     const size_t kstep = (size_t)(BK * 2);
;     const size_t hstepA = (size_t)HALF * g.lda * 2, hstepB = (size_t)HALF * g.ldb * 2;
;     const size_t tstepA = 2 * hstepA, tstepB = 2 * hstepB;
;     const unsigned ldsw = (unsigned)wid * 1024u;
;     const int aoff = lds_byte(wr * 64 + fr, fq * 8), boff = lds_byte(wc * 32 + fr, fq * 8);
;     ...
;     const char* cA = (const char*)g.A + (size_t)cur.g * g.gsA * 2 + (size_t)cur.pm * tstepA; const char* cB = (const char*)g.Bt + (size_t)cur.g * g.gsB * 2 + (size_t)cur.pn * tstepB;
;     S.a_ready(cur);
;     if constexpr (SP2) {
;         PG8_STAGE(PG8_SB(0, 0), cB, voffB); PG8_STAGE(PG8_SB(0, 1), cB + hstepB, voffB); PG8_STAGE(PG8_SA(0, 0), cA, voffA); PG8_STAGE(PG8_SA(0, 1), cA + hstepA, voffA);
;         if (wr == 1) PG8_BAR;
;         PG8_WAIT_V(2); PG8_BAR;
;         PG8_STAGE(PG8_SB(1, 0), cB + kstep, voffB); PG8_STAGE(PG8_SA(1, 0), cA + kstep, voffA); PG8_STAGE(PG8_SB(1, 1), cB + hstepB + kstep, voffB);
;         PG8_WAIT_V(6); PG8_BAR;
.LBB0_762:
	s_add_u32 s16, s78, 0x7c00000
	s_addc_u32 s17, s79, 0
	s_add_u32 s18, s78, 0x5800000
	s_mov_b64 s[20:21], 0x80
	s_addc_u32 s19, s79, 0
	s_and_b32 s40, s9, 3
	s_add_i32 m0, s1, 0x18000
	v_lshl_add_u64 v[8:9], v[8:9], 0, s[20:21]
	s_lshl_b32 s9, s10, 13
	s_lshl_b32 s11, s40, 12
	s_waitcnt vmcnt(2)
	s_barrier
	global_load_lds_dwordx4 v[8:9], off
	v_lshl_add_u64 v[6:7], v[6:7], 0, s[20:21]
	s_add_i32 m0, s1, 0x1a000
	s_add_i32 s41, s1, 0x8000
	s_add_i32 s42, s1, 0xa000
	global_load_lds_dwordx4 v[6:7], off
	v_lshl_add_u64 v[2:3], v[2:3], 0, s[20:21]
	s_mov_b32 m0, s41
	s_add_u32 s12, s28, 0xb0080
	global_load_lds_dwordx4 v[2:3], off
	v_lshl_add_u64 v[2:3], v[4:5], 0, s[20:21]
	s_mov_b32 m0, s42
	s_addc_u32 s13, s29, 0
	global_load_lds_dwordx4 v[2:3], off
	s_add_i32 m0, s1, 0x1c000
	v_lshl_add_u64 v[2:3], s[12:13], 0, v[140:141]
	global_load_lds_dwordx4 v[2:3], off
	v_lshl_add_u64 v[2:3], s[12:13], 0, v[144:145]
	s_add_i32 m0, s1, 0x1e000
	s_cmpk_lt_u32 s8, 0x100
	global_load_lds_dwordx4 v[2:3], off
	v_bfe_u32 v2, v10, 4, 2
	v_and_b32_e32 v3, 15, v10
	v_lshlrev_b32_e32 v5, 4, v2
	v_lshl_or_b32 v1, s10, 6, v3
	v_lshl_or_b32 v3, v3, 6, v5
	v_lshlrev_b32_e32 v5, 2, v10
	v_and_b32_e32 v5, 32, v5
	v_lshlrev_b32_e32 v4, 3, v2
	v_bitop3_b32 v6, v3, s9, v5 bitop3:0xde
	v_bitop3_b32 v162, v3, s11, v5 bitop3:0xde
	v_cmp_eq_u32_e64 s[8:9], 0, v2
	v_lshrrev_b32_e32 v3, 1, v11
	v_mul_lo_u32 v2, v13, s4
	s_mov_b32 s24, 0xb000
	v_mad_u64_u32 v[2:3], s[12:13], v3, s24, v[2:3]
	v_or_b32_e32 v2, v2, v12
	s_mov_b64 s[10:11], 0xb0080
	v_add_lshl_u32 v2, v2, v14, 1
	v_mov_b32_e32 v3, v141
	v_lshl_add_u64 v[146:147], v[2:3], 0, s[10:11]
	v_lshrrev_b32_e32 v3, 1, v15
	v_mul_lo_u32 v2, v16, s4
	v_mad_u64_u32 v[2:3], s[12:13], v3, s24, v[2:3]
	v_or_b32_e32 v2, v2, v17
	s_waitcnt vmcnt(6)
	v_add_lshl_u32 v2, v2, v18, 1
	v_mov_b32_e32 v3, v141
	s_cselect_b64 s[22:23], -1, 0
	v_lshl_add_u64 v[148:149], v[2:3], 0, s[10:11]
	s_add_i32 s46, 0, 0x10000
	s_add_i32 s47, 0, 0x14000
	v_mbcnt_lo_u32_b32 v2, -1, 0
	v_lshl_or_b32 v163, s40, 5, v4
	s_ashr_i32 s43, s82, 31
	s_mov_b32 s44, s82
	s_ashr_i32 s45, s96, 31
	v_mov_b64_e32 v[150:151], 0x200
	v_mov_b64_e32 v[152:153], 0x1ff
	v_add_u32_e32 v164, s46, v162
	v_add_u32_e32 v165, s47, v162
	v_add_u32_e32 v166, 0, v6
	v_mbcnt_hi_u32_b32 v167, -1, v2
	s_mov_b32 s48, 0
	s_barrier
	s_mov_b32 s98, 0
	s_branch .LBB0_765

; #define PG8_STAGE(bufoff, gbase, voff) do { _Pragma("unroll") for (int _i = 0; _i < 2; ++_i) \
;         __builtin_amdgcn_global_load_lds((const unsigned*)((const char*)(gbase) + (voff)[_i]), (PG8_LAS unsigned*)(lds + (bufoff) + ldsw + _i * 8192), 16, 0, 0); } while (0)
; #define PG8_LDA(dst, b, h) do { _Pragma("unroll") for (int m = 0; m < 4; ++m) _Pragma("unroll") for (int k = 0; k < 2; ++k) dst[m][k] = *(const PG8_LAS bf16x8*)(lds + PG8_SA(b, h) + aoff + m * 2048 + k * 1024); } while (0)
; #define PG8_LDB(dst, b, h) do { _Pragma("unroll") for (int n = 0; n < 2; ++n) _Pragma("unroll") for (int k = 0; k < 2; ++k) dst[n][k] = *(const PG8_LAS bf16x8*)(lds + PG8_SB(b, h) + boff + n * 2048 + k * 1024); } while (0)
; #define PG8_WAIT_V(n) asm volatile("s_waitcnt vmcnt(" #n ")" ::: "memory")
; #define PG8_WAIT_L(n) asm volatile("s_waitcnt lgkmcnt(" #n ")" ::: "memory")
; #define PG8_BAR __builtin_amdgcn_s_barrier()
; template <class Epi, class Sched, bool ALIGN_EPI = false, bool SP2 = false>
; __device__ __forceinline__ void gemm_phase(PG8_LAS unsigned char* lds, const Gemm g, const Sched& S, const Epi& E) {
;     ...
;         const bool has_next = S.next(ui + 1, nxt);
;         const char* nA = has_next ? (const char*)g.A + (size_t)nxt.g * g.gsA * 2 + (size_t)nxt.pm * tstepA : cA; const char* nB = has_next ? (const char*)g.Bt + (size_t)nxt.g * g.gsB * 2 + (size_t)nxt.pn * tstepB : cB;
;         for (int t = 0; t < nt; t += 2) {
;             const bool last = (t == nt - 2);
;             const char* a1 = cA + (size_t)(t + 1) * kstep;
;             const char* a2 = last ? nA : cA + (size_t)(t + 2) * kstep; const char* b2 = last ? nB : cB + (size_t)(t + 2) * kstep;
;             const char* a3 = a2 + kstep; const char* b3 = b2 + kstep;
;             if (last && has_next) S.a_ready(nxt);
;             if constexpr (SP2) {
;             PG8_LDB(B0, 0, 0); PG8_LDB(B1, 0, 1); PG8_SCHED; PG8_LDA(At, 0, 0); PG8_STAGE(PG8_SA(1, 1), a1 + hstepA, voffA);
;             PG8_WAIT_V(8); PG8_WAIT_L(0); PG8_BAR; PG8_MMA(0, 0, At, B0); PG8_MMA(0, 1, At, B1); PG8_BAR; PG8_SCHED;
;             PG8_LDA(At, 0, 1); PG8_STAGE(PG8_SB(0, 0), b2, voffB); PG8_STAGE(PG8_SB(0, 1), b2 + hstepB, voffB); PG8_STAGE(PG8_SA(0, 0), a2, voffA);
;             PG8_WAIT_V(8); PG8_WAIT_L(0); PG8_BAR; PG8_MMA(1, 0, At, B0); PG8_MMA(1, 1, At, B1); PG8_BAR; PG8_SCHED;
.LBB0_775:
	s_add_u32 s4, s28, 0x100
	s_addc_u32 s53, s29, 0
	s_mov_b32 s54, -2
	s_waitcnt lgkmcnt(0)
	s_cmp_eq_u32 s98, 1
	s_cbranch_scc0 .Lhb_24734
	s_mov_b32 s98, 0
	s_barrier
.Lhb_24734:
	ds_read_b128 v[130:133], v164
	ds_read_b128 v[134:137], v164 offset:1024
	ds_read_b128 v[154:157], v164 offset:2048
	ds_read_b128 v[158:161], v164 offset:3072
	ds_read_b128 v[168:171], v165
	ds_read_b128 v[172:175], v165 offset:1024
	ds_read_b128 v[176:179], v165 offset:2048
	ds_read_b128 v[180:183], v165 offset:3072
	s_add_u32 s28, s26, 0x100
	s_addc_u32 s29, s27, 0
	s_cmp_eq_u32 s54, 40
	s_cselect_b32 s35, s13, s29
	s_cselect_b32 s34, s12, s28
	s_cselect_b32 s31, s25, s53
	s_cselect_b32 s30, s24, s4
	v_lshl_add_u64 v[216:217], s[26:27], 0, v[146:147]
	s_add_i32 m0, s1, 0xc000
	ds_read_b128 v[184:187], v166
	ds_read_b128 v[188:191], v166 offset:1024
	ds_read_b128 v[192:195], v166 offset:2048
	ds_read_b128 v[196:199], v166 offset:3072
	ds_read_b128 v[200:203], v166 offset:4096
	ds_read_b128 v[204:207], v166 offset:5120
	ds_read_b128 v[208:211], v166 offset:6144
	ds_read_b128 v[212:215], v166 offset:7168
	global_load_lds_dwordx4 v[216:217], off
	v_lshl_add_u64 v[216:217], s[26:27], 0, v[148:149]
	s_add_i32 m0, s1, 0xe000
	s_nop 0
	global_load_lds_dwordx4 v[216:217], off
	s_waitcnt vmcnt(8)
	s_waitcnt lgkmcnt(0)
	s_barrier
	s_setprio 1
	s_waitcnt lgkmcnt(0)
	v_mfma_f32_16x16x32_bf16 v[126:129], v[130:133], v[184:187], 0
	v_mfma_f32_16x16x32_bf16 v[122:125], v[154:157], v[184:187], 0
	v_mfma_f32_16x16x32_bf16 v[110:113], v[130:133], v[192:195], 0
	v_mfma_f32_16x16x32_bf16 v[106:109], v[154:157], v[192:195], 0
	v_mfma_f32_16x16x32_bf16 v[94:97], v[130:133], v[200:203], 0
	v_mfma_f32_16x16x32_bf16 v[90:93], v[154:157], v[200:203], 0
	v_mfma_f32_16x16x32_bf16 v[78:81], v[130:133], v[208:211], 0
	v_mfma_f32_16x16x32_bf16 v[74:77], v[154:157], v[208:211], 0
	v_mfma_f32_16x16x32_bf16 v[126:129], v[134:137], v[188:191], v[126:129]
	v_mfma_f32_16x16x32_bf16 v[122:125], v[158:161], v[188:191], v[122:125]
	v_mfma_f32_16x16x32_bf16 v[110:113], v[134:137], v[196:199], v[110:113]
	v_mfma_f32_16x16x32_bf16 v[106:109], v[158:161], v[196:199], v[106:109]
	v_mfma_f32_16x16x32_bf16 v[94:97], v[134:137], v[204:207], v[94:97]
	v_mfma_f32_16x16x32_bf16 v[90:93], v[158:161], v[204:207], v[90:93]
	v_mfma_f32_16x16x32_bf16 v[78:81], v[134:137], v[212:215], v[78:81]
	v_mfma_f32_16x16x32_bf16 v[74:77], v[158:161], v[212:215], v[74:77]
	s_setprio 0
	s_setprio 1
	v_mfma_f32_16x16x32_bf16 v[118:121], v[168:171], v[184:187], 0
	v_mfma_f32_16x16x32_bf16 v[114:117], v[176:179], v[184:187], 0
	v_mfma_f32_16x16x32_bf16 v[102:105], v[168:171], v[192:195], 0
	v_mfma_f32_16x16x32_bf16 v[98:101], v[176:179], v[192:195], 0
	v_mfma_f32_16x16x32_bf16 v[86:89], v[168:171], v[200:203], 0
	v_mfma_f32_16x16x32_bf16 v[82:85], v[176:179], v[200:203], 0
	v_mfma_f32_16x16x32_bf16 v[70:73], v[168:171], v[208:211], 0
	v_mfma_f32_16x16x32_bf16 v[66:69], v[176:179], v[208:211], 0
	v_mfma_f32_16x16x32_bf16 v[118:121], v[172:175], v[188:191], v[118:121]
	v_mfma_f32_16x16x32_bf16 v[114:117], v[180:183], v[188:191], v[114:117]
	v_mfma_f32_16x16x32_bf16 v[102:105], v[172:175], v[196:199], v[102:105]
	v_mfma_f32_16x16x32_bf16 v[98:101], v[180:183], v[196:199], v[98:101]
	v_mfma_f32_16x16x32_bf16 v[86:89], v[172:175], v[204:207], v[86:89]
	v_mfma_f32_16x16x32_bf16 v[82:85], v[180:183], v[204:207], v[82:85]
	v_mfma_f32_16x16x32_bf16 v[70:73], v[172:175], v[212:215], v[70:73]
	v_mfma_f32_16x16x32_bf16 v[66:69], v[180:183], v[212:215], v[66:69]
	s_setprio 0
	s_barrier
	s_add_i32 s26, s46, s0
	v_lshl_add_u64 v[216:217], s[30:31], 0, v[140:141]
	s_mov_b32 m0, s26
	ds_read_b128 v[184:187], v166 offset:16384
	ds_read_b128 v[188:191], v166 offset:17408
	ds_read_b128 v[192:195], v166 offset:18432
	ds_read_b128 v[196:199], v166 offset:19456
	ds_read_b128 v[200:203], v166 offset:20480
	ds_read_b128 v[204:207], v166 offset:21504
	ds_read_b128 v[208:211], v166 offset:22528
	ds_read_b128 v[212:215], v166 offset:23552
	global_load_lds_dwordx4 v[216:217], off
	s_add_i32 m0, s26, 0x2000
	s_add_u32 s26, s30, 0xb0000
	v_lshl_add_u64 v[218:219], s[30:31], 0, v[144:145]
	s_addc_u32 s27, s31, 0
	s_add_i32 s55, s47, s0
	global_load_lds_dwordx4 v[218:219], off
	v_lshl_add_u64 v[220:221], s[26:27], 0, v[140:141]
	s_mov_b32 m0, s55
	v_lshl_add_u64 v[222:223], s[34:35], 0, v[142:143]
	global_load_lds_dwordx4 v[220:221], off
	v_lshl_add_u64 v[220:221], s[26:27], 0, v[144:145]
	s_add_i32 m0, s55, 0x2000
	s_nop 0
	global_load_lds_dwordx4 v[220:221], off
	v_lshl_add_u64 v[220:221], s[34:35], 0, v[138:139]
	s_mov_b32 m0, s1
	s_nop 0
	global_load_lds_dwordx4 v[220:221], off
	s_mov_b32 m0, s37
	s_nop 0
	global_load_lds_dwordx4 v[222:223], off
	s_waitcnt vmcnt(8)
	s_waitcnt lgkmcnt(0)
	s_barrier
; #define PG8_STAGE(bufoff, gbase, voff) do { _Pragma("unroll") for (int _i = 0; _i < 2; ++_i) \
;         __builtin_amdgcn_global_load_lds((const unsigned*)((const char*)(gbase) + (voff)[_i]), (PG8_LAS unsigned*)(lds + (bufoff) + ldsw + _i * 8192), 16, 0, 0); } while (0)
; #define PG8_LDA(dst, b, h) do { _Pragma("unroll") for (int m = 0; m < 4; ++m) _Pragma("unroll") for (int k = 0; k < 2; ++k) dst[m][k] = *(const PG8_LAS bf16x8*)(lds + PG8_SA(b, h) + aoff + m * 2048 + k * 1024); } while (0)
; #define PG8_LDB(dst, b, h) do { _Pragma("unroll") for (int n = 0; n < 2; ++n) _Pragma("unroll") for (int k = 0; k < 2; ++k) dst[n][k] = *(const PG8_LAS bf16x8*)(lds + PG8_SB(b, h) + boff + n * 2048 + k * 1024); } while (0)
; #define PG8_MMA(ai, bj, At, Bt) do { __builtin_amdgcn_s_setprio(1); _Pragma("unroll") for (int m = 0; m < 4; ++m) _Pragma("unroll") for (int n = 0; n < 2; ++n) _Pragma("unroll") for (int k = 0; k < 2; ++k) \
;         acc[ai][bj][m][n] = __builtin_amdgcn_mfma_f32_16x16x32_bf16(Bt[n][k], At[m][k], acc[ai][bj][m][n], 0, 0, 0); __builtin_amdgcn_s_setprio(0); } while (0)
; #define PG8_WAIT_V(n) asm volatile("s_waitcnt vmcnt(" #n ")" ::: "memory")
; #define PG8_WAIT_L(n) asm volatile("s_waitcnt lgkmcnt(" #n ")" ::: "memory")
; #define PG8_BAR __builtin_amdgcn_s_barrier()
; template <class Epi, class Sched, bool ALIGN_EPI = false, bool SP2 = false>
; __device__ __forceinline__ void gemm_phase(PG8_LAS unsigned char* lds, const Gemm g, const Sched& S, const Epi& E) {
;     ...
;             PG8_WAIT_V(8); PG8_WAIT_L(0); PG8_BAR; PG8_MMA(0, 0, At, B0); PG8_MMA(0, 1, At, B1); PG8_BAR; PG8_SCHED;
;             PG8_LDA(At, 0, 1); PG8_STAGE(PG8_SB(0, 0), b2, voffB); PG8_STAGE(PG8_SB(0, 1), b2 + hstepB, voffB); PG8_STAGE(PG8_SA(0, 0), a2, voffA);
;             PG8_WAIT_V(8); PG8_WAIT_L(0); PG8_BAR; PG8_MMA(1, 0, At, B0); PG8_MMA(1, 1, At, B1); PG8_BAR; PG8_SCHED;
;             PG8_LDB(B0, 1, 0); PG8_LDB(B1, 1, 1); PG8_SCHED; PG8_LDA(At, 1, 0); PG8_STAGE(PG8_SA(0, 1), a2 + hstepA, voffA);
;             PG8_WAIT_V(8); PG8_WAIT_L(0); PG8_BAR; PG8_MMA(0, 0, At, B0); PG8_MMA(0, 1, At, B1); PG8_BAR; PG8_SCHED;
;             PG8_LDA(At, 1, 1); PG8_STAGE(PG8_SB(1, 0), b3, voffB); PG8_STAGE(PG8_SB(1, 1), b3 + hstepB, voffB); PG8_STAGE(PG8_SA(1, 0), a3, voffA);
;             PG8_WAIT_V(8); PG8_WAIT_L(0); PG8_BAR; PG8_MMA(1, 0, At, B0); PG8_MMA(1, 1, At, B1); PG8_BAR; PG8_SCHED;
	s_setprio 1
	s_waitcnt lgkmcnt(0)
	v_mfma_f32_16x16x32_bf16 v[62:65], v[130:133], v[184:187], 0
	v_mfma_f32_16x16x32_bf16 v[58:61], v[154:157], v[184:187], 0
	v_mfma_f32_16x16x32_bf16 v[46:49], v[130:133], v[192:195], 0
	v_mfma_f32_16x16x32_bf16 v[42:45], v[154:157], v[192:195], 0
	v_mfma_f32_16x16x32_bf16 v[30:33], v[130:133], v[200:203], 0
	v_mfma_f32_16x16x32_bf16 v[26:29], v[154:157], v[200:203], 0
	v_mfma_f32_16x16x32_bf16 v[14:17], v[130:133], v[208:211], 0
	v_mfma_f32_16x16x32_bf16 v[10:13], v[154:157], v[208:211], 0
	v_mfma_f32_16x16x32_bf16 v[62:65], v[134:137], v[188:191], v[62:65]
	v_mfma_f32_16x16x32_bf16 v[58:61], v[158:161], v[188:191], v[58:61]
	v_mfma_f32_16x16x32_bf16 v[46:49], v[134:137], v[196:199], v[46:49]
	v_mfma_f32_16x16x32_bf16 v[42:45], v[158:161], v[196:199], v[42:45]
	v_mfma_f32_16x16x32_bf16 v[30:33], v[134:137], v[204:207], v[30:33]
	v_mfma_f32_16x16x32_bf16 v[26:29], v[158:161], v[204:207], v[26:29]
	v_mfma_f32_16x16x32_bf16 v[14:17], v[134:137], v[212:215], v[14:17]
	v_mfma_f32_16x16x32_bf16 v[10:13], v[158:161], v[212:215], v[10:13]
	s_setprio 0
	s_setprio 1
	v_mfma_f32_16x16x32_bf16 v[54:57], v[168:171], v[184:187], 0
	v_mfma_f32_16x16x32_bf16 v[50:53], v[176:179], v[184:187], 0
	v_mfma_f32_16x16x32_bf16 v[38:41], v[168:171], v[192:195], 0
	v_mfma_f32_16x16x32_bf16 v[34:37], v[176:179], v[192:195], 0
	v_mfma_f32_16x16x32_bf16 v[22:25], v[168:171], v[200:203], 0
	v_mfma_f32_16x16x32_bf16 v[18:21], v[176:179], v[200:203], 0
	v_mfma_f32_16x16x32_bf16 v[6:9], v[168:171], v[208:211], 0
	v_mfma_f32_16x16x32_bf16 v[2:5], v[176:179], v[208:211], 0
	v_mfma_f32_16x16x32_bf16 v[54:57], v[172:175], v[188:191], v[54:57]
	v_mfma_f32_16x16x32_bf16 v[50:53], v[180:183], v[188:191], v[50:53]
	v_mfma_f32_16x16x32_bf16 v[38:41], v[172:175], v[196:199], v[38:41]
	v_mfma_f32_16x16x32_bf16 v[34:37], v[180:183], v[196:199], v[34:37]
	v_mfma_f32_16x16x32_bf16 v[22:25], v[172:175], v[204:207], v[22:25]
	v_mfma_f32_16x16x32_bf16 v[18:21], v[180:183], v[204:207], v[18:21]
	v_mfma_f32_16x16x32_bf16 v[6:9], v[172:175], v[212:215], v[6:9]
	v_mfma_f32_16x16x32_bf16 v[2:5], v[180:183], v[212:215], v[2:5]
	s_setprio 0
	s_barrier
	s_add_i32 s55, 0, 0x18000
	s_add_i32 s56, 0, 0x1c000
	v_add_u32_e32 v158, s55, v162
	v_add_u32_e32 v180, s56, v162
	ds_read_b128 v[130:133], v158
	ds_read_b128 v[134:137], v158 offset:1024
	ds_read_b128 v[154:157], v158 offset:2048
	ds_read_b128 v[158:161], v158 offset:3072
	ds_read_b128 v[168:171], v180
	ds_read_b128 v[172:175], v180 offset:1024
	ds_read_b128 v[176:179], v180 offset:2048
	ds_read_b128 v[180:183], v180 offset:3072
	s_add_u32 s26, s34, 0xb0000
	s_addc_u32 s27, s35, 0
	s_mov_b32 m0, s38
	v_lshl_add_u64 v[224:225], s[26:27], 0, v[138:139]
	ds_read_b128 v[184:187], v166 offset:32768
	ds_read_b128 v[188:191], v166 offset:33792
	ds_read_b128 v[192:195], v166 offset:34816
	ds_read_b128 v[196:199], v166 offset:35840
	ds_read_b128 v[200:203], v166 offset:36864
	ds_read_b128 v[204:207], v166 offset:37888
	ds_read_b128 v[208:211], v166 offset:38912
	ds_read_b128 v[212:215], v166 offset:39936
	global_load_lds_dwordx4 v[224:225], off
	v_lshl_add_u64 v[224:225], s[26:27], 0, v[142:143]
	s_mov_b32 m0, s39
	s_nop 0
	global_load_lds_dwordx4 v[224:225], off
	s_waitcnt vmcnt(8)
	s_waitcnt lgkmcnt(0)
	s_barrier
	s_setprio 1
	s_waitcnt lgkmcnt(0)
	v_mfma_f32_16x16x32_bf16 v[126:129], v[130:133], v[184:187], v[126:129]
	v_mfma_f32_16x16x32_bf16 v[122:125], v[154:157], v[184:187], v[122:125]
	v_mfma_f32_16x16x32_bf16 v[110:113], v[130:133], v[192:195], v[110:113]
	v_mfma_f32_16x16x32_bf16 v[106:109], v[154:157], v[192:195], v[106:109]
	v_mfma_f32_16x16x32_bf16 v[94:97], v[130:133], v[200:203], v[94:97]
	v_mfma_f32_16x16x32_bf16 v[90:93], v[154:157], v[200:203], v[90:93]
	v_mfma_f32_16x16x32_bf16 v[78:81], v[130:133], v[208:211], v[78:81]
	v_mfma_f32_16x16x32_bf16 v[74:77], v[154:157], v[208:211], v[74:77]
	v_mfma_f32_16x16x32_bf16 v[126:129], v[134:137], v[188:191], v[126:129]
	v_mfma_f32_16x16x32_bf16 v[122:125], v[158:161], v[188:191], v[122:125]
	v_mfma_f32_16x16x32_bf16 v[110:113], v[134:137], v[196:199], v[110:113]
	v_mfma_f32_16x16x32_bf16 v[106:109], v[158:161], v[196:199], v[106:109]
	v_mfma_f32_16x16x32_bf16 v[94:97], v[134:137], v[204:207], v[94:97]
	v_mfma_f32_16x16x32_bf16 v[90:93], v[158:161], v[204:207], v[90:93]
	v_mfma_f32_16x16x32_bf16 v[78:81], v[134:137], v[212:215], v[78:81]
	v_mfma_f32_16x16x32_bf16 v[74:77], v[158:161], v[212:215], v[74:77]
	s_setprio 0
	s_setprio 1
	v_mfma_f32_16x16x32_bf16 v[118:121], v[168:171], v[184:187], v[118:121]
	v_mfma_f32_16x16x32_bf16 v[114:117], v[176:179], v[184:187], v[114:117]
	v_mfma_f32_16x16x32_bf16 v[102:105], v[168:171], v[192:195], v[102:105]
	v_mfma_f32_16x16x32_bf16 v[98:101], v[176:179], v[192:195], v[98:101]
	v_mfma_f32_16x16x32_bf16 v[86:89], v[168:171], v[200:203], v[86:89]
	v_mfma_f32_16x16x32_bf16 v[82:85], v[176:179], v[200:203], v[82:85]
	v_mfma_f32_16x16x32_bf16 v[70:73], v[168:171], v[208:211], v[70:73]
	v_mfma_f32_16x16x32_bf16 v[66:69], v[176:179], v[208:211], v[66:69]
	v_mfma_f32_16x16x32_bf16 v[118:121], v[172:175], v[188:191], v[118:121]
	v_mfma_f32_16x16x32_bf16 v[114:117], v[180:183], v[188:191], v[114:117]
	v_mfma_f32_16x16x32_bf16 v[102:105], v[172:175], v[196:199], v[102:105]
	v_mfma_f32_16x16x32_bf16 v[98:101], v[180:183], v[196:199], v[98:101]
	v_mfma_f32_16x16x32_bf16 v[86:89], v[172:175], v[204:207], v[86:89]
	v_mfma_f32_16x16x32_bf16 v[82:85], v[180:183], v[204:207], v[82:85]
	v_mfma_f32_16x16x32_bf16 v[70:73], v[172:175], v[212:215], v[70:73]
	v_mfma_f32_16x16x32_bf16 v[66:69], v[180:183], v[212:215], v[66:69]
	s_setprio 0
	s_barrier
; #define PG8_STAGE(bufoff, gbase, voff) do { _Pragma("unroll") for (int _i = 0; _i < 2; ++_i) \
;         __builtin_amdgcn_global_load_lds((const unsigned*)((const char*)(gbase) + (voff)[_i]), (PG8_LAS unsigned*)(lds + (bufoff) + ldsw + _i * 8192), 16, 0, 0); } while (0)
; #define PG8_LDA(dst, b, h) do { _Pragma("unroll") for (int m = 0; m < 4; ++m) _Pragma("unroll") for (int k = 0; k < 2; ++k) dst[m][k] = *(const PG8_LAS bf16x8*)(lds + PG8_SA(b, h) + aoff + m * 2048 + k * 1024); } while (0)
; #define PG8_LDB(dst, b, h) do { _Pragma("unroll") for (int n = 0; n < 2; ++n) _Pragma("unroll") for (int k = 0; k < 2; ++k) dst[n][k] = *(const PG8_LAS bf16x8*)(lds + PG8_SB(b, h) + boff + n * 2048 + k * 1024); } while (0)
; #define PG8_MMA(ai, bj, At, Bt) do { __builtin_amdgcn_s_setprio(1); _Pragma("unroll") for (int m = 0; m < 4; ++m) _Pragma("unroll") for (int n = 0; n < 2; ++n) _Pragma("unroll") for (int k = 0; k < 2; ++k) \
;         acc[ai][bj][m][n] = __builtin_amdgcn_mfma_f32_16x16x32_bf16(Bt[n][k], At[m][k], acc[ai][bj][m][n], 0, 0, 0); __builtin_amdgcn_s_setprio(0); } while (0)
; #define PG8_WAIT_V(n) asm volatile("s_waitcnt vmcnt(" #n ")" ::: "memory")
; #define PG8_WAIT_L(n) asm volatile("s_waitcnt lgkmcnt(" #n ")" ::: "memory")
; #define PG8_BAR __builtin_amdgcn_s_barrier()
; #define PG8_SCHED __builtin_amdgcn_sched_barrier(0)
; template <class Epi, class Sched, bool ALIGN_EPI = false, bool SP2 = false>
; __device__ __forceinline__ void gemm_phase(PG8_LAS unsigned char* lds, const Gemm g, const Sched& S, const Epi& E) {
;     ...
;             PG8_LDB(B0, 1, 0); PG8_LDB(B1, 1, 1); PG8_SCHED; PG8_LDA(At, 1, 0); PG8_STAGE(PG8_SA(0, 1), a2 + hstepA, voffA);
;             PG8_WAIT_V(8); PG8_WAIT_L(0); PG8_BAR; PG8_MMA(0, 0, At, B0); PG8_MMA(0, 1, At, B1); PG8_BAR; PG8_SCHED;
;             PG8_LDA(At, 1, 1); PG8_STAGE(PG8_SB(1, 0), b3, voffB); PG8_STAGE(PG8_SB(1, 1), b3 + hstepB, voffB); PG8_STAGE(PG8_SA(1, 0), a3, voffA);
;             PG8_WAIT_V(8); PG8_WAIT_L(0); PG8_BAR; PG8_MMA(1, 0, At, B0); PG8_MMA(1, 1, At, B1); PG8_BAR; PG8_SCHED;
	s_add_i32 s26, s55, s0
	v_lshl_add_u64 v[216:217], v[216:217], 0, s[20:21]
	s_mov_b32 m0, s26
	ds_read_b128 v[184:187], v166 offset:49152
	ds_read_b128 v[188:191], v166 offset:50176
	ds_read_b128 v[192:195], v166 offset:51200
	ds_read_b128 v[196:199], v166 offset:52224
	ds_read_b128 v[200:203], v166 offset:53248
	ds_read_b128 v[204:207], v166 offset:54272
	ds_read_b128 v[208:211], v166 offset:55296
	ds_read_b128 v[212:215], v166 offset:56320
	global_load_lds_dwordx4 v[216:217], off
	s_add_i32 m0, s26, 0x2000
	s_add_u32 s26, s30, 0xb0080
	v_lshl_add_u64 v[216:217], v[218:219], 0, s[20:21]
	s_addc_u32 s27, s31, 0
	s_add_i32 s30, s56, s0
	global_load_lds_dwordx4 v[216:217], off
	v_lshl_add_u64 v[216:217], s[26:27], 0, v[140:141]
	s_mov_b32 m0, s30
	s_nop 0
	global_load_lds_dwordx4 v[216:217], off
	v_lshl_add_u64 v[216:217], s[26:27], 0, v[144:145]
	s_add_i32 m0, s30, 0x2000
	s_nop 0
	global_load_lds_dwordx4 v[216:217], off
	v_lshl_add_u64 v[216:217], v[220:221], 0, s[20:21]
	s_mov_b32 m0, s41
	s_nop 0
	global_load_lds_dwordx4 v[216:217], off
	v_lshl_add_u64 v[216:217], v[222:223], 0, s[20:21]
	s_mov_b32 m0, s42
	s_nop 0
	global_load_lds_dwordx4 v[216:217], off
	s_waitcnt vmcnt(8)
	s_waitcnt lgkmcnt(0)
	s_barrier
	s_setprio 1
	s_waitcnt lgkmcnt(0)
	v_mfma_f32_16x16x32_bf16 v[62:65], v[130:133], v[184:187], v[62:65]
	v_mfma_f32_16x16x32_bf16 v[58:61], v[154:157], v[184:187], v[58:61]
	v_mfma_f32_16x16x32_bf16 v[46:49], v[130:133], v[192:195], v[46:49]
	v_mfma_f32_16x16x32_bf16 v[42:45], v[154:157], v[192:195], v[42:45]
	v_mfma_f32_16x16x32_bf16 v[30:33], v[130:133], v[200:203], v[30:33]
	v_mfma_f32_16x16x32_bf16 v[26:29], v[154:157], v[200:203], v[26:29]
	v_mfma_f32_16x16x32_bf16 v[14:17], v[130:133], v[208:211], v[14:17]
	v_mfma_f32_16x16x32_bf16 v[10:13], v[154:157], v[208:211], v[10:13]
	v_mfma_f32_16x16x32_bf16 v[62:65], v[134:137], v[188:191], v[62:65]
	v_mfma_f32_16x16x32_bf16 v[58:61], v[158:161], v[188:191], v[58:61]
	v_mfma_f32_16x16x32_bf16 v[46:49], v[134:137], v[196:199], v[46:49]
	v_mfma_f32_16x16x32_bf16 v[42:45], v[158:161], v[196:199], v[42:45]
	v_mfma_f32_16x16x32_bf16 v[30:33], v[134:137], v[204:207], v[30:33]
	v_mfma_f32_16x16x32_bf16 v[26:29], v[158:161], v[204:207], v[26:29]
	v_mfma_f32_16x16x32_bf16 v[14:17], v[134:137], v[212:215], v[14:17]
	v_mfma_f32_16x16x32_bf16 v[10:13], v[158:161], v[212:215], v[10:13]
	s_setprio 0
	s_setprio 1
	v_mfma_f32_16x16x32_bf16 v[54:57], v[168:171], v[184:187], v[54:57]
	v_mfma_f32_16x16x32_bf16 v[50:53], v[176:179], v[184:187], v[50:53]
	v_mfma_f32_16x16x32_bf16 v[38:41], v[168:171], v[192:195], v[38:41]
	v_mfma_f32_16x16x32_bf16 v[34:37], v[176:179], v[192:195], v[34:37]
	v_mfma_f32_16x16x32_bf16 v[22:25], v[168:171], v[200:203], v[22:25]
	v_mfma_f32_16x16x32_bf16 v[18:21], v[176:179], v[200:203], v[18:21]
	v_mfma_f32_16x16x32_bf16 v[6:9], v[168:171], v[208:211], v[6:9]
	v_mfma_f32_16x16x32_bf16 v[2:5], v[176:179], v[208:211], v[2:5]
	v_mfma_f32_16x16x32_bf16 v[54:57], v[172:175], v[188:191], v[54:57]
	v_mfma_f32_16x16x32_bf16 v[50:53], v[180:183], v[188:191], v[50:53]
	v_mfma_f32_16x16x32_bf16 v[38:41], v[172:175], v[196:199], v[38:41]
	v_mfma_f32_16x16x32_bf16 v[34:37], v[180:183], v[196:199], v[34:37]
	v_mfma_f32_16x16x32_bf16 v[22:25], v[172:175], v[204:207], v[22:25]
	v_mfma_f32_16x16x32_bf16 v[18:21], v[180:183], v[204:207], v[18:21]
	v_mfma_f32_16x16x32_bf16 v[6:9], v[172:175], v[212:215], v[6:9]
	v_mfma_f32_16x16x32_bf16 v[2:5], v[180:183], v[212:215], v[2:5]
	s_setprio 0
	s_barrier
	s_add_i32 s54, s54, 2
	s_add_u32 s4, s4, 0x100
	s_addc_u32 s53, s53, 0
	s_cmp_gt_u32 s54, 41
	s_mov_b64 s[26:27], s[28:29]

; #define PG8_BAR __builtin_amdgcn_s_barrier()
; template <class Epi, class Sched, bool ALIGN_EPI = false, bool SP2 = false>
; __device__ __forceinline__ void gemm_phase(PG8_LAS unsigned char* lds, const Gemm g, const Sched& S, const Epi& E) {
;     ...
;         if constexpr (ALIGN_EPI) { if (wr == 0) PG8_BAR; }
;         if constexpr (!Epi::AFTER_DRAIN) { E(acc, cur, wr, wc, fr, fq); S.done(cur); }
;         if (!has_next) break;
; #pragma unroll
;         for (int a = 0; a < 2; ++a)
; #pragma unroll
;             for (int b = 0; b < 2; ++b)
; #pragma unroll
;                 for (int m = 0; m < 4; ++m)
; #pragma unroll
;                     for (int n = 0; n < 2; ++n) acc[a][b][m][n] = (f32x4){0.f, 0.f, 0.f, 0.f};
;         cur = nxt; cA = nA; cB = nB; ++ui;
;         if constexpr (ALIGN_EPI) { if (wr == 1) PG8_BAR; }
;     }
.LBB0_795:
	s_or_b64 exec, exec, s[28:29]
	s_and_b64 vcc, exec, s[10:11]
	s_mov_b64 s[10:11], -1
	s_cbranch_vccnz .LBB0_764
	s_andn2_b64 vcc, exec, s[14:15]
	s_cbranch_vccnz .LBB0_763
	s_mov_b32 s98, 1
	s_branch .LBB0_763

; #define PG8_STAGE(bufoff, gbase, voff) do { _Pragma("unroll") for (int _i = 0; _i < 2; ++_i) \
;         __builtin_amdgcn_global_load_lds((const unsigned*)((const char*)(gbase) + (voff)[_i]), (PG8_LAS unsigned*)(lds + (bufoff) + ldsw + _i * 8192), 16, 0, 0); } while (0)
; #define PG8_WAIT_V(n) asm volatile("s_waitcnt vmcnt(" #n ")" ::: "memory")
; #define PG8_BAR __builtin_amdgcn_s_barrier()
; template <class Epi, class Sched, bool ALIGN_EPI = false, bool SP2 = false>
; __device__ __forceinline__ void gemm_phase(PG8_LAS unsigned char* lds, const Gemm g, const Sched& S, const Epi& E) {
;     int tid_ = threadIdx.x; asm volatile("" : "+v"(tid_));
;     const int tid = tid_, wid = __builtin_amdgcn_readfirstlane(tid >> 6), lane = tid & 63, wr = wid >> 2, wc = wid & 3, fr = lane & 15, fq = lane >> 4;
;     const int K = g.K, nt = K / BK;
;     unsigned voffA[2], voffB[2];
; #pragma unroll
;     for (int i = 0; i < 2; ++i) { int R, C; stage_rc(tid * 16 + i * 8192, R, C); const int Rb = Epi::PERM ? ((R & ~31) + perm32(R & 31)) : R;
;         voffA[i] = (unsigned)(R * g.lda + C) * 2u; voffB[i] = (unsigned)(Rb * g.ldb + C) * 2u; }
;     const size_t kstep = (size_t)(BK * 2);
;     const size_t hstepA = (size_t)HALF * g.lda * 2, hstepB = (size_t)HALF * g.ldb * 2;
;     const size_t tstepA = 2 * hstepA, tstepB = 2 * hstepB;
;     const unsigned ldsw = (unsigned)wid * 1024u;
;     const int aoff = lds_byte(wr * 64 + fr, fq * 8), boff = lds_byte(wc * 32 + fr, fq * 8);
;     ...
;     const char* cA = (const char*)g.A + (size_t)cur.g * g.gsA * 2 + (size_t)cur.pm * tstepA; const char* cB = (const char*)g.Bt + (size_t)cur.g * g.gsB * 2 + (size_t)cur.pn * tstepB;
;     S.a_ready(cur);
;     if constexpr (SP2) {
;         PG8_STAGE(PG8_SB(0, 0), cB, voffB); PG8_STAGE(PG8_SB(0, 1), cB + hstepB, voffB); PG8_STAGE(PG8_SA(0, 0), cA, voffA); PG8_STAGE(PG8_SA(0, 1), cA + hstepA, voffA);
;         if (wr == 1) PG8_BAR;
;         PG8_WAIT_V(2); PG8_BAR;
;         PG8_STAGE(PG8_SB(1, 0), cB + kstep, voffB); PG8_STAGE(PG8_SA(1, 0), cA + kstep, voffA); PG8_STAGE(PG8_SB(1, 1), cB + hstepB + kstep, voffB);
;         PG8_WAIT_V(6); PG8_BAR;
.LBB0_806:
	s_add_u32 s18, s78, 0xbc00000
	s_mov_b64 s[20:21], 0x80
	s_addc_u32 s19, s79, 0
	s_add_i32 m0, s43, 0x18000
	v_lshl_add_u64 v[10:11], v[10:11], 0, s[20:21]
	s_waitcnt vmcnt(2)
	s_barrier
	global_load_lds_dwordx4 v[10:11], off
	v_lshl_add_u64 v[6:7], v[6:7], 0, s[20:21]
	s_add_i32 m0, s43, 0x1a000
	s_add_i32 s48, s43, 0x8000
	global_load_lds_dwordx4 v[6:7], off
	v_lshl_add_u64 v[6:7], v[8:9], 0, s[20:21]
	s_mov_b32 m0, s48
	s_add_i32 s49, s43, 0xa000
	global_load_lds_dwordx4 v[6:7], off
	v_lshl_add_u64 v[6:7], v[12:13], 0, s[20:21]
	s_mov_b32 m0, s49
	v_lshl_add_u64 v[4:5], v[4:5], 0, s[20:21]
	global_load_lds_dwordx4 v[6:7], off
	s_add_i32 m0, s43, 0x1c000
	v_lshl_add_u64 v[2:3], v[2:3], 0, s[20:21]
	global_load_lds_dwordx4 v[4:5], off
	s_add_i32 m0, s43, 0x1e000
	s_sext_i32_i8 s62, s6
	global_load_lds_dwordx4 v[2:3], off
	v_lshrrev_b32_e32 v3, 1, v14
	s_ashr_i32 s6, s22, 31
	v_and_b32_e32 v3, 24, v3
	v_and_b32_e32 v2, 15, v14
	s_lshr_b32 s6, s6, 26
	v_lshlrev_b32_e32 v4, 1, v3
	s_add_i32 s6, s22, s6
	v_lshl_or_b32 v1, s24, 6, v2
	v_lshl_or_b32 v2, v2, 6, v4
	v_lshlrev_b32_e32 v4, 2, v14
	s_ashr_i32 s50, s6, 6
	s_lshl_b32 s6, s24, 13
	v_and_b32_e32 v4, 32, v4
	v_bitop3_b32 v5, v2, s6, v4 bitop3:0xde
	s_lshl_b32 s6, s23, 5
	s_and_b32 s6, s6, 0x60
	s_lshl_b32 s8, s6, 7
	v_bitop3_b32 v146, v2, s8, v4 bitop3:0xde
	s_cmp_gt_i32 s22, 63
	v_add_u32_e32 v2, v17, v15
	s_cselect_b64 s[22:23], -1, 0
	s_add_i32 s51, s50, -2
	v_or_b32_e32 v147, s6, v3
	v_add_lshl_u32 v2, v2, v16, 1
	v_mov_b32_e32 v3, v133
	s_waitcnt vmcnt(6)
	s_cmpk_lt_u32 s7, 0x100
	v_lshl_add_u64 v[138:139], s[4:5], 0, v[2:3]
	v_add_u32_e32 v2, v20, v18
	s_cselect_b64 s[24:25], -1, 0
	v_add_lshl_u32 v2, v2, v19, 1
	s_add_i32 s54, 0, 0x10000
	s_add_i32 s55, 0, 0x14000
	s_ashr_i32 s52, s82, 31
	s_mov_b32 s53, s82
	v_lshl_add_u64 v[140:141], s[4:5], 0, v[2:3]
	v_mov_b64_e32 v[142:143], 0x200
	v_mov_b64_e32 v[144:145], 0x1ff
	v_add_u32_e32 v148, s54, v146
	v_add_u32_e32 v149, s55, v146
	v_add_u32_e32 v150, 0, v5
	s_mov_b64 s[26:27], 0x40000
	s_mov_b32 s56, 0x40000
	s_mov_b64 s[28:29], 0x48000
	s_mov_b32 s57, 0x48000
	s_mov_b64 s[30:31], 0x50000
	s_mov_b32 s58, 0x50000
	s_mov_b64 s[34:35], 0x58000
	s_barrier
	s_mov_b32 s98, 0
	s_branch .LBB0_809

; #define PG8_STAGE(bufoff, gbase, voff) do { _Pragma("unroll") for (int _i = 0; _i < 2; ++_i) \
;         __builtin_amdgcn_global_load_lds((const unsigned*)((const char*)(gbase) + (voff)[_i]), (PG8_LAS unsigned*)(lds + (bufoff) + ldsw + _i * 8192), 16, 0, 0); } while (0)
; #define PG8_LDA(dst, b, h) do { _Pragma("unroll") for (int m = 0; m < 4; ++m) _Pragma("unroll") for (int k = 0; k < 2; ++k) dst[m][k] = *(const PG8_LAS bf16x8*)(lds + PG8_SA(b, h) + aoff + m * 2048 + k * 1024); } while (0)
; #define PG8_LDB(dst, b, h) do { _Pragma("unroll") for (int n = 0; n < 2; ++n) _Pragma("unroll") for (int k = 0; k < 2; ++k) dst[n][k] = *(const PG8_LAS bf16x8*)(lds + PG8_SB(b, h) + boff + n * 2048 + k * 1024); } while (0)
; #define PG8_WAIT_V(n) asm volatile("s_waitcnt vmcnt(" #n ")" ::: "memory")
; #define PG8_WAIT_L(n) asm volatile("s_waitcnt lgkmcnt(" #n ")" ::: "memory")
; template <class Epi, class Sched, bool ALIGN_EPI = false, bool SP2 = false>
; __device__ __forceinline__ void gemm_phase(PG8_LAS unsigned char* lds, const Gemm g, const Sched& S, const Epi& E) {
;     ...
;         const bool has_next = S.next(ui + 1, nxt);
;         const char* nA = has_next ? (const char*)g.A + (size_t)nxt.g * g.gsA * 2 + (size_t)nxt.pm * tstepA : cA; const char* nB = has_next ? (const char*)g.Bt + (size_t)nxt.g * g.gsB * 2 + (size_t)nxt.pn * tstepB : cB;
;         for (int t = 0; t < nt; t += 2) {
;             const bool last = (t == nt - 2);
;             const char* a1 = cA + (size_t)(t + 1) * kstep;
;             const char* a2 = last ? nA : cA + (size_t)(t + 2) * kstep; const char* b2 = last ? nB : cB + (size_t)(t + 2) * kstep;
;             const char* a3 = a2 + kstep; const char* b3 = b2 + kstep;
;             if (last && has_next) S.a_ready(nxt);
;             if constexpr (SP2) {
;             PG8_LDB(B0, 0, 0); PG8_LDB(B1, 0, 1); PG8_SCHED; PG8_LDA(At, 0, 0); PG8_STAGE(PG8_SA(1, 1), a1 + hstepA, voffA);
;             PG8_WAIT_V(8); PG8_WAIT_L(0); PG8_BAR; PG8_MMA(0, 0, At, B0); PG8_MMA(0, 1, At, B1); PG8_BAR; PG8_SCHED;
;     ...
; #pragma unroll
;         for (int a = 0; a < 2; ++a)
; #pragma unroll
;             for (int b = 0; b < 2; ++b)
; #pragma unroll
;                 for (int m = 0; m < 4; ++m)
; #pragma unroll
;                     for (int n = 0; n < 2; ++n) acc[a][b][m][n] = (f32x4){0.f, 0.f, 0.f, 0.f};
;         cur = nxt; cA = nA; cB = nB; ++ui;
.LBB0_819:
	v_mov_b32_e32 v125, 0
	s_andn2_b64 vcc, exec, s[22:23]
	v_mov_b32_e32 v124, v125
	v_mov_b32_e32 v123, v125
	v_mov_b32_e32 v122, v125
	v_mov_b32_e32 v129, v125
	v_mov_b32_e32 v128, v125
	v_mov_b32_e32 v127, v125
	v_mov_b32_e32 v126, v125
	v_mov_b32_e32 v113, v125
	v_mov_b32_e32 v112, v125
	v_mov_b32_e32 v111, v125
	v_mov_b32_e32 v110, v125
	v_mov_b32_e32 v109, v125
	v_mov_b32_e32 v108, v125
	v_mov_b32_e32 v107, v125
	v_mov_b32_e32 v106, v125
	v_mov_b32_e32 v97, v125
	v_mov_b32_e32 v96, v125
	v_mov_b32_e32 v95, v125
	v_mov_b32_e32 v94, v125
	v_mov_b32_e32 v93, v125
	v_mov_b32_e32 v92, v125
	v_mov_b32_e32 v91, v125
	v_mov_b32_e32 v90, v125
	v_mov_b32_e32 v81, v125
	v_mov_b32_e32 v80, v125
	v_mov_b32_e32 v79, v125
	v_mov_b32_e32 v78, v125
	v_mov_b32_e32 v77, v125
	v_mov_b32_e32 v76, v125
	v_mov_b32_e32 v75, v125
	v_mov_b32_e32 v74, v125
	v_mov_b32_e32 v121, v125
	v_mov_b32_e32 v120, v125
	v_mov_b32_e32 v119, v125
	v_mov_b32_e32 v118, v125
	v_mov_b32_e32 v117, v125
	v_mov_b32_e32 v116, v125
	v_mov_b32_e32 v115, v125
	v_mov_b32_e32 v114, v125
	v_mov_b32_e32 v105, v125
	v_mov_b32_e32 v104, v125
	v_mov_b32_e32 v103, v125
	v_mov_b32_e32 v102, v125
	v_mov_b32_e32 v101, v125
	v_mov_b32_e32 v100, v125
	v_mov_b32_e32 v99, v125
	v_mov_b32_e32 v98, v125
	v_mov_b32_e32 v89, v125
	v_mov_b32_e32 v88, v125
	v_mov_b32_e32 v87, v125
	v_mov_b32_e32 v86, v125
	v_mov_b32_e32 v85, v125
	v_mov_b32_e32 v84, v125
	v_mov_b32_e32 v83, v125
	v_mov_b32_e32 v82, v125
	v_mov_b32_e32 v73, v125
	v_mov_b32_e32 v72, v125
	v_mov_b32_e32 v71, v125
	v_mov_b32_e32 v70, v125
	v_mov_b32_e32 v69, v125
	v_mov_b32_e32 v68, v125
	v_mov_b32_e32 v67, v125
	v_mov_b32_e32 v66, v125
	v_mov_b32_e32 v65, v125
	v_mov_b32_e32 v64, v125
	v_mov_b32_e32 v63, v125
	v_mov_b32_e32 v62, v125
	v_mov_b32_e32 v61, v125
	v_mov_b32_e32 v60, v125
	v_mov_b32_e32 v59, v125
	v_mov_b32_e32 v58, v125
	v_mov_b32_e32 v49, v125
	v_mov_b32_e32 v48, v125
	v_mov_b32_e32 v47, v125
	v_mov_b32_e32 v46, v125
	v_mov_b32_e32 v45, v125
	v_mov_b32_e32 v44, v125
	v_mov_b32_e32 v43, v125
	v_mov_b32_e32 v42, v125
	v_mov_b32_e32 v33, v125
	v_mov_b32_e32 v32, v125
	v_mov_b32_e32 v31, v125
	v_mov_b32_e32 v30, v125
	v_mov_b32_e32 v29, v125
	v_mov_b32_e32 v28, v125
	v_mov_b32_e32 v27, v125
	v_mov_b32_e32 v26, v125
	v_mov_b32_e32 v17, v125
	v_mov_b32_e32 v16, v125
	v_mov_b32_e32 v15, v125
	v_mov_b32_e32 v14, v125
	v_mov_b32_e32 v13, v125
	v_mov_b32_e32 v12, v125
	v_mov_b32_e32 v11, v125
	v_mov_b32_e32 v10, v125
	v_mov_b32_e32 v57, v125
	v_mov_b32_e32 v56, v125
	v_mov_b32_e32 v55, v125
	v_mov_b32_e32 v54, v125
	v_mov_b32_e32 v53, v125
	v_mov_b32_e32 v52, v125
	v_mov_b32_e32 v51, v125
	v_mov_b32_e32 v50, v125
	v_mov_b32_e32 v41, v125
	v_mov_b32_e32 v40, v125
	v_mov_b32_e32 v39, v125
	v_mov_b32_e32 v38, v125
	v_mov_b32_e32 v37, v125
	v_mov_b32_e32 v36, v125
	v_mov_b32_e32 v35, v125
	v_mov_b32_e32 v34, v125
	v_mov_b32_e32 v25, v125
	v_mov_b32_e32 v24, v125
	v_mov_b32_e32 v23, v125
	v_mov_b32_e32 v22, v125
	v_mov_b32_e32 v21, v125
	v_mov_b32_e32 v20, v125
	v_mov_b32_e32 v19, v125
	v_mov_b32_e32 v18, v125
	v_mov_b32_e32 v9, v125
	v_mov_b32_e32 v8, v125
	v_mov_b32_e32 v7, v125
	v_mov_b32_e32 v6, v125
	v_mov_b32_e32 v5, v125
	v_mov_b32_e32 v4, v125
	v_mov_b32_e32 v3, v125
	v_mov_b32_e32 v2, v125
	s_cbranch_vccnz .LBB0_822
	s_add_u32 s38, s38, 0x80
	s_addc_u32 s39, s39, 0
	s_add_u32 s63, s40, 0x100
	s_addc_u32 s64, s41, 0
	s_mov_b32 s40, 0
	s_cmp_eq_u32 s98, 1
	s_cbranch_scc0 .Lhb_26547
	s_mov_b32 s98, 0
	s_barrier
.Lhb_26547:
	ds_read_b128 v[152:155], v148
	ds_read_b128 v[156:159], v148 offset:1024
	ds_read_b128 v[160:163], v148 offset:2048
	ds_read_b128 v[164:167], v148 offset:3072
	ds_read_b128 v[168:171], v149
	ds_read_b128 v[172:175], v149 offset:1024
	ds_read_b128 v[176:179], v149 offset:2048
	ds_read_b128 v[180:183], v149 offset:3072
	s_add_i32 s65, s40, 2
	s_add_u32 s66, s38, 0x80
	s_addc_u32 s41, s39, 0
	s_cmp_eq_u32 s51, s40
	s_cselect_b32 s40, s8, s66
	s_cselect_b32 s41, s9, s41
	s_cselect_b32 s67, s37, s64
	s_cselect_b32 s66, s36, s63
	v_lshl_add_u64 v[216:217], s[38:39], 0, v[138:139]
	s_add_i32 m0, s43, 0xc000
	ds_read_b128 v[184:187], v150
	ds_read_b128 v[188:191], v150 offset:1024
	ds_read_b128 v[192:195], v150 offset:2048
	ds_read_b128 v[196:199], v150 offset:3072
	ds_read_b128 v[200:203], v150 offset:4096
	ds_read_b128 v[204:207], v150 offset:5120
	ds_read_b128 v[208:211], v150 offset:6144
	ds_read_b128 v[212:215], v150 offset:7168
	global_load_lds_dwordx4 v[216:217], off
	v_lshl_add_u64 v[216:217], s[38:39], 0, v[140:141]
	s_add_i32 m0, s43, 0xe000
	s_nop 0
	global_load_lds_dwordx4 v[216:217], off
	s_waitcnt vmcnt(8)
	s_waitcnt lgkmcnt(0)
	s_barrier
; #define PG8_STAGE(bufoff, gbase, voff) do { _Pragma("unroll") for (int _i = 0; _i < 2; ++_i) \
;         __builtin_amdgcn_global_load_lds((const unsigned*)((const char*)(gbase) + (voff)[_i]), (PG8_LAS unsigned*)(lds + (bufoff) + ldsw + _i * 8192), 16, 0, 0); } while (0)
; #define PG8_LDA(dst, b, h) do { _Pragma("unroll") for (int m = 0; m < 4; ++m) _Pragma("unroll") for (int k = 0; k < 2; ++k) dst[m][k] = *(const PG8_LAS bf16x8*)(lds + PG8_SA(b, h) + aoff + m * 2048 + k * 1024); } while (0)
; #define PG8_LDB(dst, b, h) do { _Pragma("unroll") for (int n = 0; n < 2; ++n) _Pragma("unroll") for (int k = 0; k < 2; ++k) dst[n][k] = *(const PG8_LAS bf16x8*)(lds + PG8_SB(b, h) + boff + n * 2048 + k * 1024); } while (0)
; #define PG8_MMA(ai, bj, At, Bt) do { __builtin_amdgcn_s_setprio(1); _Pragma("unroll") for (int m = 0; m < 4; ++m) _Pragma("unroll") for (int n = 0; n < 2; ++n) _Pragma("unroll") for (int k = 0; k < 2; ++k) \
;         acc[ai][bj][m][n] = __builtin_amdgcn_mfma_f32_16x16x32_bf16(Bt[n][k], At[m][k], acc[ai][bj][m][n], 0, 0, 0); __builtin_amdgcn_s_setprio(0); } while (0)
; #define PG8_WAIT_V(n) asm volatile("s_waitcnt vmcnt(" #n ")" ::: "memory")
; #define PG8_WAIT_L(n) asm volatile("s_waitcnt lgkmcnt(" #n ")" ::: "memory")
; #define PG8_BAR __builtin_amdgcn_s_barrier()
; #define PG8_SCHED __builtin_amdgcn_sched_barrier(0)
; template <class Epi, class Sched, bool ALIGN_EPI = false, bool SP2 = false>
; __device__ __forceinline__ void gemm_phase(PG8_LAS unsigned char* lds, const Gemm g, const Sched& S, const Epi& E) {
;     ...
;             PG8_WAIT_V(8); PG8_WAIT_L(0); PG8_BAR; PG8_MMA(0, 0, At, B0); PG8_MMA(0, 1, At, B1); PG8_BAR; PG8_SCHED;
;             PG8_LDA(At, 0, 1); PG8_STAGE(PG8_SB(0, 0), b2, voffB); PG8_STAGE(PG8_SB(0, 1), b2 + hstepB, voffB); PG8_STAGE(PG8_SA(0, 0), a2, voffA);
;             PG8_WAIT_V(8); PG8_WAIT_L(0); PG8_BAR; PG8_MMA(1, 0, At, B0); PG8_MMA(1, 1, At, B1); PG8_BAR; PG8_SCHED;
;             PG8_LDB(B0, 1, 0); PG8_LDB(B1, 1, 1); PG8_SCHED; PG8_LDA(At, 1, 0); PG8_STAGE(PG8_SA(0, 1), a2 + hstepA, voffA);
;             PG8_WAIT_V(8); PG8_WAIT_L(0); PG8_BAR; PG8_MMA(0, 0, At, B0); PG8_MMA(0, 1, At, B1); PG8_BAR; PG8_SCHED;
	s_setprio 1
	s_waitcnt lgkmcnt(0)
	v_mfma_f32_16x16x32_bf16 v[122:125], v[152:155], v[184:187], 0
	v_mfma_f32_16x16x32_bf16 v[126:129], v[160:163], v[184:187], 0
	v_mfma_f32_16x16x32_bf16 v[110:113], v[152:155], v[192:195], 0
	v_mfma_f32_16x16x32_bf16 v[106:109], v[160:163], v[192:195], 0
	v_mfma_f32_16x16x32_bf16 v[94:97], v[152:155], v[200:203], 0
	v_mfma_f32_16x16x32_bf16 v[90:93], v[160:163], v[200:203], 0
	v_mfma_f32_16x16x32_bf16 v[78:81], v[152:155], v[208:211], 0
	v_mfma_f32_16x16x32_bf16 v[74:77], v[160:163], v[208:211], 0
	v_mfma_f32_16x16x32_bf16 v[122:125], v[156:159], v[188:191], v[122:125]
	v_mfma_f32_16x16x32_bf16 v[126:129], v[164:167], v[188:191], v[126:129]
	v_mfma_f32_16x16x32_bf16 v[110:113], v[156:159], v[196:199], v[110:113]
	v_mfma_f32_16x16x32_bf16 v[106:109], v[164:167], v[196:199], v[106:109]
	v_mfma_f32_16x16x32_bf16 v[94:97], v[156:159], v[204:207], v[94:97]
	v_mfma_f32_16x16x32_bf16 v[90:93], v[164:167], v[204:207], v[90:93]
	v_mfma_f32_16x16x32_bf16 v[78:81], v[156:159], v[212:215], v[78:81]
	v_mfma_f32_16x16x32_bf16 v[74:77], v[164:167], v[212:215], v[74:77]
	s_setprio 0
	s_setprio 1
	v_mfma_f32_16x16x32_bf16 v[118:121], v[168:171], v[184:187], 0
	v_mfma_f32_16x16x32_bf16 v[114:117], v[176:179], v[184:187], 0
	v_mfma_f32_16x16x32_bf16 v[102:105], v[168:171], v[192:195], 0
	v_mfma_f32_16x16x32_bf16 v[98:101], v[176:179], v[192:195], 0
	v_mfma_f32_16x16x32_bf16 v[86:89], v[168:171], v[200:203], 0
	v_mfma_f32_16x16x32_bf16 v[82:85], v[176:179], v[200:203], 0
	v_mfma_f32_16x16x32_bf16 v[70:73], v[168:171], v[208:211], 0
	v_mfma_f32_16x16x32_bf16 v[66:69], v[176:179], v[208:211], 0
	v_mfma_f32_16x16x32_bf16 v[118:121], v[172:175], v[188:191], v[118:121]
	v_mfma_f32_16x16x32_bf16 v[114:117], v[180:183], v[188:191], v[114:117]
	v_mfma_f32_16x16x32_bf16 v[102:105], v[172:175], v[196:199], v[102:105]
	v_mfma_f32_16x16x32_bf16 v[98:101], v[180:183], v[196:199], v[98:101]
	v_mfma_f32_16x16x32_bf16 v[86:89], v[172:175], v[204:207], v[86:89]
	v_mfma_f32_16x16x32_bf16 v[82:85], v[180:183], v[204:207], v[82:85]
	v_mfma_f32_16x16x32_bf16 v[70:73], v[172:175], v[212:215], v[70:73]
	v_mfma_f32_16x16x32_bf16 v[66:69], v[180:183], v[212:215], v[66:69]
	s_setprio 0
	s_barrier
	s_add_i32 s68, s54, s42
	v_lshl_add_u64 v[216:217], s[66:67], 0, v[132:133]
	s_mov_b32 m0, s68
	ds_read_b128 v[184:187], v150 offset:16384
	ds_read_b128 v[188:191], v150 offset:17408
	ds_read_b128 v[192:195], v150 offset:18432
	ds_read_b128 v[196:199], v150 offset:19456
	ds_read_b128 v[200:203], v150 offset:20480
	ds_read_b128 v[204:207], v150 offset:21504
	ds_read_b128 v[208:211], v150 offset:22528
	ds_read_b128 v[212:215], v150 offset:23552
	global_load_lds_dwordx4 v[216:217], off
	s_add_i32 m0, s68, 0x2000
	v_lshl_add_u64 v[218:219], s[66:67], 0, v[136:137]
	s_add_u32 s66, s66, s10
	s_addc_u32 s67, s67, s11
	s_add_i32 s68, s55, s42
	global_load_lds_dwordx4 v[218:219], off
	v_lshl_add_u64 v[220:221], s[66:67], 0, v[132:133]
	s_mov_b32 m0, s68
	v_lshl_add_u64 v[222:223], s[66:67], 0, v[136:137]
	global_load_lds_dwordx4 v[220:221], off
	s_add_i32 m0, s68, 0x2000
	v_lshl_add_u64 v[224:225], s[40:41], 0, v[130:131]
	global_load_lds_dwordx4 v[222:223], off
	s_mov_b32 m0, s43
	v_lshl_add_u64 v[226:227], s[40:41], 0, v[134:135]
	global_load_lds_dwordx4 v[224:225], off
	s_mov_b32 m0, s44
	s_nop 0
	global_load_lds_dwordx4 v[226:227], off
	s_waitcnt vmcnt(8)
	s_waitcnt lgkmcnt(0)
	s_barrier
	s_setprio 1
	s_waitcnt lgkmcnt(0)
	v_mfma_f32_16x16x32_bf16 v[62:65], v[152:155], v[184:187], 0
	v_mfma_f32_16x16x32_bf16 v[58:61], v[160:163], v[184:187], 0
	v_mfma_f32_16x16x32_bf16 v[46:49], v[152:155], v[192:195], 0
	v_mfma_f32_16x16x32_bf16 v[42:45], v[160:163], v[192:195], 0
	v_mfma_f32_16x16x32_bf16 v[30:33], v[152:155], v[200:203], 0
	v_mfma_f32_16x16x32_bf16 v[26:29], v[160:163], v[200:203], 0
	v_mfma_f32_16x16x32_bf16 v[14:17], v[152:155], v[208:211], 0
	v_mfma_f32_16x16x32_bf16 v[10:13], v[160:163], v[208:211], 0
	v_mfma_f32_16x16x32_bf16 v[62:65], v[156:159], v[188:191], v[62:65]
	v_mfma_f32_16x16x32_bf16 v[58:61], v[164:167], v[188:191], v[58:61]
	v_mfma_f32_16x16x32_bf16 v[46:49], v[156:159], v[196:199], v[46:49]
	v_mfma_f32_16x16x32_bf16 v[42:45], v[164:167], v[196:199], v[42:45]
	v_mfma_f32_16x16x32_bf16 v[30:33], v[156:159], v[204:207], v[30:33]
	v_mfma_f32_16x16x32_bf16 v[26:29], v[164:167], v[204:207], v[26:29]
	v_mfma_f32_16x16x32_bf16 v[14:17], v[156:159], v[212:215], v[14:17]
	v_mfma_f32_16x16x32_bf16 v[10:13], v[164:167], v[212:215], v[10:13]
	s_setprio 0
	s_setprio 1
	v_mfma_f32_16x16x32_bf16 v[54:57], v[168:171], v[184:187], 0
	v_mfma_f32_16x16x32_bf16 v[50:53], v[176:179], v[184:187], 0
	v_mfma_f32_16x16x32_bf16 v[38:41], v[168:171], v[192:195], 0
	v_mfma_f32_16x16x32_bf16 v[34:37], v[176:179], v[192:195], 0
	v_mfma_f32_16x16x32_bf16 v[22:25], v[168:171], v[200:203], 0
	v_mfma_f32_16x16x32_bf16 v[18:21], v[176:179], v[200:203], 0
	v_mfma_f32_16x16x32_bf16 v[6:9], v[168:171], v[208:211], 0
	v_mfma_f32_16x16x32_bf16 v[2:5], v[176:179], v[208:211], 0
	v_mfma_f32_16x16x32_bf16 v[54:57], v[172:175], v[188:191], v[54:57]
	v_mfma_f32_16x16x32_bf16 v[50:53], v[180:183], v[188:191], v[50:53]
	v_mfma_f32_16x16x32_bf16 v[38:41], v[172:175], v[196:199], v[38:41]
	v_mfma_f32_16x16x32_bf16 v[34:37], v[180:183], v[196:199], v[34:37]
	v_mfma_f32_16x16x32_bf16 v[22:25], v[172:175], v[204:207], v[22:25]
	v_mfma_f32_16x16x32_bf16 v[18:21], v[180:183], v[204:207], v[18:21]
	v_mfma_f32_16x16x32_bf16 v[6:9], v[172:175], v[212:215], v[6:9]
	v_mfma_f32_16x16x32_bf16 v[2:5], v[180:183], v[212:215], v[2:5]
	s_setprio 0
	s_barrier
; #define PG8_STAGE(bufoff, gbase, voff) do { _Pragma("unroll") for (int _i = 0; _i < 2; ++_i) \
;         __builtin_amdgcn_global_load_lds((const unsigned*)((const char*)(gbase) + (voff)[_i]), (PG8_LAS unsigned*)(lds + (bufoff) + ldsw + _i * 8192), 16, 0, 0); } while (0)
; #define PG8_LDA(dst, b, h) do { _Pragma("unroll") for (int m = 0; m < 4; ++m) _Pragma("unroll") for (int k = 0; k < 2; ++k) dst[m][k] = *(const PG8_LAS bf16x8*)(lds + PG8_SA(b, h) + aoff + m * 2048 + k * 1024); } while (0)
; #define PG8_LDB(dst, b, h) do { _Pragma("unroll") for (int n = 0; n < 2; ++n) _Pragma("unroll") for (int k = 0; k < 2; ++k) dst[n][k] = *(const PG8_LAS bf16x8*)(lds + PG8_SB(b, h) + boff + n * 2048 + k * 1024); } while (0)
; #define PG8_MMA(ai, bj, At, Bt) do { __builtin_amdgcn_s_setprio(1); _Pragma("unroll") for (int m = 0; m < 4; ++m) _Pragma("unroll") for (int n = 0; n < 2; ++n) _Pragma("unroll") for (int k = 0; k < 2; ++k) \
;         acc[ai][bj][m][n] = __builtin_amdgcn_mfma_f32_16x16x32_bf16(Bt[n][k], At[m][k], acc[ai][bj][m][n], 0, 0, 0); __builtin_amdgcn_s_setprio(0); } while (0)
; #define PG8_WAIT_V(n) asm volatile("s_waitcnt vmcnt(" #n ")" ::: "memory")
; #define PG8_WAIT_L(n) asm volatile("s_waitcnt lgkmcnt(" #n ")" ::: "memory")
; #define PG8_BAR __builtin_amdgcn_s_barrier()
; #define PG8_SCHED __builtin_amdgcn_sched_barrier(0)
; template <class Epi, class Sched, bool ALIGN_EPI = false, bool SP2 = false>
; __device__ __forceinline__ void gemm_phase(PG8_LAS unsigned char* lds, const Gemm g, const Sched& S, const Epi& E) {
;     ...
;             PG8_LDB(B0, 1, 0); PG8_LDB(B1, 1, 1); PG8_SCHED; PG8_LDA(At, 1, 0); PG8_STAGE(PG8_SA(0, 1), a2 + hstepA, voffA);
;             PG8_WAIT_V(8); PG8_WAIT_L(0); PG8_BAR; PG8_MMA(0, 0, At, B0); PG8_MMA(0, 1, At, B1); PG8_BAR; PG8_SCHED;
;             PG8_LDA(At, 1, 1); PG8_STAGE(PG8_SB(1, 0), b3, voffB); PG8_STAGE(PG8_SB(1, 1), b3 + hstepB, voffB); PG8_STAGE(PG8_SA(1, 0), a3, voffA);
;             PG8_WAIT_V(8); PG8_WAIT_L(0); PG8_BAR; PG8_MMA(1, 0, At, B0); PG8_MMA(1, 1, At, B1); PG8_BAR; PG8_SCHED;
	s_add_i32 s66, 0, 0x18000
	v_add_u32_e32 v151, s66, v146
	s_add_i32 s67, 0, 0x1c000
	ds_read_b128 v[152:155], v151
	ds_read_b128 v[156:159], v151 offset:1024
	ds_read_b128 v[160:163], v151 offset:2048
	ds_read_b128 v[164:167], v151 offset:3072
	v_add_u32_e32 v151, s67, v146
	ds_read_b128 v[168:171], v151
	ds_read_b128 v[172:175], v151 offset:1024
	ds_read_b128 v[176:179], v151 offset:2048
	ds_read_b128 v[180:183], v151 offset:3072
	s_add_u32 s40, s40, s4
	s_addc_u32 s41, s41, s5
	s_mov_b32 m0, s45
	v_lshl_add_u64 v[228:229], s[40:41], 0, v[130:131]
	ds_read_b128 v[184:187], v150 offset:32768
	ds_read_b128 v[188:191], v150 offset:33792
	ds_read_b128 v[192:195], v150 offset:34816
	ds_read_b128 v[196:199], v150 offset:35840
	ds_read_b128 v[200:203], v150 offset:36864
	ds_read_b128 v[204:207], v150 offset:37888
	ds_read_b128 v[208:211], v150 offset:38912
	ds_read_b128 v[212:215], v150 offset:39936
	global_load_lds_dwordx4 v[228:229], off
	v_lshl_add_u64 v[228:229], s[40:41], 0, v[134:135]
	s_mov_b32 m0, s46
	s_nop 0
	global_load_lds_dwordx4 v[228:229], off
	s_waitcnt vmcnt(8)
	s_waitcnt lgkmcnt(0)
	s_barrier
	s_setprio 1
	s_waitcnt lgkmcnt(0)
	v_mfma_f32_16x16x32_bf16 v[122:125], v[152:155], v[184:187], v[122:125]
	v_mfma_f32_16x16x32_bf16 v[126:129], v[160:163], v[184:187], v[126:129]
	v_mfma_f32_16x16x32_bf16 v[110:113], v[152:155], v[192:195], v[110:113]
	v_mfma_f32_16x16x32_bf16 v[106:109], v[160:163], v[192:195], v[106:109]
	v_mfma_f32_16x16x32_bf16 v[94:97], v[152:155], v[200:203], v[94:97]
	v_mfma_f32_16x16x32_bf16 v[90:93], v[160:163], v[200:203], v[90:93]
	v_mfma_f32_16x16x32_bf16 v[78:81], v[152:155], v[208:211], v[78:81]
	v_mfma_f32_16x16x32_bf16 v[74:77], v[160:163], v[208:211], v[74:77]
	v_mfma_f32_16x16x32_bf16 v[122:125], v[156:159], v[188:191], v[122:125]
	v_mfma_f32_16x16x32_bf16 v[126:129], v[164:167], v[188:191], v[126:129]
	v_mfma_f32_16x16x32_bf16 v[110:113], v[156:159], v[196:199], v[110:113]
	v_mfma_f32_16x16x32_bf16 v[106:109], v[164:167], v[196:199], v[106:109]
	v_mfma_f32_16x16x32_bf16 v[94:97], v[156:159], v[204:207], v[94:97]
	v_mfma_f32_16x16x32_bf16 v[90:93], v[164:167], v[204:207], v[90:93]
	v_mfma_f32_16x16x32_bf16 v[78:81], v[156:159], v[212:215], v[78:81]
	v_mfma_f32_16x16x32_bf16 v[74:77], v[164:167], v[212:215], v[74:77]
	s_setprio 0
	s_setprio 1
	v_mfma_f32_16x16x32_bf16 v[118:121], v[168:171], v[184:187], v[118:121]
	v_mfma_f32_16x16x32_bf16 v[114:117], v[176:179], v[184:187], v[114:117]
	v_mfma_f32_16x16x32_bf16 v[102:105], v[168:171], v[192:195], v[102:105]
	v_mfma_f32_16x16x32_bf16 v[98:101], v[176:179], v[192:195], v[98:101]
	v_mfma_f32_16x16x32_bf16 v[86:89], v[168:171], v[200:203], v[86:89]
	v_mfma_f32_16x16x32_bf16 v[82:85], v[176:179], v[200:203], v[82:85]
	v_mfma_f32_16x16x32_bf16 v[70:73], v[168:171], v[208:211], v[70:73]
	v_mfma_f32_16x16x32_bf16 v[66:69], v[176:179], v[208:211], v[66:69]
	v_mfma_f32_16x16x32_bf16 v[118:121], v[172:175], v[188:191], v[118:121]
	v_mfma_f32_16x16x32_bf16 v[114:117], v[180:183], v[188:191], v[114:117]
	v_mfma_f32_16x16x32_bf16 v[102:105], v[172:175], v[196:199], v[102:105]
	v_mfma_f32_16x16x32_bf16 v[98:101], v[180:183], v[196:199], v[98:101]
	v_mfma_f32_16x16x32_bf16 v[86:89], v[172:175], v[204:207], v[86:89]
	v_mfma_f32_16x16x32_bf16 v[82:85], v[180:183], v[204:207], v[82:85]
	v_mfma_f32_16x16x32_bf16 v[70:73], v[172:175], v[212:215], v[70:73]
	v_mfma_f32_16x16x32_bf16 v[66:69], v[180:183], v[212:215], v[66:69]
	s_setprio 0
	s_barrier
; #define PG8_STAGE(bufoff, gbase, voff) do { _Pragma("unroll") for (int _i = 0; _i < 2; ++_i) \
;         __builtin_amdgcn_global_load_lds((const unsigned*)((const char*)(gbase) + (voff)[_i]), (PG8_LAS unsigned*)(lds + (bufoff) + ldsw + _i * 8192), 16, 0, 0); } while (0)
; #define PG8_LDA(dst, b, h) do { _Pragma("unroll") for (int m = 0; m < 4; ++m) _Pragma("unroll") for (int k = 0; k < 2; ++k) dst[m][k] = *(const PG8_LAS bf16x8*)(lds + PG8_SA(b, h) + aoff + m * 2048 + k * 1024); } while (0)
; #define PG8_MMA(ai, bj, At, Bt) do { __builtin_amdgcn_s_setprio(1); _Pragma("unroll") for (int m = 0; m < 4; ++m) _Pragma("unroll") for (int n = 0; n < 2; ++n) _Pragma("unroll") for (int k = 0; k < 2; ++k) \
;         acc[ai][bj][m][n] = __builtin_amdgcn_mfma_f32_16x16x32_bf16(Bt[n][k], At[m][k], acc[ai][bj][m][n], 0, 0, 0); __builtin_amdgcn_s_setprio(0); } while (0)
; #define PG8_WAIT_V(n) asm volatile("s_waitcnt vmcnt(" #n ")" ::: "memory")
; #define PG8_WAIT_L(n) asm volatile("s_waitcnt lgkmcnt(" #n ")" ::: "memory")
; #define PG8_BAR __builtin_amdgcn_s_barrier()
; #define PG8_SCHED __builtin_amdgcn_sched_barrier(0)
; template <class Epi, class Sched, bool ALIGN_EPI = false, bool SP2 = false>
; __device__ __forceinline__ void gemm_phase(PG8_LAS unsigned char* lds, const Gemm g, const Sched& S, const Epi& E) {
;     ...
;             PG8_WAIT_V(8); PG8_WAIT_L(0); PG8_BAR; PG8_MMA(0, 0, At, B0); PG8_MMA(0, 1, At, B1); PG8_BAR; PG8_SCHED;
;             PG8_LDA(At, 1, 1); PG8_STAGE(PG8_SB(1, 0), b3, voffB); PG8_STAGE(PG8_SB(1, 1), b3 + hstepB, voffB); PG8_STAGE(PG8_SA(1, 0), a3, voffA);
;             PG8_WAIT_V(8); PG8_WAIT_L(0); PG8_BAR; PG8_MMA(1, 0, At, B0); PG8_MMA(1, 1, At, B1); PG8_BAR; PG8_SCHED;
	s_add_i32 s40, s66, s42
	v_lshl_add_u64 v[216:217], v[216:217], 0, s[20:21]
	s_mov_b32 m0, s40
	ds_read_b128 v[184:187], v150 offset:49152
	ds_read_b128 v[188:191], v150 offset:50176
	ds_read_b128 v[192:195], v150 offset:51200
	ds_read_b128 v[196:199], v150 offset:52224
	ds_read_b128 v[200:203], v150 offset:53248
	ds_read_b128 v[204:207], v150 offset:54272
	ds_read_b128 v[208:211], v150 offset:55296
	ds_read_b128 v[212:215], v150 offset:56320
	global_load_lds_dwordx4 v[216:217], off
	v_lshl_add_u64 v[216:217], v[218:219], 0, s[20:21]
	s_add_i32 m0, s40, 0x2000
	s_add_i32 s40, s67, s42
	global_load_lds_dwordx4 v[216:217], off
	v_lshl_add_u64 v[216:217], v[220:221], 0, s[20:21]
	s_mov_b32 m0, s40
	s_nop 0
	global_load_lds_dwordx4 v[216:217], off
	v_lshl_add_u64 v[216:217], v[222:223], 0, s[20:21]
	s_add_i32 m0, s40, 0x2000
	s_nop 0
	global_load_lds_dwordx4 v[216:217], off
	v_lshl_add_u64 v[216:217], v[224:225], 0, s[20:21]
	s_mov_b32 m0, s48
	s_nop 0
	global_load_lds_dwordx4 v[216:217], off
	v_lshl_add_u64 v[216:217], v[226:227], 0, s[20:21]
	s_mov_b32 m0, s49
	s_nop 0
	global_load_lds_dwordx4 v[216:217], off
	s_waitcnt vmcnt(8)
	s_waitcnt lgkmcnt(0)
	s_barrier
	s_setprio 1
	s_waitcnt lgkmcnt(0)
	v_mfma_f32_16x16x32_bf16 v[62:65], v[152:155], v[184:187], v[62:65]
	v_mfma_f32_16x16x32_bf16 v[58:61], v[160:163], v[184:187], v[58:61]
	v_mfma_f32_16x16x32_bf16 v[46:49], v[152:155], v[192:195], v[46:49]
	v_mfma_f32_16x16x32_bf16 v[42:45], v[160:163], v[192:195], v[42:45]
	v_mfma_f32_16x16x32_bf16 v[30:33], v[152:155], v[200:203], v[30:33]
	v_mfma_f32_16x16x32_bf16 v[26:29], v[160:163], v[200:203], v[26:29]
	v_mfma_f32_16x16x32_bf16 v[14:17], v[152:155], v[208:211], v[14:17]
	v_mfma_f32_16x16x32_bf16 v[10:13], v[160:163], v[208:211], v[10:13]
	v_mfma_f32_16x16x32_bf16 v[62:65], v[156:159], v[188:191], v[62:65]
	v_mfma_f32_16x16x32_bf16 v[58:61], v[164:167], v[188:191], v[58:61]
	v_mfma_f32_16x16x32_bf16 v[46:49], v[156:159], v[196:199], v[46:49]
	v_mfma_f32_16x16x32_bf16 v[42:45], v[164:167], v[196:199], v[42:45]
	v_mfma_f32_16x16x32_bf16 v[30:33], v[156:159], v[204:207], v[30:33]
	v_mfma_f32_16x16x32_bf16 v[26:29], v[164:167], v[204:207], v[26:29]
	v_mfma_f32_16x16x32_bf16 v[14:17], v[156:159], v[212:215], v[14:17]
	v_mfma_f32_16x16x32_bf16 v[10:13], v[164:167], v[212:215], v[10:13]
	s_setprio 0
	s_setprio 1
	v_mfma_f32_16x16x32_bf16 v[54:57], v[168:171], v[184:187], v[54:57]
	v_mfma_f32_16x16x32_bf16 v[50:53], v[176:179], v[184:187], v[50:53]
	v_mfma_f32_16x16x32_bf16 v[38:41], v[168:171], v[192:195], v[38:41]
	v_mfma_f32_16x16x32_bf16 v[34:37], v[176:179], v[192:195], v[34:37]
	v_mfma_f32_16x16x32_bf16 v[22:25], v[168:171], v[200:203], v[22:25]
	v_mfma_f32_16x16x32_bf16 v[18:21], v[176:179], v[200:203], v[18:21]
	v_mfma_f32_16x16x32_bf16 v[6:9], v[168:171], v[208:211], v[6:9]
	v_mfma_f32_16x16x32_bf16 v[2:5], v[176:179], v[208:211], v[2:5]
	v_mfma_f32_16x16x32_bf16 v[54:57], v[172:175], v[188:191], v[54:57]
	v_mfma_f32_16x16x32_bf16 v[50:53], v[180:183], v[188:191], v[50:53]
	v_mfma_f32_16x16x32_bf16 v[38:41], v[172:175], v[196:199], v[38:41]
	v_mfma_f32_16x16x32_bf16 v[34:37], v[180:183], v[196:199], v[34:37]
	v_mfma_f32_16x16x32_bf16 v[22:25], v[172:175], v[204:207], v[22:25]
	v_mfma_f32_16x16x32_bf16 v[18:21], v[180:183], v[204:207], v[18:21]
	v_mfma_f32_16x16x32_bf16 v[6:9], v[172:175], v[212:215], v[6:9]
	v_mfma_f32_16x16x32_bf16 v[2:5], v[180:183], v[212:215], v[2:5]
	s_setprio 0
	s_barrier
	s_add_u32 s38, s38, 0x100
	s_addc_u32 s39, s39, 0
	s_add_u32 s63, s63, 0x100
	s_addc_u32 s64, s64, 0
	s_cmp_ge_i32 s65, s50
	s_mov_b32 s40, s65

; __device__ __forceinline__ unsigned cvt_pk_bf16(float lo, float hi) { unsigned r; asm volatile("v_cvt_pk_bf16_f32 %0, %1, %2" : "=v"(r) : "v"(lo), "v"(hi)); return r; }
; #define PG8_BAR __builtin_amdgcn_s_barrier()
; template <class Epi, class Sched, bool ALIGN_EPI = false, bool SP2 = false>
; __device__ __forceinline__ void gemm_phase(PG8_LAS unsigned char* lds, const Gemm g, const Sched& S, const Epi& E) {
;     ...
;         if constexpr (!Epi::AFTER_DRAIN) { E(acc, cur, wr, wc, fr, fq); S.done(cur); }
;         if (!has_next) break;
; #pragma unroll
;         for (int a = 0; a < 2; ++a)
; #pragma unroll
;             for (int b = 0; b < 2; ++b)
; #pragma unroll
;                 for (int m = 0; m < 4; ++m)
; #pragma unroll
;                     for (int n = 0; n < 2; ++n) acc[a][b][m][n] = (f32x4){0.f, 0.f, 0.f, 0.f};
;         cur = nxt; cA = nA; cB = nB; ++ui;
;         if constexpr (ALIGN_EPI) { if (wr == 1) PG8_BAR; }
;     __device__ __forceinline__ void operator()(const pg8::f32x4 (&acc)[2][2][4][2], const Unit& u, int wr, int wc, int fr, int fq) const {
;         const int row0 = u.pm * BM + wr * 64 + fr, col0 = u.pn * BM + wc * 32 + 8 * fq;
; #pragma unroll
;         for (int ai = 0; ai < 2; ++ai)
; #pragma unroll
;             for (int m = 0; m < 4; ++m)
; #pragma unroll
;                 for (int bj = 0; bj < 2; ++bj) { const pg8::f32x4 v0 = acc[ai][bj][m][0], v1 = acc[ai][bj][m][1];
;                     v4u w; w.x = cvt_pk_bf16(v0[0], v0[1]); w.y = cvt_pk_bf16(v0[2], v0[3]); w.z = cvt_pk_bf16(v1[0], v1[1]); w.w = cvt_pk_bf16(v1[2], v1[3]);
;                     *(v4u*)(O + (size_t)(row0 + ai * HALF + m * 16) * DM_ + col0 + bj * HALF) = w; }
;     }
.LBB0_824:
	v_lshl_add_u32 v152, s59, 8, v1
	v_lshl_or_b32 v154, s62, 8, v147
	v_ashrrev_i32_e32 v153, 31, v152
	v_ashrrev_i32_e32 v155, 31, v154
	v_lshlrev_b64 v[156:157], 11, v[152:153]
	v_cvt_pk_bf16_f32 v122, v122, v123
	v_cvt_pk_bf16_f32 v123, v124, v125
	v_cvt_pk_bf16_f32 v124, v126, v127
	v_cvt_pk_bf16_f32 v125, v128, v129
	v_lshl_add_u64 v[126:127], s[18:19], 0, v[156:157]
	v_lshlrev_b64 v[128:129], 1, v[154:155]
	v_lshl_add_u64 v[126:127], v[126:127], 0, v[128:129]
	global_store_dwordx4 v[126:127], v[122:125], off
	v_cvt_pk_bf16_f32 v118, v118, v119
	v_cvt_pk_bf16_f32 v119, v120, v121
	v_cvt_pk_bf16_f32 v120, v114, v115
	v_or_b32_e32 v114, 16, v152
	v_ashrrev_i32_e32 v115, 31, v114
	v_lshlrev_b64 v[114:115], 11, v[114:115]
	v_cvt_pk_bf16_f32 v121, v116, v117
	global_store_dwordx4 v[126:127], v[118:121], off offset:256
	v_cvt_pk_bf16_f32 v110, v110, v111
	v_cvt_pk_bf16_f32 v111, v112, v113
	v_cvt_pk_bf16_f32 v112, v106, v107
	v_lshl_add_u64 v[106:107], s[18:19], 0, v[114:115]
	v_lshl_add_u64 v[106:107], v[106:107], 0, v[128:129]
	v_cvt_pk_bf16_f32 v113, v108, v109
	global_store_dwordx4 v[106:107], v[110:113], off
	v_cvt_pk_bf16_f32 v102, v102, v103
	v_cvt_pk_bf16_f32 v103, v104, v105
	v_cvt_pk_bf16_f32 v104, v98, v99
	v_or_b32_e32 v98, 32, v152
	v_ashrrev_i32_e32 v99, 31, v98
	v_lshlrev_b64 v[98:99], 11, v[98:99]
	v_cvt_pk_bf16_f32 v105, v100, v101
	global_store_dwordx4 v[106:107], v[102:105], off offset:256
	v_cvt_pk_bf16_f32 v94, v94, v95
	v_cvt_pk_bf16_f32 v95, v96, v97
	v_cvt_pk_bf16_f32 v96, v90, v91
	v_lshl_add_u64 v[90:91], s[18:19], 0, v[98:99]
	v_lshl_add_u64 v[90:91], v[90:91], 0, v[128:129]
	v_cvt_pk_bf16_f32 v97, v92, v93
	global_store_dwordx4 v[90:91], v[94:97], off
	v_cvt_pk_bf16_f32 v86, v86, v87
	v_cvt_pk_bf16_f32 v87, v88, v89
	v_cvt_pk_bf16_f32 v88, v82, v83
	v_or_b32_e32 v82, 48, v152
	v_ashrrev_i32_e32 v83, 31, v82
	v_lshlrev_b64 v[82:83], 11, v[82:83]
	v_cvt_pk_bf16_f32 v89, v84, v85
	global_store_dwordx4 v[90:91], v[86:89], off offset:256
	v_cvt_pk_bf16_f32 v78, v78, v79
	v_cvt_pk_bf16_f32 v79, v80, v81
	v_cvt_pk_bf16_f32 v80, v74, v75
	v_lshl_add_u64 v[74:75], s[18:19], 0, v[82:83]
	v_lshl_add_u64 v[74:75], v[74:75], 0, v[128:129]
	v_cvt_pk_bf16_f32 v81, v76, v77
	global_store_dwordx4 v[74:75], v[78:81], off
	v_cvt_pk_bf16_f32 v70, v70, v71
	v_cvt_pk_bf16_f32 v71, v72, v73
	v_cvt_pk_bf16_f32 v72, v66, v67
	v_cvt_pk_bf16_f32 v73, v68, v69
	global_store_dwordx4 v[74:75], v[70:73], off offset:256
	v_cvt_pk_bf16_f32 v62, v62, v63
	v_cvt_pk_bf16_f32 v63, v64, v65
	v_cvt_pk_bf16_f32 v64, v58, v59
	v_cvt_pk_bf16_f32 v65, v60, v61
	v_add_co_u32_e32 v60, vcc, s56, v126
	v_lshl_add_u64 v[58:59], v[126:127], 0, s[26:27]
	s_nop 0
	v_addc_co_u32_e32 v61, vcc, 0, v127, vcc
	global_store_dwordx4 v[60:61], v[62:65], off
	v_cvt_pk_bf16_f32 v54, v54, v55
	v_cvt_pk_bf16_f32 v55, v56, v57
	v_cvt_pk_bf16_f32 v56, v50, v51
	v_cvt_pk_bf16_f32 v57, v52, v53
	global_store_dwordx4 v[58:59], v[54:57], off offset:256
	v_cvt_pk_bf16_f32 v46, v46, v47
	v_cvt_pk_bf16_f32 v47, v48, v49
	v_cvt_pk_bf16_f32 v48, v42, v43
	v_cvt_pk_bf16_f32 v49, v44, v45
	v_add_co_u32_e32 v44, vcc, s57, v126
	v_lshl_add_u64 v[42:43], v[126:127], 0, s[28:29]
	s_nop 0
	v_addc_co_u32_e32 v45, vcc, 0, v127, vcc
	global_store_dwordx4 v[44:45], v[46:49], off
	v_cvt_pk_bf16_f32 v38, v38, v39
	v_cvt_pk_bf16_f32 v39, v40, v41
	v_cvt_pk_bf16_f32 v40, v34, v35
	v_cvt_pk_bf16_f32 v41, v36, v37
	global_store_dwordx4 v[42:43], v[38:41], off offset:256
	v_cvt_pk_bf16_f32 v30, v30, v31
	v_cvt_pk_bf16_f32 v31, v32, v33
	v_cvt_pk_bf16_f32 v32, v26, v27
	v_cvt_pk_bf16_f32 v33, v28, v29
	v_add_co_u32_e32 v28, vcc, s58, v126
	v_lshl_add_u64 v[26:27], v[126:127], 0, s[30:31]
	s_nop 0
	v_addc_co_u32_e32 v29, vcc, 0, v127, vcc
	global_store_dwordx4 v[28:29], v[30:33], off
	v_cvt_pk_bf16_f32 v22, v22, v23
	v_cvt_pk_bf16_f32 v23, v24, v25
	v_cvt_pk_bf16_f32 v24, v18, v19
	v_cvt_pk_bf16_f32 v25, v20, v21
	global_store_dwordx4 v[26:27], v[22:25], off offset:256
	v_cvt_pk_bf16_f32 v14, v14, v15
	v_cvt_pk_bf16_f32 v15, v16, v17
	v_cvt_pk_bf16_f32 v16, v10, v11
	v_cvt_pk_bf16_f32 v17, v12, v13
	v_add_co_u32_e32 v12, vcc, 0x58000, v126
	v_lshl_add_u64 v[10:11], v[126:127], 0, s[34:35]
	s_nop 0
	v_addc_co_u32_e32 v13, vcc, 0, v127, vcc
	s_and_b64 vcc, exec, s[6:7]
	s_mov_b64 s[6:7], -1
	global_store_dwordx4 v[12:13], v[14:17], off
	v_cvt_pk_bf16_f32 v6, v6, v7
	v_cvt_pk_bf16_f32 v7, v8, v9
	v_cvt_pk_bf16_f32 v8, v2, v3
	v_cvt_pk_bf16_f32 v9, v4, v5
	global_store_dwordx4 v[10:11], v[6:9], off offset:256
	s_cbranch_vccnz .LBB0_808
	s_andn2_b64 vcc, exec, s[16:17]
	s_cbranch_vccnz .LBB0_807
	s_mov_b32 s98, 1
	s_branch .LBB0_807

; #define PG8_STAGE(bufoff, gbase, voff) do { _Pragma("unroll") for (int _i = 0; _i < 2; ++_i) \
;         __builtin_amdgcn_global_load_lds((const unsigned*)((const char*)(gbase) + (voff)[_i]), (PG8_LAS unsigned*)(lds + (bufoff) + ldsw + _i * 8192), 16, 0, 0); } while (0)
; #define PG8_WAIT_V(n) asm volatile("s_waitcnt vmcnt(" #n ")" ::: "memory")
; #define PG8_BAR __builtin_amdgcn_s_barrier()
; template <class Epi, class Sched, bool ALIGN_EPI = false, bool SP2 = false>
; __device__ __forceinline__ void gemm_phase(PG8_LAS unsigned char* lds, const Gemm g, const Sched& S, const Epi& E) {
;     int tid_ = threadIdx.x; asm volatile("" : "+v"(tid_));
;     const int tid = tid_, wid = __builtin_amdgcn_readfirstlane(tid >> 6), lane = tid & 63, wr = wid >> 2, wc = wid & 3, fr = lane & 15, fq = lane >> 4;
;     const int K = g.K, nt = K / BK;
;     unsigned voffA[2], voffB[2];
; #pragma unroll
;     for (int i = 0; i < 2; ++i) { int R, C; stage_rc(tid * 16 + i * 8192, R, C); const int Rb = Epi::PERM ? ((R & ~31) + perm32(R & 31)) : R;
;         voffA[i] = (unsigned)(R * g.lda + C) * 2u; voffB[i] = (unsigned)(Rb * g.ldb + C) * 2u; }
;     const size_t kstep = (size_t)(BK * 2);
;     const size_t hstepA = (size_t)HALF * g.lda * 2, hstepB = (size_t)HALF * g.ldb * 2;
;     const size_t tstepA = 2 * hstepA, tstepB = 2 * hstepB;
;     const unsigned ldsw = (unsigned)wid * 1024u;
;     const int aoff = lds_byte(wr * 64 + fr, fq * 8), boff = lds_byte(wc * 32 + fr, fq * 8);
;     ...
;     const char* cA = (const char*)g.A + (size_t)cur.g * g.gsA * 2 + (size_t)cur.pm * tstepA; const char* cB = (const char*)g.Bt + (size_t)cur.g * g.gsB * 2 + (size_t)cur.pn * tstepB;
;     S.a_ready(cur);
;     if constexpr (SP2) {
;         PG8_STAGE(PG8_SB(0, 0), cB, voffB); PG8_STAGE(PG8_SB(0, 1), cB + hstepB, voffB); PG8_STAGE(PG8_SA(0, 0), cA, voffA); PG8_STAGE(PG8_SA(0, 1), cA + hstepA, voffA);
;         if (wr == 1) PG8_BAR;
;         PG8_WAIT_V(2); PG8_BAR;
;         PG8_STAGE(PG8_SB(1, 0), cB + kstep, voffB); PG8_STAGE(PG8_SA(1, 0), cA + kstep, voffA); PG8_STAGE(PG8_SB(1, 1), cB + hstepB + kstep, voffB);
;         PG8_WAIT_V(6); PG8_BAR;
.LBB0_893:
	s_add_u32 s16, s78, 0xbc00000
	s_addc_u32 s17, s79, 0
	s_add_u32 s18, s78, 0xfc00000
	s_addc_u32 s19, s79, 0
	s_add_u32 s20, s78, 0x5a00000
	s_mov_b64 s[22:23], 0x80
	s_addc_u32 s21, s79, 0
	s_and_b32 s49, s1, 3
	s_add_i32 m0, s44, 0x18000
	v_lshl_add_u64 v[8:9], v[8:9], 0, s[22:23]
	s_lshl_b32 s1, s2, 13
	s_lshl_b32 s5, s49, 12
	s_waitcnt vmcnt(2)
	s_barrier
	global_load_lds_dwordx4 v[8:9], off
	v_lshl_add_u64 v[6:7], v[6:7], 0, s[22:23]
	s_add_i32 m0, s44, 0x1a000
	s_add_i32 s50, s44, 0x8000
	s_add_i32 s51, s44, 0xa000
	global_load_lds_dwordx4 v[6:7], off
	v_lshl_add_u64 v[2:3], v[2:3], 0, s[22:23]
	s_mov_b32 m0, s50
	s_add_u32 s6, s38, 0x40080
	global_load_lds_dwordx4 v[2:3], off
	v_lshl_add_u64 v[2:3], v[4:5], 0, s[22:23]
	s_mov_b32 m0, s51
	s_addc_u32 s7, s39, 0
	global_load_lds_dwordx4 v[2:3], off
	s_add_i32 m0, s44, 0x1c000
	v_lshl_add_u64 v[2:3], s[6:7], 0, v[148:149]
	global_load_lds_dwordx4 v[2:3], off
	v_lshl_add_u64 v[2:3], s[6:7], 0, v[152:153]
	s_add_i32 m0, s44, 0x1e000
	v_bfe_u32 v4, v10, 4, 2
	global_load_lds_dwordx4 v[2:3], off
	v_and_b32_e32 v3, 15, v10
	v_lshlrev_b32_e32 v2, 4, v4
	v_lshlrev_b32_e32 v6, 2, v10
	v_lshl_or_b32 v1, s2, 6, v3
	v_lshl_or_b32 v3, v3, 6, v2
	v_and_b32_e32 v6, 32, v6
	v_bitop3_b32 v7, v3, s1, v6 bitop3:0xde
	v_bitop3_b32 v184, v3, s5, v6 bitop3:0xde
	v_mov_b32_e32 v3, v149
	s_cmpk_lt_u32 s0, 0x100
	v_lshl_add_u64 v[2:3], s[78:79], 0, v[2:3]
	s_mov_b64 s[0:1], 0x5800000
	v_lshl_add_u64 v[154:155], v[2:3], 0, s[0:1]
	v_lshlrev_b32_e32 v2, 14, v11
	v_and_b32_e32 v2, 0xffff8000, v2
	v_lshl_add_u32 v2, v12, 11, v2
	v_and_b32_e32 v3, 1, v11
	v_lshl_or_b32 v2, v3, 6, v2
	v_lshl_add_u32 v156, v13, 1, v2
	v_lshlrev_b32_e32 v2, 14, v14
	v_and_b32_e32 v2, 0xffff8000, v2
	v_lshl_add_u32 v2, v15, 11, v2
	v_and_b32_e32 v3, 1, v14
	s_waitcnt vmcnt(6)
	v_lshl_or_b32 v2, v3, 6, v2
	v_lshlrev_b32_e32 v5, 3, v4
	s_cselect_b64 s[24:25], -1, 0
	v_lshl_add_u32 v158, v16, 1, v2
	s_add_i32 s55, 0, 0x10000
	s_add_i32 s56, 0, 0x14000
	v_mbcnt_lo_u32_b32 v2, -1, 0
	v_lshl_or_b32 v185, s49, 5, v5
	v_cmp_eq_u32_e64 s[6:7], 0, v4
	s_ashr_i32 s52, s82, 31
	s_mov_b32 s53, s82
	s_ashr_i32 s54, s96, 31
	v_mov_b32_e32 v157, v149
	v_mov_b32_e32 v159, v149
	v_mov_b64_e32 v[160:161], 0x200
	v_mov_b64_e32 v[162:163], 0x1ff
	v_add_u32_e32 v186, s55, v184
	v_add_u32_e32 v187, s56, v184
	v_add_u32_e32 v188, 0, v7
	v_mbcnt_hi_u32_b32 v189, -1, v2
	v_mov_b32_e32 v190, 0x358637bd
	s_mov_b32 s57, 0
	s_barrier
	s_mov_b32 s98, 0
	s_branch .LBB0_896

; #define PG8_STAGE(bufoff, gbase, voff) do { _Pragma("unroll") for (int _i = 0; _i < 2; ++_i) \
;         __builtin_amdgcn_global_load_lds((const unsigned*)((const char*)(gbase) + (voff)[_i]), (PG8_LAS unsigned*)(lds + (bufoff) + ldsw + _i * 8192), 16, 0, 0); } while (0)
; #define PG8_LDA(dst, b, h) do { _Pragma("unroll") for (int m = 0; m < 4; ++m) _Pragma("unroll") for (int k = 0; k < 2; ++k) dst[m][k] = *(const PG8_LAS bf16x8*)(lds + PG8_SA(b, h) + aoff + m * 2048 + k * 1024); } while (0)
; #define PG8_LDB(dst, b, h) do { _Pragma("unroll") for (int n = 0; n < 2; ++n) _Pragma("unroll") for (int k = 0; k < 2; ++k) dst[n][k] = *(const PG8_LAS bf16x8*)(lds + PG8_SB(b, h) + boff + n * 2048 + k * 1024); } while (0)
; #define PG8_WAIT_V(n) asm volatile("s_waitcnt vmcnt(" #n ")" ::: "memory")
; #define PG8_WAIT_L(n) asm volatile("s_waitcnt lgkmcnt(" #n ")" ::: "memory")
; #define PG8_BAR __builtin_amdgcn_s_barrier()
; template <class Epi, class Sched, bool ALIGN_EPI = false, bool SP2 = false>
; __device__ __forceinline__ void gemm_phase(PG8_LAS unsigned char* lds, const Gemm g, const Sched& S, const Epi& E) {
;     ...
;         const bool has_next = S.next(ui + 1, nxt);
;         const char* nA = has_next ? (const char*)g.A + (size_t)nxt.g * g.gsA * 2 + (size_t)nxt.pm * tstepA : cA; const char* nB = has_next ? (const char*)g.Bt + (size_t)nxt.g * g.gsB * 2 + (size_t)nxt.pn * tstepB : cB;
;         for (int t = 0; t < nt; t += 2) {
;             const bool last = (t == nt - 2);
;             const char* a1 = cA + (size_t)(t + 1) * kstep;
;             const char* a2 = last ? nA : cA + (size_t)(t + 2) * kstep; const char* b2 = last ? nB : cB + (size_t)(t + 2) * kstep;
;             const char* a3 = a2 + kstep; const char* b3 = b2 + kstep;
;             if (last && has_next) S.a_ready(nxt);
;             if constexpr (SP2) {
;             PG8_LDB(B0, 0, 0); PG8_LDB(B1, 0, 1); PG8_SCHED; PG8_LDA(At, 0, 0); PG8_STAGE(PG8_SA(1, 1), a1 + hstepA, voffA);
;             PG8_WAIT_V(8); PG8_WAIT_L(0); PG8_BAR; PG8_MMA(0, 0, At, B0); PG8_MMA(0, 1, At, B1); PG8_BAR; PG8_SCHED;
;             PG8_LDA(At, 0, 1); PG8_STAGE(PG8_SB(0, 0), b2, voffB); PG8_STAGE(PG8_SB(0, 1), b2 + hstepB, voffB); PG8_STAGE(PG8_SA(0, 0), a2, voffA);
;             PG8_WAIT_V(8); PG8_WAIT_L(0); PG8_BAR; PG8_MMA(1, 0, At, B0); PG8_MMA(1, 1, At, B1); PG8_BAR; PG8_SCHED;
.LBB0_902:
	s_ashr_i32 s29, s28, 31
	s_lshl_b64 s[0:1], s[28:29], 19
	s_add_u32 s30, s10, s0
	s_addc_u32 s31, s11, s1
	s_and_b64 s[0:1], s[8:9], exec
	s_cselect_b32 s0, s31, s37
	s_cselect_b32 s1, s30, s36
	s_ashr_i32 s27, s26, 31
	s_lshl_b64 s[34:35], s[26:27], 19
	s_add_u32 s34, s3, s34
	s_addc_u32 s35, s42, s35
	s_and_b64 s[40:41], s[8:9], exec
	s_cselect_b32 s2, s35, s39
	s_cselect_b32 s5, s34, s38
	s_add_u32 s36, s36, 0x40080
	s_addc_u32 s37, s37, 0
	s_add_u32 s27, s38, 0x100
	s_addc_u32 s29, s39, 0
	s_mov_b32 s33, -2
	s_waitcnt lgkmcnt(0)
	s_cmp_eq_u32 s98, 1
	s_cbranch_scc0 .Lhb_28205
	s_mov_b32 s98, 0
	s_barrier
.Lhb_28205:
	ds_read_b128 v[130:133], v186
	ds_read_b128 v[134:137], v186 offset:1024
	ds_read_b128 v[138:141], v186 offset:2048
	ds_read_b128 v[142:145], v186 offset:3072
	ds_read_b128 v[164:167], v187
	ds_read_b128 v[168:171], v187 offset:1024
	ds_read_b128 v[172:175], v187 offset:2048
	ds_read_b128 v[176:179], v187 offset:3072
	s_add_u32 s38, s36, 0xfffc0080
	s_addc_u32 s39, s37, -1
	s_cmp_eq_u32 s33, 12
	s_cselect_b32 s41, s0, s39
	s_cselect_b32 s40, s1, s38
	s_cselect_b32 s39, s2, s29
	s_cselect_b32 s38, s5, s27
	v_lshl_add_u64 v[220:221], s[36:37], 0, v[156:157]
	s_add_i32 m0, s44, 0xc000
	ds_read_b128 v[180:183], v188
	ds_read_b128 v[192:195], v188 offset:1024
	ds_read_b128 v[196:199], v188 offset:2048
	ds_read_b128 v[200:203], v188 offset:3072
	ds_read_b128 v[204:207], v188 offset:4096
	ds_read_b128 v[208:211], v188 offset:5120
	ds_read_b128 v[212:215], v188 offset:6144
	ds_read_b128 v[216:219], v188 offset:7168
	global_load_lds_dwordx4 v[220:221], off
	v_lshl_add_u64 v[220:221], s[36:37], 0, v[158:159]
	s_add_i32 m0, s44, 0xe000
	s_nop 0
	global_load_lds_dwordx4 v[220:221], off
	s_waitcnt vmcnt(8)
	s_waitcnt lgkmcnt(0)
	s_barrier
	s_setprio 1
	s_waitcnt lgkmcnt(0)
	v_mfma_f32_16x16x32_bf16 v[126:129], v[130:133], v[180:183], 0
	v_mfma_f32_16x16x32_bf16 v[122:125], v[138:141], v[180:183], 0
	v_mfma_f32_16x16x32_bf16 v[110:113], v[130:133], v[196:199], 0
	v_mfma_f32_16x16x32_bf16 v[106:109], v[138:141], v[196:199], 0
	v_mfma_f32_16x16x32_bf16 v[94:97], v[130:133], v[204:207], 0
	v_mfma_f32_16x16x32_bf16 v[90:93], v[138:141], v[204:207], 0
	v_mfma_f32_16x16x32_bf16 v[78:81], v[130:133], v[212:215], 0
	v_mfma_f32_16x16x32_bf16 v[74:77], v[138:141], v[212:215], 0
	v_mfma_f32_16x16x32_bf16 v[126:129], v[134:137], v[192:195], v[126:129]
	v_mfma_f32_16x16x32_bf16 v[122:125], v[142:145], v[192:195], v[122:125]
	v_mfma_f32_16x16x32_bf16 v[110:113], v[134:137], v[200:203], v[110:113]
	v_mfma_f32_16x16x32_bf16 v[106:109], v[142:145], v[200:203], v[106:109]
	v_mfma_f32_16x16x32_bf16 v[94:97], v[134:137], v[208:211], v[94:97]
	v_mfma_f32_16x16x32_bf16 v[90:93], v[142:145], v[208:211], v[90:93]
	v_mfma_f32_16x16x32_bf16 v[78:81], v[134:137], v[216:219], v[78:81]
	v_mfma_f32_16x16x32_bf16 v[74:77], v[142:145], v[216:219], v[74:77]
	s_setprio 0
	s_setprio 1
	v_mfma_f32_16x16x32_bf16 v[118:121], v[164:167], v[180:183], 0
	v_mfma_f32_16x16x32_bf16 v[114:117], v[172:175], v[180:183], 0
	v_mfma_f32_16x16x32_bf16 v[102:105], v[164:167], v[196:199], 0
	v_mfma_f32_16x16x32_bf16 v[98:101], v[172:175], v[196:199], 0
	v_mfma_f32_16x16x32_bf16 v[86:89], v[164:167], v[204:207], 0
	v_mfma_f32_16x16x32_bf16 v[82:85], v[172:175], v[204:207], 0
	v_mfma_f32_16x16x32_bf16 v[70:73], v[164:167], v[212:215], 0
	v_mfma_f32_16x16x32_bf16 v[66:69], v[172:175], v[212:215], 0
	v_mfma_f32_16x16x32_bf16 v[118:121], v[168:171], v[192:195], v[118:121]
	v_mfma_f32_16x16x32_bf16 v[114:117], v[176:179], v[192:195], v[114:117]
	v_mfma_f32_16x16x32_bf16 v[102:105], v[168:171], v[200:203], v[102:105]
	v_mfma_f32_16x16x32_bf16 v[98:101], v[176:179], v[200:203], v[98:101]
	v_mfma_f32_16x16x32_bf16 v[86:89], v[168:171], v[208:211], v[86:89]
	v_mfma_f32_16x16x32_bf16 v[82:85], v[176:179], v[208:211], v[82:85]
	v_mfma_f32_16x16x32_bf16 v[70:73], v[168:171], v[216:219], v[70:73]
	v_mfma_f32_16x16x32_bf16 v[66:69], v[176:179], v[216:219], v[66:69]
	s_setprio 0
	s_barrier
	s_add_i32 s58, s55, s43
	v_lshl_add_u64 v[220:221], s[38:39], 0, v[148:149]
	s_mov_b32 m0, s58
	ds_read_b128 v[180:183], v188 offset:16384
	ds_read_b128 v[192:195], v188 offset:17408
	ds_read_b128 v[196:199], v188 offset:18432
	ds_read_b128 v[200:203], v188 offset:19456
	ds_read_b128 v[204:207], v188 offset:20480
	ds_read_b128 v[208:211], v188 offset:21504
	ds_read_b128 v[212:215], v188 offset:22528
	ds_read_b128 v[216:219], v188 offset:23552
	global_load_lds_dwordx4 v[220:221], off
	s_add_i32 m0, s58, 0x2000
	s_add_u32 s58, s38, 0x40000
	v_lshl_add_u64 v[222:223], s[38:39], 0, v[152:153]
	s_addc_u32 s59, s39, 0
	s_add_i32 s60, s56, s43
	global_load_lds_dwordx4 v[222:223], off
	v_lshl_add_u64 v[224:225], s[58:59], 0, v[148:149]
	s_mov_b32 m0, s60
	v_lshl_add_u64 v[226:227], s[40:41], 0, v[150:151]
	global_load_lds_dwordx4 v[224:225], off
	v_lshl_add_u64 v[224:225], s[58:59], 0, v[152:153]
	s_add_i32 m0, s60, 0x2000
	s_nop 0
	global_load_lds_dwordx4 v[224:225], off
	v_lshl_add_u64 v[224:225], s[40:41], 0, v[146:147]
	s_mov_b32 m0, s44
	s_nop 0
	global_load_lds_dwordx4 v[224:225], off
	s_mov_b32 m0, s45
	s_nop 0
	global_load_lds_dwordx4 v[226:227], off
	s_waitcnt vmcnt(8)
	s_waitcnt lgkmcnt(0)
	s_barrier
; #define PG8_STAGE(bufoff, gbase, voff) do { _Pragma("unroll") for (int _i = 0; _i < 2; ++_i) \
;         __builtin_amdgcn_global_load_lds((const unsigned*)((const char*)(gbase) + (voff)[_i]), (PG8_LAS unsigned*)(lds + (bufoff) + ldsw + _i * 8192), 16, 0, 0); } while (0)
; #define PG8_LDA(dst, b, h) do { _Pragma("unroll") for (int m = 0; m < 4; ++m) _Pragma("unroll") for (int k = 0; k < 2; ++k) dst[m][k] = *(const PG8_LAS bf16x8*)(lds + PG8_SA(b, h) + aoff + m * 2048 + k * 1024); } while (0)
; #define PG8_LDB(dst, b, h) do { _Pragma("unroll") for (int n = 0; n < 2; ++n) _Pragma("unroll") for (int k = 0; k < 2; ++k) dst[n][k] = *(const PG8_LAS bf16x8*)(lds + PG8_SB(b, h) + boff + n * 2048 + k * 1024); } while (0)
; #define PG8_MMA(ai, bj, At, Bt) do { __builtin_amdgcn_s_setprio(1); _Pragma("unroll") for (int m = 0; m < 4; ++m) _Pragma("unroll") for (int n = 0; n < 2; ++n) _Pragma("unroll") for (int k = 0; k < 2; ++k) \
;         acc[ai][bj][m][n] = __builtin_amdgcn_mfma_f32_16x16x32_bf16(Bt[n][k], At[m][k], acc[ai][bj][m][n], 0, 0, 0); __builtin_amdgcn_s_setprio(0); } while (0)
; #define PG8_WAIT_V(n) asm volatile("s_waitcnt vmcnt(" #n ")" ::: "memory")
; #define PG8_WAIT_L(n) asm volatile("s_waitcnt lgkmcnt(" #n ")" ::: "memory")
; #define PG8_BAR __builtin_amdgcn_s_barrier()
; #define PG8_SCHED __builtin_amdgcn_sched_barrier(0)
; template <class Epi, class Sched, bool ALIGN_EPI = false, bool SP2 = false>
; __device__ __forceinline__ void gemm_phase(PG8_LAS unsigned char* lds, const Gemm g, const Sched& S, const Epi& E) {
;     ...
;             PG8_WAIT_V(8); PG8_WAIT_L(0); PG8_BAR; PG8_MMA(0, 0, At, B0); PG8_MMA(0, 1, At, B1); PG8_BAR; PG8_SCHED;
;             PG8_LDA(At, 0, 1); PG8_STAGE(PG8_SB(0, 0), b2, voffB); PG8_STAGE(PG8_SB(0, 1), b2 + hstepB, voffB); PG8_STAGE(PG8_SA(0, 0), a2, voffA);
;             PG8_WAIT_V(8); PG8_WAIT_L(0); PG8_BAR; PG8_MMA(1, 0, At, B0); PG8_MMA(1, 1, At, B1); PG8_BAR; PG8_SCHED;
;             PG8_LDB(B0, 1, 0); PG8_LDB(B1, 1, 1); PG8_SCHED; PG8_LDA(At, 1, 0); PG8_STAGE(PG8_SA(0, 1), a2 + hstepA, voffA);
;             PG8_WAIT_V(8); PG8_WAIT_L(0); PG8_BAR; PG8_MMA(0, 0, At, B0); PG8_MMA(0, 1, At, B1); PG8_BAR; PG8_SCHED;
;             PG8_LDA(At, 1, 1); PG8_STAGE(PG8_SB(1, 0), b3, voffB); PG8_STAGE(PG8_SB(1, 1), b3 + hstepB, voffB); PG8_STAGE(PG8_SA(1, 0), a3, voffA);
	s_setprio 1
	s_waitcnt lgkmcnt(0)
	v_mfma_f32_16x16x32_bf16 v[62:65], v[130:133], v[180:183], 0
	v_mfma_f32_16x16x32_bf16 v[58:61], v[138:141], v[180:183], 0
	v_mfma_f32_16x16x32_bf16 v[46:49], v[130:133], v[196:199], 0
	v_mfma_f32_16x16x32_bf16 v[42:45], v[138:141], v[196:199], 0
	v_mfma_f32_16x16x32_bf16 v[30:33], v[130:133], v[204:207], 0
	v_mfma_f32_16x16x32_bf16 v[26:29], v[138:141], v[204:207], 0
	v_mfma_f32_16x16x32_bf16 v[14:17], v[130:133], v[212:215], 0
	v_mfma_f32_16x16x32_bf16 v[10:13], v[138:141], v[212:215], 0
	v_mfma_f32_16x16x32_bf16 v[62:65], v[134:137], v[192:195], v[62:65]
	v_mfma_f32_16x16x32_bf16 v[58:61], v[142:145], v[192:195], v[58:61]
	v_mfma_f32_16x16x32_bf16 v[46:49], v[134:137], v[200:203], v[46:49]
	v_mfma_f32_16x16x32_bf16 v[42:45], v[142:145], v[200:203], v[42:45]
	v_mfma_f32_16x16x32_bf16 v[30:33], v[134:137], v[208:211], v[30:33]
	v_mfma_f32_16x16x32_bf16 v[26:29], v[142:145], v[208:211], v[26:29]
	v_mfma_f32_16x16x32_bf16 v[14:17], v[134:137], v[216:219], v[14:17]
	v_mfma_f32_16x16x32_bf16 v[10:13], v[142:145], v[216:219], v[10:13]
	s_setprio 0
	s_setprio 1
	v_mfma_f32_16x16x32_bf16 v[54:57], v[164:167], v[180:183], 0
	v_mfma_f32_16x16x32_bf16 v[50:53], v[172:175], v[180:183], 0
	v_mfma_f32_16x16x32_bf16 v[38:41], v[164:167], v[196:199], 0
	v_mfma_f32_16x16x32_bf16 v[34:37], v[172:175], v[196:199], 0
	v_mfma_f32_16x16x32_bf16 v[22:25], v[164:167], v[204:207], 0
	v_mfma_f32_16x16x32_bf16 v[18:21], v[172:175], v[204:207], 0
	v_mfma_f32_16x16x32_bf16 v[6:9], v[164:167], v[212:215], 0
	v_mfma_f32_16x16x32_bf16 v[2:5], v[172:175], v[212:215], 0
	v_mfma_f32_16x16x32_bf16 v[54:57], v[168:171], v[192:195], v[54:57]
	v_mfma_f32_16x16x32_bf16 v[50:53], v[176:179], v[192:195], v[50:53]
	v_mfma_f32_16x16x32_bf16 v[38:41], v[168:171], v[200:203], v[38:41]
	v_mfma_f32_16x16x32_bf16 v[34:37], v[176:179], v[200:203], v[34:37]
	v_mfma_f32_16x16x32_bf16 v[22:25], v[168:171], v[208:211], v[22:25]
	v_mfma_f32_16x16x32_bf16 v[18:21], v[176:179], v[208:211], v[18:21]
	v_mfma_f32_16x16x32_bf16 v[6:9], v[168:171], v[216:219], v[6:9]
	v_mfma_f32_16x16x32_bf16 v[2:5], v[176:179], v[216:219], v[2:5]
	s_setprio 0
	s_barrier
	s_add_i32 s58, 0, 0x18000
	s_add_i32 s59, 0, 0x1c000
	v_add_u32_e32 v142, s58, v184
	v_add_u32_e32 v176, s59, v184
	ds_read_b128 v[130:133], v142
	ds_read_b128 v[134:137], v142 offset:1024
	ds_read_b128 v[138:141], v142 offset:2048
	ds_read_b128 v[142:145], v142 offset:3072
	ds_read_b128 v[164:167], v176
	ds_read_b128 v[168:171], v176 offset:1024
	ds_read_b128 v[172:175], v176 offset:2048
	ds_read_b128 v[176:179], v176 offset:3072
	s_add_u32 s40, s40, 0x40000
	s_addc_u32 s41, s41, 0
	s_mov_b32 m0, s46
	v_lshl_add_u64 v[228:229], s[40:41], 0, v[146:147]
	ds_read_b128 v[180:183], v188 offset:32768
	ds_read_b128 v[192:195], v188 offset:33792
	ds_read_b128 v[196:199], v188 offset:34816
	ds_read_b128 v[200:203], v188 offset:35840
	ds_read_b128 v[204:207], v188 offset:36864
	ds_read_b128 v[208:211], v188 offset:37888
	ds_read_b128 v[212:215], v188 offset:38912
	ds_read_b128 v[216:219], v188 offset:39936
	global_load_lds_dwordx4 v[228:229], off
	v_lshl_add_u64 v[228:229], s[40:41], 0, v[150:151]
	s_mov_b32 m0, s47
	s_nop 0
	global_load_lds_dwordx4 v[228:229], off
	s_waitcnt vmcnt(8)
	s_waitcnt lgkmcnt(0)
	s_barrier
	s_setprio 1
	s_waitcnt lgkmcnt(0)
	v_mfma_f32_16x16x32_bf16 v[126:129], v[130:133], v[180:183], v[126:129]
	v_mfma_f32_16x16x32_bf16 v[122:125], v[138:141], v[180:183], v[122:125]
	v_mfma_f32_16x16x32_bf16 v[110:113], v[130:133], v[196:199], v[110:113]
	v_mfma_f32_16x16x32_bf16 v[106:109], v[138:141], v[196:199], v[106:109]
	v_mfma_f32_16x16x32_bf16 v[94:97], v[130:133], v[204:207], v[94:97]
	v_mfma_f32_16x16x32_bf16 v[90:93], v[138:141], v[204:207], v[90:93]
	v_mfma_f32_16x16x32_bf16 v[78:81], v[130:133], v[212:215], v[78:81]
	v_mfma_f32_16x16x32_bf16 v[74:77], v[138:141], v[212:215], v[74:77]
	v_mfma_f32_16x16x32_bf16 v[126:129], v[134:137], v[192:195], v[126:129]
	v_mfma_f32_16x16x32_bf16 v[122:125], v[142:145], v[192:195], v[122:125]
	v_mfma_f32_16x16x32_bf16 v[110:113], v[134:137], v[200:203], v[110:113]
	v_mfma_f32_16x16x32_bf16 v[106:109], v[142:145], v[200:203], v[106:109]
	v_mfma_f32_16x16x32_bf16 v[94:97], v[134:137], v[208:211], v[94:97]
	v_mfma_f32_16x16x32_bf16 v[90:93], v[142:145], v[208:211], v[90:93]
	v_mfma_f32_16x16x32_bf16 v[78:81], v[134:137], v[216:219], v[78:81]
	v_mfma_f32_16x16x32_bf16 v[74:77], v[142:145], v[216:219], v[74:77]
	s_setprio 0
	s_setprio 1
	v_mfma_f32_16x16x32_bf16 v[118:121], v[164:167], v[180:183], v[118:121]
	v_mfma_f32_16x16x32_bf16 v[114:117], v[172:175], v[180:183], v[114:117]
	v_mfma_f32_16x16x32_bf16 v[102:105], v[164:167], v[196:199], v[102:105]
	v_mfma_f32_16x16x32_bf16 v[98:101], v[172:175], v[196:199], v[98:101]
	v_mfma_f32_16x16x32_bf16 v[86:89], v[164:167], v[204:207], v[86:89]
	v_mfma_f32_16x16x32_bf16 v[82:85], v[172:175], v[204:207], v[82:85]
	v_mfma_f32_16x16x32_bf16 v[70:73], v[164:167], v[212:215], v[70:73]
	v_mfma_f32_16x16x32_bf16 v[66:69], v[172:175], v[212:215], v[66:69]
	v_mfma_f32_16x16x32_bf16 v[118:121], v[168:171], v[192:195], v[118:121]
	v_mfma_f32_16x16x32_bf16 v[114:117], v[176:179], v[192:195], v[114:117]
	v_mfma_f32_16x16x32_bf16 v[102:105], v[168:171], v[200:203], v[102:105]
	v_mfma_f32_16x16x32_bf16 v[98:101], v[176:179], v[200:203], v[98:101]
	v_mfma_f32_16x16x32_bf16 v[86:89], v[168:171], v[208:211], v[86:89]
	v_mfma_f32_16x16x32_bf16 v[82:85], v[176:179], v[208:211], v[82:85]
	v_mfma_f32_16x16x32_bf16 v[70:73], v[168:171], v[216:219], v[70:73]
	v_mfma_f32_16x16x32_bf16 v[66:69], v[176:179], v[216:219], v[66:69]
	s_setprio 0
	s_barrier
; #define PG8_STAGE(bufoff, gbase, voff) do { _Pragma("unroll") for (int _i = 0; _i < 2; ++_i) \
;         __builtin_amdgcn_global_load_lds((const unsigned*)((const char*)(gbase) + (voff)[_i]), (PG8_LAS unsigned*)(lds + (bufoff) + ldsw + _i * 8192), 16, 0, 0); } while (0)
; #define PG8_LDA(dst, b, h) do { _Pragma("unroll") for (int m = 0; m < 4; ++m) _Pragma("unroll") for (int k = 0; k < 2; ++k) dst[m][k] = *(const PG8_LAS bf16x8*)(lds + PG8_SA(b, h) + aoff + m * 2048 + k * 1024); } while (0)
; #define PG8_MMA(ai, bj, At, Bt) do { __builtin_amdgcn_s_setprio(1); _Pragma("unroll") for (int m = 0; m < 4; ++m) _Pragma("unroll") for (int n = 0; n < 2; ++n) _Pragma("unroll") for (int k = 0; k < 2; ++k) \
;         acc[ai][bj][m][n] = __builtin_amdgcn_mfma_f32_16x16x32_bf16(Bt[n][k], At[m][k], acc[ai][bj][m][n], 0, 0, 0); __builtin_amdgcn_s_setprio(0); } while (0)
; #define PG8_WAIT_V(n) asm volatile("s_waitcnt vmcnt(" #n ")" ::: "memory")
; #define PG8_WAIT_L(n) asm volatile("s_waitcnt lgkmcnt(" #n ")" ::: "memory")
; #define PG8_BAR __builtin_amdgcn_s_barrier()
; #define PG8_SCHED __builtin_amdgcn_sched_barrier(0)
; template <class Epi, class Sched, bool ALIGN_EPI = false, bool SP2 = false>
; __device__ __forceinline__ void gemm_phase(PG8_LAS unsigned char* lds, const Gemm g, const Sched& S, const Epi& E) {
;     ...
;             PG8_WAIT_V(8); PG8_WAIT_L(0); PG8_BAR; PG8_MMA(0, 0, At, B0); PG8_MMA(0, 1, At, B1); PG8_BAR; PG8_SCHED;
;             PG8_LDA(At, 1, 1); PG8_STAGE(PG8_SB(1, 0), b3, voffB); PG8_STAGE(PG8_SB(1, 1), b3 + hstepB, voffB); PG8_STAGE(PG8_SA(1, 0), a3, voffA);
;             PG8_WAIT_V(8); PG8_WAIT_L(0); PG8_BAR; PG8_MMA(1, 0, At, B0); PG8_MMA(1, 1, At, B1); PG8_BAR; PG8_SCHED;
	s_add_i32 s40, s58, s43
	v_lshl_add_u64 v[220:221], v[220:221], 0, s[22:23]
	s_mov_b32 m0, s40
	ds_read_b128 v[180:183], v188 offset:49152
	ds_read_b128 v[192:195], v188 offset:50176
	ds_read_b128 v[196:199], v188 offset:51200
	ds_read_b128 v[200:203], v188 offset:52224
	ds_read_b128 v[204:207], v188 offset:53248
	ds_read_b128 v[208:211], v188 offset:54272
	ds_read_b128 v[212:215], v188 offset:55296
	ds_read_b128 v[216:219], v188 offset:56320
	global_load_lds_dwordx4 v[220:221], off
	s_add_i32 m0, s40, 0x2000
	s_add_u32 s38, s38, 0x40080
	v_lshl_add_u64 v[220:221], v[222:223], 0, s[22:23]
	s_addc_u32 s39, s39, 0
	s_add_i32 s40, s59, s43
	global_load_lds_dwordx4 v[220:221], off
	v_lshl_add_u64 v[220:221], s[38:39], 0, v[148:149]
	s_mov_b32 m0, s40
	s_nop 0
	global_load_lds_dwordx4 v[220:221], off
	v_lshl_add_u64 v[220:221], s[38:39], 0, v[152:153]
	s_add_i32 m0, s40, 0x2000
	s_nop 0
	global_load_lds_dwordx4 v[220:221], off
	v_lshl_add_u64 v[220:221], v[224:225], 0, s[22:23]
	s_mov_b32 m0, s50
	s_nop 0
	global_load_lds_dwordx4 v[220:221], off
	v_lshl_add_u64 v[220:221], v[226:227], 0, s[22:23]
	s_mov_b32 m0, s51
	s_nop 0
	global_load_lds_dwordx4 v[220:221], off
	s_waitcnt vmcnt(8)
	s_waitcnt lgkmcnt(0)
	s_barrier
	s_setprio 1
	s_waitcnt lgkmcnt(0)
	v_mfma_f32_16x16x32_bf16 v[62:65], v[130:133], v[180:183], v[62:65]
	v_mfma_f32_16x16x32_bf16 v[58:61], v[138:141], v[180:183], v[58:61]
	v_mfma_f32_16x16x32_bf16 v[46:49], v[130:133], v[196:199], v[46:49]
	v_mfma_f32_16x16x32_bf16 v[42:45], v[138:141], v[196:199], v[42:45]
	v_mfma_f32_16x16x32_bf16 v[30:33], v[130:133], v[204:207], v[30:33]
	v_mfma_f32_16x16x32_bf16 v[26:29], v[138:141], v[204:207], v[26:29]
	v_mfma_f32_16x16x32_bf16 v[14:17], v[130:133], v[212:215], v[14:17]
	v_mfma_f32_16x16x32_bf16 v[10:13], v[138:141], v[212:215], v[10:13]
	v_mfma_f32_16x16x32_bf16 v[62:65], v[134:137], v[192:195], v[62:65]
	v_mfma_f32_16x16x32_bf16 v[58:61], v[142:145], v[192:195], v[58:61]
	v_mfma_f32_16x16x32_bf16 v[46:49], v[134:137], v[200:203], v[46:49]
	v_mfma_f32_16x16x32_bf16 v[42:45], v[142:145], v[200:203], v[42:45]
	v_mfma_f32_16x16x32_bf16 v[30:33], v[134:137], v[208:211], v[30:33]
	v_mfma_f32_16x16x32_bf16 v[26:29], v[142:145], v[208:211], v[26:29]
	v_mfma_f32_16x16x32_bf16 v[14:17], v[134:137], v[216:219], v[14:17]
	v_mfma_f32_16x16x32_bf16 v[10:13], v[142:145], v[216:219], v[10:13]
	s_setprio 0
	s_setprio 1
	v_mfma_f32_16x16x32_bf16 v[54:57], v[164:167], v[180:183], v[54:57]
	v_mfma_f32_16x16x32_bf16 v[50:53], v[172:175], v[180:183], v[50:53]
	v_mfma_f32_16x16x32_bf16 v[38:41], v[164:167], v[196:199], v[38:41]
	v_mfma_f32_16x16x32_bf16 v[34:37], v[172:175], v[196:199], v[34:37]
	v_mfma_f32_16x16x32_bf16 v[22:25], v[164:167], v[204:207], v[22:25]
	v_mfma_f32_16x16x32_bf16 v[18:21], v[172:175], v[204:207], v[18:21]
	v_mfma_f32_16x16x32_bf16 v[6:9], v[164:167], v[212:215], v[6:9]
	v_mfma_f32_16x16x32_bf16 v[2:5], v[172:175], v[212:215], v[2:5]
	v_mfma_f32_16x16x32_bf16 v[54:57], v[168:171], v[192:195], v[54:57]
	v_mfma_f32_16x16x32_bf16 v[50:53], v[176:179], v[192:195], v[50:53]
	v_mfma_f32_16x16x32_bf16 v[38:41], v[168:171], v[200:203], v[38:41]
	v_mfma_f32_16x16x32_bf16 v[34:37], v[176:179], v[200:203], v[34:37]
	v_mfma_f32_16x16x32_bf16 v[22:25], v[168:171], v[208:211], v[22:25]
	v_mfma_f32_16x16x32_bf16 v[18:21], v[176:179], v[208:211], v[18:21]
	v_mfma_f32_16x16x32_bf16 v[6:9], v[168:171], v[216:219], v[6:9]
	v_mfma_f32_16x16x32_bf16 v[2:5], v[176:179], v[216:219], v[2:5]
	s_setprio 0
	s_barrier
	s_add_i32 s33, s33, 2
	s_add_u32 s36, s36, 0x100
	s_addc_u32 s37, s37, 0
	s_add_u32 s27, s27, 0x100
	s_addc_u32 s29, s29, 0
	s_cmp_gt_u32 s33, 13

; #define PG8_BAR __builtin_amdgcn_s_barrier()
; template <class Epi, class Sched, bool ALIGN_EPI = false, bool SP2 = false>
; __device__ __forceinline__ void gemm_phase(PG8_LAS unsigned char* lds, const Gemm g, const Sched& S, const Epi& E) {
;     ...
;         if constexpr (ALIGN_EPI) { if (wr == 0) PG8_BAR; }
;         if constexpr (!Epi::AFTER_DRAIN) { E(acc, cur, wr, wc, fr, fq); S.done(cur); }
;         if (!has_next) break;
; #pragma unroll
;         for (int a = 0; a < 2; ++a)
; #pragma unroll
;             for (int b = 0; b < 2; ++b)
; #pragma unroll
;                 for (int m = 0; m < 4; ++m)
; #pragma unroll
;                     for (int n = 0; n < 2; ++n) acc[a][b][m][n] = (f32x4){0.f, 0.f, 0.f, 0.f};
;         cur = nxt; cA = nA; cB = nB; ++ui;
;         if constexpr (ALIGN_EPI) { if (wr == 1) PG8_BAR; }
;     }
.LBB0_922:
	s_or_b64 exec, exec, s[36:37]
	s_andn2_b64 vcc, exec, s[8:9]
	s_mov_b64 s[4:5], -1
	s_cbranch_vccnz .LBB0_895
	s_andn2_b64 vcc, exec, s[14:15]
	s_cbranch_vccnz .LBB0_894
	s_mov_b32 s98, 1
	s_branch .LBB0_894

; #define PG8_STAGE(bufoff, gbase, voff) do { _Pragma("unroll") for (int _i = 0; _i < 2; ++_i) \
;         __builtin_amdgcn_global_load_lds((const unsigned*)((const char*)(gbase) + (voff)[_i]), (PG8_LAS unsigned*)(lds + (bufoff) + ldsw + _i * 8192), 16, 0, 0); } while (0)
; #define PG8_WAIT_V(n) asm volatile("s_waitcnt vmcnt(" #n ")" ::: "memory")
; #define PG8_BAR __builtin_amdgcn_s_barrier()
; template <class Epi, class Sched, bool ALIGN_EPI = false, bool SP2 = false>
; __device__ __forceinline__ void gemm_phase(PG8_LAS unsigned char* lds, const Gemm g, const Sched& S, const Epi& E) {
;     int tid_ = threadIdx.x; asm volatile("" : "+v"(tid_));
;     const int tid = tid_, wid = __builtin_amdgcn_readfirstlane(tid >> 6), lane = tid & 63, wr = wid >> 2, wc = wid & 3, fr = lane & 15, fq = lane >> 4;
;     const int K = g.K, nt = K / BK;
;     unsigned voffA[2], voffB[2];
; #pragma unroll
;     for (int i = 0; i < 2; ++i) { int R, C; stage_rc(tid * 16 + i * 8192, R, C); const int Rb = Epi::PERM ? ((R & ~31) + perm32(R & 31)) : R;
;         voffA[i] = (unsigned)(R * g.lda + C) * 2u; voffB[i] = (unsigned)(Rb * g.ldb + C) * 2u; }
;     const size_t kstep = (size_t)(BK * 2);
;     const size_t hstepA = (size_t)HALF * g.lda * 2, hstepB = (size_t)HALF * g.ldb * 2;
;     const size_t tstepA = 2 * hstepA, tstepB = 2 * hstepB;
;     const unsigned ldsw = (unsigned)wid * 1024u;
;     const int aoff = lds_byte(wr * 64 + fr, fq * 8), boff = lds_byte(wc * 32 + fr, fq * 8);
;     ...
;     const char* cA = (const char*)g.A + (size_t)cur.g * g.gsA * 2 + (size_t)cur.pm * tstepA; const char* cB = (const char*)g.Bt + (size_t)cur.g * g.gsB * 2 + (size_t)cur.pn * tstepB;
;     S.a_ready(cur);
;     if constexpr (SP2) {
;         PG8_STAGE(PG8_SB(0, 0), cB, voffB); PG8_STAGE(PG8_SB(0, 1), cB + hstepB, voffB); PG8_STAGE(PG8_SA(0, 0), cA, voffA); PG8_STAGE(PG8_SA(0, 1), cA + hstepA, voffA);
;         if (wr == 1) PG8_BAR;
;         PG8_WAIT_V(2); PG8_BAR;
;         PG8_STAGE(PG8_SB(1, 0), cB + kstep, voffB); PG8_STAGE(PG8_SA(1, 0), cA + kstep, voffA); PG8_STAGE(PG8_SB(1, 1), cB + hstepB + kstep, voffB);
;         PG8_WAIT_V(6); PG8_BAR;
.LBB0_983:
	s_add_u32 s44, s78, 0x13c00000
	s_addc_u32 s45, s79, 0
	s_add_u32 s10, s78, 0x100000
	s_mov_b64 s[12:13], 0x80
	s_addc_u32 s11, s79, 0
	s_and_b32 s2, s7, 3
	s_add_i32 m0, s38, 0x18000
	v_lshl_add_u64 v[8:9], v[8:9], 0, s[12:13]
	s_lshl_b32 s46, s0, 6
	s_lshl_b32 s5, s0, 13
	s_lshl_b32 s16, s2, 5
	s_lshl_b32 s17, s2, 12
	s_waitcnt vmcnt(2)
	s_barrier
	global_load_lds_dwordx4 v[8:9], off
	v_lshl_add_u64 v[6:7], v[6:7], 0, s[12:13]
	s_add_i32 m0, s38, 0x1a000
	s_add_i32 s2, s38, 0x8000
	s_add_i32 s33, s38, 0xa000
	global_load_lds_dwordx4 v[6:7], off
	v_lshl_add_u64 v[2:3], v[2:3], 0, s[12:13]
	s_mov_b32 m0, s2
	s_add_u32 s14, s26, 0x40080
	global_load_lds_dwordx4 v[2:3], off
	v_lshl_add_u64 v[2:3], v[4:5], 0, s[12:13]
	s_mov_b32 m0, s33
	s_addc_u32 s15, s27, 0
	global_load_lds_dwordx4 v[2:3], off
	s_add_i32 m0, s38, 0x1c000
	v_lshl_add_u64 v[2:3], s[14:15], 0, v[134:135]
	global_load_lds_dwordx4 v[2:3], off
	v_lshl_add_u64 v[2:3], s[14:15], 0, v[130:131]
	s_add_i32 m0, s38, 0x1e000
	s_cmpk_lt_u32 s1, 0x100
	global_load_lds_dwordx4 v[2:3], off
	v_bfe_u32 v3, v12, 4, 2
	v_and_b32_e32 v1, 15, v12
	v_lshlrev_b32_e32 v2, 3, v3
	v_lshlrev_b32_e32 v138, 4, v3
	v_lshlrev_b32_e32 v5, 2, v12
	s_cselect_b64 s[14:15], -1, 0
	v_lshlrev_b32_e32 v3, 2, v3
	s_lshl_b32 s1, s7, 4
	v_lshl_or_b32 v4, v1, 6, v138
	v_and_b32_e32 v5, 32, v5
	v_and_or_b32 v140, s1, 16, v3
	v_lshlrev_b32_e32 v3, 14, v15
	s_sext_i32_i8 s0, s6
	v_bitop3_b32 v6, v4, s5, v5 bitop3:0xde
	v_bitop3_b32 v141, v4, s17, v5 bitop3:0xde
	v_lshl_add_u64 v[4:5], s[78:79], 0, v[138:139]
	s_mov_b64 s[6:7], 0x5a00000
	v_and_b32_e32 v3, 0xffff8000, v3
	v_lshl_add_u64 v[142:143], v[4:5], 0, s[6:7]
	v_lshl_add_u32 v3, v14, 11, v3
	v_and_b32_e32 v4, 1, v15
	v_lshl_or_b32 v3, v4, 6, v3
	v_lshl_add_u32 v144, v16, 1, v3
	v_lshlrev_b32_e32 v3, 14, v10
	v_and_b32_e32 v3, 0xffff8000, v3
	v_lshl_add_u32 v3, v11, 11, v3
	v_and_b32_e32 v4, 1, v10
	s_waitcnt vmcnt(6)
	v_lshl_or_b32 v3, v4, 6, v3
	s_and_b32 s1, s16, 64
	v_lshl_add_u32 v146, v13, 1, v3
	s_add_i32 s49, 0, 0x10000
	s_add_i32 s50, 0, 0x14000
	v_mbcnt_lo_u32_b32 v3, -1, 0
	s_ashr_i32 s47, s82, 31
	s_mov_b32 s48, s82
	v_mov_b32_e32 v145, v139
	v_mov_b32_e32 v147, v139
	v_mov_b64_e32 v[148:149], 0x600
	v_mov_b64_e32 v[150:151], 0x5ff
	v_add_u32_e32 v157, s49, v141
	v_add_u32_e32 v159, s50, v141
	v_add_u32_e32 v161, 0, v6
	v_mbcnt_hi_u32_b32 v163, -1, v3
	v_mov_b32_e32 v171, 0x358637bd
	s_lshl_b32 s51, s16, 1
	v_lshlrev_b32_e32 v152, 1, v2
	s_lshl_b32 s52, s1, 1
	s_movk_i32 s53, 0x1000
	s_movk_i32 s54, 0x3000
	v_mov_b32_e32 v173, 0x3e38aa3b
	s_barrier
	s_mov_b32 s98, 0
	s_branch .LBB0_986

; #define PG8_STAGE(bufoff, gbase, voff) do { _Pragma("unroll") for (int _i = 0; _i < 2; ++_i) \
;         __builtin_amdgcn_global_load_lds((const unsigned*)((const char*)(gbase) + (voff)[_i]), (PG8_LAS unsigned*)(lds + (bufoff) + ldsw + _i * 8192), 16, 0, 0); } while (0)
; #define PG8_LDA(dst, b, h) do { _Pragma("unroll") for (int m = 0; m < 4; ++m) _Pragma("unroll") for (int k = 0; k < 2; ++k) dst[m][k] = *(const PG8_LAS bf16x8*)(lds + PG8_SA(b, h) + aoff + m * 2048 + k * 1024); } while (0)
; #define PG8_LDB(dst, b, h) do { _Pragma("unroll") for (int n = 0; n < 2; ++n) _Pragma("unroll") for (int k = 0; k < 2; ++k) dst[n][k] = *(const PG8_LAS bf16x8*)(lds + PG8_SB(b, h) + boff + n * 2048 + k * 1024); } while (0)
; #define PG8_WAIT_V(n) asm volatile("s_waitcnt vmcnt(" #n ")" ::: "memory")
; #define PG8_WAIT_L(n) asm volatile("s_waitcnt lgkmcnt(" #n ")" ::: "memory")
; #define PG8_BAR __builtin_amdgcn_s_barrier()
; template <class Epi, class Sched, bool ALIGN_EPI = false, bool SP2 = false>
; __device__ __forceinline__ void gemm_phase(PG8_LAS unsigned char* lds, const Gemm g, const Sched& S, const Epi& E) {
;     ...
;         const bool has_next = S.next(ui + 1, nxt);
;         const char* nA = has_next ? (const char*)g.A + (size_t)nxt.g * g.gsA * 2 + (size_t)nxt.pm * tstepA : cA; const char* nB = has_next ? (const char*)g.Bt + (size_t)nxt.g * g.gsB * 2 + (size_t)nxt.pn * tstepB : cB;
;         for (int t = 0; t < nt; t += 2) {
;             const bool last = (t == nt - 2);
;             const char* a1 = cA + (size_t)(t + 1) * kstep;
;             const char* a2 = last ? nA : cA + (size_t)(t + 2) * kstep; const char* b2 = last ? nB : cB + (size_t)(t + 2) * kstep;
;             const char* a3 = a2 + kstep; const char* b3 = b2 + kstep;
;             if (last && has_next) S.a_ready(nxt);
;             if constexpr (SP2) {
;             PG8_LDB(B0, 0, 0); PG8_LDB(B1, 0, 1); PG8_SCHED; PG8_LDA(At, 0, 0); PG8_STAGE(PG8_SA(1, 1), a1 + hstepA, voffA);
;             PG8_WAIT_V(8); PG8_WAIT_L(0); PG8_BAR; PG8_MMA(0, 0, At, B0); PG8_MMA(0, 1, At, B1); PG8_BAR; PG8_SCHED;
;             PG8_LDA(At, 0, 1); PG8_STAGE(PG8_SB(0, 0), b2, voffB); PG8_STAGE(PG8_SB(0, 1), b2 + hstepB, voffB); PG8_STAGE(PG8_SA(0, 0), a2, voffA);
;             PG8_WAIT_V(8); PG8_WAIT_L(0); PG8_BAR; PG8_MMA(1, 0, At, B0); PG8_MMA(1, 1, At, B1); PG8_BAR; PG8_SCHED;
.LBB0_988:
	s_ashr_i32 s19, s18, 31
	s_lshl_b64 s[20:21], s[18:19], 19
	s_add_u32 s20, s3, s20
	s_addc_u32 s21, s30, s21
	s_and_b64 s[22:23], s[6:7], exec
	s_cselect_b32 s1, s21, s25
	s_cselect_b32 s5, s20, s24
	s_ashr_i32 s17, s16, 31
	s_lshl_b64 s[22:23], s[16:17], 19
	s_add_u32 s22, s31, s22
	s_addc_u32 s23, s34, s23
	s_and_b64 s[28:29], s[6:7], exec
	s_cselect_b32 s17, s23, s27
	s_cselect_b32 s19, s22, s26
	s_add_u32 s24, s24, 0x40080
	s_addc_u32 s25, s25, 0
	s_add_u32 s55, s26, 0x100
	s_addc_u32 s56, s27, 0
	s_mov_b32 s57, -2
	s_cmp_eq_u32 s98, 1
	s_cbranch_scc0 .Lhb_31128
	s_mov_b32 s98, 0
	s_barrier
.Lhb_31128:
	ds_read_b128 v[164:167], v157
	ds_read_b128 v[174:177], v157 offset:1024
	ds_read_b128 v[178:181], v157 offset:2048
	ds_read_b128 v[182:185], v157 offset:3072
	ds_read_b128 v[186:189], v159
	ds_read_b128 v[190:193], v159 offset:1024
	ds_read_b128 v[194:197], v159 offset:2048
	ds_read_b128 v[198:201], v159 offset:3072
	s_add_u32 s26, s24, 0xfffc0080
	s_addc_u32 s27, s25, -1
	s_cmp_eq_u32 s57, 12
	s_cselect_b32 s29, s1, s27
	s_cselect_b32 s28, s5, s26
	s_cselect_b32 s27, s17, s56
	s_cselect_b32 s26, s19, s55
	v_lshl_add_u64 v[154:155], s[24:25], 0, v[144:145]
	s_add_i32 m0, s38, 0xc000
	ds_read_b128 v[202:205], v161
	ds_read_b128 v[206:209], v161 offset:1024
	ds_read_b128 v[210:213], v161 offset:2048
	ds_read_b128 v[214:217], v161 offset:3072
	ds_read_b128 v[218:221], v161 offset:4096
	ds_read_b128 v[222:225], v161 offset:5120
	ds_read_b128 v[226:229], v161 offset:6144
	ds_read_b128 v[230:233], v161 offset:7168
	global_load_lds_dwordx4 v[154:155], off
	v_lshl_add_u64 v[154:155], s[24:25], 0, v[146:147]
	s_add_i32 m0, s38, 0xe000
	s_nop 0
	global_load_lds_dwordx4 v[154:155], off
	s_waitcnt vmcnt(8)
	s_waitcnt lgkmcnt(0)
	s_barrier
	s_setprio 1
	s_waitcnt lgkmcnt(0)
	v_mfma_f32_16x16x32_bf16 v[126:129], v[164:167], v[202:205], 0
	v_mfma_f32_16x16x32_bf16 v[122:125], v[178:181], v[202:205], 0
	v_mfma_f32_16x16x32_bf16 v[110:113], v[164:167], v[210:213], 0
	v_mfma_f32_16x16x32_bf16 v[106:109], v[178:181], v[210:213], 0
	v_mfma_f32_16x16x32_bf16 v[94:97], v[164:167], v[218:221], 0
	v_mfma_f32_16x16x32_bf16 v[90:93], v[178:181], v[218:221], 0
	v_mfma_f32_16x16x32_bf16 v[78:81], v[164:167], v[226:229], 0
	v_mfma_f32_16x16x32_bf16 v[74:77], v[178:181], v[226:229], 0
	v_mfma_f32_16x16x32_bf16 v[126:129], v[174:177], v[206:209], v[126:129]
	v_mfma_f32_16x16x32_bf16 v[122:125], v[182:185], v[206:209], v[122:125]
	v_mfma_f32_16x16x32_bf16 v[110:113], v[174:177], v[214:217], v[110:113]
	v_mfma_f32_16x16x32_bf16 v[106:109], v[182:185], v[214:217], v[106:109]
	v_mfma_f32_16x16x32_bf16 v[94:97], v[174:177], v[222:225], v[94:97]
	v_mfma_f32_16x16x32_bf16 v[90:93], v[182:185], v[222:225], v[90:93]
	v_mfma_f32_16x16x32_bf16 v[78:81], v[174:177], v[230:233], v[78:81]
	v_mfma_f32_16x16x32_bf16 v[74:77], v[182:185], v[230:233], v[74:77]
	s_setprio 0
	s_setprio 1
	v_mfma_f32_16x16x32_bf16 v[118:121], v[186:189], v[202:205], 0
	v_mfma_f32_16x16x32_bf16 v[114:117], v[194:197], v[202:205], 0
	v_mfma_f32_16x16x32_bf16 v[102:105], v[186:189], v[210:213], 0
	v_mfma_f32_16x16x32_bf16 v[98:101], v[194:197], v[210:213], 0
	v_mfma_f32_16x16x32_bf16 v[86:89], v[186:189], v[218:221], 0
	v_mfma_f32_16x16x32_bf16 v[82:85], v[194:197], v[218:221], 0
	v_mfma_f32_16x16x32_bf16 v[70:73], v[186:189], v[226:229], 0
	v_mfma_f32_16x16x32_bf16 v[66:69], v[194:197], v[226:229], 0
	v_mfma_f32_16x16x32_bf16 v[118:121], v[190:193], v[206:209], v[118:121]
	v_mfma_f32_16x16x32_bf16 v[114:117], v[198:201], v[206:209], v[114:117]
	v_mfma_f32_16x16x32_bf16 v[102:105], v[190:193], v[214:217], v[102:105]
	v_mfma_f32_16x16x32_bf16 v[98:101], v[198:201], v[214:217], v[98:101]
	v_mfma_f32_16x16x32_bf16 v[86:89], v[190:193], v[222:225], v[86:89]
	v_mfma_f32_16x16x32_bf16 v[82:85], v[198:201], v[222:225], v[82:85]
	v_mfma_f32_16x16x32_bf16 v[70:73], v[190:193], v[230:233], v[70:73]
	v_mfma_f32_16x16x32_bf16 v[66:69], v[198:201], v[230:233], v[66:69]
	s_setprio 0
	s_barrier
	s_add_i32 s58, s49, s35
	v_lshl_add_u64 v[154:155], s[26:27], 0, v[134:135]
	s_mov_b32 m0, s58
	ds_read_b128 v[202:205], v161 offset:16384
	ds_read_b128 v[206:209], v161 offset:17408
	ds_read_b128 v[210:213], v161 offset:18432
	ds_read_b128 v[214:217], v161 offset:19456
	ds_read_b128 v[218:221], v161 offset:20480
	ds_read_b128 v[222:225], v161 offset:21504
	ds_read_b128 v[226:229], v161 offset:22528
	ds_read_b128 v[230:233], v161 offset:23552
	global_load_lds_dwordx4 v[154:155], off
	s_add_i32 m0, s58, 0x2000
	s_add_u32 s58, s26, 0x40000
	v_lshl_add_u64 v[168:169], s[26:27], 0, v[130:131]
	s_addc_u32 s59, s27, 0
	s_add_i32 s60, s50, s35
	global_load_lds_dwordx4 v[168:169], off
	v_lshl_add_u64 v[234:235], s[58:59], 0, v[134:135]
	s_mov_b32 m0, s60
	v_lshl_add_u64 v[236:237], s[28:29], 0, v[132:133]
	global_load_lds_dwordx4 v[234:235], off
	v_lshl_add_u64 v[234:235], s[58:59], 0, v[130:131]
	s_add_i32 m0, s60, 0x2000
	s_nop 0
	global_load_lds_dwordx4 v[234:235], off
	v_lshl_add_u64 v[234:235], s[28:29], 0, v[136:137]
	s_mov_b32 m0, s38
	s_nop 0
	global_load_lds_dwordx4 v[234:235], off
	s_mov_b32 m0, s39
	s_nop 0
	global_load_lds_dwordx4 v[236:237], off
	s_waitcnt vmcnt(8)
	s_waitcnt lgkmcnt(0)
	s_barrier
; #define PG8_STAGE(bufoff, gbase, voff) do { _Pragma("unroll") for (int _i = 0; _i < 2; ++_i) \
;         __builtin_amdgcn_global_load_lds((const unsigned*)((const char*)(gbase) + (voff)[_i]), (PG8_LAS unsigned*)(lds + (bufoff) + ldsw + _i * 8192), 16, 0, 0); } while (0)
; #define PG8_LDA(dst, b, h) do { _Pragma("unroll") for (int m = 0; m < 4; ++m) _Pragma("unroll") for (int k = 0; k < 2; ++k) dst[m][k] = *(const PG8_LAS bf16x8*)(lds + PG8_SA(b, h) + aoff + m * 2048 + k * 1024); } while (0)
; #define PG8_LDB(dst, b, h) do { _Pragma("unroll") for (int n = 0; n < 2; ++n) _Pragma("unroll") for (int k = 0; k < 2; ++k) dst[n][k] = *(const PG8_LAS bf16x8*)(lds + PG8_SB(b, h) + boff + n * 2048 + k * 1024); } while (0)
; #define PG8_MMA(ai, bj, At, Bt) do { __builtin_amdgcn_s_setprio(1); _Pragma("unroll") for (int m = 0; m < 4; ++m) _Pragma("unroll") for (int n = 0; n < 2; ++n) _Pragma("unroll") for (int k = 0; k < 2; ++k) \
;         acc[ai][bj][m][n] = __builtin_amdgcn_mfma_f32_16x16x32_bf16(Bt[n][k], At[m][k], acc[ai][bj][m][n], 0, 0, 0); __builtin_amdgcn_s_setprio(0); } while (0)
; #define PG8_WAIT_V(n) asm volatile("s_waitcnt vmcnt(" #n ")" ::: "memory")
; #define PG8_WAIT_L(n) asm volatile("s_waitcnt lgkmcnt(" #n ")" ::: "memory")
; #define PG8_BAR __builtin_amdgcn_s_barrier()
; #define PG8_SCHED __builtin_amdgcn_sched_barrier(0)
; template <class Epi, class Sched, bool ALIGN_EPI = false, bool SP2 = false>
; __device__ __forceinline__ void gemm_phase(PG8_LAS unsigned char* lds, const Gemm g, const Sched& S, const Epi& E) {
;     ...
;             PG8_WAIT_V(8); PG8_WAIT_L(0); PG8_BAR; PG8_MMA(0, 0, At, B0); PG8_MMA(0, 1, At, B1); PG8_BAR; PG8_SCHED;
;             PG8_LDA(At, 0, 1); PG8_STAGE(PG8_SB(0, 0), b2, voffB); PG8_STAGE(PG8_SB(0, 1), b2 + hstepB, voffB); PG8_STAGE(PG8_SA(0, 0), a2, voffA);
;             PG8_WAIT_V(8); PG8_WAIT_L(0); PG8_BAR; PG8_MMA(1, 0, At, B0); PG8_MMA(1, 1, At, B1); PG8_BAR; PG8_SCHED;
;             PG8_LDB(B0, 1, 0); PG8_LDB(B1, 1, 1); PG8_SCHED; PG8_LDA(At, 1, 0); PG8_STAGE(PG8_SA(0, 1), a2 + hstepA, voffA);
;             PG8_WAIT_V(8); PG8_WAIT_L(0); PG8_BAR; PG8_MMA(0, 0, At, B0); PG8_MMA(0, 1, At, B1); PG8_BAR; PG8_SCHED;
;             PG8_LDA(At, 1, 1); PG8_STAGE(PG8_SB(1, 0), b3, voffB); PG8_STAGE(PG8_SB(1, 1), b3 + hstepB, voffB); PG8_STAGE(PG8_SA(1, 0), a3, voffA);
	s_setprio 1
	s_waitcnt lgkmcnt(0)
	v_mfma_f32_16x16x32_bf16 v[62:65], v[164:167], v[202:205], 0
	v_mfma_f32_16x16x32_bf16 v[58:61], v[178:181], v[202:205], 0
	v_mfma_f32_16x16x32_bf16 v[46:49], v[164:167], v[210:213], 0
	v_mfma_f32_16x16x32_bf16 v[42:45], v[178:181], v[210:213], 0
	v_mfma_f32_16x16x32_bf16 v[30:33], v[164:167], v[218:221], 0
	v_mfma_f32_16x16x32_bf16 v[26:29], v[178:181], v[218:221], 0
	v_mfma_f32_16x16x32_bf16 v[14:17], v[164:167], v[226:229], 0
	v_mfma_f32_16x16x32_bf16 v[10:13], v[178:181], v[226:229], 0
	v_mfma_f32_16x16x32_bf16 v[62:65], v[174:177], v[206:209], v[62:65]
	v_mfma_f32_16x16x32_bf16 v[58:61], v[182:185], v[206:209], v[58:61]
	v_mfma_f32_16x16x32_bf16 v[46:49], v[174:177], v[214:217], v[46:49]
	v_mfma_f32_16x16x32_bf16 v[42:45], v[182:185], v[214:217], v[42:45]
	v_mfma_f32_16x16x32_bf16 v[30:33], v[174:177], v[222:225], v[30:33]
	v_mfma_f32_16x16x32_bf16 v[26:29], v[182:185], v[222:225], v[26:29]
	v_mfma_f32_16x16x32_bf16 v[14:17], v[174:177], v[230:233], v[14:17]
	v_mfma_f32_16x16x32_bf16 v[10:13], v[182:185], v[230:233], v[10:13]
	s_setprio 0
	s_setprio 1
	v_mfma_f32_16x16x32_bf16 v[54:57], v[186:189], v[202:205], 0
	v_mfma_f32_16x16x32_bf16 v[50:53], v[194:197], v[202:205], 0
	v_mfma_f32_16x16x32_bf16 v[38:41], v[186:189], v[210:213], 0
	v_mfma_f32_16x16x32_bf16 v[34:37], v[194:197], v[210:213], 0
	v_mfma_f32_16x16x32_bf16 v[22:25], v[186:189], v[218:221], 0
	v_mfma_f32_16x16x32_bf16 v[18:21], v[194:197], v[218:221], 0
	v_mfma_f32_16x16x32_bf16 v[6:9], v[186:189], v[226:229], 0
	v_mfma_f32_16x16x32_bf16 v[2:5], v[194:197], v[226:229], 0
	v_mfma_f32_16x16x32_bf16 v[54:57], v[190:193], v[206:209], v[54:57]
	v_mfma_f32_16x16x32_bf16 v[50:53], v[198:201], v[206:209], v[50:53]
	v_mfma_f32_16x16x32_bf16 v[38:41], v[190:193], v[214:217], v[38:41]
	v_mfma_f32_16x16x32_bf16 v[34:37], v[198:201], v[214:217], v[34:37]
	v_mfma_f32_16x16x32_bf16 v[22:25], v[190:193], v[222:225], v[22:25]
	v_mfma_f32_16x16x32_bf16 v[18:21], v[198:201], v[222:225], v[18:21]
	v_mfma_f32_16x16x32_bf16 v[6:9], v[190:193], v[230:233], v[6:9]
	v_mfma_f32_16x16x32_bf16 v[2:5], v[198:201], v[230:233], v[2:5]
	s_setprio 0
	s_barrier
	s_add_i32 s58, 0, 0x18000
	v_add_u32_e32 v138, s58, v141
	s_add_i32 s59, 0, 0x1c000
	ds_read_b128 v[164:167], v138
	ds_read_b128 v[174:177], v138 offset:1024
	ds_read_b128 v[178:181], v138 offset:2048
	ds_read_b128 v[182:185], v138 offset:3072
	v_add_u32_e32 v138, s59, v141
	ds_read_b128 v[186:189], v138
	ds_read_b128 v[190:193], v138 offset:1024
	ds_read_b128 v[194:197], v138 offset:2048
	ds_read_b128 v[198:201], v138 offset:3072
	s_add_u32 s28, s28, 0x40000
	s_addc_u32 s29, s29, 0
	s_mov_b32 m0, s40
	v_lshl_add_u64 v[238:239], s[28:29], 0, v[136:137]
	ds_read_b128 v[202:205], v161 offset:32768
	ds_read_b128 v[206:209], v161 offset:33792
	ds_read_b128 v[210:213], v161 offset:34816
	ds_read_b128 v[214:217], v161 offset:35840
	ds_read_b128 v[218:221], v161 offset:36864
	ds_read_b128 v[222:225], v161 offset:37888
	ds_read_b128 v[226:229], v161 offset:38912
	ds_read_b128 v[230:233], v161 offset:39936
	global_load_lds_dwordx4 v[238:239], off
	v_lshl_add_u64 v[238:239], s[28:29], 0, v[132:133]
	s_mov_b32 m0, s41
	s_nop 0
	global_load_lds_dwordx4 v[238:239], off
	s_waitcnt vmcnt(8)
	s_waitcnt lgkmcnt(0)
	s_barrier
	s_setprio 1
	s_waitcnt lgkmcnt(0)
	v_mfma_f32_16x16x32_bf16 v[126:129], v[164:167], v[202:205], v[126:129]
	v_mfma_f32_16x16x32_bf16 v[122:125], v[178:181], v[202:205], v[122:125]
	v_mfma_f32_16x16x32_bf16 v[110:113], v[164:167], v[210:213], v[110:113]
	v_mfma_f32_16x16x32_bf16 v[106:109], v[178:181], v[210:213], v[106:109]
	v_mfma_f32_16x16x32_bf16 v[94:97], v[164:167], v[218:221], v[94:97]
	v_mfma_f32_16x16x32_bf16 v[90:93], v[178:181], v[218:221], v[90:93]
	v_mfma_f32_16x16x32_bf16 v[78:81], v[164:167], v[226:229], v[78:81]
	v_mfma_f32_16x16x32_bf16 v[74:77], v[178:181], v[226:229], v[74:77]
	v_mfma_f32_16x16x32_bf16 v[126:129], v[174:177], v[206:209], v[126:129]
	v_mfma_f32_16x16x32_bf16 v[122:125], v[182:185], v[206:209], v[122:125]
	v_mfma_f32_16x16x32_bf16 v[110:113], v[174:177], v[214:217], v[110:113]
	v_mfma_f32_16x16x32_bf16 v[106:109], v[182:185], v[214:217], v[106:109]
	v_mfma_f32_16x16x32_bf16 v[94:97], v[174:177], v[222:225], v[94:97]
	v_mfma_f32_16x16x32_bf16 v[90:93], v[182:185], v[222:225], v[90:93]
	v_mfma_f32_16x16x32_bf16 v[78:81], v[174:177], v[230:233], v[78:81]
	v_mfma_f32_16x16x32_bf16 v[74:77], v[182:185], v[230:233], v[74:77]
	s_setprio 0
	s_setprio 1
	v_mfma_f32_16x16x32_bf16 v[118:121], v[186:189], v[202:205], v[118:121]
	v_mfma_f32_16x16x32_bf16 v[114:117], v[194:197], v[202:205], v[114:117]
	v_mfma_f32_16x16x32_bf16 v[102:105], v[186:189], v[210:213], v[102:105]
	v_mfma_f32_16x16x32_bf16 v[98:101], v[194:197], v[210:213], v[98:101]
	v_mfma_f32_16x16x32_bf16 v[86:89], v[186:189], v[218:221], v[86:89]
	v_mfma_f32_16x16x32_bf16 v[82:85], v[194:197], v[218:221], v[82:85]
	v_mfma_f32_16x16x32_bf16 v[70:73], v[186:189], v[226:229], v[70:73]
	v_mfma_f32_16x16x32_bf16 v[66:69], v[194:197], v[226:229], v[66:69]
	v_mfma_f32_16x16x32_bf16 v[118:121], v[190:193], v[206:209], v[118:121]
	v_mfma_f32_16x16x32_bf16 v[114:117], v[198:201], v[206:209], v[114:117]
	v_mfma_f32_16x16x32_bf16 v[102:105], v[190:193], v[214:217], v[102:105]
	v_mfma_f32_16x16x32_bf16 v[98:101], v[198:201], v[214:217], v[98:101]
	v_mfma_f32_16x16x32_bf16 v[86:89], v[190:193], v[222:225], v[86:89]
	v_mfma_f32_16x16x32_bf16 v[82:85], v[198:201], v[222:225], v[82:85]
	v_mfma_f32_16x16x32_bf16 v[70:73], v[190:193], v[230:233], v[70:73]
	v_mfma_f32_16x16x32_bf16 v[66:69], v[198:201], v[230:233], v[66:69]
	s_setprio 0
	s_barrier
; #define PG8_STAGE(bufoff, gbase, voff) do { _Pragma("unroll") for (int _i = 0; _i < 2; ++_i) \
;         __builtin_amdgcn_global_load_lds((const unsigned*)((const char*)(gbase) + (voff)[_i]), (PG8_LAS unsigned*)(lds + (bufoff) + ldsw + _i * 8192), 16, 0, 0); } while (0)
; #define PG8_LDA(dst, b, h) do { _Pragma("unroll") for (int m = 0; m < 4; ++m) _Pragma("unroll") for (int k = 0; k < 2; ++k) dst[m][k] = *(const PG8_LAS bf16x8*)(lds + PG8_SA(b, h) + aoff + m * 2048 + k * 1024); } while (0)
; #define PG8_MMA(ai, bj, At, Bt) do { __builtin_amdgcn_s_setprio(1); _Pragma("unroll") for (int m = 0; m < 4; ++m) _Pragma("unroll") for (int n = 0; n < 2; ++n) _Pragma("unroll") for (int k = 0; k < 2; ++k) \
;         acc[ai][bj][m][n] = __builtin_amdgcn_mfma_f32_16x16x32_bf16(Bt[n][k], At[m][k], acc[ai][bj][m][n], 0, 0, 0); __builtin_amdgcn_s_setprio(0); } while (0)
; #define PG8_WAIT_V(n) asm volatile("s_waitcnt vmcnt(" #n ")" ::: "memory")
; #define PG8_WAIT_L(n) asm volatile("s_waitcnt lgkmcnt(" #n ")" ::: "memory")
; #define PG8_BAR __builtin_amdgcn_s_barrier()
; #define PG8_SCHED __builtin_amdgcn_sched_barrier(0)
; template <class Epi, class Sched, bool ALIGN_EPI = false, bool SP2 = false>
; __device__ __forceinline__ void gemm_phase(PG8_LAS unsigned char* lds, const Gemm g, const Sched& S, const Epi& E) {
;     ...
;             PG8_WAIT_V(8); PG8_WAIT_L(0); PG8_BAR; PG8_MMA(0, 0, At, B0); PG8_MMA(0, 1, At, B1); PG8_BAR; PG8_SCHED;
;             PG8_LDA(At, 1, 1); PG8_STAGE(PG8_SB(1, 0), b3, voffB); PG8_STAGE(PG8_SB(1, 1), b3 + hstepB, voffB); PG8_STAGE(PG8_SA(1, 0), a3, voffA);
;             PG8_WAIT_V(8); PG8_WAIT_L(0); PG8_BAR; PG8_MMA(1, 0, At, B0); PG8_MMA(1, 1, At, B1); PG8_BAR; PG8_SCHED;
	s_add_i32 s28, s58, s35
	v_lshl_add_u64 v[154:155], v[154:155], 0, s[12:13]
	s_mov_b32 m0, s28
	ds_read_b128 v[202:205], v161 offset:49152
	ds_read_b128 v[206:209], v161 offset:50176
	ds_read_b128 v[210:213], v161 offset:51200
	ds_read_b128 v[214:217], v161 offset:52224
	ds_read_b128 v[218:221], v161 offset:53248
	ds_read_b128 v[222:225], v161 offset:54272
	ds_read_b128 v[226:229], v161 offset:55296
	ds_read_b128 v[230:233], v161 offset:56320
	global_load_lds_dwordx4 v[154:155], off
	s_add_i32 m0, s28, 0x2000
	s_add_u32 s26, s26, 0x40080
	v_lshl_add_u64 v[154:155], v[168:169], 0, s[12:13]
	s_addc_u32 s27, s27, 0
	s_add_i32 s28, s59, s35
	global_load_lds_dwordx4 v[154:155], off
	v_lshl_add_u64 v[154:155], s[26:27], 0, v[134:135]
	s_mov_b32 m0, s28
	s_nop 0
	global_load_lds_dwordx4 v[154:155], off
	v_lshl_add_u64 v[154:155], s[26:27], 0, v[130:131]
	s_add_i32 m0, s28, 0x2000
	s_nop 0
	global_load_lds_dwordx4 v[154:155], off
	v_lshl_add_u64 v[154:155], v[234:235], 0, s[12:13]
	s_mov_b32 m0, s2
	s_nop 0
	global_load_lds_dwordx4 v[154:155], off
	v_lshl_add_u64 v[154:155], v[236:237], 0, s[12:13]
	s_mov_b32 m0, s33
	s_nop 0
	global_load_lds_dwordx4 v[154:155], off
	s_waitcnt vmcnt(8)
	s_waitcnt lgkmcnt(0)
	s_barrier
	s_setprio 1
	s_waitcnt lgkmcnt(0)
	v_mfma_f32_16x16x32_bf16 v[62:65], v[164:167], v[202:205], v[62:65]
	v_mfma_f32_16x16x32_bf16 v[58:61], v[178:181], v[202:205], v[58:61]
	v_mfma_f32_16x16x32_bf16 v[46:49], v[164:167], v[210:213], v[46:49]
	v_mfma_f32_16x16x32_bf16 v[42:45], v[178:181], v[210:213], v[42:45]
	v_mfma_f32_16x16x32_bf16 v[30:33], v[164:167], v[218:221], v[30:33]
	v_mfma_f32_16x16x32_bf16 v[26:29], v[178:181], v[218:221], v[26:29]
	v_mfma_f32_16x16x32_bf16 v[14:17], v[164:167], v[226:229], v[14:17]
	v_mfma_f32_16x16x32_bf16 v[10:13], v[178:181], v[226:229], v[10:13]
	v_mfma_f32_16x16x32_bf16 v[62:65], v[174:177], v[206:209], v[62:65]
	v_mfma_f32_16x16x32_bf16 v[58:61], v[182:185], v[206:209], v[58:61]
	v_mfma_f32_16x16x32_bf16 v[46:49], v[174:177], v[214:217], v[46:49]
	v_mfma_f32_16x16x32_bf16 v[42:45], v[182:185], v[214:217], v[42:45]
	v_mfma_f32_16x16x32_bf16 v[30:33], v[174:177], v[222:225], v[30:33]
	v_mfma_f32_16x16x32_bf16 v[26:29], v[182:185], v[222:225], v[26:29]
	v_mfma_f32_16x16x32_bf16 v[14:17], v[174:177], v[230:233], v[14:17]
	v_mfma_f32_16x16x32_bf16 v[10:13], v[182:185], v[230:233], v[10:13]
	s_setprio 0
	s_setprio 1
	v_mfma_f32_16x16x32_bf16 v[54:57], v[186:189], v[202:205], v[54:57]
	v_mfma_f32_16x16x32_bf16 v[50:53], v[194:197], v[202:205], v[50:53]
	v_mfma_f32_16x16x32_bf16 v[38:41], v[186:189], v[210:213], v[38:41]
	v_mfma_f32_16x16x32_bf16 v[34:37], v[194:197], v[210:213], v[34:37]
	v_mfma_f32_16x16x32_bf16 v[22:25], v[186:189], v[218:221], v[22:25]
	v_mfma_f32_16x16x32_bf16 v[18:21], v[194:197], v[218:221], v[18:21]
	v_mfma_f32_16x16x32_bf16 v[6:9], v[186:189], v[226:229], v[6:9]
	v_mfma_f32_16x16x32_bf16 v[2:5], v[194:197], v[226:229], v[2:5]
	v_mfma_f32_16x16x32_bf16 v[54:57], v[190:193], v[206:209], v[54:57]
	v_mfma_f32_16x16x32_bf16 v[50:53], v[198:201], v[206:209], v[50:53]
	v_mfma_f32_16x16x32_bf16 v[38:41], v[190:193], v[214:217], v[38:41]
	v_mfma_f32_16x16x32_bf16 v[34:37], v[198:201], v[214:217], v[34:37]
	v_mfma_f32_16x16x32_bf16 v[22:25], v[190:193], v[222:225], v[22:25]
	v_mfma_f32_16x16x32_bf16 v[18:21], v[198:201], v[222:225], v[18:21]
	v_mfma_f32_16x16x32_bf16 v[6:9], v[190:193], v[230:233], v[6:9]
	v_mfma_f32_16x16x32_bf16 v[2:5], v[198:201], v[230:233], v[2:5]
	s_setprio 0
	s_barrier
	s_add_i32 s57, s57, 2
	s_add_u32 s24, s24, 0x100
	s_addc_u32 s25, s25, 0
	s_add_u32 s55, s55, 0x100
	s_addc_u32 s56, s56, 0
	s_cmp_gt_u32 s57, 13

; #define PG8_STAGE(bufoff, gbase, voff) do { _Pragma("unroll") for (int _i = 0; _i < 2; ++_i) \
;         __builtin_amdgcn_global_load_lds((const unsigned*)((const char*)(gbase) + (voff)[_i]), (PG8_LAS unsigned*)(lds + (bufoff) + ldsw + _i * 8192), 16, 0, 0); } while (0)
; #define PG8_WAIT_V(n) asm volatile("s_waitcnt vmcnt(" #n ")" ::: "memory")
; #define PG8_BAR __builtin_amdgcn_s_barrier()
; template <class Epi, class Sched, bool ALIGN_EPI = false, bool SP2 = false>
; __device__ __forceinline__ void gemm_phase(PG8_LAS unsigned char* lds, const Gemm g, const Sched& S, const Epi& E) {
;     int tid_ = threadIdx.x; asm volatile("" : "+v"(tid_));
;     const int tid = tid_, wid = __builtin_amdgcn_readfirstlane(tid >> 6), lane = tid & 63, wr = wid >> 2, wc = wid & 3, fr = lane & 15, fq = lane >> 4;
;     const int K = g.K, nt = K / BK;
;     unsigned voffA[2], voffB[2];
; #pragma unroll
;     for (int i = 0; i < 2; ++i) { int R, C; stage_rc(tid * 16 + i * 8192, R, C); const int Rb = Epi::PERM ? ((R & ~31) + perm32(R & 31)) : R;
;         voffA[i] = (unsigned)(R * g.lda + C) * 2u; voffB[i] = (unsigned)(Rb * g.ldb + C) * 2u; }
;     const size_t kstep = (size_t)(BK * 2);
;     const size_t hstepA = (size_t)HALF * g.lda * 2, hstepB = (size_t)HALF * g.ldb * 2;
;     const size_t tstepA = 2 * hstepA, tstepB = 2 * hstepB;
;     const unsigned ldsw = (unsigned)wid * 1024u;
;     const int aoff = lds_byte(wr * 64 + fr, fq * 8), boff = lds_byte(wc * 32 + fr, fq * 8);
;     ...
;     const char* cA = (const char*)g.A + (size_t)cur.g * g.gsA * 2 + (size_t)cur.pm * tstepA; const char* cB = (const char*)g.Bt + (size_t)cur.g * g.gsB * 2 + (size_t)cur.pn * tstepB;
;     S.a_ready(cur);
;     if constexpr (SP2) {
;         PG8_STAGE(PG8_SB(0, 0), cB, voffB); PG8_STAGE(PG8_SB(0, 1), cB + hstepB, voffB); PG8_STAGE(PG8_SA(0, 0), cA, voffA); PG8_STAGE(PG8_SA(0, 1), cA + hstepA, voffA);
;         if (wr == 1) PG8_BAR;
;         PG8_WAIT_V(2); PG8_BAR;
;         PG8_STAGE(PG8_SB(1, 0), cB + kstep, voffB); PG8_STAGE(PG8_SA(1, 0), cA + kstep, voffA); PG8_STAGE(PG8_SB(1, 1), cB + hstepB + kstep, voffB);
;         PG8_WAIT_V(6); PG8_BAR;
.LBB0_1457:
	s_add_u32 s12, s78, 0xfc00000
	s_addc_u32 s13, s79, 0
	s_add_u32 s14, s78, 0x5800000
	s_mov_b64 s[16:17], 0x80
	s_addc_u32 s15, s79, 0
	s_and_b32 s42, s6, 3
	s_add_i32 m0, s1, 0x18000
	v_lshl_add_u64 v[8:9], v[8:9], 0, s[16:17]
	s_lshl_b32 s6, s7, 13
	s_lshl_b32 s9, s42, 12
	s_waitcnt vmcnt(2)
	s_barrier
	global_load_lds_dwordx4 v[8:9], off
	v_lshl_add_u64 v[6:7], v[6:7], 0, s[16:17]
	s_add_i32 m0, s1, 0x1a000
	s_add_i32 s43, s1, 0x8000
	s_add_i32 s44, s1, 0xa000
	global_load_lds_dwordx4 v[6:7], off
	v_lshl_add_u64 v[2:3], v[2:3], 0, s[16:17]
	s_mov_b32 m0, s43
	s_add_u32 s18, s34, 0x40080
	global_load_lds_dwordx4 v[2:3], off
	v_lshl_add_u64 v[2:3], v[4:5], 0, s[16:17]
	s_mov_b32 m0, s44
	s_addc_u32 s19, s35, 0
	global_load_lds_dwordx4 v[2:3], off
	s_add_i32 m0, s1, 0x1c000
	v_lshl_add_u64 v[2:3], s[18:19], 0, v[140:141]
	global_load_lds_dwordx4 v[2:3], off
	v_lshl_add_u64 v[2:3], s[18:19], 0, v[144:145]
	s_add_i32 m0, s1, 0x1e000
	s_cmpk_lt_u32 s8, 0x100
	global_load_lds_dwordx4 v[2:3], off
	v_bfe_u32 v2, v10, 4, 2
	v_and_b32_e32 v3, 15, v10
	v_lshlrev_b32_e32 v5, 4, v2
	v_lshl_or_b32 v1, s7, 6, v3
	v_lshl_or_b32 v3, v3, 6, v5
	v_lshlrev_b32_e32 v5, 2, v10
	v_and_b32_e32 v5, 32, v5
	v_lshlrev_b32_e32 v4, 3, v2
	v_bitop3_b32 v6, v3, s6, v5 bitop3:0xde
	v_cmp_eq_u32_e64 s[6:7], 0, v2
	v_lshlrev_b32_e32 v2, 14, v11
	v_and_b32_e32 v2, 0xffff8000, v2
	v_bitop3_b32 v162, v3, s9, v5 bitop3:0xde
	v_lshl_add_u32 v2, v12, 11, v2
	v_and_b32_e32 v3, 1, v11
	v_lshl_or_b32 v2, v3, 6, v2
	v_lshl_add_u32 v146, v13, 1, v2
	v_lshlrev_b32_e32 v2, 14, v14
	v_and_b32_e32 v2, 0xffff8000, v2
	v_lshl_add_u32 v2, v15, 11, v2
	v_and_b32_e32 v3, 1, v14
	s_waitcnt vmcnt(6)
	v_lshl_or_b32 v2, v3, 6, v2
	s_cselect_b64 s[18:19], -1, 0
	v_lshl_add_u32 v148, v16, 1, v2
	s_add_i32 s48, 0, 0x10000
	s_add_i32 s49, 0, 0x14000
	v_mbcnt_lo_u32_b32 v2, -1, 0
	v_lshl_or_b32 v163, s42, 5, v4
	s_ashr_i32 s45, s82, 31
	s_mov_b32 s46, s82
	s_ashr_i32 s47, s96, 31
	v_mov_b32_e32 v147, v141
	v_mov_b32_e32 v149, v141
	v_mov_b64_e32 v[150:151], 0x200
	v_mov_b64_e32 v[152:153], 0x1ff
	v_add_u32_e32 v164, s48, v162
	v_add_u32_e32 v165, s49, v162
	v_add_u32_e32 v166, 0, v6
	v_mbcnt_hi_u32_b32 v167, -1, v2
	s_mov_b32 s50, 0
	s_barrier
	s_mov_b32 s98, 0
	s_branch .LBB0_1460

; #define PG8_STAGE(bufoff, gbase, voff) do { _Pragma("unroll") for (int _i = 0; _i < 2; ++_i) \
;         __builtin_amdgcn_global_load_lds((const unsigned*)((const char*)(gbase) + (voff)[_i]), (PG8_LAS unsigned*)(lds + (bufoff) + ldsw + _i * 8192), 16, 0, 0); } while (0)
; #define PG8_LDA(dst, b, h) do { _Pragma("unroll") for (int m = 0; m < 4; ++m) _Pragma("unroll") for (int k = 0; k < 2; ++k) dst[m][k] = *(const PG8_LAS bf16x8*)(lds + PG8_SA(b, h) + aoff + m * 2048 + k * 1024); } while (0)
; #define PG8_LDB(dst, b, h) do { _Pragma("unroll") for (int n = 0; n < 2; ++n) _Pragma("unroll") for (int k = 0; k < 2; ++k) dst[n][k] = *(const PG8_LAS bf16x8*)(lds + PG8_SB(b, h) + boff + n * 2048 + k * 1024); } while (0)
; #define PG8_WAIT_V(n) asm volatile("s_waitcnt vmcnt(" #n ")" ::: "memory")
; #define PG8_WAIT_L(n) asm volatile("s_waitcnt lgkmcnt(" #n ")" ::: "memory")
; #define PG8_BAR __builtin_amdgcn_s_barrier()
; template <class Epi, class Sched, bool ALIGN_EPI = false, bool SP2 = false>
; __device__ __forceinline__ void gemm_phase(PG8_LAS unsigned char* lds, const Gemm g, const Sched& S, const Epi& E) {
;     ...
;         const bool has_next = S.next(ui + 1, nxt);
;         const char* nA = has_next ? (const char*)g.A + (size_t)nxt.g * g.gsA * 2 + (size_t)nxt.pm * tstepA : cA; const char* nB = has_next ? (const char*)g.Bt + (size_t)nxt.g * g.gsB * 2 + (size_t)nxt.pn * tstepB : cB;
;         for (int t = 0; t < nt; t += 2) {
;             const bool last = (t == nt - 2);
;             const char* a1 = cA + (size_t)(t + 1) * kstep;
;             const char* a2 = last ? nA : cA + (size_t)(t + 2) * kstep; const char* b2 = last ? nB : cB + (size_t)(t + 2) * kstep;
;             const char* a3 = a2 + kstep; const char* b3 = b2 + kstep;
;             if (last && has_next) S.a_ready(nxt);
;             if constexpr (SP2) {
;             PG8_LDB(B0, 0, 0); PG8_LDB(B1, 0, 1); PG8_SCHED; PG8_LDA(At, 0, 0); PG8_STAGE(PG8_SA(1, 1), a1 + hstepA, voffA);
;             PG8_WAIT_V(8); PG8_WAIT_L(0); PG8_BAR; PG8_MMA(0, 0, At, B0); PG8_MMA(0, 1, At, B1); PG8_BAR; PG8_SCHED;
;             PG8_LDA(At, 0, 1); PG8_STAGE(PG8_SB(0, 0), b2, voffB); PG8_STAGE(PG8_SB(0, 1), b2 + hstepB, voffB); PG8_STAGE(PG8_SA(0, 0), a2, voffA);
;             PG8_WAIT_V(8); PG8_WAIT_L(0); PG8_BAR; PG8_MMA(1, 0, At, B0); PG8_MMA(1, 1, At, B1); PG8_BAR; PG8_SCHED;
.LBB0_1466:
	s_ashr_i32 s23, s22, 31
	s_lshl_b64 s[24:25], s[22:23], 19
	s_add_u32 s24, s2, s24
	s_addc_u32 s25, s3, s25
	s_and_b64 s[26:27], s[8:9], exec
	s_cselect_b32 s23, s25, s31
	s_cselect_b32 s29, s24, s30
	s_ashr_i32 s21, s20, 31
	s_lshl_b64 s[26:27], s[20:21], 19
	s_add_u32 s26, s33, s26
	s_addc_u32 s27, s38, s27
	s_and_b64 s[36:37], s[8:9], exec
	s_cselect_b32 s21, s27, s35
	s_cselect_b32 s51, s26, s34
	s_add_u32 s30, s30, 0x40080
	s_addc_u32 s31, s31, 0
	s_add_u32 s52, s34, 0x100
	s_addc_u32 s53, s35, 0
	s_mov_b32 s54, -2
	s_waitcnt lgkmcnt(0)
	s_cmp_eq_u32 s98, 1
	s_cbranch_scc0 .Lhb_50412
	s_mov_b32 s98, 0
	s_barrier
.Lhb_50412:
	ds_read_b128 v[130:133], v164
	ds_read_b128 v[134:137], v164 offset:1024
	ds_read_b128 v[154:157], v164 offset:2048
	ds_read_b128 v[158:161], v164 offset:3072
	ds_read_b128 v[168:171], v165
	ds_read_b128 v[172:175], v165 offset:1024
	ds_read_b128 v[176:179], v165 offset:2048
	ds_read_b128 v[180:183], v165 offset:3072
	s_add_u32 s34, s30, 0xfffc0080
	s_addc_u32 s35, s31, -1
	s_cmp_eq_u32 s54, 12
	s_cselect_b32 s37, s23, s35
	s_cselect_b32 s36, s29, s34
	s_cselect_b32 s35, s21, s53
	s_cselect_b32 s34, s51, s52
	v_lshl_add_u64 v[216:217], s[30:31], 0, v[146:147]
	s_add_i32 m0, s1, 0xc000
	ds_read_b128 v[184:187], v166
	ds_read_b128 v[188:191], v166 offset:1024
	ds_read_b128 v[192:195], v166 offset:2048
	ds_read_b128 v[196:199], v166 offset:3072
	ds_read_b128 v[200:203], v166 offset:4096
	ds_read_b128 v[204:207], v166 offset:5120
	ds_read_b128 v[208:211], v166 offset:6144
	ds_read_b128 v[212:215], v166 offset:7168
	global_load_lds_dwordx4 v[216:217], off
	v_lshl_add_u64 v[216:217], s[30:31], 0, v[148:149]
	s_add_i32 m0, s1, 0xe000
	s_nop 0
	global_load_lds_dwordx4 v[216:217], off
	s_waitcnt vmcnt(8)
	s_waitcnt lgkmcnt(0)
	s_barrier
	s_setprio 1
	s_waitcnt lgkmcnt(0)
	v_mfma_f32_16x16x32_bf16 v[126:129], v[130:133], v[184:187], 0
	v_mfma_f32_16x16x32_bf16 v[122:125], v[154:157], v[184:187], 0
	v_mfma_f32_16x16x32_bf16 v[110:113], v[130:133], v[192:195], 0
	v_mfma_f32_16x16x32_bf16 v[106:109], v[154:157], v[192:195], 0
	v_mfma_f32_16x16x32_bf16 v[94:97], v[130:133], v[200:203], 0
	v_mfma_f32_16x16x32_bf16 v[90:93], v[154:157], v[200:203], 0
	v_mfma_f32_16x16x32_bf16 v[78:81], v[130:133], v[208:211], 0
	v_mfma_f32_16x16x32_bf16 v[74:77], v[154:157], v[208:211], 0
	v_mfma_f32_16x16x32_bf16 v[126:129], v[134:137], v[188:191], v[126:129]
	v_mfma_f32_16x16x32_bf16 v[122:125], v[158:161], v[188:191], v[122:125]
	v_mfma_f32_16x16x32_bf16 v[110:113], v[134:137], v[196:199], v[110:113]
	v_mfma_f32_16x16x32_bf16 v[106:109], v[158:161], v[196:199], v[106:109]
	v_mfma_f32_16x16x32_bf16 v[94:97], v[134:137], v[204:207], v[94:97]
	v_mfma_f32_16x16x32_bf16 v[90:93], v[158:161], v[204:207], v[90:93]
	v_mfma_f32_16x16x32_bf16 v[78:81], v[134:137], v[212:215], v[78:81]
	v_mfma_f32_16x16x32_bf16 v[74:77], v[158:161], v[212:215], v[74:77]
	s_setprio 0
	s_setprio 1
	v_mfma_f32_16x16x32_bf16 v[118:121], v[168:171], v[184:187], 0
	v_mfma_f32_16x16x32_bf16 v[114:117], v[176:179], v[184:187], 0
	v_mfma_f32_16x16x32_bf16 v[102:105], v[168:171], v[192:195], 0
	v_mfma_f32_16x16x32_bf16 v[98:101], v[176:179], v[192:195], 0
	v_mfma_f32_16x16x32_bf16 v[86:89], v[168:171], v[200:203], 0
	v_mfma_f32_16x16x32_bf16 v[82:85], v[176:179], v[200:203], 0
	v_mfma_f32_16x16x32_bf16 v[70:73], v[168:171], v[208:211], 0
	v_mfma_f32_16x16x32_bf16 v[66:69], v[176:179], v[208:211], 0
	v_mfma_f32_16x16x32_bf16 v[118:121], v[172:175], v[188:191], v[118:121]
	v_mfma_f32_16x16x32_bf16 v[114:117], v[180:183], v[188:191], v[114:117]
	v_mfma_f32_16x16x32_bf16 v[102:105], v[172:175], v[196:199], v[102:105]
	v_mfma_f32_16x16x32_bf16 v[98:101], v[180:183], v[196:199], v[98:101]
	v_mfma_f32_16x16x32_bf16 v[86:89], v[172:175], v[204:207], v[86:89]
	v_mfma_f32_16x16x32_bf16 v[82:85], v[180:183], v[204:207], v[82:85]
	v_mfma_f32_16x16x32_bf16 v[70:73], v[172:175], v[212:215], v[70:73]
	v_mfma_f32_16x16x32_bf16 v[66:69], v[180:183], v[212:215], v[66:69]
	s_setprio 0
	s_barrier
	s_add_i32 s55, s48, s0
	v_lshl_add_u64 v[216:217], s[34:35], 0, v[140:141]
	s_mov_b32 m0, s55
	ds_read_b128 v[184:187], v166 offset:16384
	ds_read_b128 v[188:191], v166 offset:17408
	ds_read_b128 v[192:195], v166 offset:18432
	ds_read_b128 v[196:199], v166 offset:19456
	ds_read_b128 v[200:203], v166 offset:20480
	ds_read_b128 v[204:207], v166 offset:21504
	ds_read_b128 v[208:211], v166 offset:22528
	ds_read_b128 v[212:215], v166 offset:23552
	global_load_lds_dwordx4 v[216:217], off
	s_add_i32 m0, s55, 0x2000
	s_add_u32 s56, s34, 0x40000
	v_lshl_add_u64 v[218:219], s[34:35], 0, v[144:145]
	s_addc_u32 s57, s35, 0
	s_add_i32 s55, s49, s0
	global_load_lds_dwordx4 v[218:219], off
	v_lshl_add_u64 v[220:221], s[56:57], 0, v[140:141]
	s_mov_b32 m0, s55
	v_lshl_add_u64 v[222:223], s[36:37], 0, v[142:143]
	global_load_lds_dwordx4 v[220:221], off
	v_lshl_add_u64 v[220:221], s[56:57], 0, v[144:145]
	s_add_i32 m0, s55, 0x2000
	s_nop 0
	global_load_lds_dwordx4 v[220:221], off
	v_lshl_add_u64 v[220:221], s[36:37], 0, v[138:139]
	s_mov_b32 m0, s1
	s_nop 0
	global_load_lds_dwordx4 v[220:221], off
	s_mov_b32 m0, s39
	s_nop 0
	global_load_lds_dwordx4 v[222:223], off
	s_waitcnt vmcnt(8)
	s_waitcnt lgkmcnt(0)
	s_barrier
; #define PG8_STAGE(bufoff, gbase, voff) do { _Pragma("unroll") for (int _i = 0; _i < 2; ++_i) \
;         __builtin_amdgcn_global_load_lds((const unsigned*)((const char*)(gbase) + (voff)[_i]), (PG8_LAS unsigned*)(lds + (bufoff) + ldsw + _i * 8192), 16, 0, 0); } while (0)
; #define PG8_LDA(dst, b, h) do { _Pragma("unroll") for (int m = 0; m < 4; ++m) _Pragma("unroll") for (int k = 0; k < 2; ++k) dst[m][k] = *(const PG8_LAS bf16x8*)(lds + PG8_SA(b, h) + aoff + m * 2048 + k * 1024); } while (0)
; #define PG8_LDB(dst, b, h) do { _Pragma("unroll") for (int n = 0; n < 2; ++n) _Pragma("unroll") for (int k = 0; k < 2; ++k) dst[n][k] = *(const PG8_LAS bf16x8*)(lds + PG8_SB(b, h) + boff + n * 2048 + k * 1024); } while (0)
; #define PG8_MMA(ai, bj, At, Bt) do { __builtin_amdgcn_s_setprio(1); _Pragma("unroll") for (int m = 0; m < 4; ++m) _Pragma("unroll") for (int n = 0; n < 2; ++n) _Pragma("unroll") for (int k = 0; k < 2; ++k) \
;         acc[ai][bj][m][n] = __builtin_amdgcn_mfma_f32_16x16x32_bf16(Bt[n][k], At[m][k], acc[ai][bj][m][n], 0, 0, 0); __builtin_amdgcn_s_setprio(0); } while (0)
; #define PG8_WAIT_V(n) asm volatile("s_waitcnt vmcnt(" #n ")" ::: "memory")
; #define PG8_WAIT_L(n) asm volatile("s_waitcnt lgkmcnt(" #n ")" ::: "memory")
; #define PG8_BAR __builtin_amdgcn_s_barrier()
; #define PG8_SCHED __builtin_amdgcn_sched_barrier(0)
; template <class Epi, class Sched, bool ALIGN_EPI = false, bool SP2 = false>
; __device__ __forceinline__ void gemm_phase(PG8_LAS unsigned char* lds, const Gemm g, const Sched& S, const Epi& E) {
;     ...
;             PG8_WAIT_V(8); PG8_WAIT_L(0); PG8_BAR; PG8_MMA(0, 0, At, B0); PG8_MMA(0, 1, At, B1); PG8_BAR; PG8_SCHED;
;             PG8_LDA(At, 0, 1); PG8_STAGE(PG8_SB(0, 0), b2, voffB); PG8_STAGE(PG8_SB(0, 1), b2 + hstepB, voffB); PG8_STAGE(PG8_SA(0, 0), a2, voffA);
;             PG8_WAIT_V(8); PG8_WAIT_L(0); PG8_BAR; PG8_MMA(1, 0, At, B0); PG8_MMA(1, 1, At, B1); PG8_BAR; PG8_SCHED;
;             PG8_LDB(B0, 1, 0); PG8_LDB(B1, 1, 1); PG8_SCHED; PG8_LDA(At, 1, 0); PG8_STAGE(PG8_SA(0, 1), a2 + hstepA, voffA);
;             PG8_WAIT_V(8); PG8_WAIT_L(0); PG8_BAR; PG8_MMA(0, 0, At, B0); PG8_MMA(0, 1, At, B1); PG8_BAR; PG8_SCHED;
;             PG8_LDA(At, 1, 1); PG8_STAGE(PG8_SB(1, 0), b3, voffB); PG8_STAGE(PG8_SB(1, 1), b3 + hstepB, voffB); PG8_STAGE(PG8_SA(1, 0), a3, voffA);
	s_setprio 1
	s_waitcnt lgkmcnt(0)
	v_mfma_f32_16x16x32_bf16 v[62:65], v[130:133], v[184:187], 0
	v_mfma_f32_16x16x32_bf16 v[58:61], v[154:157], v[184:187], 0
	v_mfma_f32_16x16x32_bf16 v[46:49], v[130:133], v[192:195], 0
	v_mfma_f32_16x16x32_bf16 v[42:45], v[154:157], v[192:195], 0
	v_mfma_f32_16x16x32_bf16 v[30:33], v[130:133], v[200:203], 0
	v_mfma_f32_16x16x32_bf16 v[26:29], v[154:157], v[200:203], 0
	v_mfma_f32_16x16x32_bf16 v[14:17], v[130:133], v[208:211], 0
	v_mfma_f32_16x16x32_bf16 v[10:13], v[154:157], v[208:211], 0
	v_mfma_f32_16x16x32_bf16 v[62:65], v[134:137], v[188:191], v[62:65]
	v_mfma_f32_16x16x32_bf16 v[58:61], v[158:161], v[188:191], v[58:61]
	v_mfma_f32_16x16x32_bf16 v[46:49], v[134:137], v[196:199], v[46:49]
	v_mfma_f32_16x16x32_bf16 v[42:45], v[158:161], v[196:199], v[42:45]
	v_mfma_f32_16x16x32_bf16 v[30:33], v[134:137], v[204:207], v[30:33]
	v_mfma_f32_16x16x32_bf16 v[26:29], v[158:161], v[204:207], v[26:29]
	v_mfma_f32_16x16x32_bf16 v[14:17], v[134:137], v[212:215], v[14:17]
	v_mfma_f32_16x16x32_bf16 v[10:13], v[158:161], v[212:215], v[10:13]
	s_setprio 0
	s_setprio 1
	v_mfma_f32_16x16x32_bf16 v[54:57], v[168:171], v[184:187], 0
	v_mfma_f32_16x16x32_bf16 v[50:53], v[176:179], v[184:187], 0
	v_mfma_f32_16x16x32_bf16 v[38:41], v[168:171], v[192:195], 0
	v_mfma_f32_16x16x32_bf16 v[34:37], v[176:179], v[192:195], 0
	v_mfma_f32_16x16x32_bf16 v[22:25], v[168:171], v[200:203], 0
	v_mfma_f32_16x16x32_bf16 v[18:21], v[176:179], v[200:203], 0
	v_mfma_f32_16x16x32_bf16 v[6:9], v[168:171], v[208:211], 0
	v_mfma_f32_16x16x32_bf16 v[2:5], v[176:179], v[208:211], 0
	v_mfma_f32_16x16x32_bf16 v[54:57], v[172:175], v[188:191], v[54:57]
	v_mfma_f32_16x16x32_bf16 v[50:53], v[180:183], v[188:191], v[50:53]
	v_mfma_f32_16x16x32_bf16 v[38:41], v[172:175], v[196:199], v[38:41]
	v_mfma_f32_16x16x32_bf16 v[34:37], v[180:183], v[196:199], v[34:37]
	v_mfma_f32_16x16x32_bf16 v[22:25], v[172:175], v[204:207], v[22:25]
	v_mfma_f32_16x16x32_bf16 v[18:21], v[180:183], v[204:207], v[18:21]
	v_mfma_f32_16x16x32_bf16 v[6:9], v[172:175], v[212:215], v[6:9]
	v_mfma_f32_16x16x32_bf16 v[2:5], v[180:183], v[212:215], v[2:5]
	s_setprio 0
	s_barrier
	s_add_i32 s55, 0, 0x18000
	s_add_i32 s56, 0, 0x1c000
	v_add_u32_e32 v158, s55, v162
	v_add_u32_e32 v180, s56, v162
	ds_read_b128 v[130:133], v158
	ds_read_b128 v[134:137], v158 offset:1024
	ds_read_b128 v[154:157], v158 offset:2048
	ds_read_b128 v[158:161], v158 offset:3072
	ds_read_b128 v[168:171], v180
	ds_read_b128 v[172:175], v180 offset:1024
	ds_read_b128 v[176:179], v180 offset:2048
	ds_read_b128 v[180:183], v180 offset:3072
	s_add_u32 s36, s36, 0x40000
	s_addc_u32 s37, s37, 0
	s_mov_b32 m0, s40
	v_lshl_add_u64 v[224:225], s[36:37], 0, v[138:139]
	ds_read_b128 v[184:187], v166 offset:32768
	ds_read_b128 v[188:191], v166 offset:33792
	ds_read_b128 v[192:195], v166 offset:34816
	ds_read_b128 v[196:199], v166 offset:35840
	ds_read_b128 v[200:203], v166 offset:36864
	ds_read_b128 v[204:207], v166 offset:37888
	ds_read_b128 v[208:211], v166 offset:38912
	ds_read_b128 v[212:215], v166 offset:39936
	global_load_lds_dwordx4 v[224:225], off
	v_lshl_add_u64 v[224:225], s[36:37], 0, v[142:143]
	s_mov_b32 m0, s41
	s_nop 0
	global_load_lds_dwordx4 v[224:225], off
	s_waitcnt vmcnt(8)
	s_waitcnt lgkmcnt(0)
	s_barrier
	s_setprio 1
	s_waitcnt lgkmcnt(0)
	v_mfma_f32_16x16x32_bf16 v[126:129], v[130:133], v[184:187], v[126:129]
	v_mfma_f32_16x16x32_bf16 v[122:125], v[154:157], v[184:187], v[122:125]
	v_mfma_f32_16x16x32_bf16 v[110:113], v[130:133], v[192:195], v[110:113]
	v_mfma_f32_16x16x32_bf16 v[106:109], v[154:157], v[192:195], v[106:109]
	v_mfma_f32_16x16x32_bf16 v[94:97], v[130:133], v[200:203], v[94:97]
	v_mfma_f32_16x16x32_bf16 v[90:93], v[154:157], v[200:203], v[90:93]
	v_mfma_f32_16x16x32_bf16 v[78:81], v[130:133], v[208:211], v[78:81]
	v_mfma_f32_16x16x32_bf16 v[74:77], v[154:157], v[208:211], v[74:77]
	v_mfma_f32_16x16x32_bf16 v[126:129], v[134:137], v[188:191], v[126:129]
	v_mfma_f32_16x16x32_bf16 v[122:125], v[158:161], v[188:191], v[122:125]
	v_mfma_f32_16x16x32_bf16 v[110:113], v[134:137], v[196:199], v[110:113]
	v_mfma_f32_16x16x32_bf16 v[106:109], v[158:161], v[196:199], v[106:109]
	v_mfma_f32_16x16x32_bf16 v[94:97], v[134:137], v[204:207], v[94:97]
	v_mfma_f32_16x16x32_bf16 v[90:93], v[158:161], v[204:207], v[90:93]
	v_mfma_f32_16x16x32_bf16 v[78:81], v[134:137], v[212:215], v[78:81]
	v_mfma_f32_16x16x32_bf16 v[74:77], v[158:161], v[212:215], v[74:77]
	s_setprio 0
	s_setprio 1
	v_mfma_f32_16x16x32_bf16 v[118:121], v[168:171], v[184:187], v[118:121]
	v_mfma_f32_16x16x32_bf16 v[114:117], v[176:179], v[184:187], v[114:117]
	v_mfma_f32_16x16x32_bf16 v[102:105], v[168:171], v[192:195], v[102:105]
	v_mfma_f32_16x16x32_bf16 v[98:101], v[176:179], v[192:195], v[98:101]
	v_mfma_f32_16x16x32_bf16 v[86:89], v[168:171], v[200:203], v[86:89]
	v_mfma_f32_16x16x32_bf16 v[82:85], v[176:179], v[200:203], v[82:85]
	v_mfma_f32_16x16x32_bf16 v[70:73], v[168:171], v[208:211], v[70:73]
	v_mfma_f32_16x16x32_bf16 v[66:69], v[176:179], v[208:211], v[66:69]
	v_mfma_f32_16x16x32_bf16 v[118:121], v[172:175], v[188:191], v[118:121]
	v_mfma_f32_16x16x32_bf16 v[114:117], v[180:183], v[188:191], v[114:117]
	v_mfma_f32_16x16x32_bf16 v[102:105], v[172:175], v[196:199], v[102:105]
	v_mfma_f32_16x16x32_bf16 v[98:101], v[180:183], v[196:199], v[98:101]
	v_mfma_f32_16x16x32_bf16 v[86:89], v[172:175], v[204:207], v[86:89]
	v_mfma_f32_16x16x32_bf16 v[82:85], v[180:183], v[204:207], v[82:85]
	v_mfma_f32_16x16x32_bf16 v[70:73], v[172:175], v[212:215], v[70:73]
	v_mfma_f32_16x16x32_bf16 v[66:69], v[180:183], v[212:215], v[66:69]
	s_setprio 0
	s_barrier
; #define PG8_STAGE(bufoff, gbase, voff) do { _Pragma("unroll") for (int _i = 0; _i < 2; ++_i) \
;         __builtin_amdgcn_global_load_lds((const unsigned*)((const char*)(gbase) + (voff)[_i]), (PG8_LAS unsigned*)(lds + (bufoff) + ldsw + _i * 8192), 16, 0, 0); } while (0)
; #define PG8_LDA(dst, b, h) do { _Pragma("unroll") for (int m = 0; m < 4; ++m) _Pragma("unroll") for (int k = 0; k < 2; ++k) dst[m][k] = *(const PG8_LAS bf16x8*)(lds + PG8_SA(b, h) + aoff + m * 2048 + k * 1024); } while (0)
; #define PG8_MMA(ai, bj, At, Bt) do { __builtin_amdgcn_s_setprio(1); _Pragma("unroll") for (int m = 0; m < 4; ++m) _Pragma("unroll") for (int n = 0; n < 2; ++n) _Pragma("unroll") for (int k = 0; k < 2; ++k) \
;         acc[ai][bj][m][n] = __builtin_amdgcn_mfma_f32_16x16x32_bf16(Bt[n][k], At[m][k], acc[ai][bj][m][n], 0, 0, 0); __builtin_amdgcn_s_setprio(0); } while (0)
; #define PG8_WAIT_V(n) asm volatile("s_waitcnt vmcnt(" #n ")" ::: "memory")
; #define PG8_WAIT_L(n) asm volatile("s_waitcnt lgkmcnt(" #n ")" ::: "memory")
; #define PG8_BAR __builtin_amdgcn_s_barrier()
; #define PG8_SCHED __builtin_amdgcn_sched_barrier(0)
; template <class Epi, class Sched, bool ALIGN_EPI = false, bool SP2 = false>
; __device__ __forceinline__ void gemm_phase(PG8_LAS unsigned char* lds, const Gemm g, const Sched& S, const Epi& E) {
;     ...
;             PG8_WAIT_V(8); PG8_WAIT_L(0); PG8_BAR; PG8_MMA(0, 0, At, B0); PG8_MMA(0, 1, At, B1); PG8_BAR; PG8_SCHED;
;             PG8_LDA(At, 1, 1); PG8_STAGE(PG8_SB(1, 0), b3, voffB); PG8_STAGE(PG8_SB(1, 1), b3 + hstepB, voffB); PG8_STAGE(PG8_SA(1, 0), a3, voffA);
;             PG8_WAIT_V(8); PG8_WAIT_L(0); PG8_BAR; PG8_MMA(1, 0, At, B0); PG8_MMA(1, 1, At, B1); PG8_BAR; PG8_SCHED;
	s_add_i32 s36, s55, s0
	v_lshl_add_u64 v[216:217], v[216:217], 0, s[16:17]
	s_mov_b32 m0, s36
	ds_read_b128 v[184:187], v166 offset:49152
	ds_read_b128 v[188:191], v166 offset:50176
	ds_read_b128 v[192:195], v166 offset:51200
	ds_read_b128 v[196:199], v166 offset:52224
	ds_read_b128 v[200:203], v166 offset:53248
	ds_read_b128 v[204:207], v166 offset:54272
	ds_read_b128 v[208:211], v166 offset:55296
	ds_read_b128 v[212:215], v166 offset:56320
	global_load_lds_dwordx4 v[216:217], off
	s_add_i32 m0, s36, 0x2000
	s_add_u32 s34, s34, 0x40080
	v_lshl_add_u64 v[216:217], v[218:219], 0, s[16:17]
	s_addc_u32 s35, s35, 0
	s_add_i32 s36, s56, s0
	global_load_lds_dwordx4 v[216:217], off
	v_lshl_add_u64 v[216:217], s[34:35], 0, v[140:141]
	s_mov_b32 m0, s36
	s_nop 0
	global_load_lds_dwordx4 v[216:217], off
	v_lshl_add_u64 v[216:217], s[34:35], 0, v[144:145]
	s_add_i32 m0, s36, 0x2000
	s_nop 0
	global_load_lds_dwordx4 v[216:217], off
	v_lshl_add_u64 v[216:217], v[220:221], 0, s[16:17]
	s_mov_b32 m0, s43
	s_nop 0
	global_load_lds_dwordx4 v[216:217], off
	v_lshl_add_u64 v[216:217], v[222:223], 0, s[16:17]
	s_mov_b32 m0, s44
	s_nop 0
	global_load_lds_dwordx4 v[216:217], off
	s_waitcnt vmcnt(8)
	s_waitcnt lgkmcnt(0)
	s_barrier
	s_setprio 1
	s_waitcnt lgkmcnt(0)
	v_mfma_f32_16x16x32_bf16 v[62:65], v[130:133], v[184:187], v[62:65]
	v_mfma_f32_16x16x32_bf16 v[58:61], v[154:157], v[184:187], v[58:61]
	v_mfma_f32_16x16x32_bf16 v[46:49], v[130:133], v[192:195], v[46:49]
	v_mfma_f32_16x16x32_bf16 v[42:45], v[154:157], v[192:195], v[42:45]
	v_mfma_f32_16x16x32_bf16 v[30:33], v[130:133], v[200:203], v[30:33]
	v_mfma_f32_16x16x32_bf16 v[26:29], v[154:157], v[200:203], v[26:29]
	v_mfma_f32_16x16x32_bf16 v[14:17], v[130:133], v[208:211], v[14:17]
	v_mfma_f32_16x16x32_bf16 v[10:13], v[154:157], v[208:211], v[10:13]
	v_mfma_f32_16x16x32_bf16 v[62:65], v[134:137], v[188:191], v[62:65]
	v_mfma_f32_16x16x32_bf16 v[58:61], v[158:161], v[188:191], v[58:61]
	v_mfma_f32_16x16x32_bf16 v[46:49], v[134:137], v[196:199], v[46:49]
	v_mfma_f32_16x16x32_bf16 v[42:45], v[158:161], v[196:199], v[42:45]
	v_mfma_f32_16x16x32_bf16 v[30:33], v[134:137], v[204:207], v[30:33]
	v_mfma_f32_16x16x32_bf16 v[26:29], v[158:161], v[204:207], v[26:29]
	v_mfma_f32_16x16x32_bf16 v[14:17], v[134:137], v[212:215], v[14:17]
	v_mfma_f32_16x16x32_bf16 v[10:13], v[158:161], v[212:215], v[10:13]
	s_setprio 0
	s_setprio 1
	v_mfma_f32_16x16x32_bf16 v[54:57], v[168:171], v[184:187], v[54:57]
	v_mfma_f32_16x16x32_bf16 v[50:53], v[176:179], v[184:187], v[50:53]
	v_mfma_f32_16x16x32_bf16 v[38:41], v[168:171], v[192:195], v[38:41]
	v_mfma_f32_16x16x32_bf16 v[34:37], v[176:179], v[192:195], v[34:37]
	v_mfma_f32_16x16x32_bf16 v[22:25], v[168:171], v[200:203], v[22:25]
	v_mfma_f32_16x16x32_bf16 v[18:21], v[176:179], v[200:203], v[18:21]
	v_mfma_f32_16x16x32_bf16 v[6:9], v[168:171], v[208:211], v[6:9]
	v_mfma_f32_16x16x32_bf16 v[2:5], v[176:179], v[208:211], v[2:5]
	v_mfma_f32_16x16x32_bf16 v[54:57], v[172:175], v[188:191], v[54:57]
	v_mfma_f32_16x16x32_bf16 v[50:53], v[180:183], v[188:191], v[50:53]
	v_mfma_f32_16x16x32_bf16 v[38:41], v[172:175], v[196:199], v[38:41]
	v_mfma_f32_16x16x32_bf16 v[34:37], v[180:183], v[196:199], v[34:37]
	v_mfma_f32_16x16x32_bf16 v[22:25], v[172:175], v[204:207], v[22:25]
	v_mfma_f32_16x16x32_bf16 v[18:21], v[180:183], v[204:207], v[18:21]
	v_mfma_f32_16x16x32_bf16 v[6:9], v[172:175], v[212:215], v[6:9]
	v_mfma_f32_16x16x32_bf16 v[2:5], v[180:183], v[212:215], v[2:5]
	s_setprio 0
	s_barrier
	s_add_i32 s54, s54, 2
	s_add_u32 s30, s30, 0x100
	s_addc_u32 s31, s31, 0
	s_add_u32 s52, s52, 0x100
	s_addc_u32 s53, s53, 0
	s_cmp_gt_u32 s54, 13

; #define PG8_BAR __builtin_amdgcn_s_barrier()
; template <class Epi, class Sched, bool ALIGN_EPI = false, bool SP2 = false>
; __device__ __forceinline__ void gemm_phase(PG8_LAS unsigned char* lds, const Gemm g, const Sched& S, const Epi& E) {
;     ...
;         if constexpr (ALIGN_EPI) { if (wr == 0) PG8_BAR; }
;         if constexpr (!Epi::AFTER_DRAIN) { E(acc, cur, wr, wc, fr, fq); S.done(cur); }
;         if (!has_next) break;
; #pragma unroll
;         for (int a = 0; a < 2; ++a)
; #pragma unroll
;             for (int b = 0; b < 2; ++b)
; #pragma unroll
;                 for (int m = 0; m < 4; ++m)
; #pragma unroll
;                     for (int n = 0; n < 2; ++n) acc[a][b][m][n] = (f32x4){0.f, 0.f, 0.f, 0.f};
;         cur = nxt; cA = nA; cB = nB; ++ui;
;         if constexpr (ALIGN_EPI) { if (wr == 1) PG8_BAR; }
;     }
.LBB0_1486:
	s_or_b64 exec, exec, s[30:31]
	s_andn2_b64 vcc, exec, s[8:9]
	s_mov_b64 s[8:9], -1
	s_cbranch_vccnz .LBB0_1459
	s_andn2_b64 vcc, exec, s[10:11]
	s_cbranch_vccnz .LBB0_1458
	s_mov_b32 s98, 1
	s_branch .LBB0_1458

; #define PG8_STAGE(bufoff, gbase, voff) do { _Pragma("unroll") for (int _i = 0; _i < 2; ++_i) \
;         __builtin_amdgcn_global_load_lds((const unsigned*)((const char*)(gbase) + (voff)[_i]), (PG8_LAS unsigned*)(lds + (bufoff) + ldsw + _i * 8192), 16, 0, 0); } while (0)
; #define PG8_WAIT_V(n) asm volatile("s_waitcnt vmcnt(" #n ")" ::: "memory")
; #define PG8_BAR __builtin_amdgcn_s_barrier()
; template <class Epi, class Sched, bool ALIGN_EPI = false, bool SP2 = false>
; __device__ __forceinline__ void gemm_phase(PG8_LAS unsigned char* lds, const Gemm g, const Sched& S, const Epi& E) {
;     int tid_ = threadIdx.x; asm volatile("" : "+v"(tid_));
;     const int tid = tid_, wid = __builtin_amdgcn_readfirstlane(tid >> 6), lane = tid & 63, wr = wid >> 2, wc = wid & 3, fr = lane & 15, fq = lane >> 4;
;     const int K = g.K, nt = K / BK;
;     unsigned voffA[2], voffB[2];
; #pragma unroll
;     for (int i = 0; i < 2; ++i) { int R, C; stage_rc(tid * 16 + i * 8192, R, C); const int Rb = Epi::PERM ? ((R & ~31) + perm32(R & 31)) : R;
;         voffA[i] = (unsigned)(R * g.lda + C) * 2u; voffB[i] = (unsigned)(Rb * g.ldb + C) * 2u; }
;     const size_t kstep = (size_t)(BK * 2);
;     const size_t hstepA = (size_t)HALF * g.lda * 2, hstepB = (size_t)HALF * g.ldb * 2;
;     const size_t tstepA = 2 * hstepA, tstepB = 2 * hstepB;
;     const unsigned ldsw = (unsigned)wid * 1024u;
;     const int aoff = lds_byte(wr * 64 + fr, fq * 8), boff = lds_byte(wc * 32 + fr, fq * 8);
;     ...
;     const char* cA = (const char*)g.A + (size_t)cur.g * g.gsA * 2 + (size_t)cur.pm * tstepA; const char* cB = (const char*)g.Bt + (size_t)cur.g * g.gsB * 2 + (size_t)cur.pn * tstepB;
;     S.a_ready(cur);
;     if constexpr (SP2) {
;         PG8_STAGE(PG8_SB(0, 0), cB, voffB); PG8_STAGE(PG8_SB(0, 1), cB + hstepB, voffB); PG8_STAGE(PG8_SA(0, 0), cA, voffA); PG8_STAGE(PG8_SA(0, 1), cA + hstepA, voffA);
;         if (wr == 1) PG8_BAR;
;         PG8_WAIT_V(2); PG8_BAR;
;         PG8_STAGE(PG8_SB(1, 0), cB + kstep, voffB); PG8_STAGE(PG8_SA(1, 0), cA + kstep, voffA); PG8_STAGE(PG8_SB(1, 1), cB + hstepB + kstep, voffB);
;         PG8_WAIT_V(6); PG8_BAR;
.LBB0_1547:
	s_add_u32 s8, s78, 0x13c00000
	s_addc_u32 s9, s79, 0
	s_lshl_b32 s10, s10, 5
	s_and_b32 s16, s10, 0x60
	s_mov_b64 s[10:11], 0x80
	s_add_i32 m0, s23, 0x18000
	v_lshl_add_u64 v[8:9], v[8:9], 0, s[10:11]
	s_lshl_b32 s13, s12, 13
	s_lshl_b32 s17, s16, 7
	s_waitcnt vmcnt(2)
	s_barrier
	global_load_lds_dwordx4 v[8:9], off
	v_lshl_add_u64 v[6:7], v[6:7], 0, s[10:11]
	s_add_i32 m0, s23, 0x1a000
	s_add_i32 s38, s23, 0x8000
	s_add_i32 s39, s23, 0xa000
	global_load_lds_dwordx4 v[6:7], off
	v_lshl_add_u64 v[2:3], v[2:3], 0, s[10:11]
	s_mov_b32 m0, s38
	s_add_u32 s14, s26, 0x40080
	global_load_lds_dwordx4 v[2:3], off
	v_lshl_add_u64 v[2:3], v[4:5], 0, s[10:11]
	s_mov_b32 m0, s39
	s_addc_u32 s15, s27, 0
	global_load_lds_dwordx4 v[2:3], off
	s_add_i32 m0, s23, 0x1c000
	v_lshl_add_u64 v[2:3], s[14:15], 0, v[134:135]
	global_load_lds_dwordx4 v[2:3], off
	v_lshl_add_u64 v[2:3], s[14:15], 0, v[130:131]
	s_add_i32 m0, s23, 0x1e000
	v_bfe_u32 v4, v12, 4, 2
	global_load_lds_dwordx4 v[2:3], off
	v_and_b32_e32 v3, 15, v12
	v_lshlrev_b32_e32 v2, 4, v4
	v_lshlrev_b32_e32 v5, 2, v12
	v_lshl_or_b32 v1, s12, 6, v3
	v_lshl_or_b32 v3, v3, 6, v2
	v_and_b32_e32 v5, 32, v5
	v_bitop3_b32 v6, v3, s13, v5 bitop3:0xde
	v_bitop3_b32 v166, v3, s17, v5 bitop3:0xde
	v_mov_b32_e32 v3, v135
	s_sext_i32_i8 s45, s6
	s_cmpk_lt_u32 s7, 0x100
	v_lshl_add_u64 v[2:3], s[78:79], 0, v[2:3]
	s_mov_b64 s[6:7], 0x5800000
	v_lshl_add_u64 v[138:139], v[2:3], 0, s[6:7]
	v_lshlrev_b32_e32 v2, 14, v15
	v_and_b32_e32 v2, 0xffff8000, v2
	v_lshl_add_u32 v2, v14, 11, v2
	v_and_b32_e32 v3, 1, v15
	v_lshl_or_b32 v2, v3, 6, v2
	v_lshl_add_u32 v140, v16, 1, v2
	v_lshlrev_b32_e32 v2, 14, v10
	v_and_b32_e32 v2, 0xffff8000, v2
	v_lshl_add_u32 v2, v11, 11, v2
	v_and_b32_e32 v3, 1, v10
	s_waitcnt vmcnt(6)
	v_lshl_or_b32 v2, v3, 6, v2
	s_cselect_b64 s[12:13], -1, 0
	v_lshl_add_u32 v142, v13, 1, v2
	s_add_i32 s42, 0, 0x10000
	s_add_i32 s43, 0, 0x14000
	v_mbcnt_lo_u32_b32 v2, -1, 0
	s_ashr_i32 s40, s82, 31
	s_mov_b32 s41, s82
	v_lshl_or_b32 v167, v4, 3, s16
	v_mov_b32_e32 v141, v135
	v_mov_b32_e32 v143, v135
	v_mov_b64_e32 v[144:145], 0xb00
	v_mov_b64_e32 v[146:147], 0xaff
	v_add_u32_e32 v168, s42, v166
	v_add_u32_e32 v169, s43, v166
	v_add_u32_e32 v170, 0, v6
	v_mbcnt_hi_u32_b32 v171, -1, v2
	v_mov_b32_e32 v172, 0x358637bd
	s_movk_i32 s44, 0x1600
	s_barrier
	s_mov_b32 s98, 0
	s_branch .LBB0_1550

; #define PG8_STAGE(bufoff, gbase, voff) do { _Pragma("unroll") for (int _i = 0; _i < 2; ++_i) \
;         __builtin_amdgcn_global_load_lds((const unsigned*)((const char*)(gbase) + (voff)[_i]), (PG8_LAS unsigned*)(lds + (bufoff) + ldsw + _i * 8192), 16, 0, 0); } while (0)
; #define PG8_WAIT_V(n) asm volatile("s_waitcnt vmcnt(" #n ")" ::: "memory")
; #define PG8_BAR __builtin_amdgcn_s_barrier()
; template <class Epi, class Sched, bool ALIGN_EPI = false, bool SP2 = false>
; __device__ __forceinline__ void gemm_phase(PG8_LAS unsigned char* lds, const Gemm g, const Sched& S, const Epi& E) {
;     int tid_ = threadIdx.x; asm volatile("" : "+v"(tid_));
;     const int tid = tid_, wid = __builtin_amdgcn_readfirstlane(tid >> 6), lane = tid & 63, wr = wid >> 2, wc = wid & 3, fr = lane & 15, fq = lane >> 4;
;     const int K = g.K, nt = K / BK;
;     unsigned voffA[2], voffB[2];
; #pragma unroll
;     for (int i = 0; i < 2; ++i) { int R, C; stage_rc(tid * 16 + i * 8192, R, C); const int Rb = Epi::PERM ? ((R & ~31) + perm32(R & 31)) : R;
;         voffA[i] = (unsigned)(R * g.lda + C) * 2u; voffB[i] = (unsigned)(Rb * g.ldb + C) * 2u; }
;     const size_t kstep = (size_t)(BK * 2);
;     const size_t hstepA = (size_t)HALF * g.lda * 2, hstepB = (size_t)HALF * g.ldb * 2;
;     const size_t tstepA = 2 * hstepA, tstepB = 2 * hstepB;
;     const unsigned ldsw = (unsigned)wid * 1024u;
;     const int aoff = lds_byte(wr * 64 + fr, fq * 8), boff = lds_byte(wc * 32 + fr, fq * 8);
;     ...
;     const char* cA = (const char*)g.A + (size_t)cur.g * g.gsA * 2 + (size_t)cur.pm * tstepA; const char* cB = (const char*)g.Bt + (size_t)cur.g * g.gsB * 2 + (size_t)cur.pn * tstepB;
;     S.a_ready(cur);
;     if constexpr (SP2) {
;         PG8_STAGE(PG8_SB(0, 0), cB, voffB); PG8_STAGE(PG8_SB(0, 1), cB + hstepB, voffB); PG8_STAGE(PG8_SA(0, 0), cA, voffA); PG8_STAGE(PG8_SA(0, 1), cA + hstepA, voffA);
;         if (wr == 1) PG8_BAR;
;         PG8_WAIT_V(2); PG8_BAR;
;         PG8_STAGE(PG8_SB(1, 0), cB + kstep, voffB); PG8_STAGE(PG8_SA(1, 0), cA + kstep, voffA); PG8_STAGE(PG8_SB(1, 1), cB + hstepB + kstep, voffB);
;         PG8_WAIT_V(6); PG8_BAR;
.LBB0_1624:
	s_add_u32 s16, s78, 0xfc00000
	s_addc_u32 s17, s79, 0
	s_add_u32 s18, s78, 0x5a00000
	s_mov_b64 s[20:21], 0x80
	s_addc_u32 s19, s79, 0
	s_and_b32 s40, s9, 3
	s_add_i32 m0, s1, 0x18000
	v_lshl_add_u64 v[8:9], v[8:9], 0, s[20:21]
	s_lshl_b32 s9, s10, 13
	s_lshl_b32 s11, s40, 12
	s_waitcnt vmcnt(2)
	s_barrier
	global_load_lds_dwordx4 v[8:9], off
	v_lshl_add_u64 v[6:7], v[6:7], 0, s[20:21]
	s_add_i32 m0, s1, 0x1a000
	s_add_i32 s41, s1, 0x8000
	s_add_i32 s42, s1, 0xa000
	global_load_lds_dwordx4 v[6:7], off
	v_lshl_add_u64 v[2:3], v[2:3], 0, s[20:21]
	s_mov_b32 m0, s41
	s_add_u32 s12, s28, 0xb0080
	global_load_lds_dwordx4 v[2:3], off
	v_lshl_add_u64 v[2:3], v[4:5], 0, s[20:21]
	s_mov_b32 m0, s42
	s_addc_u32 s13, s29, 0
	global_load_lds_dwordx4 v[2:3], off
	s_add_i32 m0, s1, 0x1c000
	v_lshl_add_u64 v[2:3], s[12:13], 0, v[140:141]
	global_load_lds_dwordx4 v[2:3], off
	v_lshl_add_u64 v[2:3], s[12:13], 0, v[144:145]
	s_add_i32 m0, s1, 0x1e000
	s_cmpk_lt_u32 s8, 0x100
	global_load_lds_dwordx4 v[2:3], off
	v_bfe_u32 v2, v10, 4, 2
	v_and_b32_e32 v3, 15, v10
	v_lshlrev_b32_e32 v5, 4, v2
	v_lshl_or_b32 v1, s10, 6, v3
	v_lshl_or_b32 v3, v3, 6, v5
	v_lshlrev_b32_e32 v5, 2, v10
	v_and_b32_e32 v5, 32, v5
	v_lshlrev_b32_e32 v4, 3, v2
	v_bitop3_b32 v6, v3, s9, v5 bitop3:0xde
	v_bitop3_b32 v162, v3, s11, v5 bitop3:0xde
	v_cmp_eq_u32_e64 s[8:9], 0, v2
	v_lshrrev_b32_e32 v3, 1, v11
	v_mul_lo_u32 v2, v13, s4
	s_mov_b32 s24, 0xb000
	v_mad_u64_u32 v[2:3], s[12:13], v3, s24, v[2:3]
	v_or_b32_e32 v2, v2, v12
	s_mov_b64 s[10:11], 0xb0080
	v_add_lshl_u32 v2, v2, v14, 1
	v_mov_b32_e32 v3, v141
	v_lshl_add_u64 v[146:147], v[2:3], 0, s[10:11]
	v_lshrrev_b32_e32 v3, 1, v15
	v_mul_lo_u32 v2, v16, s4
	v_mad_u64_u32 v[2:3], s[12:13], v3, s24, v[2:3]
	v_or_b32_e32 v2, v2, v17
	s_waitcnt vmcnt(6)
	v_add_lshl_u32 v2, v2, v18, 1
	v_mov_b32_e32 v3, v141
	s_cselect_b64 s[22:23], -1, 0
	v_lshl_add_u64 v[148:149], v[2:3], 0, s[10:11]
	s_add_i32 s46, 0, 0x10000
	s_add_i32 s47, 0, 0x14000
	v_mbcnt_lo_u32_b32 v2, -1, 0
	v_lshl_or_b32 v163, s40, 5, v4
	s_ashr_i32 s43, s82, 31
	s_mov_b32 s44, s82
	s_ashr_i32 s45, s96, 31
	v_mov_b64_e32 v[150:151], 0x200
	v_mov_b64_e32 v[152:153], 0x1ff
	v_add_u32_e32 v164, s46, v162
	v_add_u32_e32 v165, s47, v162
	v_add_u32_e32 v166, 0, v6
	v_mbcnt_hi_u32_b32 v167, -1, v2
	s_mov_b32 s48, 0
	s_barrier
	s_mov_b32 s98, 0
	s_branch .LBB0_1627

; #define PG8_STAGE(bufoff, gbase, voff) do { _Pragma("unroll") for (int _i = 0; _i < 2; ++_i) \
;         __builtin_amdgcn_global_load_lds((const unsigned*)((const char*)(gbase) + (voff)[_i]), (PG8_LAS unsigned*)(lds + (bufoff) + ldsw + _i * 8192), 16, 0, 0); } while (0)
; #define PG8_WAIT_V(n) asm volatile("s_waitcnt vmcnt(" #n ")" ::: "memory")
; #define PG8_BAR __builtin_amdgcn_s_barrier()
; template <class Epi, class Sched, bool ALIGN_EPI = false, bool SP2 = false>
; __device__ __forceinline__ void gemm_phase(PG8_LAS unsigned char* lds, const Gemm g, const Sched& S, const Epi& E) {
;     int tid_ = threadIdx.x; asm volatile("" : "+v"(tid_));
;     const int tid = tid_, wid = __builtin_amdgcn_readfirstlane(tid >> 6), lane = tid & 63, wr = wid >> 2, wc = wid & 3, fr = lane & 15, fq = lane >> 4;
;     const int K = g.K, nt = K / BK;
;     unsigned voffA[2], voffB[2];
; #pragma unroll
;     for (int i = 0; i < 2; ++i) { int R, C; stage_rc(tid * 16 + i * 8192, R, C); const int Rb = Epi::PERM ? ((R & ~31) + perm32(R & 31)) : R;
;         voffA[i] = (unsigned)(R * g.lda + C) * 2u; voffB[i] = (unsigned)(Rb * g.ldb + C) * 2u; }
;     const size_t kstep = (size_t)(BK * 2);
;     const size_t hstepA = (size_t)HALF * g.lda * 2, hstepB = (size_t)HALF * g.ldb * 2;
;     const size_t tstepA = 2 * hstepA, tstepB = 2 * hstepB;
;     const unsigned ldsw = (unsigned)wid * 1024u;
;     const int aoff = lds_byte(wr * 64 + fr, fq * 8), boff = lds_byte(wc * 32 + fr, fq * 8);
;     ...
;     const char* cA = (const char*)g.A + (size_t)cur.g * g.gsA * 2 + (size_t)cur.pm * tstepA; const char* cB = (const char*)g.Bt + (size_t)cur.g * g.gsB * 2 + (size_t)cur.pn * tstepB;
;     S.a_ready(cur);
;     if constexpr (SP2) {
;         PG8_STAGE(PG8_SB(0, 0), cB, voffB); PG8_STAGE(PG8_SB(0, 1), cB + hstepB, voffB); PG8_STAGE(PG8_SA(0, 0), cA, voffA); PG8_STAGE(PG8_SA(0, 1), cA + hstepA, voffA);
;         if (wr == 1) PG8_BAR;
;         PG8_WAIT_V(2); PG8_BAR;
;         PG8_STAGE(PG8_SB(1, 0), cB + kstep, voffB); PG8_STAGE(PG8_SA(1, 0), cA + kstep, voffA); PG8_STAGE(PG8_SB(1, 1), cB + hstepB + kstep, voffB);
;         PG8_WAIT_V(6); PG8_BAR;
.LBB0_1755:
	s_add_u32 s16, s78, 0xbc00000
	s_addc_u32 s17, s79, 0
	s_add_u32 s18, s78, 0x5800000
	s_addc_u32 s19, s79, 0
	s_add_u32 s20, s78, 0x7c00000
	s_mov_b64 s[22:23], 0x80
	s_addc_u32 s21, s79, 0
	s_and_b32 s49, s1, 3
	s_add_i32 m0, s44, 0x18000
	v_lshl_add_u64 v[8:9], v[8:9], 0, s[22:23]
	s_lshl_b32 s1, s2, 13
	s_lshl_b32 s5, s49, 12
	s_waitcnt vmcnt(2)
	s_barrier
	global_load_lds_dwordx4 v[8:9], off
	v_lshl_add_u64 v[6:7], v[6:7], 0, s[22:23]
	s_add_i32 m0, s44, 0x1a000
	s_add_i32 s50, s44, 0x8000
	s_add_i32 s51, s44, 0xa000
	global_load_lds_dwordx4 v[6:7], off
	v_lshl_add_u64 v[2:3], v[2:3], 0, s[22:23]
	s_mov_b32 m0, s50
	s_add_u32 s6, s38, 0x40080
	global_load_lds_dwordx4 v[2:3], off
	v_lshl_add_u64 v[2:3], v[4:5], 0, s[22:23]
	s_mov_b32 m0, s51
	s_addc_u32 s7, s39, 0
	global_load_lds_dwordx4 v[2:3], off
	s_add_i32 m0, s44, 0x1c000
	v_lshl_add_u64 v[2:3], s[6:7], 0, v[148:149]
	global_load_lds_dwordx4 v[2:3], off
	v_lshl_add_u64 v[2:3], s[6:7], 0, v[152:153]
	s_add_i32 m0, s44, 0x1e000
	v_bfe_u32 v4, v10, 4, 2
	global_load_lds_dwordx4 v[2:3], off
	v_and_b32_e32 v3, 15, v10
	v_lshlrev_b32_e32 v2, 4, v4
	v_lshlrev_b32_e32 v6, 2, v10
	v_lshl_or_b32 v1, s2, 6, v3
	v_lshl_or_b32 v3, v3, 6, v2
	v_and_b32_e32 v6, 32, v6
	v_bitop3_b32 v7, v3, s1, v6 bitop3:0xde
	v_bitop3_b32 v184, v3, s5, v6 bitop3:0xde
	v_mov_b32_e32 v3, v149
	s_cmpk_lt_u32 s0, 0x100
	v_lshl_add_u64 v[2:3], s[78:79], 0, v[2:3]
	s_mov_b64 s[0:1], 0x5a00000
	v_lshl_add_u64 v[154:155], v[2:3], 0, s[0:1]
	v_lshlrev_b32_e32 v2, 14, v11
	v_and_b32_e32 v2, 0xffff8000, v2
	v_lshl_add_u32 v2, v12, 11, v2
	v_and_b32_e32 v3, 1, v11
	v_lshl_or_b32 v2, v3, 6, v2
	v_lshl_add_u32 v156, v13, 1, v2
	v_lshlrev_b32_e32 v2, 14, v14
	v_and_b32_e32 v2, 0xffff8000, v2
	v_lshl_add_u32 v2, v15, 11, v2
	v_and_b32_e32 v3, 1, v14
	s_waitcnt vmcnt(6)
	v_lshl_or_b32 v2, v3, 6, v2
	v_lshlrev_b32_e32 v5, 3, v4
	s_cselect_b64 s[24:25], -1, 0
	v_lshl_add_u32 v158, v16, 1, v2
	s_add_i32 s55, 0, 0x10000
	s_add_i32 s56, 0, 0x14000
	v_mbcnt_lo_u32_b32 v2, -1, 0
	v_lshl_or_b32 v185, s49, 5, v5
	v_cmp_eq_u32_e64 s[6:7], 0, v4
	s_ashr_i32 s52, s82, 31
	s_mov_b32 s53, s82
	s_ashr_i32 s54, s96, 31
	v_mov_b32_e32 v157, v149
	v_mov_b32_e32 v159, v149
	v_mov_b64_e32 v[160:161], 0x200
	v_mov_b64_e32 v[162:163], 0x1ff
	v_add_u32_e32 v186, s55, v184
	v_add_u32_e32 v187, s56, v184
	v_add_u32_e32 v188, 0, v7
	v_mbcnt_hi_u32_b32 v189, -1, v2
	v_mov_b32_e32 v190, 0x358637bd
	s_mov_b32 s57, 0
	s_barrier
	s_mov_b32 s98, 0
	s_branch .LBB0_1758
